# v36 + lane^16/lane^32 all-reduce steps via v_permlane16/32_swap instead of ds_bpermute in GEMM epilogue row statistics and wave sums
# baseline (speedup 1.0000x reference)
; #define LAS __attribute__((address_space(3)))
; __device__ __forceinline__ void xprep_row(const f32x4 (&v)[8], const int m, LAS float* wf, bf16_t* XB, float* LOGF, const float* bfg, const int lane) {
;         unsigned* o4 = (unsigned*)((unsigned char*)XB + (size_t)m * DM) + lane;
; #pragma unroll
;         for (int j = 0; j < 8; ++j) o4[64 * j] = pg8::pack4i8(v[j] * ASC_XI8);
;         float f[8];
; #pragma unroll
;         for (int e = 0; e < 8; ++e) { float s = 0.f;
; #pragma unroll
;             for (int j = 0; j < 8; ++j) { const f32x4 w = *(const LAS f32x4*)(wf + e * 2048 + 256 * j + 4 * lane); s = fmaf(v[j][0], w[0], s); s = fmaf(v[j][1], w[1], s); s = fmaf(v[j][2], w[2], s); s = fmaf(v[j][3], w[3], s); }
;             f[e] = wave_sum(s); }
.LBB0_989:
	s_or_b64 exec, exec, s[28:29]
	ds_read_b128 v[98:101], v65
	ds_read_b128 v[102:105], v65 offset:1024
	s_waitcnt vmcnt(7) lgkmcnt(4)
	v_pk_mul_f32 v[88:89], v[2:3], s[26:27] op_sel_hi:[1,0]
	s_waitcnt lgkmcnt(3)
	v_pk_mul_f32 v[90:91], v[0:1], s[26:27] op_sel_hi:[1,0]
	v_med3_f32 v88, v88, s35, v85
	v_med3_f32 v75, v90, s35, v85
	v_med3_f32 v90, v91, s35, v85
	v_med3_f32 v89, v89, s35, v85
	v_ashrrev_i32_e32 v79, 31, v78
	v_add_f32_e32 v75, 0x4b400000, v75
	v_add_f32_e32 v90, 0x4b400000, v90
	v_add_f32_e32 v88, 0x4b400000, v88
	v_add_f32_e32 v89, 0x4b400000, v89
	v_lshlrev_b64 v[80:81], 11, v[78:79]
	v_perm_b32 v75, v90, v75, s36
	v_perm_b32 v88, v89, v88, s37
	v_lshl_add_u64 v[80:81], v[68:69], 0, v[80:81]
	v_or_b32_e32 v75, v75, v88
	s_waitcnt vmcnt(6)
	v_pk_mul_f32 v[88:89], v[6:7], s[26:27] op_sel_hi:[1,0]
	v_pk_mul_f32 v[90:91], v[4:5], s[26:27] op_sel_hi:[1,0]
	s_waitcnt lgkmcnt(1)
	v_fma_f32 v97, v0, v98, 0
	global_store_dword v[80:81], v75, off
	v_med3_f32 v75, v90, s35, v85
	v_med3_f32 v90, v91, s35, v85
	v_med3_f32 v88, v88, s35, v85
	v_med3_f32 v89, v89, s35, v85
	v_fmac_f32_e32 v97, v1, v99
	v_add_f32_e32 v75, 0x4b400000, v75
	v_add_f32_e32 v90, 0x4b400000, v90
	v_add_f32_e32 v88, 0x4b400000, v88
	v_add_f32_e32 v89, 0x4b400000, v89
	v_fmac_f32_e32 v97, v2, v100
	v_perm_b32 v75, v90, v75, s36
	v_perm_b32 v88, v89, v88, s37
	v_fmac_f32_e32 v97, v3, v101
	ds_read_b128 v[98:101], v65 offset:2048
	v_or_b32_e32 v75, v75, v88
	s_waitcnt vmcnt(6)
	v_pk_mul_f32 v[88:89], v[10:11], s[26:27] op_sel_hi:[1,0]
	v_pk_mul_f32 v[90:91], v[8:9], s[26:27] op_sel_hi:[1,0]
	s_waitcnt lgkmcnt(1)
	v_fmac_f32_e32 v97, v4, v102
	global_store_dword v[80:81], v75, off offset:256
	v_med3_f32 v75, v90, s35, v85
	v_med3_f32 v90, v91, s35, v85
	v_med3_f32 v88, v88, s35, v85
	v_med3_f32 v89, v89, s35, v85
	v_fmac_f32_e32 v97, v5, v103
	v_add_f32_e32 v75, 0x4b400000, v75
	v_add_f32_e32 v90, 0x4b400000, v90
	v_add_f32_e32 v88, 0x4b400000, v88
	v_add_f32_e32 v89, 0x4b400000, v89
	v_fmac_f32_e32 v97, v6, v104
	v_perm_b32 v75, v90, v75, s36
	v_perm_b32 v88, v89, v88, s37
	v_fmac_f32_e32 v97, v7, v105
	ds_read_b128 v[102:105], v65 offset:3072
	v_or_b32_e32 v75, v75, v88
	s_waitcnt vmcnt(6)
	v_pk_mul_f32 v[88:89], v[14:15], s[26:27] op_sel_hi:[1,0]
	v_pk_mul_f32 v[90:91], v[12:13], s[26:27] op_sel_hi:[1,0]
	s_waitcnt lgkmcnt(1)
	v_fmac_f32_e32 v97, v8, v98
	global_store_dword v[80:81], v75, off offset:512
	v_med3_f32 v75, v90, s35, v85
	v_med3_f32 v90, v91, s35, v85
	v_med3_f32 v88, v88, s35, v85
	v_med3_f32 v89, v89, s35, v85
	v_fmac_f32_e32 v97, v9, v99
	v_add_f32_e32 v75, 0x4b400000, v75
	v_add_f32_e32 v90, 0x4b400000, v90
	v_add_f32_e32 v88, 0x4b400000, v88
	v_add_f32_e32 v89, 0x4b400000, v89
	v_fmac_f32_e32 v97, v10, v100
	v_perm_b32 v75, v90, v75, s36
	v_perm_b32 v88, v89, v88, s37
	v_fmac_f32_e32 v97, v11, v101
	ds_read_b128 v[98:101], v65 offset:4096
	v_or_b32_e32 v75, v75, v88
	s_waitcnt vmcnt(6)
	v_pk_mul_f32 v[88:89], v[18:19], s[26:27] op_sel_hi:[1,0]
	v_pk_mul_f32 v[90:91], v[16:17], s[26:27] op_sel_hi:[1,0]
	s_waitcnt lgkmcnt(1)
	v_fmac_f32_e32 v97, v12, v102
	global_store_dword v[80:81], v75, off offset:768
	v_med3_f32 v75, v90, s35, v85
	v_med3_f32 v90, v91, s35, v85
	v_med3_f32 v88, v88, s35, v85
	v_med3_f32 v89, v89, s35, v85
	v_fmac_f32_e32 v97, v13, v103
	v_add_f32_e32 v75, 0x4b400000, v75
	v_add_f32_e32 v90, 0x4b400000, v90
	v_add_f32_e32 v88, 0x4b400000, v88
	v_add_f32_e32 v89, 0x4b400000, v89
	v_fmac_f32_e32 v97, v14, v104
	v_perm_b32 v75, v90, v75, s36
	v_perm_b32 v88, v89, v88, s37
	v_fmac_f32_e32 v97, v15, v105
	ds_read_b128 v[102:105], v65 offset:5120
	v_or_b32_e32 v75, v75, v88
	s_waitcnt vmcnt(6)
	v_pk_mul_f32 v[88:89], v[22:23], s[26:27] op_sel_hi:[1,0]
	v_pk_mul_f32 v[90:91], v[20:21], s[26:27] op_sel_hi:[1,0]
	s_waitcnt lgkmcnt(1)
	v_fmac_f32_e32 v97, v16, v98
	global_store_dword v[80:81], v75, off offset:1024
	v_med3_f32 v75, v90, s35, v85
	v_med3_f32 v90, v91, s35, v85
	v_med3_f32 v88, v88, s35, v85
	v_med3_f32 v89, v89, s35, v85
	v_fmac_f32_e32 v97, v17, v99
	v_add_f32_e32 v75, 0x4b400000, v75
	v_add_f32_e32 v90, 0x4b400000, v90
	v_add_f32_e32 v88, 0x4b400000, v88
	v_add_f32_e32 v89, 0x4b400000, v89
	v_fmac_f32_e32 v97, v18, v100
	v_perm_b32 v75, v90, v75, s36
	v_perm_b32 v88, v89, v88, s37
	v_fmac_f32_e32 v97, v19, v101
	ds_read_b128 v[98:101], v65 offset:6144
	v_or_b32_e32 v75, v75, v88
	s_waitcnt vmcnt(6)
	v_pk_mul_f32 v[88:89], v[26:27], s[26:27] op_sel_hi:[1,0]
	v_pk_mul_f32 v[90:91], v[24:25], s[26:27] op_sel_hi:[1,0]
	s_waitcnt lgkmcnt(1)
	v_fmac_f32_e32 v97, v20, v102
	global_store_dword v[80:81], v75, off offset:1280
	v_med3_f32 v75, v90, s35, v85
	v_med3_f32 v90, v91, s35, v85
	v_med3_f32 v88, v88, s35, v85
	v_med3_f32 v89, v89, s35, v85
	v_fmac_f32_e32 v97, v21, v103
	v_add_f32_e32 v75, 0x4b400000, v75
	v_add_f32_e32 v90, 0x4b400000, v90
	v_add_f32_e32 v88, 0x4b400000, v88
	v_add_f32_e32 v89, 0x4b400000, v89
	v_fmac_f32_e32 v97, v22, v104
	v_perm_b32 v75, v90, v75, s36
	v_perm_b32 v88, v89, v88, s37
	v_fmac_f32_e32 v97, v23, v105
	ds_read_b128 v[102:105], v65 offset:7168
	v_or_b32_e32 v75, v75, v88
	s_waitcnt vmcnt(6)
	v_pk_mul_f32 v[88:89], v[30:31], s[26:27] op_sel_hi:[1,0]
	s_waitcnt lgkmcnt(1)
	v_fmac_f32_e32 v97, v24, v98
	v_med3_f32 v88, v88, s35, v85
	v_fmac_f32_e32 v97, v25, v99
	v_add_f32_e32 v95, 0x4b400000, v88
	v_med3_f32 v88, v89, s35, v85
	v_fmac_f32_e32 v97, v26, v100
	v_add_f32_e32 v96, 0x4b400000, v88
	v_and_b32_e32 v88, 64, v86
	v_fmac_f32_e32 v97, v27, v101
	v_add_u32_e32 v93, 64, v88
	v_xor_b32_e32 v88, 1, v86
	s_waitcnt lgkmcnt(0)
; #define LAS __attribute__((address_space(3)))
; __device__ __forceinline__ float wave_sum(float v) {
; #pragma unroll
;     for (int o = 1; o < 64; o <<= 1) v += __shfl_xor(v, o);
;     return v;
; }
; __device__ __forceinline__ void xprep_row(const f32x4 (&v)[8], const int m, LAS float* wf, bf16_t* XB, float* LOGF, const float* bfg, const int lane) {
;     ...
;         for (int e = 0; e < 8; ++e) { float s = 0.f;
; #pragma unroll
;             for (int j = 0; j < 8; ++j) { const f32x4 w = *(const LAS f32x4*)(wf + e * 2048 + 256 * j + 4 * lane); s = fmaf(v[j][0], w[0], s); s = fmaf(v[j][1], w[1], s); s = fmaf(v[j][2], w[2], s); s = fmaf(v[j][3], w[3], s); }
;             f[e] = wave_sum(s); }
	v_fmac_f32_e32 v97, v28, v102
	v_pk_mul_f32 v[90:91], v[28:29], s[26:27] op_sel_hi:[1,0]
	v_cmp_lt_i32_e32 vcc, v88, v93
	v_fmac_f32_e32 v97, v29, v103
	global_store_dword v[80:81], v75, off offset:1536
	v_med3_f32 v75, v90, s35, v85
	v_med3_f32 v90, v91, s35, v85
	v_cndmask_b32_e32 v88, v86, v88, vcc
	v_fmac_f32_e32 v97, v30, v104
	v_add_f32_e32 v94, 0x4b400000, v90
	v_lshlrev_b32_e32 v90, 2, v88
	v_fmac_f32_e32 v97, v31, v105
	s_nop 1
	v_mov_b32_dpp v102, v97 quad_perm:[1,0,3,2] row_mask:0xf bank_mask:0xf
	ds_read_b128 v[98:101], v65 offset:8192
	v_xor_b32_e32 v88, 2, v86
	v_cmp_lt_i32_e32 vcc, v88, v93
	v_xor_b32_e32 v91, 8, v86
	s_waitcnt lgkmcnt(0)
	v_add_f32_e32 v97, v97, v102
	ds_read_b128 v[102:105], v65 offset:9216
	s_waitcnt lgkmcnt(1)
	v_fma_f32 v108, v0, v98, 0
	v_fmac_f32_e32 v108, v1, v99
	v_fmac_f32_e32 v108, v2, v100
	v_fmac_f32_e32 v108, v3, v101
	ds_read_b128 v[98:101], v65 offset:10240
	s_waitcnt lgkmcnt(1)
	v_fmac_f32_e32 v108, v4, v102
	v_fmac_f32_e32 v108, v5, v103
	v_fmac_f32_e32 v108, v6, v104
	v_fmac_f32_e32 v108, v7, v105
	ds_read_b128 v[102:105], v65 offset:11264
	s_waitcnt lgkmcnt(1)
	v_fmac_f32_e32 v108, v8, v98
	v_fmac_f32_e32 v108, v9, v99
	v_fmac_f32_e32 v108, v10, v100
	v_fmac_f32_e32 v108, v11, v101
	ds_read_b128 v[98:101], v65 offset:12288
	s_waitcnt lgkmcnt(1)
	v_fmac_f32_e32 v108, v12, v102
	v_fmac_f32_e32 v108, v13, v103
	v_fmac_f32_e32 v108, v14, v104
	v_fmac_f32_e32 v108, v15, v105
	ds_read_b128 v[102:105], v65 offset:13312
	s_waitcnt lgkmcnt(1)
	v_fmac_f32_e32 v108, v16, v98
	v_fmac_f32_e32 v108, v17, v99
	v_fmac_f32_e32 v108, v18, v100
	v_fmac_f32_e32 v108, v19, v101
	ds_read_b128 v[98:101], v65 offset:14336
	s_waitcnt lgkmcnt(1)
	v_fmac_f32_e32 v108, v20, v102
	v_fmac_f32_e32 v108, v21, v103
	v_fmac_f32_e32 v108, v22, v104
	v_fmac_f32_e32 v108, v23, v105
	ds_read_b128 v[102:105], v65 offset:15360
	s_waitcnt lgkmcnt(1)
	v_fmac_f32_e32 v108, v24, v98
	v_fmac_f32_e32 v108, v25, v99
	v_cndmask_b32_e32 v88, v86, v88, vcc
	v_fmac_f32_e32 v108, v26, v100
	v_lshlrev_b32_e32 v89, 2, v88
	v_fmac_f32_e32 v108, v27, v101
	s_nop 1
	v_mov_b32_dpp v107, v97 quad_perm:[2,3,0,1] row_mask:0xf bank_mask:0xf
	s_waitcnt lgkmcnt(0)
	v_fmac_f32_e32 v108, v28, v102
	v_fmac_f32_e32 v108, v29, v103
	v_xor_b32_e32 v88, 4, v86
	v_fmac_f32_e32 v108, v30, v104
	v_cmp_lt_i32_e32 vcc, v88, v93
	v_fmac_f32_e32 v108, v31, v105
	s_nop 1
	v_mov_b32_dpp v98, v108 quad_perm:[1,0,3,2] row_mask:0xf bank_mask:0xf
	v_cndmask_b32_e32 v88, v86, v88, vcc
	v_lshlrev_b32_e32 v88, 2, v88
	s_waitcnt lgkmcnt(0)
	v_add_f32_e32 v97, v97, v107
	s_nop 1
	v_mov_b32_dpp v99, v97 row_half_mirror row_mask:0xf bank_mask:0xf
	s_waitcnt lgkmcnt(0)
	v_add_f32_e32 v102, v108, v98
	s_nop 1
	v_mov_b32_dpp v103, v102 quad_perm:[2,3,0,1] row_mask:0xf bank_mask:0xf
	v_cmp_lt_i32_e32 vcc, v91, v93
	v_xor_b32_e32 v92, 16, v86
	s_waitcnt lgkmcnt(0)
	v_add_f32_e32 v97, v97, v99
	ds_read_b128 v[98:101], v65 offset:16384
	s_waitcnt lgkmcnt(1)
	v_add_f32_e32 v107, v102, v103
	ds_read_b128 v[102:105], v65 offset:17408
	v_cndmask_b32_e32 v91, v86, v91, vcc
	v_cmp_lt_i32_e32 vcc, v92, v93
	s_waitcnt lgkmcnt(1)
	v_fma_f32 v109, v0, v98, 0
	v_fmac_f32_e32 v109, v1, v99
	v_fmac_f32_e32 v109, v2, v100
	v_fmac_f32_e32 v109, v3, v101
	ds_read_b128 v[98:101], v65 offset:18432
	s_waitcnt lgkmcnt(1)
	v_fmac_f32_e32 v109, v4, v102
	v_fmac_f32_e32 v109, v5, v103
	v_fmac_f32_e32 v109, v6, v104
	v_fmac_f32_e32 v109, v7, v105
	ds_read_b128 v[102:105], v65 offset:19456
	s_waitcnt lgkmcnt(1)
	v_fmac_f32_e32 v109, v8, v98
	v_fmac_f32_e32 v109, v9, v99
	v_fmac_f32_e32 v109, v10, v100
	v_fmac_f32_e32 v109, v11, v101
	ds_read_b128 v[98:101], v65 offset:20480
	s_waitcnt lgkmcnt(1)
	v_fmac_f32_e32 v109, v12, v102
	v_fmac_f32_e32 v109, v13, v103
	v_fmac_f32_e32 v109, v14, v104
	v_fmac_f32_e32 v109, v15, v105
	ds_read_b128 v[102:105], v65 offset:21504
	s_waitcnt lgkmcnt(1)
	v_fmac_f32_e32 v109, v16, v98
	v_fmac_f32_e32 v109, v17, v99
	v_fmac_f32_e32 v109, v18, v100
	v_fmac_f32_e32 v109, v19, v101
	ds_read_b128 v[98:101], v65 offset:22528
	s_waitcnt lgkmcnt(1)
	v_fmac_f32_e32 v109, v20, v102
	v_fmac_f32_e32 v109, v21, v103
	v_fmac_f32_e32 v109, v22, v104
	v_fmac_f32_e32 v109, v23, v105
	ds_read_b128 v[102:105], v65 offset:23552
	s_waitcnt lgkmcnt(1)
	v_fmac_f32_e32 v109, v24, v98
	v_fmac_f32_e32 v109, v25, v99
	v_fmac_f32_e32 v109, v26, v100
	v_fmac_f32_e32 v109, v27, v101
	s_waitcnt lgkmcnt(0)
	v_fmac_f32_e32 v109, v28, v102
	v_fmac_f32_e32 v109, v29, v103
	v_xor_b32_e32 v106, 32, v86
	v_fmac_f32_e32 v109, v30, v104
	v_lshlrev_b32_e32 v91, 2, v91
	v_cndmask_b32_e32 v92, v86, v92, vcc
	v_cmp_lt_i32_e32 vcc, v106, v93
	v_fmac_f32_e32 v109, v31, v105
	s_nop 1
	v_mov_b32_dpp v108, v107 row_half_mirror row_mask:0xf bank_mask:0xf
	v_cndmask_b32_e32 v93, v86, v106, vcc
	s_nop 1
	v_mov_b32_dpp v106, v97 row_mirror row_mask:0xf bank_mask:0xf
	s_nop 1
	v_mov_b32_dpp v98, v109 quad_perm:[1,0,3,2] row_mask:0xf bank_mask:0xf
	v_lshlrev_b32_e32 v92, 2, v92
	s_waitcnt lgkmcnt(0)
	v_add_f32_e32 v104, v107, v108
	s_nop 1
	v_mov_b32_dpp v105, v104 row_mirror row_mask:0xf bank_mask:0xf
	s_waitcnt lgkmcnt(1)
	v_add_f32_e32 v97, v97, v106
	s_waitcnt lgkmcnt(0)
	v_add_f32_e32 v106, v109, v98
	v_mov_b32_e32 v99, v97
	s_nop 1
	v_permlane16_swap_b32_e32 v97, v99
	s_nop 1
	v_mov_b32_dpp v107, v106 quad_perm:[2,3,0,1] row_mask:0xf bank_mask:0xf
	ds_read_b128 v[100:103], v65 offset:24576
	v_lshlrev_b32_e32 v93, 2, v93
	v_add_f32_e32 v75, 0x4b400000, v75
	s_waitcnt lgkmcnt(0)
	v_add_f32_e32 v97, v97, v99
	v_add_f32_e32 v99, v104, v105
	s_waitcnt lgkmcnt(0)
	v_add_f32_e32 v108, v106, v107
	ds_read_b128 v[104:107], v65 offset:25600
	s_waitcnt lgkmcnt(1)
; #define LAS __attribute__((address_space(3)))
; __device__ __forceinline__ float wave_sum(float v) {
; #pragma unroll
;     for (int o = 1; o < 64; o <<= 1) v += __shfl_xor(v, o);
;     return v;
; }
; __device__ __forceinline__ void xprep_row(const f32x4 (&v)[8], const int m, LAS float* wf, bf16_t* XB, float* LOGF, const float* bfg, const int lane) {
;     ...
;         for (int e = 0; e < 8; ++e) { float s = 0.f;
; #pragma unroll
;             for (int j = 0; j < 8; ++j) { const f32x4 w = *(const LAS f32x4*)(wf + e * 2048 + 256 * j + 4 * lane); s = fmaf(v[j][0], w[0], s); s = fmaf(v[j][1], w[1], s); s = fmaf(v[j][2], w[2], s); s = fmaf(v[j][3], w[3], s); }
;             f[e] = wave_sum(s); }
	v_fma_f32 v110, v0, v100, 0
	v_fmac_f32_e32 v110, v1, v101
	v_fmac_f32_e32 v110, v2, v102
	v_fmac_f32_e32 v110, v3, v103
	ds_read_b128 v[100:103], v65 offset:26624
	s_waitcnt lgkmcnt(1)
	v_fmac_f32_e32 v110, v4, v104
	v_fmac_f32_e32 v110, v5, v105
	v_fmac_f32_e32 v110, v6, v106
	v_fmac_f32_e32 v110, v7, v107
	ds_read_b128 v[104:107], v65 offset:27648
	s_waitcnt lgkmcnt(1)
	v_fmac_f32_e32 v110, v8, v100
	v_fmac_f32_e32 v110, v9, v101
	v_fmac_f32_e32 v110, v10, v102
	v_fmac_f32_e32 v110, v11, v103
	ds_read_b128 v[100:103], v65 offset:28672
	s_waitcnt lgkmcnt(1)
	v_fmac_f32_e32 v110, v12, v104
	v_fmac_f32_e32 v110, v13, v105
	v_fmac_f32_e32 v110, v14, v106
	v_fmac_f32_e32 v110, v15, v107
	ds_read_b128 v[104:107], v65 offset:29696
	s_waitcnt lgkmcnt(1)
	v_fmac_f32_e32 v110, v16, v100
	v_fmac_f32_e32 v110, v17, v101
	v_fmac_f32_e32 v110, v18, v102
	v_fmac_f32_e32 v110, v19, v103
	ds_read_b128 v[100:103], v65 offset:30720
	s_waitcnt lgkmcnt(1)
	v_fmac_f32_e32 v110, v20, v104
	v_fmac_f32_e32 v110, v21, v105
	v_fmac_f32_e32 v110, v22, v106
	v_fmac_f32_e32 v110, v23, v107
	ds_read_b128 v[104:107], v65 offset:31744
	s_waitcnt lgkmcnt(1)
	v_fmac_f32_e32 v110, v24, v100
	v_fmac_f32_e32 v110, v25, v101
	v_fmac_f32_e32 v110, v26, v102
	v_fmac_f32_e32 v110, v27, v103
	ds_read_b128 v[100:103], v65 offset:32768
	s_waitcnt lgkmcnt(1)
	v_fmac_f32_e32 v110, v28, v104
	v_fmac_f32_e32 v110, v29, v105
	v_fmac_f32_e32 v110, v30, v106
	v_fmac_f32_e32 v110, v31, v107
	ds_read_b128 v[104:107], v65 offset:33792
	s_waitcnt lgkmcnt(1)
	v_fma_f32 v112, v0, v100, 0
	v_fmac_f32_e32 v112, v1, v101
	v_fmac_f32_e32 v112, v2, v102
	v_fmac_f32_e32 v112, v3, v103
	ds_read_b128 v[100:103], v65 offset:34816
	s_waitcnt lgkmcnt(1)
	v_fmac_f32_e32 v112, v4, v104
	v_fmac_f32_e32 v112, v5, v105
	v_fmac_f32_e32 v112, v6, v106
	v_fmac_f32_e32 v112, v7, v107
	ds_read_b128 v[104:107], v65 offset:35840
	s_waitcnt lgkmcnt(1)
	v_fmac_f32_e32 v112, v8, v100
	v_fmac_f32_e32 v112, v9, v101
	v_fmac_f32_e32 v112, v10, v102
	v_fmac_f32_e32 v112, v11, v103
	ds_read_b128 v[100:103], v65 offset:36864
	s_waitcnt lgkmcnt(1)
	v_fmac_f32_e32 v112, v12, v104
	v_fmac_f32_e32 v112, v13, v105
	v_fmac_f32_e32 v112, v14, v106
	v_fmac_f32_e32 v112, v15, v107
	ds_read_b128 v[104:107], v65 offset:37888
	s_waitcnt lgkmcnt(1)
	v_fmac_f32_e32 v112, v16, v100
	v_fmac_f32_e32 v112, v17, v101
	v_fmac_f32_e32 v112, v18, v102
	v_fmac_f32_e32 v112, v19, v103
	ds_read_b128 v[100:103], v65 offset:38912
	s_waitcnt lgkmcnt(1)
	v_fmac_f32_e32 v112, v20, v104
	s_nop 1
	v_mov_b32_dpp v111, v110 quad_perm:[1,0,3,2] row_mask:0xf bank_mask:0xf
	v_fmac_f32_e32 v112, v21, v105
	v_fmac_f32_e32 v112, v22, v106
	v_fmac_f32_e32 v112, v23, v107
	ds_read_b128 v[104:107], v65 offset:39936
	s_waitcnt lgkmcnt(1)
	v_fmac_f32_e32 v112, v24, v100
	v_fmac_f32_e32 v112, v25, v101
	v_fmac_f32_e32 v112, v26, v102
	s_waitcnt lgkmcnt(0)
	v_add_f32_e32 v102, v110, v111
	v_fmac_f32_e32 v112, v27, v103
	s_nop 1
	v_mov_b32_dpp v103, v102 quad_perm:[2,3,0,1] row_mask:0xf bank_mask:0xf
	s_waitcnt lgkmcnt(0)
	v_fmac_f32_e32 v112, v28, v104
	v_fmac_f32_e32 v112, v29, v105
	v_fmac_f32_e32 v112, v30, v106
	v_fmac_f32_e32 v112, v31, v107
	s_nop 1
	v_mov_b32_dpp v100, v112 quad_perm:[1,0,3,2] row_mask:0xf bank_mask:0xf
	s_waitcnt lgkmcnt(0)
	v_add_f32_e32 v102, v102, v103
	s_nop 1
	v_mov_b32_dpp v103, v102 row_half_mirror row_mask:0xf bank_mask:0xf
	s_nop 1
	v_mov_b32_dpp v109, v108 row_half_mirror row_mask:0xf bank_mask:0xf
	v_mov_b32_e32 v101, v99
	s_nop 1
	v_permlane16_swap_b32_e32 v99, v101
	s_waitcnt lgkmcnt(0)
	v_add_f32_e32 v100, v112, v100
	s_nop 1
	v_mov_b32_dpp v105, v100 quad_perm:[2,3,0,1] row_mask:0xf bank_mask:0xf
	s_waitcnt lgkmcnt(0)
	v_add_f32_e32 v102, v102, v103
	s_nop 1
	v_mov_b32_dpp v103, v102 row_mirror row_mask:0xf bank_mask:0xf
	s_waitcnt lgkmcnt(2)
	v_add_f32_e32 v104, v108, v109
	s_nop 1
	v_mov_b32_dpp v106, v104 row_mirror row_mask:0xf bank_mask:0xf
	s_waitcnt lgkmcnt(0)
	v_add_f32_e32 v100, v100, v105
	v_add_f32_e32 v99, v99, v101
	s_nop 1
	v_mov_b32_dpp v101, v100 row_half_mirror row_mask:0xf bank_mask:0xf
	s_waitcnt lgkmcnt(1)
	v_add_f32_e32 v103, v102, v103
	v_mov_b32_e32 v108, v103
	s_nop 1
	v_permlane16_swap_b32_e32 v103, v108
	s_waitcnt lgkmcnt(0)
	v_add_f32_e32 v104, v104, v106
	v_mov_b32_e32 v105, v104
	s_nop 1
	v_permlane16_swap_b32_e32 v104, v105
	s_waitcnt lgkmcnt(0)
	v_add_f32_e32 v106, v100, v101
	s_nop 1
	v_mov_b32_dpp v107, v106 row_mirror row_mask:0xf bank_mask:0xf
	s_waitcnt lgkmcnt(0)
	v_add_f32_e32 v103, v103, v108
	ds_read_b128 v[108:111], v65 offset:40960
	ds_read_b128 v[112:115], v65 offset:41984
	s_waitcnt lgkmcnt(3)
	v_add_f32_e32 v101, v104, v105
	s_waitcnt lgkmcnt(2)
	v_add_f32_e32 v105, v106, v107
	ds_bpermute_b32 v106, v92, v105
	s_waitcnt lgkmcnt(2)
	v_fma_f32 v107, v0, v108, 0
	v_fmac_f32_e32 v107, v1, v109
	v_fmac_f32_e32 v107, v2, v110
	v_fmac_f32_e32 v107, v3, v111
	ds_read_b128 v[108:111], v65 offset:43008
	s_waitcnt lgkmcnt(2)
	v_fmac_f32_e32 v107, v4, v112
	v_fmac_f32_e32 v107, v5, v113
	v_fmac_f32_e32 v107, v6, v114
	v_fmac_f32_e32 v107, v7, v115
	ds_read_b128 v[112:115], v65 offset:44032
	s_waitcnt lgkmcnt(1)
	v_fmac_f32_e32 v107, v8, v108
	v_fmac_f32_e32 v107, v9, v109
	v_fmac_f32_e32 v107, v10, v110
	v_fmac_f32_e32 v107, v11, v111
	ds_read_b128 v[108:111], v65 offset:45056
	s_waitcnt lgkmcnt(1)
	v_fmac_f32_e32 v107, v12, v112
	v_fmac_f32_e32 v107, v13, v113
	v_fmac_f32_e32 v107, v14, v114
	v_fmac_f32_e32 v107, v15, v115
	ds_read_b128 v[112:115], v65 offset:46080
	s_waitcnt lgkmcnt(1)
	v_fmac_f32_e32 v107, v16, v108
	v_fmac_f32_e32 v107, v17, v109
	v_fmac_f32_e32 v107, v18, v110
	v_fmac_f32_e32 v107, v19, v111
	ds_read_b128 v[108:111], v65 offset:47104
	s_waitcnt lgkmcnt(1)
; #define LAS __attribute__((address_space(3)))
; __device__ __forceinline__ float wave_sum(float v) {
; #pragma unroll
;     for (int o = 1; o < 64; o <<= 1) v += __shfl_xor(v, o);
;     return v;
; }
; __device__ __forceinline__ void xprep_row(const f32x4 (&v)[8], const int m, LAS float* wf, bf16_t* XB, float* LOGF, const float* bfg, const int lane) {
;     ...
;         for (int e = 0; e < 8; ++e) { float s = 0.f;
; #pragma unroll
;             for (int j = 0; j < 8; ++j) { const f32x4 w = *(const LAS f32x4*)(wf + e * 2048 + 256 * j + 4 * lane); s = fmaf(v[j][0], w[0], s); s = fmaf(v[j][1], w[1], s); s = fmaf(v[j][2], w[2], s); s = fmaf(v[j][3], w[3], s); }
;             f[e] = wave_sum(s); }
	v_fmac_f32_e32 v107, v20, v112
	v_fmac_f32_e32 v107, v21, v113
	v_fmac_f32_e32 v107, v22, v114
	v_fmac_f32_e32 v107, v23, v115
	ds_read_b128 v[112:115], v65 offset:48128
	s_waitcnt lgkmcnt(1)
	v_fmac_f32_e32 v107, v24, v108
	v_fmac_f32_e32 v107, v25, v109
	v_fmac_f32_e32 v107, v26, v110
	v_fmac_f32_e32 v107, v27, v111
	ds_read_b128 v[108:111], v65 offset:49152
	s_waitcnt lgkmcnt(1)
	v_fmac_f32_e32 v107, v28, v112
	v_fmac_f32_e32 v107, v29, v113
	v_fmac_f32_e32 v107, v30, v114
	v_fmac_f32_e32 v107, v31, v115
	ds_read_b128 v[112:115], v65 offset:50176
	s_waitcnt lgkmcnt(1)
	v_fma_f32 v117, v0, v108, 0
	v_fmac_f32_e32 v117, v1, v109
	v_fmac_f32_e32 v117, v2, v110
	v_fmac_f32_e32 v117, v3, v111
	ds_read_b128 v[108:111], v65 offset:51200
	s_waitcnt lgkmcnt(1)
	v_fmac_f32_e32 v117, v4, v112
	v_fmac_f32_e32 v117, v5, v113
	v_fmac_f32_e32 v117, v6, v114
	v_fmac_f32_e32 v117, v7, v115
	ds_read_b128 v[112:115], v65 offset:52224
	s_waitcnt lgkmcnt(1)
	v_fmac_f32_e32 v117, v8, v108
	v_fmac_f32_e32 v117, v9, v109
	v_fmac_f32_e32 v117, v10, v110
	v_fmac_f32_e32 v117, v11, v111
	ds_read_b128 v[108:111], v65 offset:53248
	s_waitcnt lgkmcnt(1)
	v_fmac_f32_e32 v117, v12, v112
	v_fmac_f32_e32 v117, v13, v113
	v_fmac_f32_e32 v117, v14, v114
	v_fmac_f32_e32 v117, v15, v115
	ds_read_b128 v[112:115], v65 offset:54272
	s_waitcnt lgkmcnt(1)
	v_fmac_f32_e32 v117, v16, v108
	v_fmac_f32_e32 v117, v17, v109
	v_fmac_f32_e32 v117, v18, v110
	v_fmac_f32_e32 v117, v19, v111
	ds_read_b128 v[108:111], v65 offset:55296
	s_waitcnt lgkmcnt(1)
	v_fmac_f32_e32 v117, v20, v112
	v_fmac_f32_e32 v117, v21, v113
	v_fmac_f32_e32 v117, v22, v114
	v_fmac_f32_e32 v117, v23, v115
	ds_read_b128 v[112:115], v65 offset:56320
	s_waitcnt lgkmcnt(1)
	v_fmac_f32_e32 v117, v24, v108
	v_fmac_f32_e32 v117, v25, v109
	v_fmac_f32_e32 v117, v26, v110
	v_fmac_f32_e32 v117, v27, v111
	ds_read_b128 v[108:111], v65 offset:57344
	s_waitcnt lgkmcnt(1)
	v_fmac_f32_e32 v117, v28, v112
	v_fmac_f32_e32 v117, v29, v113
	v_fmac_f32_e32 v117, v30, v114
	v_fmac_f32_e32 v117, v31, v115
	ds_read_b128 v[112:115], v65 offset:58368
	s_waitcnt lgkmcnt(1)
	v_fma_f32 v119, v0, v108, 0
	v_fmac_f32_e32 v119, v1, v109
	v_fmac_f32_e32 v119, v2, v110
	v_fmac_f32_e32 v119, v3, v111
	ds_read_b128 v[108:111], v65 offset:59392
	s_waitcnt lgkmcnt(1)
	v_fmac_f32_e32 v119, v4, v112
	v_fmac_f32_e32 v119, v5, v113
	v_fmac_f32_e32 v119, v6, v114
	v_fmac_f32_e32 v119, v7, v115
	ds_read_b128 v[112:115], v65 offset:60416
	s_waitcnt lgkmcnt(1)
	v_fmac_f32_e32 v119, v8, v108
	v_fmac_f32_e32 v119, v9, v109
	v_fmac_f32_e32 v119, v10, v110
	v_fmac_f32_e32 v119, v11, v111
	ds_read_b128 v[108:111], v65 offset:61440
	s_waitcnt lgkmcnt(1)
	v_fmac_f32_e32 v119, v12, v112
	v_fmac_f32_e32 v119, v13, v113
	v_fmac_f32_e32 v119, v14, v114
	v_fmac_f32_e32 v119, v15, v115
	ds_read_b128 v[112:115], v65 offset:62464
	s_waitcnt lgkmcnt(1)
	v_fmac_f32_e32 v119, v16, v108
	v_fmac_f32_e32 v119, v17, v109
	v_fmac_f32_e32 v119, v18, v110
	v_fmac_f32_e32 v119, v19, v111
	ds_read_b128 v[108:111], v65 offset:63488
	s_waitcnt lgkmcnt(1)
	v_fmac_f32_e32 v119, v20, v112
	v_fmac_f32_e32 v119, v21, v113
	v_fmac_f32_e32 v119, v22, v114
	v_fmac_f32_e32 v119, v23, v115
	ds_read_b128 v[112:115], v65 offset:64512
	s_waitcnt lgkmcnt(1)
	v_fmac_f32_e32 v119, v24, v108
	v_fmac_f32_e32 v119, v25, v109
	v_fmac_f32_e32 v119, v26, v110
	v_fmac_f32_e32 v119, v27, v111
	s_waitcnt lgkmcnt(0)
	v_fmac_f32_e32 v119, v28, v112
	v_fmac_f32_e32 v119, v29, v113
	v_fmac_f32_e32 v119, v30, v114
	v_fmac_f32_e32 v119, v31, v115
	s_nop 1
	v_mov_b32_dpp v116, v107 quad_perm:[1,0,3,2] row_mask:0xf bank_mask:0xf
	s_nop 1
	v_mov_b32_dpp v118, v117 quad_perm:[1,0,3,2] row_mask:0xf bank_mask:0xf
	s_nop 1
	v_mov_b32_dpp v108, v119 quad_perm:[1,0,3,2] row_mask:0xf bank_mask:0xf
	v_add_f32_e32 v105, v105, v106
	ds_bpermute_b32 v98, v93, v97
	s_waitcnt lgkmcnt(0)
	v_add_f32_e32 v107, v107, v116
	s_waitcnt lgkmcnt(2)
	v_add_f32_e32 v110, v117, v118
	s_waitcnt lgkmcnt(1)
	v_add_f32_e32 v108, v119, v108
	s_nop 1
	v_mov_b32_dpp v109, v107 quad_perm:[2,3,0,1] row_mask:0xf bank_mask:0xf
	s_nop 1
	v_mov_b32_dpp v111, v110 quad_perm:[2,3,0,1] row_mask:0xf bank_mask:0xf
	s_nop 1
	v_mov_b32_dpp v112, v108 quad_perm:[2,3,0,1] row_mask:0xf bank_mask:0xf
	v_mov_b32_e32 v100, v99
	s_nop 1
	v_permlane32_swap_b32_e32 v99, v100
	v_mov_b32_e32 v102, v101
	s_nop 1
	v_permlane32_swap_b32_e32 v101, v102
	s_waitcnt lgkmcnt(0)
	v_add_f32_e32 v107, v107, v109
	s_waitcnt lgkmcnt(0)
	v_add_f32_e32 v110, v110, v111
	s_waitcnt lgkmcnt(2)
	v_add_f32_e32 v108, v108, v112
	s_nop 1
	v_mov_b32_dpp v109, v107 row_half_mirror row_mask:0xf bank_mask:0xf
	s_nop 1
	v_mov_b32_dpp v111, v110 row_half_mirror row_mask:0xf bank_mask:0xf
	s_nop 1
	v_mov_b32_dpp v112, v108 row_half_mirror row_mask:0xf bank_mask:0xf
	v_mov_b32_e32 v104, v103
	s_nop 1
	v_permlane32_swap_b32_e32 v103, v104
	v_mov_b32_e32 v106, v105
	s_nop 1
	v_permlane32_swap_b32_e32 v105, v106
	s_waitcnt lgkmcnt(0)
	v_add_f32_e32 v107, v107, v109
	s_waitcnt lgkmcnt(0)
	v_add_f32_e32 v110, v110, v111
	s_waitcnt lgkmcnt(2)
	v_add_f32_e32 v108, v108, v112
	s_nop 1
	v_mov_b32_dpp v109, v107 row_mirror row_mask:0xf bank_mask:0xf
	s_nop 1
	v_mov_b32_dpp v111, v110 row_mirror row_mask:0xf bank_mask:0xf
	s_nop 1
	v_mov_b32_dpp v112, v108 row_mirror row_mask:0xf bank_mask:0xf
	v_perm_b32 v75, v94, v75, s36
	v_perm_b32 v94, v96, v95, s37
	s_waitcnt lgkmcnt(0)
	v_add_f32_e32 v107, v107, v109
	s_waitcnt lgkmcnt(1)
	v_add_f32_e32 v110, v110, v111
	s_waitcnt lgkmcnt(0)
	v_add_f32_e32 v112, v108, v112
	v_mov_b32_e32 v109, v107
	s_nop 1
	v_permlane16_swap_b32_e32 v107, v109
	v_mov_b32_e32 v111, v110
	s_nop 1
	v_permlane16_swap_b32_e32 v110, v111
	v_mov_b32_e32 v113, v112
	s_nop 1
	v_permlane16_swap_b32_e32 v112, v113
	v_or_b32_e32 v75, v75, v94
	global_store_dword v[80:81], v75, off offset:1792
	s_waitcnt lgkmcnt(0)
	v_add_f32_e32 v107, v107, v109
	s_waitcnt lgkmcnt(1)
	v_add_f32_e32 v109, v110, v111
	s_waitcnt lgkmcnt(0)
	v_add_f32_e32 v111, v112, v113
	v_mov_b32_e32 v108, v107
	s_nop 1
	v_permlane32_swap_b32_e32 v107, v108
	v_mov_b32_e32 v110, v109
	s_nop 1
	v_permlane32_swap_b32_e32 v109, v110
	v_mov_b32_e32 v112, v111
	s_nop 1
	v_permlane32_swap_b32_e32 v111, v112
	s_and_saveexec_b64 s[28:29], s[2:3]
	s_cbranch_execz .LBB0_991
; __device__ __forceinline__ void xprep_row(const f32x4 (&v)[8], const int m, LAS float* wf, bf16_t* XB, float* LOGF, const float* bfg, const int lane) {
;     ...
;         if (lane < 8) { float z = 0.f;
; #pragma unroll
;             for (int e = 0; e < 8; ++e) z = (lane == e) ? f[e] : z;
;             z += bfg[lane];
;             LOGF[(size_t)m * 8 + lane] = fminf(z, 0.f) - log1pf(expf(-fabsf(z))); }
	global_load_dword v75, v[70:71], off
	v_add_f32_e32 v97, v97, v98
	v_add_f32_e32 v99, v99, v100
	v_cndmask_b32_e64 v97, 0, v97, s[4:5]
	v_add_f32_e32 v101, v101, v102
	v_cndmask_b32_e64 v97, v97, v99, s[6:7]
	v_add_f32_e32 v96, v103, v104
	v_cndmask_b32_e64 v97, v97, v101, s[8:9]
	v_add_f32_e32 v95, v105, v106
	v_cndmask_b32_e64 v96, v97, v96, s[10:11]
	s_waitcnt lgkmcnt(0)
	v_add_f32_e32 v94, v107, v108
	v_cndmask_b32_e64 v95, v96, v95, s[12:13]
	s_waitcnt lgkmcnt(1)
	v_add_f32_e32 v81, v109, v110
	v_cndmask_b32_e64 v94, v95, v94, s[14:15]
	s_waitcnt lgkmcnt(0)
	v_add_f32_e32 v80, v111, v112
	v_cndmask_b32_e64 v81, v94, v81, s[16:17]
	v_cndmask_b32_e64 v80, v81, v80, s[18:19]
	s_waitcnt vmcnt(0)
	v_add_f32_e32 v75, v80, v75
	v_mul_f32_e64 v80, |v75|, s38
	v_fma_f32 v81, |v75|, s38, -v80
	v_rndne_f32_e32 v94, v80
	v_fma_f32 v81, |v75|, s39, v81
	v_sub_f32_e32 v80, v80, v94
	v_add_f32_e32 v80, v80, v81
	v_cvt_i32_f32_e32 v94, v94
	v_exp_f32_e32 v95, v80
	v_cmp_ngt_f32_e64 vcc, |v75|, s40
	v_lshlrev_b64 v[80:81], 5, v[78:79]
	v_min_f32_e32 v79, 0, v75
	v_ldexp_f32 v94, v95, v94
	v_cndmask_b32_e32 v94, 0, v94, vcc
	v_cmp_nlt_f32_e64 vcc, |v75|, s41
	v_lshl_add_u64 v[80:81], v[72:73], 0, v[80:81]
	s_nop 0
	v_cndmask_b32_e32 v108, v87, v94, vcc
	v_add_f32_e32 v75, 1.0, v108
	v_add_f32_e32 v96, -1.0, v75
	v_frexp_mant_f32_e32 v97, v75
	v_cvt_f64_f32_e32 v[94:95], v75
	v_sub_f32_e32 v98, v96, v75
	v_frexp_exp_i32_f64_e32 v94, v[94:95]
	v_cmp_gt_f32_e32 vcc, s43, v97
	v_sub_f32_e32 v96, v108, v96
	v_add_f32_e32 v95, 1.0, v98
	v_subbrev_co_u32_e32 v94, vcc, 0, v94, vcc
	v_add_f32_e32 v95, v96, v95
	v_sub_u32_e32 v96, 0, v94
	v_ldexp_f32 v75, v75, v96
	v_ldexp_f32 v95, v95, v96
	v_add_f32_e32 v96, -1.0, v75
	v_add_f32_e32 v98, 1.0, v75
	v_add_f32_e32 v97, 1.0, v96
	v_add_f32_e32 v99, -1.0, v98
	v_sub_f32_e32 v97, v75, v97
	v_sub_f32_e32 v75, v75, v99
	v_add_f32_e32 v75, v95, v75
	v_add_f32_e32 v99, v95, v97
	v_add_f32_e32 v95, v98, v75
	v_rcp_f32_e32 v102, v95
	v_add_f32_e32 v97, v96, v99
	v_sub_f32_e32 v98, v98, v95
	v_add_f32_e32 v75, v75, v98
	v_mul_f32_e32 v104, v97, v102
	v_mul_f32_e32 v98, v95, v104
	v_fma_f32 v100, v104, v95, -v98
	v_sub_f32_e32 v96, v96, v97
	v_fmac_f32_e32 v100, v104, v75
	v_add_f32_e32 v103, v99, v96
	v_add_f32_e32 v96, v98, v100
	v_sub_f32_e32 v99, v97, v96
	v_mov_b32_e32 v101, v96
	v_pk_add_f32 v[96:97], v[96:97], v[98:99] neg_lo:[0,1] neg_hi:[0,1]
	v_cvt_f32_i32_e32 v94, v94
	v_pk_add_f32 v[96:97], v[96:97], v[100:101] neg_lo:[0,1] neg_hi:[0,1]
	v_cmp_neq_f32_e32 vcc, s42, v108
	v_add_f32_e32 v97, v103, v97
	v_add_f32_e32 v96, v96, v97
	v_add_f32_e32 v97, v99, v96
	v_mul_f32_e32 v101, v102, v97
	v_mul_f32_e32 v98, v95, v101
	v_fma_f32 v100, v101, v95, -v98
	v_sub_f32_e32 v99, v99, v97
	v_fmac_f32_e32 v100, v101, v75
	v_add_f32_e32 v103, v96, v99
	v_add_f32_e32 v105, v104, v101
	v_add_f32_e32 v96, v98, v100
	v_sub_f32_e32 v95, v105, v104
	v_sub_f32_e32 v99, v97, v96
	v_sub_f32_e32 v75, v101, v95
	v_mov_b32_e32 v101, v96
	v_pk_add_f32 v[96:97], v[96:97], v[98:99] neg_lo:[0,1] neg_hi:[0,1]
	s_nop 0
	v_pk_add_f32 v[96:97], v[96:97], v[100:101] neg_lo:[0,1] neg_hi:[0,1]
	s_nop 0
	v_add_f32_e32 v95, v103, v97
	v_add_f32_e32 v95, v96, v95
	v_add_f32_e32 v95, v99, v95
	v_mul_f32_e32 v95, v102, v95
	v_add_f32_e32 v75, v75, v95
	v_add_f32_e32 v95, v105, v75
	v_mul_f32_e32 v96, v95, v95
	v_sub_f32_e32 v98, v95, v105
	v_fmamk_f32 v99, v96, 0x3e9b6dac, v84
	v_ldexp_f32 v97, v95, 1
	v_sub_f32_e32 v98, v75, v98
	v_mul_f32_e32 v95, v95, v96
	v_fmaak_f32 v75, v96, v99, 0x3f2aaada
	v_ldexp_f32 v101, v98, 1
	v_pk_mul_f32 v[98:99], v[94:95], v[74:75]
	s_nop 0
	v_fma_f32 v96, v94, s44, -v98
	v_fmac_f32_e32 v96, 0xb102e308, v94
	v_pk_add_f32 v[94:95], v[98:99], v[96:97]
	v_mov_b32_e32 v100, v98
	v_sub_f32_e32 v75, v95, v97
	v_sub_f32_e32 v75, v99, v75
	v_add_f32_e32 v101, v101, v75
	v_pk_add_f32 v[102:103], v[94:95], v[98:99] neg_lo:[0,1] neg_hi:[0,1]
	v_pk_add_f32 v[98:99], v[94:95], v[100:101]
	v_mov_b32_e32 v97, v94
	v_mov_b32_e32 v103, v99
	v_pk_add_f32 v[106:107], v[96:97], v[102:103] neg_lo:[0,1] neg_hi:[0,1]
	v_pk_add_f32 v[96:97], v[96:97], v[102:103]
	v_mov_b32_e32 v105, v94
	v_pk_add_f32 v[102:103], v[96:97], v[94:95] op_sel:[1,0] op_sel_hi:[0,1] neg_lo:[0,1] neg_hi:[0,1]
	v_mov_b32_e32 v104, v101
	v_mov_b32_e32 v100, v99
	v_mov_b32_e32 v101, v97
	v_pk_mov_b32 v[94:95], v[94:95], v[102:103] op_sel:[1,0]
	v_pk_add_f32 v[98:99], v[98:99], v[102:103] op_sel_hi:[1,0] neg_lo:[0,1] neg_hi:[0,1]
	v_pk_add_f32 v[94:95], v[100:101], v[94:95] neg_lo:[0,1] neg_hi:[0,1]
	v_mov_b32_e32 v98, v106
	v_pk_add_f32 v[94:95], v[104:105], v[94:95] neg_lo:[0,1] neg_hi:[0,1]
	v_mov_b32_e32 v107, v97
	v_pk_add_f32 v[98:99], v[98:99], v[94:95]
	s_nop 0
	v_pk_add_f32 v[100:101], v[98:99], v[98:99] op_sel:[0,1] op_sel_hi:[1,0]
	s_nop 0
	v_pk_add_f32 v[96:97], v[96:97], v[100:101] op_sel:[1,0] op_sel_hi:[0,1]
	v_mov_b32_e32 v99, v96
	v_mov_b32_e32 v95, v100
	v_pk_add_f32 v[100:101], v[98:99], v[106:107] neg_lo:[0,1] neg_hi:[0,1]
	s_nop 0
	v_sub_f32_e32 v75, v98, v100
	v_pk_add_f32 v[94:95], v[94:95], v[100:101] neg_lo:[0,1] neg_hi:[0,1]
	v_sub_f32_e32 v75, v106, v75
	v_add_f32_e32 v75, v94, v75
	v_add_f32_e32 v75, v75, v95
	v_add_f32_e32 v75, v96, v75
	v_cndmask_b32_e32 v75, v87, v75, vcc
	v_cmp_lt_f32_e64 vcc, |v108|, s45
	s_nop 1
	v_cndmask_b32_e32 v75, v75, v108, vcc
	v_sub_f32_e32 v75, v79, v75
	global_store_dword v[80:81], v75, off

; #define LAS __attribute__((address_space(3)))
; __device__ __forceinline__ void xprep_row(const f32x4 (&v)[8], const int m, LAS float* wf, bf16_t* XB, float* LOGF, const float* bfg, const int lane) {
;         unsigned* o4 = (unsigned*)((unsigned char*)XB + (size_t)m * DM) + lane;
; #pragma unroll
;         for (int j = 0; j < 8; ++j) o4[64 * j] = pg8::pack4i8(v[j] * ASC_XI8);
;         float f[8];
; #pragma unroll
;         for (int e = 0; e < 8; ++e) { float s = 0.f;
; #pragma unroll
;             for (int j = 0; j < 8; ++j) { const f32x4 w = *(const LAS f32x4*)(wf + e * 2048 + 256 * j + 4 * lane); s = fmaf(v[j][0], w[0], s); s = fmaf(v[j][1], w[1], s); s = fmaf(v[j][2], w[2], s); s = fmaf(v[j][3], w[3], s); }
;             f[e] = wave_sum(s); }
.LBB0_994:
	s_or_b64 exec, exec, s[30:31]
	v_pk_mul_f32 v[80:81], v[46:47], s[26:27] op_sel_hi:[1,0]
	v_pk_mul_f32 v[94:95], v[44:45], s[26:27] op_sel_hi:[1,0]
	v_med3_f32 v80, v80, s35, v85
	v_med3_f32 v75, v94, s35, v85
	v_med3_f32 v94, v95, s35, v85
	v_med3_f32 v81, v81, s35, v85
	v_add_f32_e32 v75, 0x4b400000, v75
	v_add_f32_e32 v94, 0x4b400000, v94
	v_add_f32_e32 v80, 0x4b400000, v80
	v_add_f32_e32 v81, 0x4b400000, v81
	v_lshlrev_b64 v[78:79], 11, v[76:77]
	v_perm_b32 v75, v94, v75, s36
	v_perm_b32 v80, v81, v80, s37
	v_lshl_add_u64 v[78:79], v[68:69], 0, v[78:79]
	v_or_b32_e32 v75, v75, v80
	v_pk_mul_f32 v[80:81], v[42:43], s[26:27] op_sel_hi:[1,0]
	v_pk_mul_f32 v[94:95], v[40:41], s[26:27] op_sel_hi:[1,0]
	global_store_dword v[78:79], v75, off
	v_med3_f32 v75, v94, s35, v85
	v_med3_f32 v94, v95, s35, v85
	v_med3_f32 v80, v80, s35, v85
	v_med3_f32 v81, v81, s35, v85
	v_add_f32_e32 v75, 0x4b400000, v75
	v_add_f32_e32 v94, 0x4b400000, v94
	v_add_f32_e32 v80, 0x4b400000, v80
	v_add_f32_e32 v81, 0x4b400000, v81
	v_perm_b32 v75, v94, v75, s36
	v_perm_b32 v80, v81, v80, s37
	v_or_b32_e32 v75, v75, v80
	v_pk_mul_f32 v[80:81], v[38:39], s[26:27] op_sel_hi:[1,0]
	v_pk_mul_f32 v[94:95], v[36:37], s[26:27] op_sel_hi:[1,0]
	global_store_dword v[78:79], v75, off offset:256
	v_med3_f32 v75, v94, s35, v85
	v_med3_f32 v94, v95, s35, v85
	v_med3_f32 v80, v80, s35, v85
	v_med3_f32 v81, v81, s35, v85
	v_add_f32_e32 v75, 0x4b400000, v75
	v_add_f32_e32 v94, 0x4b400000, v94
	v_add_f32_e32 v80, 0x4b400000, v80
	v_add_f32_e32 v81, 0x4b400000, v81
	v_perm_b32 v75, v94, v75, s36
	v_perm_b32 v80, v81, v80, s37
	v_or_b32_e32 v75, v75, v80
	v_pk_mul_f32 v[80:81], v[34:35], s[26:27] op_sel_hi:[1,0]
	v_pk_mul_f32 v[94:95], v[32:33], s[26:27] op_sel_hi:[1,0]
	global_store_dword v[78:79], v75, off offset:512
	v_med3_f32 v75, v94, s35, v85
	v_med3_f32 v94, v95, s35, v85
	v_med3_f32 v80, v80, s35, v85
	v_med3_f32 v81, v81, s35, v85
	v_add_f32_e32 v75, 0x4b400000, v75
	v_add_f32_e32 v94, 0x4b400000, v94
	v_add_f32_e32 v80, 0x4b400000, v80
	v_add_f32_e32 v81, 0x4b400000, v81
	v_perm_b32 v75, v94, v75, s36
	v_perm_b32 v80, v81, v80, s37
	v_or_b32_e32 v75, v75, v80
	v_pk_mul_f32 v[80:81], v[62:63], s[26:27] op_sel_hi:[1,0]
	v_pk_mul_f32 v[94:95], v[60:61], s[26:27] op_sel_hi:[1,0]
	global_store_dword v[78:79], v75, off offset:768
	v_med3_f32 v75, v94, s35, v85
	v_med3_f32 v94, v95, s35, v85
	v_med3_f32 v80, v80, s35, v85
	v_med3_f32 v81, v81, s35, v85
	v_add_f32_e32 v75, 0x4b400000, v75
	v_add_f32_e32 v94, 0x4b400000, v94
	v_add_f32_e32 v80, 0x4b400000, v80
	v_add_f32_e32 v81, 0x4b400000, v81
	v_perm_b32 v75, v94, v75, s36
	v_perm_b32 v80, v81, v80, s37
	v_or_b32_e32 v75, v75, v80
	v_pk_mul_f32 v[80:81], v[58:59], s[26:27] op_sel_hi:[1,0]
	v_pk_mul_f32 v[94:95], v[56:57], s[26:27] op_sel_hi:[1,0]
	global_store_dword v[78:79], v75, off offset:1024
	v_med3_f32 v75, v94, s35, v85
	v_med3_f32 v94, v95, s35, v85
	v_med3_f32 v80, v80, s35, v85
	v_med3_f32 v81, v81, s35, v85
	v_add_f32_e32 v75, 0x4b400000, v75
	v_add_f32_e32 v94, 0x4b400000, v94
	v_add_f32_e32 v80, 0x4b400000, v80
	v_add_f32_e32 v81, 0x4b400000, v81
	v_perm_b32 v75, v94, v75, s36
	v_perm_b32 v80, v81, v80, s37
	v_or_b32_e32 v75, v75, v80
	v_pk_mul_f32 v[94:95], v[52:53], s[26:27] op_sel_hi:[1,0]
	global_store_dword v[78:79], v75, off offset:1280
	v_med3_f32 v75, v94, s35, v85
	v_med3_f32 v94, v95, s35, v85
	v_add_f32_e32 v75, 0x4b400000, v75
	v_add_f32_e32 v94, 0x4b400000, v94
	v_perm_b32 v75, v94, v75, s36
	ds_read_b128 v[94:97], v65
	ds_read_b128 v[98:101], v65 offset:1024
	v_pk_mul_f32 v[80:81], v[54:55], s[26:27] op_sel_hi:[1,0]
	v_pk_mul_f32 v[102:103], v[50:51], s[26:27] op_sel_hi:[1,0]
	v_med3_f32 v80, v80, s35, v85
	s_waitcnt lgkmcnt(1)
	v_fma_f32 v104, v44, v94, 0
	v_fmac_f32_e32 v104, v45, v95
	v_fmac_f32_e32 v104, v46, v96
	v_fmac_f32_e32 v104, v47, v97
	ds_read_b128 v[94:97], v65 offset:2048
	s_waitcnt lgkmcnt(1)
	v_fmac_f32_e32 v104, v40, v98
	v_fmac_f32_e32 v104, v41, v99
	v_fmac_f32_e32 v104, v42, v100
	v_fmac_f32_e32 v104, v43, v101
	ds_read_b128 v[98:101], v65 offset:3072
	s_waitcnt lgkmcnt(1)
	v_fmac_f32_e32 v104, v36, v94
	v_fmac_f32_e32 v104, v37, v95
	v_fmac_f32_e32 v104, v38, v96
	v_fmac_f32_e32 v104, v39, v97
	ds_read_b128 v[94:97], v65 offset:4096
	s_waitcnt lgkmcnt(1)
	v_fmac_f32_e32 v104, v32, v98
	v_fmac_f32_e32 v104, v33, v99
	v_fmac_f32_e32 v104, v34, v100
	v_fmac_f32_e32 v104, v35, v101
	ds_read_b128 v[98:101], v65 offset:5120
	s_waitcnt lgkmcnt(1)
	v_fmac_f32_e32 v104, v60, v94
	v_fmac_f32_e32 v104, v61, v95
	v_fmac_f32_e32 v104, v62, v96
	v_fmac_f32_e32 v104, v63, v97
	ds_read_b128 v[94:97], v65 offset:6144
	s_waitcnt lgkmcnt(1)
	v_fmac_f32_e32 v104, v56, v98
	v_fmac_f32_e32 v104, v57, v99
	v_fmac_f32_e32 v104, v58, v100
	v_fmac_f32_e32 v104, v59, v101
	ds_read_b128 v[98:101], v65 offset:7168
	s_waitcnt lgkmcnt(1)
	v_fmac_f32_e32 v104, v52, v94
	v_fmac_f32_e32 v104, v53, v95
	v_fmac_f32_e32 v104, v54, v96
	v_fmac_f32_e32 v104, v55, v97
	s_waitcnt lgkmcnt(0)
	v_fmac_f32_e32 v104, v48, v98
	v_fmac_f32_e32 v104, v49, v99
	v_fmac_f32_e32 v104, v50, v100
	v_fmac_f32_e32 v104, v51, v101
	s_nop 1
	v_mov_b32_dpp v98, v104 quad_perm:[1,0,3,2] row_mask:0xf bank_mask:0xf
	v_med3_f32 v81, v81, s35, v85
	ds_read_b128 v[94:97], v65 offset:8192
	v_add_f32_e32 v80, 0x4b400000, v80
	v_add_f32_e32 v81, 0x4b400000, v81
	v_perm_b32 v80, v81, v80, s37
	v_or_b32_e32 v75, v75, v80
	v_pk_mul_f32 v[80:81], v[48:49], s[26:27] op_sel_hi:[1,0]
	global_store_dword v[78:79], v75, off offset:1536
	v_med3_f32 v75, v80, s35, v85
	v_med3_f32 v80, v81, s35, v85
	v_med3_f32 v81, v102, s35, v85
	s_waitcnt lgkmcnt(0)
; #define LAS __attribute__((address_space(3)))
; __device__ __forceinline__ float wave_sum(float v) {
; #pragma unroll
;     for (int o = 1; o < 64; o <<= 1) v += __shfl_xor(v, o);
;     return v;
; }
; __device__ __forceinline__ void xprep_row(const f32x4 (&v)[8], const int m, LAS float* wf, bf16_t* XB, float* LOGF, const float* bfg, const int lane) {
;     ...
;         for (int e = 0; e < 8; ++e) { float s = 0.f;
; #pragma unroll
;             for (int j = 0; j < 8; ++j) { const f32x4 w = *(const LAS f32x4*)(wf + e * 2048 + 256 * j + 4 * lane); s = fmaf(v[j][0], w[0], s); s = fmaf(v[j][1], w[1], s); s = fmaf(v[j][2], w[2], s); s = fmaf(v[j][3], w[3], s); }
;             f[e] = wave_sum(s); }
	v_add_f32_e32 v102, v104, v98
	ds_read_b128 v[98:101], v65 offset:9216
	s_waitcnt lgkmcnt(1)
	v_fma_f32 v105, v44, v94, 0
	v_fmac_f32_e32 v105, v45, v95
	v_fmac_f32_e32 v105, v46, v96
	v_fmac_f32_e32 v105, v47, v97
	ds_read_b128 v[94:97], v65 offset:10240
	s_waitcnt lgkmcnt(1)
	v_fmac_f32_e32 v105, v40, v98
	v_fmac_f32_e32 v105, v41, v99
	v_fmac_f32_e32 v105, v42, v100
	v_fmac_f32_e32 v105, v43, v101
	ds_read_b128 v[98:101], v65 offset:11264
	s_waitcnt lgkmcnt(1)
	v_fmac_f32_e32 v105, v36, v94
	v_fmac_f32_e32 v105, v37, v95
	v_fmac_f32_e32 v105, v38, v96
	v_fmac_f32_e32 v105, v39, v97
	ds_read_b128 v[94:97], v65 offset:12288
	s_waitcnt lgkmcnt(1)
	v_fmac_f32_e32 v105, v32, v98
	v_fmac_f32_e32 v105, v33, v99
	v_fmac_f32_e32 v105, v34, v100
	v_fmac_f32_e32 v105, v35, v101
	ds_read_b128 v[98:101], v65 offset:13312
	s_waitcnt lgkmcnt(1)
	v_fmac_f32_e32 v105, v60, v94
	v_fmac_f32_e32 v105, v61, v95
	v_fmac_f32_e32 v105, v62, v96
	v_fmac_f32_e32 v105, v63, v97
	ds_read_b128 v[94:97], v65 offset:14336
	s_waitcnt lgkmcnt(1)
	v_fmac_f32_e32 v105, v56, v98
	v_fmac_f32_e32 v105, v57, v99
	v_fmac_f32_e32 v105, v58, v100
	v_fmac_f32_e32 v105, v59, v101
	ds_read_b128 v[98:101], v65 offset:15360
	s_waitcnt lgkmcnt(1)
	v_fmac_f32_e32 v105, v52, v94
	v_fmac_f32_e32 v105, v53, v95
	v_fmac_f32_e32 v105, v54, v96
	v_fmac_f32_e32 v105, v55, v97
	s_nop 1
	v_mov_b32_dpp v104, v102 quad_perm:[2,3,0,1] row_mask:0xf bank_mask:0xf
	s_waitcnt lgkmcnt(0)
	v_fmac_f32_e32 v105, v48, v98
	v_fmac_f32_e32 v105, v49, v99
	v_fmac_f32_e32 v105, v50, v100
	v_fmac_f32_e32 v105, v51, v101
	s_nop 1
	v_mov_b32_dpp v94, v105 quad_perm:[1,0,3,2] row_mask:0xf bank_mask:0xf
	s_waitcnt lgkmcnt(0)
	v_add_f32_e32 v95, v102, v104
	s_nop 1
	v_mov_b32_dpp v96, v95 row_half_mirror row_mask:0xf bank_mask:0xf
	v_med3_f32 v97, v103, s35, v85
	v_add_f32_e32 v75, 0x4b400000, v75
	s_waitcnt lgkmcnt(0)
	v_add_f32_e32 v100, v105, v94
	s_nop 1
	v_mov_b32_dpp v101, v100 quad_perm:[2,3,0,1] row_mask:0xf bank_mask:0xf
	v_add_f32_e32 v94, 0x4b400000, v97
	s_waitcnt lgkmcnt(0)
	v_add_f32_e32 v95, v95, v96
	ds_read_b128 v[96:99], v65 offset:16384
	s_nop 1
	v_mov_b32_dpp v104, v95 row_mirror row_mask:0xf bank_mask:0xf
	s_waitcnt lgkmcnt(1)
	v_add_f32_e32 v105, v100, v101
	ds_read_b128 v[100:103], v65 offset:17408
	s_nop 1
	v_mov_b32_dpp v106, v105 row_half_mirror row_mask:0xf bank_mask:0xf
	s_waitcnt lgkmcnt(1)
	v_fma_f32 v107, v44, v96, 0
	v_fmac_f32_e32 v107, v45, v97
	v_fmac_f32_e32 v107, v46, v98
	v_fmac_f32_e32 v107, v47, v99
	ds_read_b128 v[96:99], v65 offset:18432
	s_waitcnt lgkmcnt(0)
	v_fmac_f32_e32 v107, v40, v100
	v_fmac_f32_e32 v107, v41, v101
	v_fmac_f32_e32 v107, v42, v102
	v_fmac_f32_e32 v107, v43, v103
	ds_read_b128 v[100:103], v65 offset:19456
	s_waitcnt lgkmcnt(1)
	v_fmac_f32_e32 v107, v36, v96
	v_fmac_f32_e32 v107, v37, v97
	v_fmac_f32_e32 v107, v38, v98
	v_fmac_f32_e32 v107, v39, v99
	ds_read_b128 v[96:99], v65 offset:20480
	s_waitcnt lgkmcnt(1)
	v_fmac_f32_e32 v107, v32, v100
	v_fmac_f32_e32 v107, v33, v101
	v_fmac_f32_e32 v107, v34, v102
	v_fmac_f32_e32 v107, v35, v103
	ds_read_b128 v[100:103], v65 offset:21504
	s_waitcnt lgkmcnt(1)
	v_fmac_f32_e32 v107, v60, v96
	v_fmac_f32_e32 v107, v61, v97
	v_fmac_f32_e32 v107, v62, v98
	v_fmac_f32_e32 v107, v63, v99
	ds_read_b128 v[96:99], v65 offset:22528
	s_waitcnt lgkmcnt(1)
	v_fmac_f32_e32 v107, v56, v100
	v_fmac_f32_e32 v107, v57, v101
	v_fmac_f32_e32 v107, v58, v102
	v_fmac_f32_e32 v107, v59, v103
	ds_read_b128 v[100:103], v65 offset:23552
	s_waitcnt lgkmcnt(1)
	v_fmac_f32_e32 v107, v52, v96
	v_fmac_f32_e32 v107, v53, v97
	v_fmac_f32_e32 v107, v54, v98
	v_fmac_f32_e32 v107, v55, v99
	s_waitcnt lgkmcnt(0)
	v_fmac_f32_e32 v107, v48, v100
	v_fmac_f32_e32 v107, v49, v101
	v_fmac_f32_e32 v107, v50, v102
	v_fmac_f32_e32 v107, v51, v103
	s_nop 1
	v_mov_b32_dpp v96, v107 quad_perm:[1,0,3,2] row_mask:0xf bank_mask:0xf
	v_add_f32_e32 v95, v95, v104
	v_add_f32_e32 v102, v105, v106
	v_mov_b32_e32 v97, v95
	s_nop 1
	v_permlane16_swap_b32_e32 v95, v97
	s_nop 1
	v_mov_b32_dpp v103, v102 row_mirror row_mask:0xf bank_mask:0xf
	s_waitcnt lgkmcnt(0)
	v_add_f32_e32 v104, v107, v96
	s_nop 1
	v_mov_b32_dpp v105, v104 quad_perm:[2,3,0,1] row_mask:0xf bank_mask:0xf
	ds_read_b128 v[98:101], v65 offset:24576
	s_waitcnt lgkmcnt(2)
	v_add_f32_e32 v95, v95, v97
	s_waitcnt lgkmcnt(1)
	v_add_f32_e32 v97, v102, v103
	ds_bpermute_b32 v96, v93, v95
	s_waitcnt lgkmcnt(1)
	v_add_f32_e32 v106, v104, v105
	ds_read_b128 v[102:105], v65 offset:25600
	s_waitcnt lgkmcnt(1)
	v_fma_f32 v108, v44, v98, 0
	v_fmac_f32_e32 v108, v45, v99
	v_fmac_f32_e32 v108, v46, v100
	v_fmac_f32_e32 v108, v47, v101
	ds_read_b128 v[98:101], v65 offset:26624
	s_waitcnt lgkmcnt(0)
	v_fmac_f32_e32 v108, v40, v102
	v_fmac_f32_e32 v108, v41, v103
	v_fmac_f32_e32 v108, v42, v104
	v_fmac_f32_e32 v108, v43, v105
	ds_read_b128 v[102:105], v65 offset:27648
	s_waitcnt lgkmcnt(1)
	v_fmac_f32_e32 v108, v36, v98
	v_fmac_f32_e32 v108, v37, v99
	v_fmac_f32_e32 v108, v38, v100
	v_fmac_f32_e32 v108, v39, v101
	ds_read_b128 v[98:101], v65 offset:28672
	s_waitcnt lgkmcnt(1)
	v_fmac_f32_e32 v108, v32, v102
	v_fmac_f32_e32 v108, v33, v103
	v_fmac_f32_e32 v108, v34, v104
	v_fmac_f32_e32 v108, v35, v105
	ds_read_b128 v[102:105], v65 offset:29696
	s_waitcnt lgkmcnt(1)
	v_fmac_f32_e32 v108, v60, v98
	v_fmac_f32_e32 v108, v61, v99
	v_fmac_f32_e32 v108, v62, v100
	v_fmac_f32_e32 v108, v63, v101
	ds_read_b128 v[98:101], v65 offset:30720
	s_waitcnt lgkmcnt(1)
	v_fmac_f32_e32 v108, v56, v102
	v_fmac_f32_e32 v108, v57, v103
	v_fmac_f32_e32 v108, v58, v104
	v_fmac_f32_e32 v108, v59, v105
	ds_read_b128 v[102:105], v65 offset:31744
	s_waitcnt lgkmcnt(1)
; #define LAS __attribute__((address_space(3)))
; __device__ __forceinline__ float wave_sum(float v) {
; #pragma unroll
;     for (int o = 1; o < 64; o <<= 1) v += __shfl_xor(v, o);
;     return v;
; }
; __device__ __forceinline__ void xprep_row(const f32x4 (&v)[8], const int m, LAS float* wf, bf16_t* XB, float* LOGF, const float* bfg, const int lane) {
;     ...
;         for (int e = 0; e < 8; ++e) { float s = 0.f;
; #pragma unroll
;             for (int j = 0; j < 8; ++j) { const f32x4 w = *(const LAS f32x4*)(wf + e * 2048 + 256 * j + 4 * lane); s = fmaf(v[j][0], w[0], s); s = fmaf(v[j][1], w[1], s); s = fmaf(v[j][2], w[2], s); s = fmaf(v[j][3], w[3], s); }
;             f[e] = wave_sum(s); }
	v_fmac_f32_e32 v108, v52, v98
	v_fmac_f32_e32 v108, v53, v99
	v_fmac_f32_e32 v108, v54, v100
	v_fmac_f32_e32 v108, v55, v101
	ds_read_b128 v[98:101], v65 offset:32768
	s_waitcnt lgkmcnt(1)
	v_fmac_f32_e32 v108, v48, v102
	v_fmac_f32_e32 v108, v49, v103
	v_fmac_f32_e32 v108, v50, v104
	v_fmac_f32_e32 v108, v51, v105
	ds_read_b128 v[102:105], v65 offset:33792
	s_waitcnt lgkmcnt(1)
	v_fma_f32 v110, v44, v98, 0
	v_fmac_f32_e32 v110, v45, v99
	v_fmac_f32_e32 v110, v46, v100
	v_fmac_f32_e32 v110, v47, v101
	ds_read_b128 v[98:101], v65 offset:34816
	s_waitcnt lgkmcnt(1)
	v_fmac_f32_e32 v110, v40, v102
	v_fmac_f32_e32 v110, v41, v103
	v_fmac_f32_e32 v110, v42, v104
	v_fmac_f32_e32 v110, v43, v105
	ds_read_b128 v[102:105], v65 offset:35840
	s_waitcnt lgkmcnt(1)
	v_fmac_f32_e32 v110, v36, v98
	v_fmac_f32_e32 v110, v37, v99
	v_fmac_f32_e32 v110, v38, v100
	v_fmac_f32_e32 v110, v39, v101
	ds_read_b128 v[98:101], v65 offset:36864
	s_waitcnt lgkmcnt(1)
	v_fmac_f32_e32 v110, v32, v102
	v_fmac_f32_e32 v110, v33, v103
	v_fmac_f32_e32 v110, v34, v104
	v_fmac_f32_e32 v110, v35, v105
	ds_read_b128 v[102:105], v65 offset:37888
	s_waitcnt lgkmcnt(1)
	v_fmac_f32_e32 v110, v60, v98
	v_fmac_f32_e32 v110, v61, v99
	v_fmac_f32_e32 v110, v62, v100
	v_fmac_f32_e32 v110, v63, v101
	ds_read_b128 v[98:101], v65 offset:38912
	s_waitcnt lgkmcnt(1)
	v_fmac_f32_e32 v110, v56, v102
	s_nop 1
	v_mov_b32_dpp v109, v108 quad_perm:[1,0,3,2] row_mask:0xf bank_mask:0xf
	v_fmac_f32_e32 v110, v57, v103
	v_fmac_f32_e32 v110, v58, v104
	v_fmac_f32_e32 v110, v59, v105
	ds_read_b128 v[102:105], v65 offset:39936
	s_waitcnt lgkmcnt(1)
	v_fmac_f32_e32 v110, v52, v98
	v_fmac_f32_e32 v110, v53, v99
	v_fmac_f32_e32 v110, v54, v100
	s_waitcnt lgkmcnt(0)
	v_add_f32_e32 v100, v108, v109
	v_fmac_f32_e32 v110, v55, v101
	s_nop 1
	v_mov_b32_dpp v101, v100 quad_perm:[2,3,0,1] row_mask:0xf bank_mask:0xf
	s_waitcnt lgkmcnt(0)
	v_fmac_f32_e32 v110, v48, v102
	v_fmac_f32_e32 v110, v49, v103
	v_fmac_f32_e32 v110, v50, v104
	v_fmac_f32_e32 v110, v51, v105
	s_nop 1
	v_mov_b32_dpp v98, v110 quad_perm:[1,0,3,2] row_mask:0xf bank_mask:0xf
	s_waitcnt lgkmcnt(0)
	v_add_f32_e32 v100, v100, v101
	s_nop 1
	v_mov_b32_dpp v101, v100 row_half_mirror row_mask:0xf bank_mask:0xf
	s_nop 1
	v_mov_b32_dpp v107, v106 row_half_mirror row_mask:0xf bank_mask:0xf
	v_mov_b32_e32 v99, v97
	s_nop 1
	v_permlane16_swap_b32_e32 v97, v99
	s_waitcnt lgkmcnt(0)
	v_add_f32_e32 v98, v110, v98
	s_nop 1
	v_mov_b32_dpp v103, v98 quad_perm:[2,3,0,1] row_mask:0xf bank_mask:0xf
	s_waitcnt lgkmcnt(0)
	v_add_f32_e32 v100, v100, v101
	s_nop 1
	v_mov_b32_dpp v101, v100 row_mirror row_mask:0xf bank_mask:0xf
	s_waitcnt lgkmcnt(2)
	v_add_f32_e32 v102, v106, v107
	s_nop 1
	v_mov_b32_dpp v104, v102 row_mirror row_mask:0xf bank_mask:0xf
	s_waitcnt lgkmcnt(0)
	v_add_f32_e32 v98, v98, v103
	v_add_f32_e32 v97, v97, v99
	s_nop 1
	v_mov_b32_dpp v99, v98 row_half_mirror row_mask:0xf bank_mask:0xf
	s_waitcnt lgkmcnt(1)
	v_add_f32_e32 v101, v100, v101
	v_mov_b32_e32 v106, v101
	s_nop 1
	v_permlane16_swap_b32_e32 v101, v106
	s_waitcnt lgkmcnt(0)
	v_add_f32_e32 v102, v102, v104
	v_mov_b32_e32 v103, v102
	s_nop 1
	v_permlane16_swap_b32_e32 v102, v103
	s_waitcnt lgkmcnt(0)
	v_add_f32_e32 v104, v98, v99
	s_nop 1
	v_mov_b32_dpp v105, v104 row_mirror row_mask:0xf bank_mask:0xf
	s_waitcnt lgkmcnt(0)
	v_add_f32_e32 v101, v101, v106
	ds_read_b128 v[106:109], v65 offset:40960
	ds_read_b128 v[110:113], v65 offset:41984
	s_waitcnt lgkmcnt(3)
	v_add_f32_e32 v99, v102, v103
	s_waitcnt lgkmcnt(2)
	v_add_f32_e32 v103, v104, v105
	ds_bpermute_b32 v104, v92, v103
	s_waitcnt lgkmcnt(2)
	v_fma_f32 v105, v44, v106, 0
	v_fmac_f32_e32 v105, v45, v107
	v_fmac_f32_e32 v105, v46, v108
	v_fmac_f32_e32 v105, v47, v109
	ds_read_b128 v[106:109], v65 offset:43008
	s_waitcnt lgkmcnt(2)
	v_fmac_f32_e32 v105, v40, v110
	v_fmac_f32_e32 v105, v41, v111
	v_fmac_f32_e32 v105, v42, v112
	v_fmac_f32_e32 v105, v43, v113
	ds_read_b128 v[110:113], v65 offset:44032
	s_waitcnt lgkmcnt(1)
	v_fmac_f32_e32 v105, v36, v106
	v_fmac_f32_e32 v105, v37, v107
	v_fmac_f32_e32 v105, v38, v108
	v_fmac_f32_e32 v105, v39, v109
	ds_read_b128 v[106:109], v65 offset:45056
	s_waitcnt lgkmcnt(1)
	v_fmac_f32_e32 v105, v32, v110
	v_fmac_f32_e32 v105, v33, v111
	v_fmac_f32_e32 v105, v34, v112
	v_fmac_f32_e32 v105, v35, v113
	ds_read_b128 v[110:113], v65 offset:46080
	s_waitcnt lgkmcnt(1)
	v_fmac_f32_e32 v105, v60, v106
	v_fmac_f32_e32 v105, v61, v107
	v_fmac_f32_e32 v105, v62, v108
	v_fmac_f32_e32 v105, v63, v109
	ds_read_b128 v[106:109], v65 offset:47104
	s_waitcnt lgkmcnt(1)
	v_fmac_f32_e32 v105, v56, v110
	v_fmac_f32_e32 v105, v57, v111
	v_fmac_f32_e32 v105, v58, v112
	v_fmac_f32_e32 v105, v59, v113
	ds_read_b128 v[110:113], v65 offset:48128
	s_waitcnt lgkmcnt(1)
	v_fmac_f32_e32 v105, v52, v106
	v_fmac_f32_e32 v105, v53, v107
	v_fmac_f32_e32 v105, v54, v108
	v_fmac_f32_e32 v105, v55, v109
	ds_read_b128 v[106:109], v65 offset:49152
	s_waitcnt lgkmcnt(1)
	v_fmac_f32_e32 v105, v48, v110
	v_fmac_f32_e32 v105, v49, v111
	v_fmac_f32_e32 v105, v50, v112
	v_fmac_f32_e32 v105, v51, v113
	ds_read_b128 v[110:113], v65 offset:50176
	s_waitcnt lgkmcnt(1)
	v_fma_f32 v115, v44, v106, 0
	v_fmac_f32_e32 v115, v45, v107
	v_fmac_f32_e32 v115, v46, v108
	v_fmac_f32_e32 v115, v47, v109
	ds_read_b128 v[106:109], v65 offset:51200
	s_waitcnt lgkmcnt(1)
	v_fmac_f32_e32 v115, v40, v110
	v_fmac_f32_e32 v115, v41, v111
	v_fmac_f32_e32 v115, v42, v112
	v_fmac_f32_e32 v115, v43, v113
	ds_read_b128 v[110:113], v65 offset:52224
	s_waitcnt lgkmcnt(1)
	v_fmac_f32_e32 v115, v36, v106
	v_fmac_f32_e32 v115, v37, v107
	v_fmac_f32_e32 v115, v38, v108
	v_fmac_f32_e32 v115, v39, v109
	ds_read_b128 v[106:109], v65 offset:53248
	s_waitcnt lgkmcnt(1)
; #define LAS __attribute__((address_space(3)))
; __device__ __forceinline__ float wave_sum(float v) {
; #pragma unroll
;     for (int o = 1; o < 64; o <<= 1) v += __shfl_xor(v, o);
;     return v;
; }
; __device__ __forceinline__ void xprep_row(const f32x4 (&v)[8], const int m, LAS float* wf, bf16_t* XB, float* LOGF, const float* bfg, const int lane) {
;     ...
;         for (int e = 0; e < 8; ++e) { float s = 0.f;
; #pragma unroll
;             for (int j = 0; j < 8; ++j) { const f32x4 w = *(const LAS f32x4*)(wf + e * 2048 + 256 * j + 4 * lane); s = fmaf(v[j][0], w[0], s); s = fmaf(v[j][1], w[1], s); s = fmaf(v[j][2], w[2], s); s = fmaf(v[j][3], w[3], s); }
;             f[e] = wave_sum(s); }
	v_fmac_f32_e32 v115, v32, v110
	v_fmac_f32_e32 v115, v33, v111
	v_fmac_f32_e32 v115, v34, v112
	v_fmac_f32_e32 v115, v35, v113
	ds_read_b128 v[110:113], v65 offset:54272
	s_waitcnt lgkmcnt(1)
	v_fmac_f32_e32 v115, v60, v106
	v_fmac_f32_e32 v115, v61, v107
	v_fmac_f32_e32 v115, v62, v108
	v_fmac_f32_e32 v115, v63, v109
	ds_read_b128 v[106:109], v65 offset:55296
	s_waitcnt lgkmcnt(1)
	v_fmac_f32_e32 v115, v56, v110
	v_fmac_f32_e32 v115, v57, v111
	v_fmac_f32_e32 v115, v58, v112
	v_fmac_f32_e32 v115, v59, v113
	ds_read_b128 v[110:113], v65 offset:56320
	s_waitcnt lgkmcnt(1)
	v_fmac_f32_e32 v115, v52, v106
	v_fmac_f32_e32 v115, v53, v107
	v_fmac_f32_e32 v115, v54, v108
	v_fmac_f32_e32 v115, v55, v109
	ds_read_b128 v[106:109], v65 offset:57344
	s_waitcnt lgkmcnt(1)
	v_fmac_f32_e32 v115, v48, v110
	v_fmac_f32_e32 v115, v49, v111
	v_fmac_f32_e32 v115, v50, v112
	v_fmac_f32_e32 v115, v51, v113
	ds_read_b128 v[110:113], v65 offset:58368
	s_waitcnt lgkmcnt(1)
	v_fma_f32 v117, v44, v106, 0
	v_fmac_f32_e32 v117, v45, v107
	v_fmac_f32_e32 v117, v46, v108
	v_fmac_f32_e32 v117, v47, v109
	ds_read_b128 v[106:109], v65 offset:59392
	s_waitcnt lgkmcnt(1)
	v_fmac_f32_e32 v117, v40, v110
	v_fmac_f32_e32 v117, v41, v111
	v_fmac_f32_e32 v117, v42, v112
	v_fmac_f32_e32 v117, v43, v113
	ds_read_b128 v[110:113], v65 offset:60416
	s_waitcnt lgkmcnt(1)
	v_fmac_f32_e32 v117, v36, v106
	v_fmac_f32_e32 v117, v37, v107
	v_fmac_f32_e32 v117, v38, v108
	v_fmac_f32_e32 v117, v39, v109
	ds_read_b128 v[106:109], v65 offset:61440
	s_waitcnt lgkmcnt(1)
	v_fmac_f32_e32 v117, v32, v110
	v_fmac_f32_e32 v117, v33, v111
	v_fmac_f32_e32 v117, v34, v112
	v_fmac_f32_e32 v117, v35, v113
	ds_read_b128 v[110:113], v65 offset:62464
	s_waitcnt lgkmcnt(1)
	v_fmac_f32_e32 v117, v60, v106
	v_fmac_f32_e32 v117, v61, v107
	v_fmac_f32_e32 v117, v62, v108
	v_fmac_f32_e32 v117, v63, v109
	ds_read_b128 v[106:109], v65 offset:63488
	s_waitcnt lgkmcnt(1)
	v_fmac_f32_e32 v117, v56, v110
	v_fmac_f32_e32 v117, v57, v111
	v_fmac_f32_e32 v117, v58, v112
	v_fmac_f32_e32 v117, v59, v113
	ds_read_b128 v[110:113], v65 offset:64512
	s_waitcnt lgkmcnt(1)
	v_fmac_f32_e32 v117, v52, v106
	v_fmac_f32_e32 v117, v53, v107
	v_fmac_f32_e32 v117, v54, v108
	v_fmac_f32_e32 v117, v55, v109
	s_waitcnt lgkmcnt(0)
	v_fmac_f32_e32 v117, v48, v110
	v_fmac_f32_e32 v117, v49, v111
	v_fmac_f32_e32 v117, v50, v112
	v_fmac_f32_e32 v117, v51, v113
	s_nop 1
	v_mov_b32_dpp v114, v105 quad_perm:[1,0,3,2] row_mask:0xf bank_mask:0xf
	s_nop 1
	v_mov_b32_dpp v116, v115 quad_perm:[1,0,3,2] row_mask:0xf bank_mask:0xf
	s_nop 1
	v_mov_b32_dpp v90, v117 quad_perm:[1,0,3,2] row_mask:0xf bank_mask:0xf
	v_add_f32_e32 v103, v103, v104
	ds_bpermute_b32 v98, v93, v97
	s_waitcnt lgkmcnt(0)
	v_add_f32_e32 v105, v105, v114
	s_waitcnt lgkmcnt(2)
	v_add_f32_e32 v107, v115, v116
	s_waitcnt lgkmcnt(1)
	v_add_f32_e32 v90, v117, v90
	s_nop 1
	v_mov_b32_dpp v106, v105 quad_perm:[2,3,0,1] row_mask:0xf bank_mask:0xf
	s_nop 1
	v_mov_b32_dpp v108, v107 quad_perm:[2,3,0,1] row_mask:0xf bank_mask:0xf
	s_nop 1
	v_mov_b32_dpp v89, v90 quad_perm:[2,3,0,1] row_mask:0xf bank_mask:0xf
	ds_bpermute_b32 v100, v93, v99
	ds_bpermute_b32 v102, v93, v101
	s_waitcnt lgkmcnt(1)
	v_add_f32_e32 v105, v105, v106
	s_waitcnt lgkmcnt(0)
	v_add_f32_e32 v107, v107, v108
	s_waitcnt lgkmcnt(2)
	v_add_f32_e32 v89, v90, v89
	s_nop 1
	v_mov_b32_dpp v106, v105 row_half_mirror row_mask:0xf bank_mask:0xf
	s_nop 1
	v_mov_b32_dpp v108, v107 row_half_mirror row_mask:0xf bank_mask:0xf
	s_nop 1
	v_mov_b32_dpp v88, v89 row_half_mirror row_mask:0xf bank_mask:0xf
	v_mov_b32_e32 v104, v103
	s_nop 1
	v_permlane32_swap_b32_e32 v103, v104
	v_add_f32_e32 v80, 0x4b400000, v80
	s_waitcnt lgkmcnt(0)
	v_add_f32_e32 v90, v105, v106
	s_waitcnt lgkmcnt(2)
	v_add_f32_e32 v106, v107, v108
	s_waitcnt lgkmcnt(1)
	v_add_f32_e32 v88, v89, v88
	s_nop 1
	v_mov_b32_dpp v105, v90 row_mirror row_mask:0xf bank_mask:0xf
	s_nop 1
	v_mov_b32_dpp v107, v106 row_mirror row_mask:0xf bank_mask:0xf
	s_nop 1
	v_mov_b32_dpp v89, v88 row_mirror row_mask:0xf bank_mask:0xf
	v_add_f32_e32 v81, 0x4b400000, v81
	v_perm_b32 v75, v80, v75, s36
	s_waitcnt lgkmcnt(0)
	v_add_f32_e32 v90, v90, v105
	s_waitcnt lgkmcnt(1)
	v_add_f32_e32 v105, v106, v107
	s_waitcnt lgkmcnt(0)
	v_add_f32_e32 v107, v88, v89
	v_mov_b32_e32 v91, v90
	s_nop 1
	v_permlane16_swap_b32_e32 v90, v91
	v_mov_b32_e32 v106, v105
	s_nop 1
	v_permlane16_swap_b32_e32 v105, v106
	v_mov_b32_e32 v92, v107
	s_nop 1
	v_permlane16_swap_b32_e32 v107, v92
	v_perm_b32 v80, v94, v81, s37
	v_or_b32_e32 v75, v75, v80
	s_waitcnt lgkmcnt(0)
	v_add_f32_e32 v88, v90, v91
	s_waitcnt lgkmcnt(1)
	v_add_f32_e32 v90, v105, v106
	s_waitcnt lgkmcnt(0)
	v_add_f32_e32 v92, v107, v92
	v_mov_b32_e32 v89, v88
	s_nop 1
	v_permlane32_swap_b32_e32 v88, v89
	v_mov_b32_e32 v91, v90
	s_nop 1
	v_permlane32_swap_b32_e32 v90, v91
	v_mov_b32_e32 v93, v92
	s_nop 1
	v_permlane32_swap_b32_e32 v92, v93
	global_store_dword v[78:79], v75, off offset:1792
	s_and_saveexec_b64 s[30:31], s[2:3]
	s_cbranch_execz .LBB0_985
; __device__ __forceinline__ void xprep_row(const f32x4 (&v)[8], const int m, LAS float* wf, bf16_t* XB, float* LOGF, const float* bfg, const int lane) {
;     ...
;         if (lane < 8) { float z = 0.f;
; #pragma unroll
;             for (int e = 0; e < 8; ++e) z = (lane == e) ? f[e] : z;
;             z += bfg[lane];
;             LOGF[(size_t)m * 8 + lane] = fminf(z, 0.f) - log1pf(expf(-fabsf(z))); }
	global_load_dword v75, v[70:71], off
	s_waitcnt lgkmcnt(0)
	v_add_f32_e32 v79, v90, v91
	v_add_f32_e32 v91, v95, v96
	v_add_f32_e32 v90, v97, v98
	v_cndmask_b32_e64 v91, 0, v91, s[4:5]
	v_add_f32_e32 v80, v88, v89
	v_add_f32_e32 v89, v99, v100
	v_cndmask_b32_e64 v90, v91, v90, s[6:7]
	v_add_f32_e32 v88, v101, v102
	v_cndmask_b32_e64 v89, v90, v89, s[8:9]
	v_add_f32_e32 v81, v103, v104
	v_cndmask_b32_e64 v88, v89, v88, s[10:11]
	v_cndmask_b32_e64 v81, v88, v81, s[12:13]
	v_cndmask_b32_e64 v80, v81, v80, s[14:15]
	s_waitcnt lgkmcnt(0)
	v_add_f32_e32 v78, v92, v93
	v_cndmask_b32_e64 v79, v80, v79, s[16:17]
	v_cndmask_b32_e64 v78, v79, v78, s[18:19]
	s_waitcnt vmcnt(0)
	v_add_f32_e32 v75, v78, v75
	v_mul_f32_e64 v78, |v75|, s38
	v_fma_f32 v79, |v75|, s38, -v78
	v_rndne_f32_e32 v80, v78
	v_fma_f32 v79, |v75|, s39, v79
	v_sub_f32_e32 v78, v78, v80
	v_add_f32_e32 v78, v78, v79
	v_cvt_i32_f32_e32 v80, v80
	v_exp_f32_e32 v81, v78
	v_cmp_ngt_f32_e64 vcc, |v75|, s40
	v_lshlrev_b64 v[78:79], 5, v[76:77]
	v_min_f32_e32 v77, 0, v75
	v_ldexp_f32 v80, v81, v80
	v_cndmask_b32_e32 v80, 0, v80, vcc
	v_cmp_nlt_f32_e64 vcc, |v75|, s41
	v_lshl_add_u64 v[78:79], v[72:73], 0, v[78:79]
	s_nop 0
	v_cndmask_b32_e32 v100, v87, v80, vcc
	v_add_f32_e32 v75, 1.0, v100
	v_add_f32_e32 v88, -1.0, v75
	v_frexp_mant_f32_e32 v89, v75
	v_cvt_f64_f32_e32 v[80:81], v75
	v_sub_f32_e32 v90, v88, v75
	v_frexp_exp_i32_f64_e32 v80, v[80:81]
	v_cmp_gt_f32_e32 vcc, s43, v89
	v_sub_f32_e32 v88, v100, v88
	v_add_f32_e32 v81, 1.0, v90
	v_subbrev_co_u32_e32 v80, vcc, 0, v80, vcc
	v_add_f32_e32 v81, v88, v81
	v_sub_u32_e32 v88, 0, v80
	v_ldexp_f32 v75, v75, v88
	v_ldexp_f32 v81, v81, v88
	v_add_f32_e32 v88, -1.0, v75
	v_add_f32_e32 v90, 1.0, v75
	v_add_f32_e32 v89, 1.0, v88
	v_add_f32_e32 v91, -1.0, v90
	v_sub_f32_e32 v89, v75, v89
	v_sub_f32_e32 v75, v75, v91
	v_add_f32_e32 v75, v81, v75
	v_add_f32_e32 v91, v81, v89
	v_add_f32_e32 v81, v90, v75
	v_rcp_f32_e32 v94, v81
	v_add_f32_e32 v89, v88, v91
	v_sub_f32_e32 v90, v90, v81
	v_add_f32_e32 v75, v75, v90
	v_mul_f32_e32 v96, v89, v94
	v_mul_f32_e32 v90, v81, v96
	v_fma_f32 v92, v96, v81, -v90
	v_sub_f32_e32 v88, v88, v89
	v_fmac_f32_e32 v92, v96, v75
	v_add_f32_e32 v95, v91, v88
	v_add_f32_e32 v88, v90, v92
	v_sub_f32_e32 v91, v89, v88
	v_mov_b32_e32 v93, v88
	v_pk_add_f32 v[88:89], v[88:89], v[90:91] neg_lo:[0,1] neg_hi:[0,1]
	v_cvt_f32_i32_e32 v80, v80
	v_pk_add_f32 v[88:89], v[88:89], v[92:93] neg_lo:[0,1] neg_hi:[0,1]
	v_cmp_neq_f32_e32 vcc, s42, v100
	v_add_f32_e32 v89, v95, v89
	v_add_f32_e32 v88, v88, v89
	v_add_f32_e32 v89, v91, v88
	v_mul_f32_e32 v93, v94, v89
	v_mul_f32_e32 v90, v81, v93
	v_fma_f32 v92, v93, v81, -v90
	v_sub_f32_e32 v91, v91, v89
	v_fmac_f32_e32 v92, v93, v75
	v_add_f32_e32 v95, v88, v91
	v_add_f32_e32 v97, v96, v93
	v_add_f32_e32 v88, v90, v92
	v_sub_f32_e32 v81, v97, v96
	v_sub_f32_e32 v91, v89, v88
	v_sub_f32_e32 v75, v93, v81
	v_mov_b32_e32 v93, v88
	v_pk_add_f32 v[88:89], v[88:89], v[90:91] neg_lo:[0,1] neg_hi:[0,1]
	s_nop 0
	v_pk_add_f32 v[88:89], v[88:89], v[92:93] neg_lo:[0,1] neg_hi:[0,1]
	s_nop 0
	v_add_f32_e32 v81, v95, v89
	v_add_f32_e32 v81, v88, v81
	v_add_f32_e32 v81, v91, v81
	v_mul_f32_e32 v81, v94, v81
	v_add_f32_e32 v75, v75, v81
	v_add_f32_e32 v81, v97, v75
	v_mul_f32_e32 v88, v81, v81
	v_sub_f32_e32 v90, v81, v97
	v_fmamk_f32 v91, v88, 0x3e9b6dac, v84
	v_ldexp_f32 v89, v81, 1
	v_sub_f32_e32 v90, v75, v90
	v_mul_f32_e32 v81, v81, v88
	v_fmaak_f32 v75, v88, v91, 0x3f2aaada
	v_ldexp_f32 v93, v90, 1
	v_pk_mul_f32 v[90:91], v[80:81], v[74:75]
	s_nop 0
	v_fma_f32 v88, v80, s44, -v90
	v_fmac_f32_e32 v88, 0xb102e308, v80
	v_pk_add_f32 v[80:81], v[90:91], v[88:89]
	v_mov_b32_e32 v92, v90
	v_sub_f32_e32 v75, v81, v89
	v_sub_f32_e32 v75, v91, v75
	v_add_f32_e32 v93, v93, v75
	v_pk_add_f32 v[94:95], v[80:81], v[90:91] neg_lo:[0,1] neg_hi:[0,1]
	v_pk_add_f32 v[90:91], v[80:81], v[92:93]
	v_mov_b32_e32 v89, v80
	v_mov_b32_e32 v95, v91
	v_pk_add_f32 v[98:99], v[88:89], v[94:95] neg_lo:[0,1] neg_hi:[0,1]
	v_pk_add_f32 v[88:89], v[88:89], v[94:95]
	v_mov_b32_e32 v97, v80
	v_pk_add_f32 v[94:95], v[88:89], v[80:81] op_sel:[1,0] op_sel_hi:[0,1] neg_lo:[0,1] neg_hi:[0,1]
	v_mov_b32_e32 v96, v93
	v_mov_b32_e32 v92, v91
	v_mov_b32_e32 v93, v89
	v_pk_mov_b32 v[80:81], v[80:81], v[94:95] op_sel:[1,0]
	v_pk_add_f32 v[90:91], v[90:91], v[94:95] op_sel_hi:[1,0] neg_lo:[0,1] neg_hi:[0,1]
	v_pk_add_f32 v[80:81], v[92:93], v[80:81] neg_lo:[0,1] neg_hi:[0,1]
	v_mov_b32_e32 v90, v98
	v_pk_add_f32 v[80:81], v[96:97], v[80:81] neg_lo:[0,1] neg_hi:[0,1]
	v_mov_b32_e32 v99, v89
	v_pk_add_f32 v[90:91], v[90:91], v[80:81]
	s_nop 0
	v_pk_add_f32 v[92:93], v[90:91], v[90:91] op_sel:[0,1] op_sel_hi:[1,0]
	s_nop 0
	v_pk_add_f32 v[88:89], v[88:89], v[92:93] op_sel:[1,0] op_sel_hi:[0,1]
	v_mov_b32_e32 v91, v88
	v_mov_b32_e32 v81, v92
	v_pk_add_f32 v[92:93], v[90:91], v[98:99] neg_lo:[0,1] neg_hi:[0,1]
	s_nop 0
	v_sub_f32_e32 v75, v90, v92
	v_pk_add_f32 v[80:81], v[80:81], v[92:93] neg_lo:[0,1] neg_hi:[0,1]
	v_sub_f32_e32 v75, v98, v75
	v_add_f32_e32 v75, v80, v75
	v_add_f32_e32 v75, v75, v81
	v_add_f32_e32 v75, v88, v75
	v_cndmask_b32_e32 v75, v87, v75, vcc
	v_cmp_lt_f32_e64 vcc, |v100|, s45
	s_nop 1
	v_cndmask_b32_e32 v75, v75, v100, vcc
	v_sub_f32_e32 v75, v77, v75
	global_store_dword v[78:79], v75, off
	s_branch .LBB0_985

; __device__ __forceinline__ u32x4 pack8bf(const f32x4 a, const f32x4 b) { u32x4 w; w.x = cvt_pk_bf16(a[0], a[1]); w.y = cvt_pk_bf16(a[2], a[3]); w.z = cvt_pk_bf16(b[0], b[1]); w.w = cvt_pk_bf16(b[2], b[3]); return w; }
;     __device__ __forceinline__ float qscale(const Unit& u) const { return ((u.pn >= 8 && u.pn <= 11) || u.pn == 17) ? 0.5f : 1.0f; }
;     ...
;         if constexpr (QM == 2) { const float qs0_ = g.qs * E.qscale(cur), qs1_ = qs0_ * g.qs_b1; _Pragma("unroll") for (int a = 0; a < 2; ++a) _Pragma("unroll") for (int b = 0; b < 2; ++b) _Pragma("unroll") for (int m = 0; m < 4; ++m) _Pragma("unroll") for (int n = 0; n < 2; ++n) { const v4i t_ = __builtin_bit_cast(v4i, acc[a][b][m][n]); acc[a][b][m][n] = (f32x4){(float)t_[0], (float)t_[1], (float)t_[2], (float)t_[3]} * (b == 0 ? qs0_ : qs1_); } }
;     __device__ __forceinline__ void operator()(EPI_ARGS) const {
;         const int row0 = u.pm * BM + wr * 64 + fr; const bool rot = (u.pn >= 12 && u.pn <= 16); const int fi = 16 * wc + 4 * fq;
; #pragma unroll
;         for (int ai = 0; ai < 2; ++ai)
; #pragma unroll
;             for (int m = 0; m < 4; ++m) { const int row = row0 + ai * HALF + m * 16;
;                 f32x4 c4 = (f32x4){1.f, 1.f, 1.f, 1.f}, s4 = (f32x4){0.f, 0.f, 0.f, 0.f};
;                 if (rot) { c4 = *(const f32x4*)(cs + (size_t)row * 64 + fi); s4 = *(const f32x4*)(sn + (size_t)row * 64 + fi); }
; #pragma unroll
;                 for (int bj = 0; bj < 2; ++bj) { const int hd = 2 * u.pn + bj; const f32x4 v0 = acc[ai][bj][m][0], v1 = acc[ai][bj][m][1];
;                     const f32x4 o0 = v0 * c4 - v1 * s4, o1 = v1 * c4 + v0 * s4;
;                     *(u32x4*)(O + ((size_t)hd * NTOK + row) * 128 + 32 * wc + 8 * fq) = pack8bf(o0, o1);
;                     if (u.pn < 8) { float s = ((o0[0] * o0[0] + o0[1] * o0[1]) + (o0[2] * o0[2] + o0[3] * o0[3])) + ((o1[0] * o1[0] + o1[1] * o1[1]) + (o1[2] * o1[2] + o1[3] * o1[3]));
;                         s += __shfl_xor(s, 16); s += __shfl_xor(s, 32);
;                         if (fq == 0) nrm[((size_t)hd * NTOK + row) * 4 + wc] = s; } } }
.LBB0_1090:
	s_lshl_b32 s30, s6, 1
	s_cmp_lt_i32 s6, 8
	s_cselect_b64 s[8:9], -1, 0
	s_and_b32 s7, s6, -4
	s_cmp_eq_u32 s7, 8
	s_cselect_b64 s[28:29], -1, 0
	s_cmp_eq_u32 s6, 17
	v_cvt_f32_i32_e32 v121, v121
	v_cvt_f32_i32_e32 v123, v123
	v_cvt_f32_i32_e32 v122, v122
	v_cvt_f32_i32_e32 v120, v120
	s_cselect_b64 s[58:59], -1, 0
	v_cvt_f32_i32_e32 v127, v127
	v_cvt_f32_i32_e32 v126, v126
	v_cvt_f32_i32_e32 v125, v125
	v_cvt_f32_i32_e32 v124, v124
	s_or_b64 vcc, s[58:59], s[28:29]
	v_cndmask_b32_e32 v158, v169, v170, vcc
	s_ashr_i32 s31, s30, 31
	v_pk_mul_f32 v[122:123], v[158:159], v[122:123] op_sel_hi:[0,1]
	v_pk_mul_f32 v[120:121], v[158:159], v[120:121] op_sel_hi:[0,1]
	s_lshl_b64 s[28:29], s[30:31], 14
	v_pk_mul_f32 v[172:173], v[158:159], v[124:125] op_sel_hi:[0,1]
	v_pk_mul_f32 v[126:127], v[158:159], v[126:127] op_sel_hi:[0,1]
	s_waitcnt vmcnt(0)
	v_pk_mul_f32 v[162:163], v[120:121], v[128:129]
	v_pk_mul_f32 v[124:125], v[122:123], v[130:131]
	v_pk_mul_f32 v[120:121], v[120:121], v[132:133]
	v_pk_mul_f32 v[122:123], v[122:123], v[134:135]
	v_pk_fma_f32 v[124:125], v[126:127], v[134:135], v[124:125] neg_lo:[0,0,1] neg_hi:[0,0,1]
	v_pk_fma_f32 v[122:123], v[126:127], v[130:131], v[122:123]
	v_pk_fma_f32 v[126:127], v[172:173], v[128:129], v[120:121]
	v_lshl_add_u64 v[120:121], s[28:29], 0, v[160:161]
	v_lshlrev_b64 v[176:177], 8, v[120:121]
	s_cmp_gt_i32 s6, 7
	v_pk_fma_f32 v[162:163], v[172:173], v[132:133], v[162:163] neg_lo:[0,0,1] neg_hi:[0,0,1]
	v_lshl_add_u64 v[176:177], v[148:149], 0, v[176:177]
	v_cvt_pk_bf16_f32 v172, v162, v163
	v_cvt_pk_bf16_f32 v173, v124, v125
	v_cvt_pk_bf16_f32 v174, v126, v127
	v_cvt_pk_bf16_f32 v175, v122, v123
	global_store_dwordx4 v[176:177], v[172:175], off
	s_cbranch_scc1 .LBB0_1094
	v_mul_f32_e32 v159, v163, v163
	v_mul_f32_e32 v125, v125, v125
	v_fmac_f32_e32 v159, v162, v162
	v_fmac_f32_e32 v125, v124, v124
	v_add_f32_e32 v124, v159, v125
	v_mul_f32_e32 v125, v127, v127
	v_mul_f32_e32 v123, v123, v123
	v_fmac_f32_e32 v125, v126, v126
	v_fmac_f32_e32 v123, v122, v122
	v_add_f32_e32 v122, v125, v123
	v_add_f32_e32 v122, v124, v122
	v_and_b32_e32 v124, 64, v171
	v_xor_b32_e32 v123, 16, v171
	v_add_u32_e32 v124, 64, v124
	v_cmp_lt_i32_e32 vcc, v123, v124
	s_nop 1
	v_cndmask_b32_e32 v123, v171, v123, vcc
	v_lshlrev_b32_e32 v123, 2, v123
	v_mov_b32_e32 v123, v122
	s_nop 1
	v_permlane16_swap_b32_e32 v122, v123
	s_waitcnt lgkmcnt(0)
	v_add_f32_e32 v122, v122, v123
	v_xor_b32_e32 v123, 32, v171
	v_cmp_lt_i32_e32 vcc, v123, v124
	s_nop 1
	v_cndmask_b32_e32 v123, v171, v123, vcc
	v_lshlrev_b32_e32 v123, 2, v123
	v_mov_b32_e32 v123, v122
	s_nop 1
	v_permlane32_swap_b32_e32 v122, v123
	s_and_saveexec_b64 s[6:7], s[2:3]
	s_cbranch_execz .LBB0_1093
	v_lshl_add_u64 v[120:121], v[120:121], 4, s[16:17]
	s_waitcnt lgkmcnt(0)
	v_add_f32_e32 v122, v122, v123
	global_store_dword v[120:121], v122, off

; __device__ __forceinline__ u32x4 pack8bf(const f32x4 a, const f32x4 b) { u32x4 w; w.x = cvt_pk_bf16(a[0], a[1]); w.y = cvt_pk_bf16(a[2], a[3]); w.z = cvt_pk_bf16(b[0], b[1]); w.w = cvt_pk_bf16(b[2], b[3]); return w; }
;     __device__ __forceinline__ float qscale(const Unit& u) const { return ((u.pn >= 8 && u.pn <= 11) || u.pn == 17) ? 0.5f : 1.0f; }
;     ...
;         if constexpr (QM == 2) { const float qs0_ = g.qs * E.qscale(cur), qs1_ = qs0_ * g.qs_b1; _Pragma("unroll") for (int a = 0; a < 2; ++a) _Pragma("unroll") for (int b = 0; b < 2; ++b) _Pragma("unroll") for (int m = 0; m < 4; ++m) _Pragma("unroll") for (int n = 0; n < 2; ++n) { const v4i t_ = __builtin_bit_cast(v4i, acc[a][b][m][n]); acc[a][b][m][n] = (f32x4){(float)t_[0], (float)t_[1], (float)t_[2], (float)t_[3]} * (b == 0 ? qs0_ : qs1_); } }
;     __device__ __forceinline__ void operator()(EPI_ARGS) const {
;     ...
;                 for (int bj = 0; bj < 2; ++bj) { const int hd = 2 * u.pn + bj; const f32x4 v0 = acc[ai][bj][m][0], v1 = acc[ai][bj][m][1];
;                     const f32x4 o0 = v0 * c4 - v1 * s4, o1 = v1 * c4 + v0 * s4;
;                     *(u32x4*)(O + ((size_t)hd * NTOK + row) * 128 + 32 * wc + 8 * fq) = pack8bf(o0, o1);
;                     if (u.pn < 8) { float s = ((o0[0] * o0[0] + o0[1] * o0[1]) + (o0[2] * o0[2] + o0[3] * o0[3])) + ((o1[0] * o1[0] + o1[1] * o1[1]) + (o1[2] * o1[2] + o1[3] * o1[3]));
;                         s += __shfl_xor(s, 16); s += __shfl_xor(s, 32);
;                         if (fq == 0) nrm[((size_t)hd * NTOK + row) * 4 + wc] = s; } } }
.LBB0_1094:
	v_cvt_f32_i32_e32 v113, v113
	v_cvt_f32_i32_e32 v115, v115
	v_cvt_f32_i32_e32 v114, v114
	v_cvt_f32_i32_e32 v112, v112
	v_cvt_f32_i32_e32 v117, v117
	v_cvt_f32_i32_e32 v116, v116
	v_cvt_f32_i32_e32 v119, v119
	v_cvt_f32_i32_e32 v118, v118
	v_mov_b32_e32 v159, v158
	v_mov_b32_e32 v120, v158
	v_mov_b32_e32 v121, v158
	s_or_b32 s6, s30, 1
	v_pk_mul_f32 v[114:115], v[120:121], v[114:115]
	v_pk_mul_f32 v[112:113], v[158:159], v[112:113]
	s_ashr_i32 s7, s6, 31
	v_pk_mul_f32 v[118:119], v[120:121], v[118:119]
	s_waitcnt lgkmcnt(0)
	v_pk_mul_f32 v[122:123], v[158:159], v[116:117]
	v_pk_mul_f32 v[116:117], v[114:115], v[130:131]
	v_pk_mul_f32 v[120:121], v[112:113], v[128:129]
	v_pk_mul_f32 v[114:115], v[114:115], v[134:135]
	v_pk_mul_f32 v[112:113], v[112:113], v[132:133]
	s_lshl_b64 s[30:31], s[6:7], 14
	v_pk_fma_f32 v[116:117], v[118:119], v[134:135], v[116:117] neg_lo:[0,0,1] neg_hi:[0,0,1]
	v_pk_fma_f32 v[114:115], v[118:119], v[130:131], v[114:115]
	v_pk_fma_f32 v[118:119], v[122:123], v[128:129], v[112:113]
	v_lshl_add_u64 v[112:113], s[30:31], 0, v[160:161]
	v_lshlrev_b64 v[126:127], 8, v[112:113]
	v_cndmask_b32_e64 v128, 0, 1, s[8:9]
	v_pk_fma_f32 v[120:121], v[122:123], v[132:133], v[120:121] neg_lo:[0,0,1] neg_hi:[0,0,1]
	v_lshl_add_u64 v[126:127], v[148:149], 0, v[126:127]
	v_cmp_ne_u32_e64 s[6:7], 1, v128
	s_andn2_b64 vcc, exec, s[8:9]
	v_cvt_pk_bf16_f32 v122, v120, v121
	v_cvt_pk_bf16_f32 v123, v116, v117
	v_cvt_pk_bf16_f32 v124, v118, v119
	v_cvt_pk_bf16_f32 v125, v114, v115
	global_store_dwordx4 v[126:127], v[122:125], off
	s_cbranch_vccnz .LBB0_1098
	v_mul_f32_e32 v121, v121, v121
	v_mul_f32_e32 v117, v117, v117
	v_fmac_f32_e32 v121, v120, v120
	v_fmac_f32_e32 v117, v116, v116
	v_add_f32_e32 v116, v121, v117
	v_mul_f32_e32 v117, v119, v119
	v_mul_f32_e32 v115, v115, v115
	v_fmac_f32_e32 v117, v118, v118
	v_fmac_f32_e32 v115, v114, v114
	v_add_f32_e32 v114, v117, v115
	v_add_f32_e32 v114, v116, v114
	v_and_b32_e32 v116, 64, v171
	v_xor_b32_e32 v115, 16, v171
	v_add_u32_e32 v116, 64, v116
	v_cmp_lt_i32_e32 vcc, v115, v116
	s_nop 1
	v_cndmask_b32_e32 v115, v171, v115, vcc
	v_lshlrev_b32_e32 v115, 2, v115
	v_mov_b32_e32 v115, v114
	s_nop 1
	v_permlane16_swap_b32_e32 v114, v115
	s_waitcnt lgkmcnt(0)
	v_add_f32_e32 v114, v114, v115
	v_xor_b32_e32 v115, 32, v171
	v_cmp_lt_i32_e32 vcc, v115, v116
	s_nop 1
	v_cndmask_b32_e32 v115, v171, v115, vcc
	v_lshlrev_b32_e32 v115, 2, v115
	v_mov_b32_e32 v115, v114
	s_nop 1
	v_permlane32_swap_b32_e32 v114, v115
	s_and_saveexec_b64 s[8:9], s[2:3]
	s_cbranch_execz .LBB0_1097
	v_lshl_add_u64 v[112:113], v[112:113], 4, s[16:17]
	s_waitcnt lgkmcnt(0)
	v_add_f32_e32 v114, v114, v115
	global_store_dword v[112:113], v114, off

; __device__ __forceinline__ u32x4 pack8bf(const f32x4 a, const f32x4 b) { u32x4 w; w.x = cvt_pk_bf16(a[0], a[1]); w.y = cvt_pk_bf16(a[2], a[3]); w.z = cvt_pk_bf16(b[0], b[1]); w.w = cvt_pk_bf16(b[2], b[3]); return w; }
;     __device__ __forceinline__ float qscale(const Unit& u) const { return ((u.pn >= 8 && u.pn <= 11) || u.pn == 17) ? 0.5f : 1.0f; }
;     ...
;         if constexpr (QM == 2) { const float qs0_ = g.qs * E.qscale(cur), qs1_ = qs0_ * g.qs_b1; _Pragma("unroll") for (int a = 0; a < 2; ++a) _Pragma("unroll") for (int b = 0; b < 2; ++b) _Pragma("unroll") for (int m = 0; m < 4; ++m) _Pragma("unroll") for (int n = 0; n < 2; ++n) { const v4i t_ = __builtin_bit_cast(v4i, acc[a][b][m][n]); acc[a][b][m][n] = (f32x4){(float)t_[0], (float)t_[1], (float)t_[2], (float)t_[3]} * (b == 0 ? qs0_ : qs1_); } }
;     __device__ __forceinline__ void operator()(EPI_ARGS) const {
;     ...
;                 for (int bj = 0; bj < 2; ++bj) { const int hd = 2 * u.pn + bj; const f32x4 v0 = acc[ai][bj][m][0], v1 = acc[ai][bj][m][1];
;                     const f32x4 o0 = v0 * c4 - v1 * s4, o1 = v1 * c4 + v0 * s4;
;                     *(u32x4*)(O + ((size_t)hd * NTOK + row) * 128 + 32 * wc + 8 * fq) = pack8bf(o0, o1);
;                     if (u.pn < 8) { float s = ((o0[0] * o0[0] + o0[1] * o0[1]) + (o0[2] * o0[2] + o0[3] * o0[3])) + ((o1[0] * o1[0] + o1[1] * o1[1]) + (o1[2] * o1[2] + o1[3] * o1[3]));
;                         s += __shfl_xor(s, 16); s += __shfl_xor(s, 32);
;                         if (fq == 0) nrm[((size_t)hd * NTOK + row) * 4 + wc] = s; } } }
.LBB0_1101:
	v_cvt_f32_i32_e32 v105, v105
	v_cvt_f32_i32_e32 v104, v104
	v_cvt_f32_i32_e32 v123, v109
	v_cvt_f32_i32_e32 v122, v108
	v_cvt_f32_i32_e32 v107, v107
	v_cvt_f32_i32_e32 v106, v106
	v_cvt_f32_i32_e32 v111, v111
	v_cvt_f32_i32_e32 v110, v110
	v_pk_mul_f32 v[104:105], v[158:159], v[104:105]
	v_mov_b32_e32 v108, v158
	v_mov_b32_e32 v109, v158
	v_pk_mul_f32 v[122:123], v[158:159], v[122:123]
	s_waitcnt vmcnt(0)
	v_pk_mul_f32 v[124:125], v[104:105], v[112:113]
	v_pk_mul_f32 v[104:105], v[104:105], v[116:117]
	v_pk_mul_f32 v[106:107], v[108:109], v[106:107]
	v_pk_fma_f32 v[124:125], v[122:123], v[116:117], v[124:125] neg_lo:[0,0,1] neg_hi:[0,0,1]
	v_pk_fma_f32 v[122:123], v[122:123], v[112:113], v[104:105]
	v_lshl_add_u64 v[104:105], s[28:29], 0, v[120:121]
	v_pk_mul_f32 v[126:127], v[108:109], v[110:111]
	v_pk_mul_f32 v[110:111], v[106:107], v[114:115]
	v_pk_mul_f32 v[106:107], v[106:107], v[118:119]
	v_lshlrev_b64 v[130:131], 8, v[104:105]
	v_pk_fma_f32 v[110:111], v[126:127], v[118:119], v[110:111] neg_lo:[0,0,1] neg_hi:[0,0,1]
	v_pk_fma_f32 v[106:107], v[126:127], v[114:115], v[106:107]
	v_lshl_add_u64 v[130:131], v[148:149], 0, v[130:131]
	s_and_b64 vcc, exec, s[6:7]
	v_cvt_pk_bf16_f32 v126, v124, v125
	v_cvt_pk_bf16_f32 v127, v110, v111
	v_cvt_pk_bf16_f32 v128, v122, v123
	v_cvt_pk_bf16_f32 v129, v106, v107
	global_store_dwordx4 v[130:131], v[126:129], off
	s_cbranch_vccnz .LBB0_1105
	v_mul_f32_e32 v125, v125, v125
	v_mul_f32_e32 v111, v111, v111
	v_fmac_f32_e32 v125, v124, v124
	v_fmac_f32_e32 v111, v110, v110
	v_add_f32_e32 v110, v125, v111
	v_mul_f32_e32 v111, v123, v123
	v_mul_f32_e32 v107, v107, v107
	v_fmac_f32_e32 v111, v122, v122
	v_fmac_f32_e32 v107, v106, v106
	v_add_f32_e32 v106, v111, v107
	v_add_f32_e32 v106, v110, v106
	v_and_b32_e32 v110, 64, v171
	v_xor_b32_e32 v107, 16, v171
	v_add_u32_e32 v110, 64, v110
	v_cmp_lt_i32_e32 vcc, v107, v110
	s_nop 1
	v_cndmask_b32_e32 v107, v171, v107, vcc
	v_lshlrev_b32_e32 v107, 2, v107
	v_mov_b32_e32 v107, v106
	s_nop 1
	v_permlane16_swap_b32_e32 v106, v107
	s_waitcnt lgkmcnt(0)
	v_add_f32_e32 v106, v106, v107
	v_xor_b32_e32 v107, 32, v171
	v_cmp_lt_i32_e32 vcc, v107, v110
	s_nop 1
	v_cndmask_b32_e32 v107, v171, v107, vcc
	v_lshlrev_b32_e32 v107, 2, v107
	v_mov_b32_e32 v107, v106
	s_nop 1
	v_permlane32_swap_b32_e32 v106, v107
	s_and_saveexec_b64 s[36:37], s[2:3]
	s_cbranch_execz .LBB0_1104
	v_lshl_add_u64 v[104:105], v[104:105], 4, s[16:17]
	s_waitcnt lgkmcnt(0)
	v_add_f32_e32 v106, v106, v107
	global_store_dword v[104:105], v106, off

; __device__ __forceinline__ u32x4 pack8bf(const f32x4 a, const f32x4 b) { u32x4 w; w.x = cvt_pk_bf16(a[0], a[1]); w.y = cvt_pk_bf16(a[2], a[3]); w.z = cvt_pk_bf16(b[0], b[1]); w.w = cvt_pk_bf16(b[2], b[3]); return w; }
;     __device__ __forceinline__ float qscale(const Unit& u) const { return ((u.pn >= 8 && u.pn <= 11) || u.pn == 17) ? 0.5f : 1.0f; }
;     ...
;         if constexpr (QM == 2) { const float qs0_ = g.qs * E.qscale(cur), qs1_ = qs0_ * g.qs_b1; _Pragma("unroll") for (int a = 0; a < 2; ++a) _Pragma("unroll") for (int b = 0; b < 2; ++b) _Pragma("unroll") for (int m = 0; m < 4; ++m) _Pragma("unroll") for (int n = 0; n < 2; ++n) { const v4i t_ = __builtin_bit_cast(v4i, acc[a][b][m][n]); acc[a][b][m][n] = (f32x4){(float)t_[0], (float)t_[1], (float)t_[2], (float)t_[3]} * (b == 0 ? qs0_ : qs1_); } }
;     __device__ __forceinline__ void operator()(EPI_ARGS) const {
;     ...
;                 for (int bj = 0; bj < 2; ++bj) { const int hd = 2 * u.pn + bj; const f32x4 v0 = acc[ai][bj][m][0], v1 = acc[ai][bj][m][1];
;                     const f32x4 o0 = v0 * c4 - v1 * s4, o1 = v1 * c4 + v0 * s4;
;                     *(u32x4*)(O + ((size_t)hd * NTOK + row) * 128 + 32 * wc + 8 * fq) = pack8bf(o0, o1);
;                     if (u.pn < 8) { float s = ((o0[0] * o0[0] + o0[1] * o0[1]) + (o0[2] * o0[2] + o0[3] * o0[3])) + ((o1[0] * o1[0] + o1[1] * o1[1]) + (o1[2] * o1[2] + o1[3] * o1[3]));
;                         s += __shfl_xor(s, 16); s += __shfl_xor(s, 32);
;                         if (fq == 0) nrm[((size_t)hd * NTOK + row) * 4 + wc] = s; } } }
.LBB0_1105:
	v_cvt_f32_i32_e32 v97, v97
	v_cvt_f32_i32_e32 v99, v99
	v_cvt_f32_i32_e32 v98, v98
	v_cvt_f32_i32_e32 v96, v96
	v_cvt_f32_i32_e32 v101, v101
	v_cvt_f32_i32_e32 v100, v100
	v_cvt_f32_i32_e32 v103, v103
	v_cvt_f32_i32_e32 v102, v102
	v_pk_mul_f32 v[98:99], v[108:109], v[98:99]
	v_pk_mul_f32 v[96:97], v[158:159], v[96:97]
	s_waitcnt lgkmcnt(0)
	v_pk_mul_f32 v[106:107], v[158:159], v[100:101]
	v_pk_mul_f32 v[102:103], v[108:109], v[102:103]
	v_pk_mul_f32 v[100:101], v[98:99], v[114:115]
	v_pk_mul_f32 v[104:105], v[96:97], v[112:113]
	v_pk_mul_f32 v[98:99], v[98:99], v[118:119]
	v_pk_mul_f32 v[96:97], v[96:97], v[116:117]
	v_pk_fma_f32 v[100:101], v[102:103], v[118:119], v[100:101] neg_lo:[0,0,1] neg_hi:[0,0,1]
	v_pk_fma_f32 v[98:99], v[102:103], v[114:115], v[98:99]
	v_pk_fma_f32 v[102:103], v[106:107], v[112:113], v[96:97]
	v_lshl_add_u64 v[96:97], s[30:31], 0, v[120:121]
	v_lshlrev_b64 v[110:111], 8, v[96:97]
	v_pk_fma_f32 v[104:105], v[106:107], v[116:117], v[104:105] neg_lo:[0,0,1] neg_hi:[0,0,1]
	v_lshl_add_u64 v[110:111], v[148:149], 0, v[110:111]
	s_and_b64 vcc, exec, s[6:7]
	v_cvt_pk_bf16_f32 v106, v104, v105
	v_cvt_pk_bf16_f32 v107, v100, v101
	v_cvt_pk_bf16_f32 v108, v102, v103
	v_cvt_pk_bf16_f32 v109, v98, v99
	global_store_dwordx4 v[110:111], v[106:109], off
	s_cbranch_vccnz .LBB0_1109
	v_mul_f32_e32 v105, v105, v105
	v_mul_f32_e32 v101, v101, v101
	v_fmac_f32_e32 v105, v104, v104
	v_fmac_f32_e32 v101, v100, v100
	v_add_f32_e32 v100, v105, v101
	v_mul_f32_e32 v101, v103, v103
	v_mul_f32_e32 v99, v99, v99
	v_fmac_f32_e32 v101, v102, v102
	v_fmac_f32_e32 v99, v98, v98
	v_add_f32_e32 v98, v101, v99
	v_add_f32_e32 v98, v100, v98
	v_and_b32_e32 v100, 64, v171
	v_xor_b32_e32 v99, 16, v171
	v_add_u32_e32 v100, 64, v100
	v_cmp_lt_i32_e32 vcc, v99, v100
	s_nop 1
	v_cndmask_b32_e32 v99, v171, v99, vcc
	v_lshlrev_b32_e32 v99, 2, v99
	v_mov_b32_e32 v99, v98
	s_nop 1
	v_permlane16_swap_b32_e32 v98, v99
	s_waitcnt lgkmcnt(0)
	v_add_f32_e32 v98, v98, v99
	v_xor_b32_e32 v99, 32, v171
	v_cmp_lt_i32_e32 vcc, v99, v100
	s_nop 1
	v_cndmask_b32_e32 v99, v171, v99, vcc
	v_lshlrev_b32_e32 v99, 2, v99
	v_mov_b32_e32 v99, v98
	s_nop 1
	v_permlane32_swap_b32_e32 v98, v99
	s_and_saveexec_b64 s[36:37], s[2:3]
	s_cbranch_execz .LBB0_1108
	v_lshl_add_u64 v[96:97], v[96:97], 4, s[16:17]
	s_waitcnt lgkmcnt(0)
	v_add_f32_e32 v98, v98, v99
	global_store_dword v[96:97], v98, off

; __device__ __forceinline__ u32x4 pack8bf(const f32x4 a, const f32x4 b) { u32x4 w; w.x = cvt_pk_bf16(a[0], a[1]); w.y = cvt_pk_bf16(a[2], a[3]); w.z = cvt_pk_bf16(b[0], b[1]); w.w = cvt_pk_bf16(b[2], b[3]); return w; }
;     __device__ __forceinline__ float qscale(const Unit& u) const { return ((u.pn >= 8 && u.pn <= 11) || u.pn == 17) ? 0.5f : 1.0f; }
;     ...
;         if constexpr (QM == 2) { const float qs0_ = g.qs * E.qscale(cur), qs1_ = qs0_ * g.qs_b1; _Pragma("unroll") for (int a = 0; a < 2; ++a) _Pragma("unroll") for (int b = 0; b < 2; ++b) _Pragma("unroll") for (int m = 0; m < 4; ++m) _Pragma("unroll") for (int n = 0; n < 2; ++n) { const v4i t_ = __builtin_bit_cast(v4i, acc[a][b][m][n]); acc[a][b][m][n] = (f32x4){(float)t_[0], (float)t_[1], (float)t_[2], (float)t_[3]} * (b == 0 ? qs0_ : qs1_); } }
;     __device__ __forceinline__ void operator()(EPI_ARGS) const {
;     ...
;                 for (int bj = 0; bj < 2; ++bj) { const int hd = 2 * u.pn + bj; const f32x4 v0 = acc[ai][bj][m][0], v1 = acc[ai][bj][m][1];
;                     const f32x4 o0 = v0 * c4 - v1 * s4, o1 = v1 * c4 + v0 * s4;
;                     *(u32x4*)(O + ((size_t)hd * NTOK + row) * 128 + 32 * wc + 8 * fq) = pack8bf(o0, o1);
;                     if (u.pn < 8) { float s = ((o0[0] * o0[0] + o0[1] * o0[1]) + (o0[2] * o0[2] + o0[3] * o0[3])) + ((o1[0] * o1[0] + o1[1] * o1[1]) + (o1[2] * o1[2] + o1[3] * o1[3]));
;                         s += __shfl_xor(s, 16); s += __shfl_xor(s, 32);
;                         if (fq == 0) nrm[((size_t)hd * NTOK + row) * 4 + wc] = s; } } }
.LBB0_1112:
	v_cvt_f32_i32_e32 v89, v89
	v_cvt_f32_i32_e32 v88, v88
	v_cvt_f32_i32_e32 v107, v93
	v_cvt_f32_i32_e32 v106, v92
	v_cvt_f32_i32_e32 v91, v91
	v_cvt_f32_i32_e32 v90, v90
	v_cvt_f32_i32_e32 v95, v95
	v_cvt_f32_i32_e32 v94, v94
	v_pk_mul_f32 v[88:89], v[158:159], v[88:89]
	v_mov_b32_e32 v92, v158
	v_mov_b32_e32 v93, v158
	v_pk_mul_f32 v[106:107], v[158:159], v[106:107]
	s_waitcnt vmcnt(0)
	v_pk_mul_f32 v[108:109], v[88:89], v[96:97]
	v_pk_mul_f32 v[88:89], v[88:89], v[100:101]
	v_pk_mul_f32 v[90:91], v[92:93], v[90:91]
	v_pk_fma_f32 v[108:109], v[106:107], v[100:101], v[108:109] neg_lo:[0,0,1] neg_hi:[0,0,1]
	v_pk_fma_f32 v[106:107], v[106:107], v[96:97], v[88:89]
	v_lshl_add_u64 v[88:89], s[28:29], 0, v[104:105]
	v_pk_mul_f32 v[110:111], v[92:93], v[94:95]
	v_pk_mul_f32 v[94:95], v[90:91], v[98:99]
	v_pk_mul_f32 v[90:91], v[90:91], v[102:103]
	v_lshlrev_b64 v[114:115], 8, v[88:89]
	v_pk_fma_f32 v[94:95], v[110:111], v[102:103], v[94:95] neg_lo:[0,0,1] neg_hi:[0,0,1]
	v_pk_fma_f32 v[90:91], v[110:111], v[98:99], v[90:91]
	v_lshl_add_u64 v[114:115], v[148:149], 0, v[114:115]
	s_and_b64 vcc, exec, s[6:7]
	v_cvt_pk_bf16_f32 v110, v108, v109
	v_cvt_pk_bf16_f32 v111, v94, v95
	v_cvt_pk_bf16_f32 v112, v106, v107
	v_cvt_pk_bf16_f32 v113, v90, v91
	global_store_dwordx4 v[114:115], v[110:113], off
	s_cbranch_vccnz .LBB0_1116
	v_mul_f32_e32 v109, v109, v109
	v_mul_f32_e32 v95, v95, v95
	v_fmac_f32_e32 v109, v108, v108
	v_fmac_f32_e32 v95, v94, v94
	v_add_f32_e32 v94, v109, v95
	v_mul_f32_e32 v95, v107, v107
	v_mul_f32_e32 v91, v91, v91
	v_fmac_f32_e32 v95, v106, v106
	v_fmac_f32_e32 v91, v90, v90
	v_add_f32_e32 v90, v95, v91
	v_add_f32_e32 v90, v94, v90
	v_and_b32_e32 v94, 64, v171
	v_xor_b32_e32 v91, 16, v171
	v_add_u32_e32 v94, 64, v94
	v_cmp_lt_i32_e32 vcc, v91, v94
	s_nop 1
	v_cndmask_b32_e32 v91, v171, v91, vcc
	v_lshlrev_b32_e32 v91, 2, v91
	v_mov_b32_e32 v91, v90
	s_nop 1
	v_permlane16_swap_b32_e32 v90, v91
	s_waitcnt lgkmcnt(0)
	v_add_f32_e32 v90, v90, v91
	v_xor_b32_e32 v91, 32, v171
	v_cmp_lt_i32_e32 vcc, v91, v94
	s_nop 1
	v_cndmask_b32_e32 v91, v171, v91, vcc
	v_lshlrev_b32_e32 v91, 2, v91
	v_mov_b32_e32 v91, v90
	s_nop 1
	v_permlane32_swap_b32_e32 v90, v91
	s_and_saveexec_b64 s[36:37], s[2:3]
	s_cbranch_execz .LBB0_1115
	v_lshl_add_u64 v[88:89], v[88:89], 4, s[16:17]
	s_waitcnt lgkmcnt(0)
	v_add_f32_e32 v90, v90, v91
	global_store_dword v[88:89], v90, off

; __device__ __forceinline__ u32x4 pack8bf(const f32x4 a, const f32x4 b) { u32x4 w; w.x = cvt_pk_bf16(a[0], a[1]); w.y = cvt_pk_bf16(a[2], a[3]); w.z = cvt_pk_bf16(b[0], b[1]); w.w = cvt_pk_bf16(b[2], b[3]); return w; }
;     __device__ __forceinline__ float qscale(const Unit& u) const { return ((u.pn >= 8 && u.pn <= 11) || u.pn == 17) ? 0.5f : 1.0f; }
;     ...
;         if constexpr (QM == 2) { const float qs0_ = g.qs * E.qscale(cur), qs1_ = qs0_ * g.qs_b1; _Pragma("unroll") for (int a = 0; a < 2; ++a) _Pragma("unroll") for (int b = 0; b < 2; ++b) _Pragma("unroll") for (int m = 0; m < 4; ++m) _Pragma("unroll") for (int n = 0; n < 2; ++n) { const v4i t_ = __builtin_bit_cast(v4i, acc[a][b][m][n]); acc[a][b][m][n] = (f32x4){(float)t_[0], (float)t_[1], (float)t_[2], (float)t_[3]} * (b == 0 ? qs0_ : qs1_); } }
;     __device__ __forceinline__ void operator()(EPI_ARGS) const {
;     ...
;                 for (int bj = 0; bj < 2; ++bj) { const int hd = 2 * u.pn + bj; const f32x4 v0 = acc[ai][bj][m][0], v1 = acc[ai][bj][m][1];
;                     const f32x4 o0 = v0 * c4 - v1 * s4, o1 = v1 * c4 + v0 * s4;
;                     *(u32x4*)(O + ((size_t)hd * NTOK + row) * 128 + 32 * wc + 8 * fq) = pack8bf(o0, o1);
;                     if (u.pn < 8) { float s = ((o0[0] * o0[0] + o0[1] * o0[1]) + (o0[2] * o0[2] + o0[3] * o0[3])) + ((o1[0] * o1[0] + o1[1] * o1[1]) + (o1[2] * o1[2] + o1[3] * o1[3]));
;                         s += __shfl_xor(s, 16); s += __shfl_xor(s, 32);
;                         if (fq == 0) nrm[((size_t)hd * NTOK + row) * 4 + wc] = s; } } }
.LBB0_1116:
	v_cvt_f32_i32_e32 v81, v81
	v_cvt_f32_i32_e32 v83, v83
	v_cvt_f32_i32_e32 v82, v82
	v_cvt_f32_i32_e32 v80, v80
	v_cvt_f32_i32_e32 v85, v85
	v_cvt_f32_i32_e32 v84, v84
	v_cvt_f32_i32_e32 v87, v87
	v_cvt_f32_i32_e32 v86, v86
	v_pk_mul_f32 v[82:83], v[92:93], v[82:83]
	v_pk_mul_f32 v[80:81], v[158:159], v[80:81]
	s_waitcnt lgkmcnt(0)
	v_pk_mul_f32 v[90:91], v[158:159], v[84:85]
	v_pk_mul_f32 v[86:87], v[92:93], v[86:87]
	v_pk_mul_f32 v[84:85], v[82:83], v[98:99]
	v_pk_mul_f32 v[88:89], v[80:81], v[96:97]
	v_pk_mul_f32 v[82:83], v[82:83], v[102:103]
	v_pk_mul_f32 v[80:81], v[80:81], v[100:101]
	v_pk_fma_f32 v[84:85], v[86:87], v[102:103], v[84:85] neg_lo:[0,0,1] neg_hi:[0,0,1]
	v_pk_fma_f32 v[82:83], v[86:87], v[98:99], v[82:83]
	v_pk_fma_f32 v[86:87], v[90:91], v[96:97], v[80:81]
	v_lshl_add_u64 v[80:81], s[30:31], 0, v[104:105]
	v_lshlrev_b64 v[94:95], 8, v[80:81]
	v_pk_fma_f32 v[88:89], v[90:91], v[100:101], v[88:89] neg_lo:[0,0,1] neg_hi:[0,0,1]
	v_lshl_add_u64 v[94:95], v[148:149], 0, v[94:95]
	s_and_b64 vcc, exec, s[6:7]
	v_cvt_pk_bf16_f32 v90, v88, v89
	v_cvt_pk_bf16_f32 v91, v84, v85
	v_cvt_pk_bf16_f32 v92, v86, v87
	v_cvt_pk_bf16_f32 v93, v82, v83
	global_store_dwordx4 v[94:95], v[90:93], off
	s_cbranch_vccnz .LBB0_1120
	v_mul_f32_e32 v89, v89, v89
	v_mul_f32_e32 v85, v85, v85
	v_fmac_f32_e32 v89, v88, v88
	v_fmac_f32_e32 v85, v84, v84
	v_add_f32_e32 v84, v89, v85
	v_mul_f32_e32 v85, v87, v87
	v_mul_f32_e32 v83, v83, v83
	v_fmac_f32_e32 v85, v86, v86
	v_fmac_f32_e32 v83, v82, v82
	v_add_f32_e32 v82, v85, v83
	v_add_f32_e32 v82, v84, v82
	v_and_b32_e32 v84, 64, v171
	v_xor_b32_e32 v83, 16, v171
	v_add_u32_e32 v84, 64, v84
	v_cmp_lt_i32_e32 vcc, v83, v84
	s_nop 1
	v_cndmask_b32_e32 v83, v171, v83, vcc
	v_lshlrev_b32_e32 v83, 2, v83
	v_mov_b32_e32 v83, v82
	s_nop 1
	v_permlane16_swap_b32_e32 v82, v83
	s_waitcnt lgkmcnt(0)
	v_add_f32_e32 v82, v82, v83
	v_xor_b32_e32 v83, 32, v171
	v_cmp_lt_i32_e32 vcc, v83, v84
	s_nop 1
	v_cndmask_b32_e32 v83, v171, v83, vcc
	v_lshlrev_b32_e32 v83, 2, v83
	v_mov_b32_e32 v83, v82
	s_nop 1
	v_permlane32_swap_b32_e32 v82, v83
	s_and_saveexec_b64 s[36:37], s[2:3]
	s_cbranch_execz .LBB0_1119
	v_lshl_add_u64 v[80:81], v[80:81], 4, s[16:17]
	s_waitcnt lgkmcnt(0)
	v_add_f32_e32 v82, v82, v83
	global_store_dword v[80:81], v82, off

; __device__ __forceinline__ u32x4 pack8bf(const f32x4 a, const f32x4 b) { u32x4 w; w.x = cvt_pk_bf16(a[0], a[1]); w.y = cvt_pk_bf16(a[2], a[3]); w.z = cvt_pk_bf16(b[0], b[1]); w.w = cvt_pk_bf16(b[2], b[3]); return w; }
;     __device__ __forceinline__ float qscale(const Unit& u) const { return ((u.pn >= 8 && u.pn <= 11) || u.pn == 17) ? 0.5f : 1.0f; }
;     ...
;         if constexpr (QM == 2) { const float qs0_ = g.qs * E.qscale(cur), qs1_ = qs0_ * g.qs_b1; _Pragma("unroll") for (int a = 0; a < 2; ++a) _Pragma("unroll") for (int b = 0; b < 2; ++b) _Pragma("unroll") for (int m = 0; m < 4; ++m) _Pragma("unroll") for (int n = 0; n < 2; ++n) { const v4i t_ = __builtin_bit_cast(v4i, acc[a][b][m][n]); acc[a][b][m][n] = (f32x4){(float)t_[0], (float)t_[1], (float)t_[2], (float)t_[3]} * (b == 0 ? qs0_ : qs1_); } }
;     __device__ __forceinline__ void operator()(EPI_ARGS) const {
;     ...
;                 for (int bj = 0; bj < 2; ++bj) { const int hd = 2 * u.pn + bj; const f32x4 v0 = acc[ai][bj][m][0], v1 = acc[ai][bj][m][1];
;                     const f32x4 o0 = v0 * c4 - v1 * s4, o1 = v1 * c4 + v0 * s4;
;                     *(u32x4*)(O + ((size_t)hd * NTOK + row) * 128 + 32 * wc + 8 * fq) = pack8bf(o0, o1);
;                     if (u.pn < 8) { float s = ((o0[0] * o0[0] + o0[1] * o0[1]) + (o0[2] * o0[2] + o0[3] * o0[3])) + ((o1[0] * o1[0] + o1[1] * o1[1]) + (o1[2] * o1[2] + o1[3] * o1[3]));
;                         s += __shfl_xor(s, 16); s += __shfl_xor(s, 32);
;                         if (fq == 0) nrm[((size_t)hd * NTOK + row) * 4 + wc] = s; } } }
.LBB0_1123:
	v_cvt_f32_i32_e32 v73, v73
	v_cvt_f32_i32_e32 v72, v72
	v_cvt_f32_i32_e32 v91, v77
	v_cvt_f32_i32_e32 v90, v76
	v_cvt_f32_i32_e32 v75, v75
	v_cvt_f32_i32_e32 v74, v74
	v_cvt_f32_i32_e32 v79, v79
	v_cvt_f32_i32_e32 v78, v78
	v_pk_mul_f32 v[72:73], v[158:159], v[72:73]
	v_mov_b32_e32 v76, v158
	v_mov_b32_e32 v77, v158
	v_pk_mul_f32 v[90:91], v[158:159], v[90:91]
	s_waitcnt vmcnt(0)
	v_pk_mul_f32 v[92:93], v[72:73], v[80:81]
	v_pk_mul_f32 v[72:73], v[72:73], v[84:85]
	v_pk_mul_f32 v[74:75], v[76:77], v[74:75]
	v_pk_fma_f32 v[92:93], v[90:91], v[84:85], v[92:93] neg_lo:[0,0,1] neg_hi:[0,0,1]
	v_pk_fma_f32 v[90:91], v[90:91], v[80:81], v[72:73]
	v_lshl_add_u64 v[72:73], s[28:29], 0, v[88:89]
	v_pk_mul_f32 v[94:95], v[76:77], v[78:79]
	v_pk_mul_f32 v[78:79], v[74:75], v[82:83]
	v_pk_mul_f32 v[74:75], v[74:75], v[86:87]
	v_lshlrev_b64 v[98:99], 8, v[72:73]
	v_pk_fma_f32 v[78:79], v[94:95], v[86:87], v[78:79] neg_lo:[0,0,1] neg_hi:[0,0,1]
	v_pk_fma_f32 v[74:75], v[94:95], v[82:83], v[74:75]
	v_lshl_add_u64 v[98:99], v[148:149], 0, v[98:99]
	s_and_b64 vcc, exec, s[6:7]
	v_cvt_pk_bf16_f32 v94, v92, v93
	v_cvt_pk_bf16_f32 v95, v78, v79
	v_cvt_pk_bf16_f32 v96, v90, v91
	v_cvt_pk_bf16_f32 v97, v74, v75
	global_store_dwordx4 v[98:99], v[94:97], off
	s_cbranch_vccnz .LBB0_1127
	v_mul_f32_e32 v93, v93, v93
	v_mul_f32_e32 v79, v79, v79
	v_fmac_f32_e32 v93, v92, v92
	v_fmac_f32_e32 v79, v78, v78
	v_add_f32_e32 v78, v93, v79
	v_mul_f32_e32 v79, v91, v91
	v_mul_f32_e32 v75, v75, v75
	v_fmac_f32_e32 v79, v90, v90
	v_fmac_f32_e32 v75, v74, v74
	v_add_f32_e32 v74, v79, v75
	v_add_f32_e32 v74, v78, v74
	v_and_b32_e32 v78, 64, v171
	v_xor_b32_e32 v75, 16, v171
	v_add_u32_e32 v78, 64, v78
	v_cmp_lt_i32_e32 vcc, v75, v78
	s_nop 1
	v_cndmask_b32_e32 v75, v171, v75, vcc
	v_lshlrev_b32_e32 v75, 2, v75
	v_mov_b32_e32 v75, v74
	s_nop 1
	v_permlane16_swap_b32_e32 v74, v75
	s_waitcnt lgkmcnt(0)
	v_add_f32_e32 v74, v74, v75
	v_xor_b32_e32 v75, 32, v171
	v_cmp_lt_i32_e32 vcc, v75, v78
	s_nop 1
	v_cndmask_b32_e32 v75, v171, v75, vcc
	v_lshlrev_b32_e32 v75, 2, v75
	v_mov_b32_e32 v75, v74
	s_nop 1
	v_permlane32_swap_b32_e32 v74, v75
	s_and_saveexec_b64 s[36:37], s[2:3]
	s_cbranch_execz .LBB0_1126
	v_lshl_add_u64 v[72:73], v[72:73], 4, s[16:17]
	s_waitcnt lgkmcnt(0)
	v_add_f32_e32 v74, v74, v75
	global_store_dword v[72:73], v74, off

; __device__ __forceinline__ u32x4 pack8bf(const f32x4 a, const f32x4 b) { u32x4 w; w.x = cvt_pk_bf16(a[0], a[1]); w.y = cvt_pk_bf16(a[2], a[3]); w.z = cvt_pk_bf16(b[0], b[1]); w.w = cvt_pk_bf16(b[2], b[3]); return w; }
;     __device__ __forceinline__ float qscale(const Unit& u) const { return ((u.pn >= 8 && u.pn <= 11) || u.pn == 17) ? 0.5f : 1.0f; }
;     ...
;         if constexpr (QM == 2) { const float qs0_ = g.qs * E.qscale(cur), qs1_ = qs0_ * g.qs_b1; _Pragma("unroll") for (int a = 0; a < 2; ++a) _Pragma("unroll") for (int b = 0; b < 2; ++b) _Pragma("unroll") for (int m = 0; m < 4; ++m) _Pragma("unroll") for (int n = 0; n < 2; ++n) { const v4i t_ = __builtin_bit_cast(v4i, acc[a][b][m][n]); acc[a][b][m][n] = (f32x4){(float)t_[0], (float)t_[1], (float)t_[2], (float)t_[3]} * (b == 0 ? qs0_ : qs1_); } }
;     __device__ __forceinline__ void operator()(EPI_ARGS) const {
;     ...
;                 for (int bj = 0; bj < 2; ++bj) { const int hd = 2 * u.pn + bj; const f32x4 v0 = acc[ai][bj][m][0], v1 = acc[ai][bj][m][1];
;                     const f32x4 o0 = v0 * c4 - v1 * s4, o1 = v1 * c4 + v0 * s4;
;                     *(u32x4*)(O + ((size_t)hd * NTOK + row) * 128 + 32 * wc + 8 * fq) = pack8bf(o0, o1);
;                     if (u.pn < 8) { float s = ((o0[0] * o0[0] + o0[1] * o0[1]) + (o0[2] * o0[2] + o0[3] * o0[3])) + ((o1[0] * o1[0] + o1[1] * o1[1]) + (o1[2] * o1[2] + o1[3] * o1[3]));
;                         s += __shfl_xor(s, 16); s += __shfl_xor(s, 32);
;                         if (fq == 0) nrm[((size_t)hd * NTOK + row) * 4 + wc] = s; } } }
.LBB0_1127:
	v_cvt_f32_i32_e32 v65, v65
	v_cvt_f32_i32_e32 v67, v67
	v_cvt_f32_i32_e32 v66, v66
	v_cvt_f32_i32_e32 v64, v64
	v_cvt_f32_i32_e32 v69, v69
	v_cvt_f32_i32_e32 v68, v68
	v_cvt_f32_i32_e32 v71, v71
	v_cvt_f32_i32_e32 v70, v70
	v_pk_mul_f32 v[66:67], v[76:77], v[66:67]
	v_pk_mul_f32 v[64:65], v[158:159], v[64:65]
	s_waitcnt lgkmcnt(0)
	v_pk_mul_f32 v[74:75], v[158:159], v[68:69]
	v_pk_mul_f32 v[70:71], v[76:77], v[70:71]
	v_pk_mul_f32 v[68:69], v[66:67], v[82:83]
	v_pk_mul_f32 v[72:73], v[64:65], v[80:81]
	v_pk_mul_f32 v[66:67], v[66:67], v[86:87]
	v_pk_mul_f32 v[64:65], v[64:65], v[84:85]
	v_pk_fma_f32 v[68:69], v[70:71], v[86:87], v[68:69] neg_lo:[0,0,1] neg_hi:[0,0,1]
	v_pk_fma_f32 v[66:67], v[70:71], v[82:83], v[66:67]
	v_pk_fma_f32 v[70:71], v[74:75], v[80:81], v[64:65]
	v_lshl_add_u64 v[64:65], s[30:31], 0, v[88:89]
	v_lshlrev_b64 v[78:79], 8, v[64:65]
	v_pk_fma_f32 v[72:73], v[74:75], v[84:85], v[72:73] neg_lo:[0,0,1] neg_hi:[0,0,1]
	v_lshl_add_u64 v[78:79], v[148:149], 0, v[78:79]
	s_and_b64 vcc, exec, s[6:7]
	v_cvt_pk_bf16_f32 v74, v72, v73
	v_cvt_pk_bf16_f32 v75, v68, v69
	v_cvt_pk_bf16_f32 v76, v70, v71
	v_cvt_pk_bf16_f32 v77, v66, v67
	global_store_dwordx4 v[78:79], v[74:77], off
	s_cbranch_vccnz .LBB0_1131
	v_mul_f32_e32 v73, v73, v73
	v_mul_f32_e32 v69, v69, v69
	v_fmac_f32_e32 v73, v72, v72
	v_fmac_f32_e32 v69, v68, v68
	v_add_f32_e32 v68, v73, v69
	v_mul_f32_e32 v69, v71, v71
	v_mul_f32_e32 v67, v67, v67
	v_fmac_f32_e32 v69, v70, v70
	v_fmac_f32_e32 v67, v66, v66
	v_add_f32_e32 v66, v69, v67
	v_add_f32_e32 v66, v68, v66
	v_and_b32_e32 v68, 64, v171
	v_xor_b32_e32 v67, 16, v171
	v_add_u32_e32 v68, 64, v68
	v_cmp_lt_i32_e32 vcc, v67, v68
	s_nop 1
	v_cndmask_b32_e32 v67, v171, v67, vcc
	v_lshlrev_b32_e32 v67, 2, v67
	v_mov_b32_e32 v67, v66
	s_nop 1
	v_permlane16_swap_b32_e32 v66, v67
	s_waitcnt lgkmcnt(0)
	v_add_f32_e32 v66, v66, v67
	v_xor_b32_e32 v67, 32, v171
	v_cmp_lt_i32_e32 vcc, v67, v68
	s_nop 1
	v_cndmask_b32_e32 v67, v171, v67, vcc
	v_lshlrev_b32_e32 v67, 2, v67
	v_mov_b32_e32 v67, v66
	s_nop 1
	v_permlane32_swap_b32_e32 v66, v67
	s_and_saveexec_b64 s[36:37], s[2:3]
	s_cbranch_execz .LBB0_1130
	v_lshl_add_u64 v[64:65], v[64:65], 4, s[16:17]
	s_waitcnt lgkmcnt(0)
	v_add_f32_e32 v66, v66, v67
	global_store_dword v[64:65], v66, off

; __device__ __forceinline__ u32x4 pack8bf(const f32x4 a, const f32x4 b) { u32x4 w; w.x = cvt_pk_bf16(a[0], a[1]); w.y = cvt_pk_bf16(a[2], a[3]); w.z = cvt_pk_bf16(b[0], b[1]); w.w = cvt_pk_bf16(b[2], b[3]); return w; }
;     __device__ __forceinline__ float qscale(const Unit& u) const { return ((u.pn >= 8 && u.pn <= 11) || u.pn == 17) ? 0.5f : 1.0f; }
;     ...
;         if constexpr (QM == 2) { const float qs0_ = g.qs * E.qscale(cur), qs1_ = qs0_ * g.qs_b1; _Pragma("unroll") for (int a = 0; a < 2; ++a) _Pragma("unroll") for (int b = 0; b < 2; ++b) _Pragma("unroll") for (int m = 0; m < 4; ++m) _Pragma("unroll") for (int n = 0; n < 2; ++n) { const v4i t_ = __builtin_bit_cast(v4i, acc[a][b][m][n]); acc[a][b][m][n] = (f32x4){(float)t_[0], (float)t_[1], (float)t_[2], (float)t_[3]} * (b == 0 ? qs0_ : qs1_); } }
;     __device__ __forceinline__ void operator()(EPI_ARGS) const {
;     ...
;                 for (int bj = 0; bj < 2; ++bj) { const int hd = 2 * u.pn + bj; const f32x4 v0 = acc[ai][bj][m][0], v1 = acc[ai][bj][m][1];
;                     const f32x4 o0 = v0 * c4 - v1 * s4, o1 = v1 * c4 + v0 * s4;
;                     *(u32x4*)(O + ((size_t)hd * NTOK + row) * 128 + 32 * wc + 8 * fq) = pack8bf(o0, o1);
;                     if (u.pn < 8) { float s = ((o0[0] * o0[0] + o0[1] * o0[1]) + (o0[2] * o0[2] + o0[3] * o0[3])) + ((o1[0] * o1[0] + o1[1] * o1[1]) + (o1[2] * o1[2] + o1[3] * o1[3]));
;                         s += __shfl_xor(s, 16); s += __shfl_xor(s, 32);
;                         if (fq == 0) nrm[((size_t)hd * NTOK + row) * 4 + wc] = s; } } }
.LBB0_1134:
	v_cvt_f32_i32_e32 v57, v57
	v_cvt_f32_i32_e32 v56, v56
	v_cvt_f32_i32_e32 v75, v61
	v_cvt_f32_i32_e32 v74, v60
	v_cvt_f32_i32_e32 v59, v59
	v_cvt_f32_i32_e32 v58, v58
	v_cvt_f32_i32_e32 v63, v63
	v_cvt_f32_i32_e32 v62, v62
	v_pk_mul_f32 v[56:57], v[158:159], v[56:57]
	v_mov_b32_e32 v60, v158
	v_mov_b32_e32 v61, v158
	v_pk_mul_f32 v[74:75], v[158:159], v[74:75]
	s_waitcnt vmcnt(0)
	v_pk_mul_f32 v[76:77], v[56:57], v[64:65]
	v_pk_mul_f32 v[56:57], v[56:57], v[68:69]
	v_pk_mul_f32 v[58:59], v[60:61], v[58:59]
	v_pk_fma_f32 v[76:77], v[74:75], v[68:69], v[76:77] neg_lo:[0,0,1] neg_hi:[0,0,1]
	v_pk_fma_f32 v[74:75], v[74:75], v[64:65], v[56:57]
	v_lshl_add_u64 v[56:57], s[28:29], 0, v[72:73]
	v_pk_mul_f32 v[78:79], v[60:61], v[62:63]
	v_pk_mul_f32 v[62:63], v[58:59], v[66:67]
	v_pk_mul_f32 v[58:59], v[58:59], v[70:71]
	v_lshlrev_b64 v[82:83], 8, v[56:57]
	v_pk_fma_f32 v[62:63], v[78:79], v[70:71], v[62:63] neg_lo:[0,0,1] neg_hi:[0,0,1]
	v_pk_fma_f32 v[58:59], v[78:79], v[66:67], v[58:59]
	v_lshl_add_u64 v[82:83], v[148:149], 0, v[82:83]
	s_and_b64 vcc, exec, s[6:7]
	v_cvt_pk_bf16_f32 v78, v76, v77
	v_cvt_pk_bf16_f32 v79, v62, v63
	v_cvt_pk_bf16_f32 v80, v74, v75
	v_cvt_pk_bf16_f32 v81, v58, v59
	global_store_dwordx4 v[82:83], v[78:81], off
	s_cbranch_vccnz .LBB0_1138
	v_mul_f32_e32 v77, v77, v77
	v_mul_f32_e32 v63, v63, v63
	v_fmac_f32_e32 v77, v76, v76
	v_fmac_f32_e32 v63, v62, v62
	v_add_f32_e32 v62, v77, v63
	v_mul_f32_e32 v63, v75, v75
	v_mul_f32_e32 v59, v59, v59
	v_fmac_f32_e32 v63, v74, v74
	v_fmac_f32_e32 v59, v58, v58
	v_add_f32_e32 v58, v63, v59
	v_add_f32_e32 v58, v62, v58
	v_and_b32_e32 v62, 64, v171
	v_xor_b32_e32 v59, 16, v171
	v_add_u32_e32 v62, 64, v62
	v_cmp_lt_i32_e32 vcc, v59, v62
	s_nop 1
	v_cndmask_b32_e32 v59, v171, v59, vcc
	v_lshlrev_b32_e32 v59, 2, v59
	v_mov_b32_e32 v59, v58
	s_nop 1
	v_permlane16_swap_b32_e32 v58, v59
	s_waitcnt lgkmcnt(0)
	v_add_f32_e32 v58, v58, v59
	v_xor_b32_e32 v59, 32, v171
	v_cmp_lt_i32_e32 vcc, v59, v62
	s_nop 1
	v_cndmask_b32_e32 v59, v171, v59, vcc
	v_lshlrev_b32_e32 v59, 2, v59
	v_mov_b32_e32 v59, v58
	s_nop 1
	v_permlane32_swap_b32_e32 v58, v59
	s_and_saveexec_b64 s[36:37], s[2:3]
	s_cbranch_execz .LBB0_1137
	v_lshl_add_u64 v[56:57], v[56:57], 4, s[16:17]
	s_waitcnt lgkmcnt(0)
	v_add_f32_e32 v58, v58, v59
	global_store_dword v[56:57], v58, off

; __device__ __forceinline__ u32x4 pack8bf(const f32x4 a, const f32x4 b) { u32x4 w; w.x = cvt_pk_bf16(a[0], a[1]); w.y = cvt_pk_bf16(a[2], a[3]); w.z = cvt_pk_bf16(b[0], b[1]); w.w = cvt_pk_bf16(b[2], b[3]); return w; }
;     __device__ __forceinline__ float qscale(const Unit& u) const { return ((u.pn >= 8 && u.pn <= 11) || u.pn == 17) ? 0.5f : 1.0f; }
;     ...
;         if constexpr (QM == 2) { const float qs0_ = g.qs * E.qscale(cur), qs1_ = qs0_ * g.qs_b1; _Pragma("unroll") for (int a = 0; a < 2; ++a) _Pragma("unroll") for (int b = 0; b < 2; ++b) _Pragma("unroll") for (int m = 0; m < 4; ++m) _Pragma("unroll") for (int n = 0; n < 2; ++n) { const v4i t_ = __builtin_bit_cast(v4i, acc[a][b][m][n]); acc[a][b][m][n] = (f32x4){(float)t_[0], (float)t_[1], (float)t_[2], (float)t_[3]} * (b == 0 ? qs0_ : qs1_); } }
;     __device__ __forceinline__ void operator()(EPI_ARGS) const {
;     ...
;                 for (int bj = 0; bj < 2; ++bj) { const int hd = 2 * u.pn + bj; const f32x4 v0 = acc[ai][bj][m][0], v1 = acc[ai][bj][m][1];
;                     const f32x4 o0 = v0 * c4 - v1 * s4, o1 = v1 * c4 + v0 * s4;
;                     *(u32x4*)(O + ((size_t)hd * NTOK + row) * 128 + 32 * wc + 8 * fq) = pack8bf(o0, o1);
;                     if (u.pn < 8) { float s = ((o0[0] * o0[0] + o0[1] * o0[1]) + (o0[2] * o0[2] + o0[3] * o0[3])) + ((o1[0] * o1[0] + o1[1] * o1[1]) + (o1[2] * o1[2] + o1[3] * o1[3]));
;                         s += __shfl_xor(s, 16); s += __shfl_xor(s, 32);
;                         if (fq == 0) nrm[((size_t)hd * NTOK + row) * 4 + wc] = s; } } }
.LBB0_1138:
	v_cvt_f32_i32_e32 v49, v49
	v_cvt_f32_i32_e32 v51, v51
	v_cvt_f32_i32_e32 v50, v50
	v_cvt_f32_i32_e32 v48, v48
	v_cvt_f32_i32_e32 v53, v53
	v_cvt_f32_i32_e32 v52, v52
	v_cvt_f32_i32_e32 v55, v55
	v_cvt_f32_i32_e32 v54, v54
	v_pk_mul_f32 v[50:51], v[60:61], v[50:51]
	v_pk_mul_f32 v[48:49], v[158:159], v[48:49]
	s_waitcnt lgkmcnt(0)
	v_pk_mul_f32 v[58:59], v[158:159], v[52:53]
	v_pk_mul_f32 v[54:55], v[60:61], v[54:55]
	v_pk_mul_f32 v[52:53], v[50:51], v[66:67]
	v_pk_mul_f32 v[56:57], v[48:49], v[64:65]
	v_pk_mul_f32 v[50:51], v[50:51], v[70:71]
	v_pk_mul_f32 v[48:49], v[48:49], v[68:69]
	v_pk_fma_f32 v[52:53], v[54:55], v[70:71], v[52:53] neg_lo:[0,0,1] neg_hi:[0,0,1]
	v_pk_fma_f32 v[50:51], v[54:55], v[66:67], v[50:51]
	v_pk_fma_f32 v[54:55], v[58:59], v[64:65], v[48:49]
	v_lshl_add_u64 v[48:49], s[30:31], 0, v[72:73]
	v_lshlrev_b64 v[62:63], 8, v[48:49]
	v_pk_fma_f32 v[56:57], v[58:59], v[68:69], v[56:57] neg_lo:[0,0,1] neg_hi:[0,0,1]
	v_lshl_add_u64 v[62:63], v[148:149], 0, v[62:63]
	s_and_b64 vcc, exec, s[6:7]
	v_cvt_pk_bf16_f32 v58, v56, v57
	v_cvt_pk_bf16_f32 v59, v52, v53
	v_cvt_pk_bf16_f32 v60, v54, v55
	v_cvt_pk_bf16_f32 v61, v50, v51
	global_store_dwordx4 v[62:63], v[58:61], off
	s_cbranch_vccnz .LBB0_1142
	v_mul_f32_e32 v57, v57, v57
	v_mul_f32_e32 v53, v53, v53
	v_fmac_f32_e32 v57, v56, v56
	v_fmac_f32_e32 v53, v52, v52
	v_add_f32_e32 v52, v57, v53
	v_mul_f32_e32 v53, v55, v55
	v_mul_f32_e32 v51, v51, v51
	v_fmac_f32_e32 v53, v54, v54
	v_fmac_f32_e32 v51, v50, v50
	v_add_f32_e32 v50, v53, v51
	v_add_f32_e32 v50, v52, v50
	v_and_b32_e32 v52, 64, v171
	v_xor_b32_e32 v51, 16, v171
	v_add_u32_e32 v52, 64, v52
	v_cmp_lt_i32_e32 vcc, v51, v52
	s_nop 1
	v_cndmask_b32_e32 v51, v171, v51, vcc
	v_lshlrev_b32_e32 v51, 2, v51
	v_mov_b32_e32 v51, v50
	s_nop 1
	v_permlane16_swap_b32_e32 v50, v51
	s_waitcnt lgkmcnt(0)
	v_add_f32_e32 v50, v50, v51
	v_xor_b32_e32 v51, 32, v171
	v_cmp_lt_i32_e32 vcc, v51, v52
	s_nop 1
	v_cndmask_b32_e32 v51, v171, v51, vcc
	v_lshlrev_b32_e32 v51, 2, v51
	v_mov_b32_e32 v51, v50
	s_nop 1
	v_permlane32_swap_b32_e32 v50, v51
	s_and_saveexec_b64 s[36:37], s[2:3]
	s_cbranch_execz .LBB0_1141
	v_lshl_add_u64 v[48:49], v[48:49], 4, s[16:17]
	s_waitcnt lgkmcnt(0)
	v_add_f32_e32 v50, v50, v51
	global_store_dword v[48:49], v50, off

; __device__ __forceinline__ u32x4 pack8bf(const f32x4 a, const f32x4 b) { u32x4 w; w.x = cvt_pk_bf16(a[0], a[1]); w.y = cvt_pk_bf16(a[2], a[3]); w.z = cvt_pk_bf16(b[0], b[1]); w.w = cvt_pk_bf16(b[2], b[3]); return w; }
;     __device__ __forceinline__ float qscale(const Unit& u) const { return ((u.pn >= 8 && u.pn <= 11) || u.pn == 17) ? 0.5f : 1.0f; }
;     ...
;         if constexpr (QM == 2) { const float qs0_ = g.qs * E.qscale(cur), qs1_ = qs0_ * g.qs_b1; _Pragma("unroll") for (int a = 0; a < 2; ++a) _Pragma("unroll") for (int b = 0; b < 2; ++b) _Pragma("unroll") for (int m = 0; m < 4; ++m) _Pragma("unroll") for (int n = 0; n < 2; ++n) { const v4i t_ = __builtin_bit_cast(v4i, acc[a][b][m][n]); acc[a][b][m][n] = (f32x4){(float)t_[0], (float)t_[1], (float)t_[2], (float)t_[3]} * (b == 0 ? qs0_ : qs1_); } }
;     __device__ __forceinline__ void operator()(EPI_ARGS) const {
;     ...
;                 for (int bj = 0; bj < 2; ++bj) { const int hd = 2 * u.pn + bj; const f32x4 v0 = acc[ai][bj][m][0], v1 = acc[ai][bj][m][1];
;                     const f32x4 o0 = v0 * c4 - v1 * s4, o1 = v1 * c4 + v0 * s4;
;                     *(u32x4*)(O + ((size_t)hd * NTOK + row) * 128 + 32 * wc + 8 * fq) = pack8bf(o0, o1);
;                     if (u.pn < 8) { float s = ((o0[0] * o0[0] + o0[1] * o0[1]) + (o0[2] * o0[2] + o0[3] * o0[3])) + ((o1[0] * o1[0] + o1[1] * o1[1]) + (o1[2] * o1[2] + o1[3] * o1[3]));
;                         s += __shfl_xor(s, 16); s += __shfl_xor(s, 32);
;                         if (fq == 0) nrm[((size_t)hd * NTOK + row) * 4 + wc] = s; } } }
.LBB0_1145:
	v_cvt_f32_i32_e32 v41, v41
	v_cvt_f32_i32_e32 v40, v40
	v_cvt_f32_i32_e32 v59, v45
	v_cvt_f32_i32_e32 v58, v44
	v_cvt_f32_i32_e32 v43, v43
	v_cvt_f32_i32_e32 v42, v42
	v_cvt_f32_i32_e32 v47, v47
	v_cvt_f32_i32_e32 v46, v46
	v_pk_mul_f32 v[40:41], v[158:159], v[40:41]
	v_mov_b32_e32 v44, v158
	v_mov_b32_e32 v45, v158
	v_pk_mul_f32 v[58:59], v[158:159], v[58:59]
	s_waitcnt vmcnt(0)
	v_pk_mul_f32 v[60:61], v[40:41], v[48:49]
	v_pk_mul_f32 v[40:41], v[40:41], v[52:53]
	v_pk_mul_f32 v[42:43], v[44:45], v[42:43]
	v_pk_fma_f32 v[60:61], v[58:59], v[52:53], v[60:61] neg_lo:[0,0,1] neg_hi:[0,0,1]
	v_pk_fma_f32 v[58:59], v[58:59], v[48:49], v[40:41]
	v_lshl_add_u64 v[40:41], s[28:29], 0, v[56:57]
	v_pk_mul_f32 v[62:63], v[44:45], v[46:47]
	v_pk_mul_f32 v[46:47], v[42:43], v[50:51]
	v_pk_mul_f32 v[42:43], v[42:43], v[54:55]
	v_lshlrev_b64 v[66:67], 8, v[40:41]
	v_pk_fma_f32 v[46:47], v[62:63], v[54:55], v[46:47] neg_lo:[0,0,1] neg_hi:[0,0,1]
	v_pk_fma_f32 v[42:43], v[62:63], v[50:51], v[42:43]
	v_lshl_add_u64 v[66:67], v[148:149], 0, v[66:67]
	s_and_b64 vcc, exec, s[6:7]
	v_cvt_pk_bf16_f32 v62, v60, v61
	v_cvt_pk_bf16_f32 v63, v46, v47
	v_cvt_pk_bf16_f32 v64, v58, v59
	v_cvt_pk_bf16_f32 v65, v42, v43
	global_store_dwordx4 v[66:67], v[62:65], off
	s_cbranch_vccnz .LBB0_1149
	v_mul_f32_e32 v61, v61, v61
	v_mul_f32_e32 v47, v47, v47
	v_fmac_f32_e32 v61, v60, v60
	v_fmac_f32_e32 v47, v46, v46
	v_add_f32_e32 v46, v61, v47
	v_mul_f32_e32 v47, v59, v59
	v_mul_f32_e32 v43, v43, v43
	v_fmac_f32_e32 v47, v58, v58
	v_fmac_f32_e32 v43, v42, v42
	v_add_f32_e32 v42, v47, v43
	v_add_f32_e32 v42, v46, v42
	v_and_b32_e32 v46, 64, v171
	v_xor_b32_e32 v43, 16, v171
	v_add_u32_e32 v46, 64, v46
	v_cmp_lt_i32_e32 vcc, v43, v46
	s_nop 1
	v_cndmask_b32_e32 v43, v171, v43, vcc
	v_lshlrev_b32_e32 v43, 2, v43
	v_mov_b32_e32 v43, v42
	s_nop 1
	v_permlane16_swap_b32_e32 v42, v43
	s_waitcnt lgkmcnt(0)
	v_add_f32_e32 v42, v42, v43
	v_xor_b32_e32 v43, 32, v171
	v_cmp_lt_i32_e32 vcc, v43, v46
	s_nop 1
	v_cndmask_b32_e32 v43, v171, v43, vcc
	v_lshlrev_b32_e32 v43, 2, v43
	v_mov_b32_e32 v43, v42
	s_nop 1
	v_permlane32_swap_b32_e32 v42, v43
	s_and_saveexec_b64 s[36:37], s[2:3]
	s_cbranch_execz .LBB0_1148
	v_lshl_add_u64 v[40:41], v[40:41], 4, s[16:17]
	s_waitcnt lgkmcnt(0)
	v_add_f32_e32 v42, v42, v43
	global_store_dword v[40:41], v42, off

; __device__ __forceinline__ u32x4 pack8bf(const f32x4 a, const f32x4 b) { u32x4 w; w.x = cvt_pk_bf16(a[0], a[1]); w.y = cvt_pk_bf16(a[2], a[3]); w.z = cvt_pk_bf16(b[0], b[1]); w.w = cvt_pk_bf16(b[2], b[3]); return w; }
;     __device__ __forceinline__ float qscale(const Unit& u) const { return ((u.pn >= 8 && u.pn <= 11) || u.pn == 17) ? 0.5f : 1.0f; }
;     ...
;         if constexpr (QM == 2) { const float qs0_ = g.qs * E.qscale(cur), qs1_ = qs0_ * g.qs_b1; _Pragma("unroll") for (int a = 0; a < 2; ++a) _Pragma("unroll") for (int b = 0; b < 2; ++b) _Pragma("unroll") for (int m = 0; m < 4; ++m) _Pragma("unroll") for (int n = 0; n < 2; ++n) { const v4i t_ = __builtin_bit_cast(v4i, acc[a][b][m][n]); acc[a][b][m][n] = (f32x4){(float)t_[0], (float)t_[1], (float)t_[2], (float)t_[3]} * (b == 0 ? qs0_ : qs1_); } }
;     __device__ __forceinline__ void operator()(EPI_ARGS) const {
;     ...
;                 for (int bj = 0; bj < 2; ++bj) { const int hd = 2 * u.pn + bj; const f32x4 v0 = acc[ai][bj][m][0], v1 = acc[ai][bj][m][1];
;                     const f32x4 o0 = v0 * c4 - v1 * s4, o1 = v1 * c4 + v0 * s4;
;                     *(u32x4*)(O + ((size_t)hd * NTOK + row) * 128 + 32 * wc + 8 * fq) = pack8bf(o0, o1);
;                     if (u.pn < 8) { float s = ((o0[0] * o0[0] + o0[1] * o0[1]) + (o0[2] * o0[2] + o0[3] * o0[3])) + ((o1[0] * o1[0] + o1[1] * o1[1]) + (o1[2] * o1[2] + o1[3] * o1[3]));
;                         s += __shfl_xor(s, 16); s += __shfl_xor(s, 32);
;                         if (fq == 0) nrm[((size_t)hd * NTOK + row) * 4 + wc] = s; } } }
.LBB0_1149:
	v_cvt_f32_i32_e32 v33, v33
	v_cvt_f32_i32_e32 v35, v35
	v_cvt_f32_i32_e32 v34, v34
	v_cvt_f32_i32_e32 v32, v32
	v_cvt_f32_i32_e32 v37, v37
	v_cvt_f32_i32_e32 v36, v36
	v_cvt_f32_i32_e32 v39, v39
	v_cvt_f32_i32_e32 v38, v38
	v_pk_mul_f32 v[34:35], v[44:45], v[34:35]
	v_pk_mul_f32 v[32:33], v[158:159], v[32:33]
	s_waitcnt lgkmcnt(0)
	v_pk_mul_f32 v[42:43], v[158:159], v[36:37]
	v_pk_mul_f32 v[38:39], v[44:45], v[38:39]
	v_pk_mul_f32 v[36:37], v[34:35], v[50:51]
	v_pk_mul_f32 v[40:41], v[32:33], v[48:49]
	v_pk_mul_f32 v[34:35], v[34:35], v[54:55]
	v_pk_mul_f32 v[32:33], v[32:33], v[52:53]
	v_pk_fma_f32 v[36:37], v[38:39], v[54:55], v[36:37] neg_lo:[0,0,1] neg_hi:[0,0,1]
	v_pk_fma_f32 v[34:35], v[38:39], v[50:51], v[34:35]
	v_pk_fma_f32 v[38:39], v[42:43], v[48:49], v[32:33]
	v_lshl_add_u64 v[32:33], s[30:31], 0, v[56:57]
	v_lshlrev_b64 v[46:47], 8, v[32:33]
	v_pk_fma_f32 v[40:41], v[42:43], v[52:53], v[40:41] neg_lo:[0,0,1] neg_hi:[0,0,1]
	v_lshl_add_u64 v[46:47], v[148:149], 0, v[46:47]
	s_and_b64 vcc, exec, s[6:7]
	v_cvt_pk_bf16_f32 v42, v40, v41
	v_cvt_pk_bf16_f32 v43, v36, v37
	v_cvt_pk_bf16_f32 v44, v38, v39
	v_cvt_pk_bf16_f32 v45, v34, v35
	global_store_dwordx4 v[46:47], v[42:45], off
	s_cbranch_vccnz .LBB0_1153
	v_mul_f32_e32 v41, v41, v41
	v_mul_f32_e32 v37, v37, v37
	v_fmac_f32_e32 v41, v40, v40
	v_fmac_f32_e32 v37, v36, v36
	v_add_f32_e32 v36, v41, v37
	v_mul_f32_e32 v37, v39, v39
	v_mul_f32_e32 v35, v35, v35
	v_fmac_f32_e32 v37, v38, v38
	v_fmac_f32_e32 v35, v34, v34
	v_add_f32_e32 v34, v37, v35
	v_add_f32_e32 v34, v36, v34
	v_and_b32_e32 v36, 64, v171
	v_xor_b32_e32 v35, 16, v171
	v_add_u32_e32 v36, 64, v36
	v_cmp_lt_i32_e32 vcc, v35, v36
	s_nop 1
	v_cndmask_b32_e32 v35, v171, v35, vcc
	v_lshlrev_b32_e32 v35, 2, v35
	v_mov_b32_e32 v35, v34
	s_nop 1
	v_permlane16_swap_b32_e32 v34, v35
	s_waitcnt lgkmcnt(0)
	v_add_f32_e32 v34, v34, v35
	v_xor_b32_e32 v35, 32, v171
	v_cmp_lt_i32_e32 vcc, v35, v36
	s_nop 1
	v_cndmask_b32_e32 v35, v171, v35, vcc
	v_lshlrev_b32_e32 v35, 2, v35
	v_mov_b32_e32 v35, v34
	s_nop 1
	v_permlane32_swap_b32_e32 v34, v35
	s_and_saveexec_b64 s[36:37], s[2:3]
	s_cbranch_execz .LBB0_1152
	v_lshl_add_u64 v[32:33], v[32:33], 4, s[16:17]
	s_waitcnt lgkmcnt(0)
	v_add_f32_e32 v34, v34, v35
	global_store_dword v[32:33], v34, off

; __device__ __forceinline__ u32x4 pack8bf(const f32x4 a, const f32x4 b) { u32x4 w; w.x = cvt_pk_bf16(a[0], a[1]); w.y = cvt_pk_bf16(a[2], a[3]); w.z = cvt_pk_bf16(b[0], b[1]); w.w = cvt_pk_bf16(b[2], b[3]); return w; }
;     __device__ __forceinline__ float qscale(const Unit& u) const { return ((u.pn >= 8 && u.pn <= 11) || u.pn == 17) ? 0.5f : 1.0f; }
;     ...
;         if constexpr (QM == 2) { const float qs0_ = g.qs * E.qscale(cur), qs1_ = qs0_ * g.qs_b1; _Pragma("unroll") for (int a = 0; a < 2; ++a) _Pragma("unroll") for (int b = 0; b < 2; ++b) _Pragma("unroll") for (int m = 0; m < 4; ++m) _Pragma("unroll") for (int n = 0; n < 2; ++n) { const v4i t_ = __builtin_bit_cast(v4i, acc[a][b][m][n]); acc[a][b][m][n] = (f32x4){(float)t_[0], (float)t_[1], (float)t_[2], (float)t_[3]} * (b == 0 ? qs0_ : qs1_); } }
;     __device__ __forceinline__ void operator()(EPI_ARGS) const {
;     ...
;                 for (int bj = 0; bj < 2; ++bj) { const int hd = 2 * u.pn + bj; const f32x4 v0 = acc[ai][bj][m][0], v1 = acc[ai][bj][m][1];
;                     const f32x4 o0 = v0 * c4 - v1 * s4, o1 = v1 * c4 + v0 * s4;
;                     *(u32x4*)(O + ((size_t)hd * NTOK + row) * 128 + 32 * wc + 8 * fq) = pack8bf(o0, o1);
;                     if (u.pn < 8) { float s = ((o0[0] * o0[0] + o0[1] * o0[1]) + (o0[2] * o0[2] + o0[3] * o0[3])) + ((o1[0] * o1[0] + o1[1] * o1[1]) + (o1[2] * o1[2] + o1[3] * o1[3]));
;                         s += __shfl_xor(s, 16); s += __shfl_xor(s, 32);
;                         if (fq == 0) nrm[((size_t)hd * NTOK + row) * 4 + wc] = s; } } }
.LBB0_1156:
	v_cvt_f32_i32_e32 v25, v25
	v_cvt_f32_i32_e32 v24, v24
	v_cvt_f32_i32_e32 v43, v29
	v_cvt_f32_i32_e32 v42, v28
	v_cvt_f32_i32_e32 v27, v27
	v_cvt_f32_i32_e32 v26, v26
	v_cvt_f32_i32_e32 v31, v31
	v_cvt_f32_i32_e32 v30, v30
	v_pk_mul_f32 v[24:25], v[158:159], v[24:25]
	v_mov_b32_e32 v28, v158
	v_mov_b32_e32 v29, v158
	v_pk_mul_f32 v[42:43], v[158:159], v[42:43]
	s_waitcnt vmcnt(0)
	v_pk_mul_f32 v[44:45], v[24:25], v[32:33]
	v_pk_mul_f32 v[24:25], v[24:25], v[36:37]
	v_pk_mul_f32 v[26:27], v[28:29], v[26:27]
	v_pk_fma_f32 v[44:45], v[42:43], v[36:37], v[44:45] neg_lo:[0,0,1] neg_hi:[0,0,1]
	v_pk_fma_f32 v[42:43], v[42:43], v[32:33], v[24:25]
	v_lshl_add_u64 v[24:25], s[28:29], 0, v[40:41]
	v_pk_mul_f32 v[46:47], v[28:29], v[30:31]
	v_pk_mul_f32 v[30:31], v[26:27], v[34:35]
	v_pk_mul_f32 v[26:27], v[26:27], v[38:39]
	v_lshlrev_b64 v[50:51], 8, v[24:25]
	v_pk_fma_f32 v[30:31], v[46:47], v[38:39], v[30:31] neg_lo:[0,0,1] neg_hi:[0,0,1]
	v_pk_fma_f32 v[26:27], v[46:47], v[34:35], v[26:27]
	v_lshl_add_u64 v[50:51], v[148:149], 0, v[50:51]
	s_and_b64 vcc, exec, s[6:7]
	v_cvt_pk_bf16_f32 v46, v44, v45
	v_cvt_pk_bf16_f32 v47, v30, v31
	v_cvt_pk_bf16_f32 v48, v42, v43
	v_cvt_pk_bf16_f32 v49, v26, v27
	global_store_dwordx4 v[50:51], v[46:49], off
	s_cbranch_vccnz .LBB0_1160
	v_mul_f32_e32 v45, v45, v45
	v_mul_f32_e32 v31, v31, v31
	v_fmac_f32_e32 v45, v44, v44
	v_fmac_f32_e32 v31, v30, v30
	v_add_f32_e32 v30, v45, v31
	v_mul_f32_e32 v31, v43, v43
	v_mul_f32_e32 v27, v27, v27
	v_fmac_f32_e32 v31, v42, v42
	v_fmac_f32_e32 v27, v26, v26
	v_add_f32_e32 v26, v31, v27
	v_add_f32_e32 v26, v30, v26
	v_and_b32_e32 v30, 64, v171
	v_xor_b32_e32 v27, 16, v171
	v_add_u32_e32 v30, 64, v30
	v_cmp_lt_i32_e32 vcc, v27, v30
	s_nop 1
	v_cndmask_b32_e32 v27, v171, v27, vcc
	v_lshlrev_b32_e32 v27, 2, v27
	v_mov_b32_e32 v27, v26
	s_nop 1
	v_permlane16_swap_b32_e32 v26, v27
	s_waitcnt lgkmcnt(0)
	v_add_f32_e32 v26, v26, v27
	v_xor_b32_e32 v27, 32, v171
	v_cmp_lt_i32_e32 vcc, v27, v30
	s_nop 1
	v_cndmask_b32_e32 v27, v171, v27, vcc
	v_lshlrev_b32_e32 v27, 2, v27
	v_mov_b32_e32 v27, v26
	s_nop 1
	v_permlane32_swap_b32_e32 v26, v27
	s_and_saveexec_b64 s[36:37], s[2:3]
	s_cbranch_execz .LBB0_1159
	v_lshl_add_u64 v[24:25], v[24:25], 4, s[16:17]
	s_waitcnt lgkmcnt(0)
	v_add_f32_e32 v26, v26, v27
	global_store_dword v[24:25], v26, off

; __device__ __forceinline__ u32x4 pack8bf(const f32x4 a, const f32x4 b) { u32x4 w; w.x = cvt_pk_bf16(a[0], a[1]); w.y = cvt_pk_bf16(a[2], a[3]); w.z = cvt_pk_bf16(b[0], b[1]); w.w = cvt_pk_bf16(b[2], b[3]); return w; }
;     __device__ __forceinline__ float qscale(const Unit& u) const { return ((u.pn >= 8 && u.pn <= 11) || u.pn == 17) ? 0.5f : 1.0f; }
;     ...
;         if constexpr (QM == 2) { const float qs0_ = g.qs * E.qscale(cur), qs1_ = qs0_ * g.qs_b1; _Pragma("unroll") for (int a = 0; a < 2; ++a) _Pragma("unroll") for (int b = 0; b < 2; ++b) _Pragma("unroll") for (int m = 0; m < 4; ++m) _Pragma("unroll") for (int n = 0; n < 2; ++n) { const v4i t_ = __builtin_bit_cast(v4i, acc[a][b][m][n]); acc[a][b][m][n] = (f32x4){(float)t_[0], (float)t_[1], (float)t_[2], (float)t_[3]} * (b == 0 ? qs0_ : qs1_); } }
;     __device__ __forceinline__ void operator()(EPI_ARGS) const {
;         const int row0 = u.pm * BM + wr * 64 + fr; const bool rot = (u.pn >= 12 && u.pn <= 16); const int fi = 16 * wc + 4 * fq;
; #pragma unroll
;         for (int ai = 0; ai < 2; ++ai)
; #pragma unroll
;             for (int m = 0; m < 4; ++m) { const int row = row0 + ai * HALF + m * 16;
;                 f32x4 c4 = (f32x4){1.f, 1.f, 1.f, 1.f}, s4 = (f32x4){0.f, 0.f, 0.f, 0.f};
;                 if (rot) { c4 = *(const f32x4*)(cs + (size_t)row * 64 + fi); s4 = *(const f32x4*)(sn + (size_t)row * 64 + fi); }
; #pragma unroll
;                 for (int bj = 0; bj < 2; ++bj) { const int hd = 2 * u.pn + bj; const f32x4 v0 = acc[ai][bj][m][0], v1 = acc[ai][bj][m][1];
;                     const f32x4 o0 = v0 * c4 - v1 * s4, o1 = v1 * c4 + v0 * s4;
;                     *(u32x4*)(O + ((size_t)hd * NTOK + row) * 128 + 32 * wc + 8 * fq) = pack8bf(o0, o1);
;                     if (u.pn < 8) { float s = ((o0[0] * o0[0] + o0[1] * o0[1]) + (o0[2] * o0[2] + o0[3] * o0[3])) + ((o1[0] * o1[0] + o1[1] * o1[1]) + (o1[2] * o1[2] + o1[3] * o1[3]));
;                         s += __shfl_xor(s, 16); s += __shfl_xor(s, 32);
;                         if (fq == 0) nrm[((size_t)hd * NTOK + row) * 4 + wc] = s; } } }
.LBB0_1160:
	v_cvt_f32_i32_e32 v17, v17
	v_cvt_f32_i32_e32 v19, v19
	v_cvt_f32_i32_e32 v18, v18
	v_cvt_f32_i32_e32 v16, v16
	v_cvt_f32_i32_e32 v21, v21
	v_cvt_f32_i32_e32 v20, v20
	v_cvt_f32_i32_e32 v23, v23
	v_cvt_f32_i32_e32 v22, v22
	v_pk_mul_f32 v[18:19], v[28:29], v[18:19]
	v_pk_mul_f32 v[16:17], v[158:159], v[16:17]
	s_waitcnt lgkmcnt(0)
	v_pk_mul_f32 v[26:27], v[158:159], v[20:21]
	v_pk_mul_f32 v[22:23], v[28:29], v[22:23]
	v_pk_mul_f32 v[20:21], v[18:19], v[34:35]
	v_pk_mul_f32 v[24:25], v[16:17], v[32:33]
	v_pk_mul_f32 v[18:19], v[18:19], v[38:39]
	v_pk_mul_f32 v[16:17], v[16:17], v[36:37]
	v_pk_fma_f32 v[20:21], v[22:23], v[38:39], v[20:21] neg_lo:[0,0,1] neg_hi:[0,0,1]
	v_pk_fma_f32 v[18:19], v[22:23], v[34:35], v[18:19]
	v_pk_fma_f32 v[22:23], v[26:27], v[32:33], v[16:17]
	v_lshl_add_u64 v[16:17], s[30:31], 0, v[40:41]
	v_lshlrev_b64 v[30:31], 8, v[16:17]
	v_pk_fma_f32 v[24:25], v[26:27], v[36:37], v[24:25] neg_lo:[0,0,1] neg_hi:[0,0,1]
	v_lshl_add_u64 v[30:31], v[148:149], 0, v[30:31]
	s_and_b64 vcc, exec, s[6:7]
	v_cvt_pk_bf16_f32 v26, v24, v25
	v_cvt_pk_bf16_f32 v27, v20, v21
	v_cvt_pk_bf16_f32 v28, v22, v23
	v_cvt_pk_bf16_f32 v29, v18, v19
	global_store_dwordx4 v[30:31], v[26:29], off
	s_cbranch_vccnz .LBB0_1164
	v_mul_f32_e32 v25, v25, v25
	v_mul_f32_e32 v21, v21, v21
	v_fmac_f32_e32 v25, v24, v24
	v_fmac_f32_e32 v21, v20, v20
	v_add_f32_e32 v20, v25, v21
	v_mul_f32_e32 v21, v23, v23
	v_mul_f32_e32 v19, v19, v19
	v_fmac_f32_e32 v21, v22, v22
	v_fmac_f32_e32 v19, v18, v18
	v_add_f32_e32 v18, v21, v19
	v_add_f32_e32 v18, v20, v18
	v_and_b32_e32 v20, 64, v171
	v_xor_b32_e32 v19, 16, v171
	v_add_u32_e32 v20, 64, v20
	v_cmp_lt_i32_e32 vcc, v19, v20
	s_nop 1
	v_cndmask_b32_e32 v19, v171, v19, vcc
	v_lshlrev_b32_e32 v19, 2, v19
	v_mov_b32_e32 v19, v18
	s_nop 1
	v_permlane16_swap_b32_e32 v18, v19
	s_waitcnt lgkmcnt(0)
	v_add_f32_e32 v18, v18, v19
	v_xor_b32_e32 v19, 32, v171
	v_cmp_lt_i32_e32 vcc, v19, v20
	s_nop 1
	v_cndmask_b32_e32 v19, v171, v19, vcc
	v_lshlrev_b32_e32 v19, 2, v19
	v_mov_b32_e32 v19, v18
	s_nop 1
	v_permlane32_swap_b32_e32 v18, v19
	s_and_saveexec_b64 s[36:37], s[2:3]
	s_cbranch_execz .LBB0_1163
	v_lshl_add_u64 v[16:17], v[16:17], 4, s[16:17]
	s_waitcnt lgkmcnt(0)
	v_add_f32_e32 v18, v18, v19
	global_store_dword v[16:17], v18, off

; __device__ __forceinline__ u32x4 pack8bf(const f32x4 a, const f32x4 b) { u32x4 w; w.x = cvt_pk_bf16(a[0], a[1]); w.y = cvt_pk_bf16(a[2], a[3]); w.z = cvt_pk_bf16(b[0], b[1]); w.w = cvt_pk_bf16(b[2], b[3]); return w; }
;     __device__ __forceinline__ float qscale(const Unit& u) const { return ((u.pn >= 8 && u.pn <= 11) || u.pn == 17) ? 0.5f : 1.0f; }
;     ...
;         if constexpr (QM == 2) { const float qs0_ = g.qs * E.qscale(cur), qs1_ = qs0_ * g.qs_b1; _Pragma("unroll") for (int a = 0; a < 2; ++a) _Pragma("unroll") for (int b = 0; b < 2; ++b) _Pragma("unroll") for (int m = 0; m < 4; ++m) _Pragma("unroll") for (int n = 0; n < 2; ++n) { const v4i t_ = __builtin_bit_cast(v4i, acc[a][b][m][n]); acc[a][b][m][n] = (f32x4){(float)t_[0], (float)t_[1], (float)t_[2], (float)t_[3]} * (b == 0 ? qs0_ : qs1_); } }
;     __device__ __forceinline__ void operator()(EPI_ARGS) const {
;         const int row0 = u.pm * BM + wr * 64 + fr; const bool rot = (u.pn >= 12 && u.pn <= 16); const int fi = 16 * wc + 4 * fq;
; #pragma unroll
;         for (int ai = 0; ai < 2; ++ai)
; #pragma unroll
;             for (int m = 0; m < 4; ++m) { const int row = row0 + ai * HALF + m * 16;
;                 f32x4 c4 = (f32x4){1.f, 1.f, 1.f, 1.f}, s4 = (f32x4){0.f, 0.f, 0.f, 0.f};
;                 if (rot) { c4 = *(const f32x4*)(cs + (size_t)row * 64 + fi); s4 = *(const f32x4*)(sn + (size_t)row * 64 + fi); }
; #pragma unroll
;                 for (int bj = 0; bj < 2; ++bj) { const int hd = 2 * u.pn + bj; const f32x4 v0 = acc[ai][bj][m][0], v1 = acc[ai][bj][m][1];
;                     const f32x4 o0 = v0 * c4 - v1 * s4, o1 = v1 * c4 + v0 * s4;
;                     *(u32x4*)(O + ((size_t)hd * NTOK + row) * 128 + 32 * wc + 8 * fq) = pack8bf(o0, o1);
;                     if (u.pn < 8) { float s = ((o0[0] * o0[0] + o0[1] * o0[1]) + (o0[2] * o0[2] + o0[3] * o0[3])) + ((o1[0] * o1[0] + o1[1] * o1[1]) + (o1[2] * o1[2] + o1[3] * o1[3]));
;                         s += __shfl_xor(s, 16); s += __shfl_xor(s, 32);
;                         if (fq == 0) nrm[((size_t)hd * NTOK + row) * 4 + wc] = s; } } }
.LBB0_1167:
	v_cvt_f32_i32_e32 v9, v9
	v_cvt_f32_i32_e32 v8, v8
	v_cvt_f32_i32_e32 v27, v13
	v_cvt_f32_i32_e32 v26, v12
	v_cvt_f32_i32_e32 v11, v11
	v_cvt_f32_i32_e32 v10, v10
	v_cvt_f32_i32_e32 v15, v15
	v_cvt_f32_i32_e32 v14, v14
	v_pk_mul_f32 v[8:9], v[158:159], v[8:9]
	v_mov_b32_e32 v12, v158
	v_mov_b32_e32 v13, v158
	v_pk_mul_f32 v[26:27], v[158:159], v[26:27]
	s_waitcnt vmcnt(0)
	v_pk_mul_f32 v[28:29], v[8:9], v[16:17]
	v_pk_mul_f32 v[8:9], v[8:9], v[20:21]
	v_pk_mul_f32 v[10:11], v[12:13], v[10:11]
	v_pk_fma_f32 v[28:29], v[26:27], v[20:21], v[28:29] neg_lo:[0,0,1] neg_hi:[0,0,1]
	v_pk_fma_f32 v[26:27], v[26:27], v[16:17], v[8:9]
	v_lshl_add_u64 v[8:9], s[28:29], 0, v[24:25]
	v_pk_mul_f32 v[30:31], v[12:13], v[14:15]
	v_pk_mul_f32 v[14:15], v[10:11], v[18:19]
	v_pk_mul_f32 v[10:11], v[10:11], v[22:23]
	v_lshlrev_b64 v[34:35], 8, v[8:9]
	v_pk_fma_f32 v[14:15], v[30:31], v[22:23], v[14:15] neg_lo:[0,0,1] neg_hi:[0,0,1]
	v_pk_fma_f32 v[10:11], v[30:31], v[18:19], v[10:11]
	v_lshl_add_u64 v[34:35], v[148:149], 0, v[34:35]
	s_and_b64 vcc, exec, s[6:7]
	v_cvt_pk_bf16_f32 v30, v28, v29
	v_cvt_pk_bf16_f32 v31, v14, v15
	v_cvt_pk_bf16_f32 v32, v26, v27
	v_cvt_pk_bf16_f32 v33, v10, v11
	global_store_dwordx4 v[34:35], v[30:33], off
	s_cbranch_vccnz .LBB0_1171
	v_mul_f32_e32 v29, v29, v29
	v_mul_f32_e32 v15, v15, v15
	v_fmac_f32_e32 v29, v28, v28
	v_fmac_f32_e32 v15, v14, v14
	v_add_f32_e32 v14, v29, v15
	v_mul_f32_e32 v15, v27, v27
	v_mul_f32_e32 v11, v11, v11
	v_fmac_f32_e32 v15, v26, v26
	v_fmac_f32_e32 v11, v10, v10
	v_add_f32_e32 v10, v15, v11
	v_add_f32_e32 v10, v14, v10
	v_and_b32_e32 v14, 64, v171
	v_xor_b32_e32 v11, 16, v171
	v_add_u32_e32 v14, 64, v14
	v_cmp_lt_i32_e32 vcc, v11, v14
	s_nop 1
	v_cndmask_b32_e32 v11, v171, v11, vcc
	v_lshlrev_b32_e32 v11, 2, v11
	v_mov_b32_e32 v11, v10
	s_nop 1
	v_permlane16_swap_b32_e32 v10, v11
	s_waitcnt lgkmcnt(0)
	v_add_f32_e32 v10, v10, v11
	v_xor_b32_e32 v11, 32, v171
	v_cmp_lt_i32_e32 vcc, v11, v14
	s_nop 1
	v_cndmask_b32_e32 v11, v171, v11, vcc
	v_lshlrev_b32_e32 v11, 2, v11
	v_mov_b32_e32 v11, v10
	s_nop 1
	v_permlane32_swap_b32_e32 v10, v11
	s_and_saveexec_b64 s[8:9], s[2:3]
	s_cbranch_execz .LBB0_1170
	v_lshl_add_u64 v[8:9], v[8:9], 4, s[16:17]
	s_waitcnt lgkmcnt(0)
	v_add_f32_e32 v10, v10, v11
	global_store_dword v[8:9], v10, off

; __device__ __forceinline__ u32x4 pack8bf(const f32x4 a, const f32x4 b) { u32x4 w; w.x = cvt_pk_bf16(a[0], a[1]); w.y = cvt_pk_bf16(a[2], a[3]); w.z = cvt_pk_bf16(b[0], b[1]); w.w = cvt_pk_bf16(b[2], b[3]); return w; }
;     __device__ __forceinline__ float qscale(const Unit& u) const { return ((u.pn >= 8 && u.pn <= 11) || u.pn == 17) ? 0.5f : 1.0f; }
;     ...
;         if constexpr (QM == 2) { const float qs0_ = g.qs * E.qscale(cur), qs1_ = qs0_ * g.qs_b1; _Pragma("unroll") for (int a = 0; a < 2; ++a) _Pragma("unroll") for (int b = 0; b < 2; ++b) _Pragma("unroll") for (int m = 0; m < 4; ++m) _Pragma("unroll") for (int n = 0; n < 2; ++n) { const v4i t_ = __builtin_bit_cast(v4i, acc[a][b][m][n]); acc[a][b][m][n] = (f32x4){(float)t_[0], (float)t_[1], (float)t_[2], (float)t_[3]} * (b == 0 ? qs0_ : qs1_); } }
;     __device__ __forceinline__ void operator()(EPI_ARGS) const {
;         const int row0 = u.pm * BM + wr * 64 + fr; const bool rot = (u.pn >= 12 && u.pn <= 16); const int fi = 16 * wc + 4 * fq;
; #pragma unroll
;         for (int ai = 0; ai < 2; ++ai)
; #pragma unroll
;             for (int m = 0; m < 4; ++m) { const int row = row0 + ai * HALF + m * 16;
;                 f32x4 c4 = (f32x4){1.f, 1.f, 1.f, 1.f}, s4 = (f32x4){0.f, 0.f, 0.f, 0.f};
;                 if (rot) { c4 = *(const f32x4*)(cs + (size_t)row * 64 + fi); s4 = *(const f32x4*)(sn + (size_t)row * 64 + fi); }
; #pragma unroll
;                 for (int bj = 0; bj < 2; ++bj) { const int hd = 2 * u.pn + bj; const f32x4 v0 = acc[ai][bj][m][0], v1 = acc[ai][bj][m][1];
;                     const f32x4 o0 = v0 * c4 - v1 * s4, o1 = v1 * c4 + v0 * s4;
;                     *(u32x4*)(O + ((size_t)hd * NTOK + row) * 128 + 32 * wc + 8 * fq) = pack8bf(o0, o1);
;                     if (u.pn < 8) { float s = ((o0[0] * o0[0] + o0[1] * o0[1]) + (o0[2] * o0[2] + o0[3] * o0[3])) + ((o1[0] * o1[0] + o1[1] * o1[1]) + (o1[2] * o1[2] + o1[3] * o1[3]));
;                         s += __shfl_xor(s, 16); s += __shfl_xor(s, 32);
;                         if (fq == 0) nrm[((size_t)hd * NTOK + row) * 4 + wc] = s; } } }
.LBB0_1171:
	v_cvt_f32_i32_e32 v1, v1
	v_cvt_f32_i32_e32 v3, v3
	v_cvt_f32_i32_e32 v2, v2
	v_cvt_f32_i32_e32 v0, v0
	v_cvt_f32_i32_e32 v5, v5
	v_cvt_f32_i32_e32 v4, v4
	v_cvt_f32_i32_e32 v7, v7
	v_cvt_f32_i32_e32 v6, v6
	v_pk_mul_f32 v[2:3], v[12:13], v[2:3]
	v_pk_mul_f32 v[0:1], v[158:159], v[0:1]
	s_waitcnt lgkmcnt(0)
	v_pk_mul_f32 v[10:11], v[158:159], v[4:5]
	v_pk_mul_f32 v[6:7], v[12:13], v[6:7]
	v_pk_mul_f32 v[4:5], v[2:3], v[18:19]
	v_pk_mul_f32 v[8:9], v[0:1], v[16:17]
	v_pk_mul_f32 v[2:3], v[2:3], v[22:23]
	v_pk_mul_f32 v[0:1], v[0:1], v[20:21]
	v_pk_fma_f32 v[4:5], v[6:7], v[22:23], v[4:5] neg_lo:[0,0,1] neg_hi:[0,0,1]
	v_pk_fma_f32 v[2:3], v[6:7], v[18:19], v[2:3]
	v_pk_fma_f32 v[6:7], v[10:11], v[16:17], v[0:1]
	v_lshl_add_u64 v[0:1], s[30:31], 0, v[24:25]
	v_lshlrev_b64 v[14:15], 8, v[0:1]
	v_pk_fma_f32 v[8:9], v[10:11], v[20:21], v[8:9] neg_lo:[0,0,1] neg_hi:[0,0,1]
	v_lshl_add_u64 v[14:15], v[148:149], 0, v[14:15]
	s_and_b64 vcc, exec, s[6:7]
	v_cvt_pk_bf16_f32 v10, v8, v9
	v_cvt_pk_bf16_f32 v11, v4, v5
	v_cvt_pk_bf16_f32 v12, v6, v7
	v_cvt_pk_bf16_f32 v13, v2, v3
	global_store_dwordx4 v[14:15], v[10:13], off
	s_cbranch_vccnz .LBB0_1175
	v_mul_f32_e32 v9, v9, v9
	v_mul_f32_e32 v5, v5, v5
	v_fmac_f32_e32 v9, v8, v8
	v_fmac_f32_e32 v5, v4, v4
	v_add_f32_e32 v4, v9, v5
	v_mul_f32_e32 v5, v7, v7
	v_mul_f32_e32 v3, v3, v3
	v_fmac_f32_e32 v5, v6, v6
	v_fmac_f32_e32 v3, v2, v2
	v_add_f32_e32 v2, v5, v3
	v_add_f32_e32 v2, v4, v2
	v_and_b32_e32 v4, 64, v171
	v_xor_b32_e32 v3, 16, v171
	v_add_u32_e32 v4, 64, v4
	v_cmp_lt_i32_e32 vcc, v3, v4
	s_nop 1
	v_cndmask_b32_e32 v3, v171, v3, vcc
	v_lshlrev_b32_e32 v3, 2, v3
	v_mov_b32_e32 v3, v2
	s_nop 1
	v_permlane16_swap_b32_e32 v2, v3
	s_waitcnt lgkmcnt(0)
	v_add_f32_e32 v2, v2, v3
	v_xor_b32_e32 v3, 32, v171
	v_cmp_lt_i32_e32 vcc, v3, v4
	s_nop 1
	v_cndmask_b32_e32 v3, v171, v3, vcc
	v_lshlrev_b32_e32 v3, 2, v3
	v_mov_b32_e32 v3, v2
	s_nop 1
	v_permlane32_swap_b32_e32 v2, v3
	s_and_saveexec_b64 s[6:7], s[2:3]
	s_cbranch_execz .LBB0_1174
	v_lshl_add_u64 v[0:1], v[0:1], 4, s[16:17]
	s_waitcnt lgkmcnt(0)
	v_add_f32_e32 v2, v2, v3
	global_store_dword v[0:1], v2, off

; __device__ __forceinline__ u32x2 pack8i8(const f32x4 a, const f32x4 b) { return (u32x2){pack4i8(a), pack4i8(b)}; }
; __device__ __forceinline__ u32x4 pack8bf(const f32x4 a, const f32x4 b) { u32x4 w; w.x = cvt_pk_bf16(a[0], a[1]); w.y = cvt_pk_bf16(a[2], a[3]); w.z = cvt_pk_bf16(b[0], b[1]); w.w = cvt_pk_bf16(b[2], b[3]); return w; }
;     __device__ __forceinline__ void operator()(EPI_ARGS) const {
;     ...
;             for (int m = 0; m < 4; ++m) { const int row = row0 + ai * HALF + m * 16; const size_t off = (size_t)row * DM + col0;
;                 float mu = 0.f, rs = 1.f; if constexpr (RESLN) ln_stats(stin, row, mu, rs);
;                 float ss = 0.f, qq = 0.f;
; #pragma unroll
;                 for (int bj = 0; bj < 2; ++bj) { f32x4 r0 = __builtin_nontemporal_load((const f32x4*)(res + off + bj * HALF)), r1 = __builtin_nontemporal_load((const f32x4*)(res + off + bj * HALF + 4));
;                     if constexpr (RESLN) { r0 = (r0 - mu) * rs * gg[bj][0] + bb[bj][0]; r1 = (r1 - mu) * rs * gg[bj][1] + bb[bj][1]; }
;                     const f32x4 y0 = r0 * DN_ALPHA + acc[ai][bj][m][0] * ascale, y1 = r1 * DN_ALPHA + acc[ai][bj][m][1] * ascale;
;                     if constexpr (COPY != 4) { __builtin_nontemporal_store(y0, (f32x4*)(Y + off + bj * HALF)); __builtin_nontemporal_store(y1, (f32x4*)(Y + off + bj * HALF + 4)); }
;                     if constexpr (STATS) { ss += ((y0[0] + y0[1]) + (y0[2] + y0[3])) + ((y1[0] + y1[1]) + (y1[2] + y1[3]));
;                         qq += ((y0[0] * y0[0] + y0[1] * y0[1]) + (y0[2] * y0[2] + y0[3] * y0[3])) + ((y1[0] * y1[0] + y1[1] * y1[1]) + (y1[2] * y1[2] + y1[3] * y1[3])); }
;                     if constexpr (COPY == 1) *(u32x2*)((unsigned char*)copy + off + bj * HALF) = pack8fp8(y0 * cscale, y1 * cscale);
;                     if constexpr (COPY == 3) *(u32x2*)((unsigned char*)copy + off + bj * HALF) = pack8i8(y0 * cscale, y1 * cscale);
;                     if constexpr (COPY == 2 || COPY == 4) *(u32x4*)((bf16_t*)copy + off + bj * HALF) = pack8bf(y0, y1); }
;                 if constexpr (STATS) { ss += __shfl_xor(ss, 16); ss += __shfl_xor(ss, 32); qq += __shfl_xor(qq, 16); qq += __shfl_xor(qq, 32);
;                     if (fq == 0) { unsafeAtomicAdd(stout + 2 * (size_t)row, ss); unsafeAtomicAdd(stout + 2 * (size_t)row + 1, qq); } }
.LBB0_3689:
	v_lshl_add_u32 v2, s40, 8, v184
	v_lshl_or_b32 v0, s42, 8, v186
	v_ashrrev_i32_e32 v3, 31, v2
	v_ashrrev_i32_e32 v1, 31, v0
	v_lshlrev_b64 v[4:5], 11, v[2:3]
	v_lshl_add_u64 v[12:13], v[4:5], 0, v[0:1]
	v_lshlrev_b64 v[14:15], 2, v[12:13]
	v_lshl_add_u64 v[20:21], s[6:7], 0, v[14:15]
	global_load_dwordx4 v[4:7], v[20:21], off nt
	global_load_dwordx4 v[8:11], v[20:21], off offset:16 nt
	v_lshl_add_u64 v[24:25], s[12:13], 0, v[12:13]
	v_lshl_add_u64 v[26:27], s[10:11], 0, v[14:15]
	s_waitcnt vmcnt(0)
	v_pk_mul_f32 v[6:7], v[6:7], s[20:21] op_sel_hi:[1,0]
	v_pk_mul_f32 v[4:5], v[4:5], s[20:21] op_sel_hi:[1,0]
	v_pk_mul_f32 v[12:13], v[10:11], s[20:21] op_sel_hi:[1,0]
	v_pk_mul_f32 v[16:17], v[8:9], s[20:21] op_sel_hi:[1,0]
	v_pk_fma_f32 v[10:11], v[158:159], s[24:25], v[6:7] op_sel_hi:[1,0,1]
	v_pk_fma_f32 v[8:9], v[156:157], s[24:25], v[4:5] op_sel_hi:[1,0,1]
	v_pk_fma_f32 v[14:15], v[154:155], s[24:25], v[12:13] op_sel_hi:[1,0,1]
	v_pk_fma_f32 v[12:13], v[152:153], s[24:25], v[16:17] op_sel_hi:[1,0,1]
	v_pk_mul_f32 v[4:5], v[10:11], s[26:27] op_sel_hi:[1,0]
	v_pk_mul_f32 v[6:7], v[8:9], s[26:27] op_sel_hi:[1,0]
	v_pk_mul_f32 v[16:17], v[14:15], s[26:27] op_sel_hi:[1,0]
	v_pk_mul_f32 v[18:19], v[12:13], s[26:27] op_sel_hi:[1,0]
	v_med3_f32 v6, v6, s63, v192
	v_med3_f32 v7, v7, s63, v192
	v_med3_f32 v4, v4, s63, v192
	v_med3_f32 v5, v5, s63, v192
	v_med3_f32 v18, v18, s63, v192
	v_med3_f32 v19, v19, s63, v192
	v_med3_f32 v16, v16, s63, v192
	v_med3_f32 v17, v17, s63, v192
	v_add_f32_e32 v6, 0x4b400000, v6
	v_add_f32_e32 v7, 0x4b400000, v7
	v_add_f32_e32 v4, 0x4b400000, v4
	v_add_f32_e32 v5, 0x4b400000, v5
	v_add_f32_e32 v18, 0x4b400000, v18
	v_add_f32_e32 v19, 0x4b400000, v19
	v_add_f32_e32 v16, 0x4b400000, v16
	v_add_f32_e32 v17, 0x4b400000, v17
	v_perm_b32 v6, v7, v6, s64
	v_perm_b32 v4, v5, v4, s65
	v_perm_b32 v5, v19, v18, s64
	v_perm_b32 v7, v17, v16, s65
	v_or_b32_e32 v4, v6, v4
	v_or_b32_e32 v5, v5, v7
	global_store_dwordx4 v[26:27], v[8:11], off nt
	global_store_dwordx4 v[26:27], v[12:15], off offset:16 nt
	global_store_dwordx2 v[24:25], v[4:5], off
	global_load_dwordx4 v[16:19], v[20:21], off offset:512 nt
	s_nop 0
	global_load_dwordx4 v[20:23], v[20:21], off offset:528 nt
	v_and_b32_e32 v5, 64, v191
	v_xor_b32_e32 v4, 16, v191
	v_add_u32_e32 v5, 64, v5
	v_xor_b32_e32 v6, 32, v191
	v_cmp_lt_i32_e32 vcc, v4, v5
	v_add_f32_e32 v28, v12, v13
	v_add_f32_e32 v29, v14, v15
	v_cndmask_b32_e32 v4, v191, v4, vcc
	v_cmp_lt_i32_e32 vcc, v6, v5
	v_lshlrev_b32_e32 v7, 2, v4
	v_add_f32_e32 v4, v8, v9
	v_cndmask_b32_e32 v5, v191, v6, vcc
	v_lshlrev_b32_e32 v6, 2, v5
	v_add_f32_e32 v5, v10, v11
	v_mul_f32_e32 v9, v9, v9
	v_mul_f32_e32 v11, v11, v11
	v_mul_f32_e32 v13, v13, v13
	v_mul_f32_e32 v15, v15, v15
	v_add_f32_e32 v4, v4, v5
	v_add_f32_e32 v5, v28, v29
	v_fmac_f32_e32 v9, v8, v8
	v_fmac_f32_e32 v11, v10, v10
	v_fmac_f32_e32 v13, v12, v12
	v_fmac_f32_e32 v15, v14, v14
	v_add_f32_e32 v4, v4, v5
	v_add_f32_e32 v5, v9, v11
	v_add_f32_e32 v8, v13, v15
	v_add_f32_e32 v28, 0, v4
	v_add_f32_e32 v29, v5, v8
	s_waitcnt vmcnt(1)
	v_pk_mul_f32 v[4:5], v[18:19], s[20:21] op_sel_hi:[1,0]
	v_pk_mul_f32 v[8:9], v[16:17], s[20:21] op_sel_hi:[1,0]
	s_waitcnt vmcnt(0)
	v_pk_mul_f32 v[12:13], v[22:23], s[20:21] op_sel_hi:[1,0]
	v_pk_mul_f32 v[16:17], v[20:21], s[20:21] op_sel_hi:[1,0]
	v_pk_fma_f32 v[10:11], v[150:151], s[24:25], v[4:5] op_sel_hi:[1,0,1]
	v_pk_fma_f32 v[8:9], v[148:149], s[24:25], v[8:9] op_sel_hi:[1,0,1]
	v_pk_fma_f32 v[14:15], v[146:147], s[24:25], v[12:13] op_sel_hi:[1,0,1]
	v_pk_fma_f32 v[12:13], v[144:145], s[24:25], v[16:17] op_sel_hi:[1,0,1]
	global_store_dwordx4 v[26:27], v[8:11], off offset:512 nt
	global_store_dwordx4 v[26:27], v[12:15], off offset:528 nt
	v_add_f32_e32 v22, v8, v9
	v_add_f32_e32 v23, v10, v11
	v_add_f32_e32 v26, v12, v13
	v_add_f32_e32 v27, v14, v15
	v_mul_f32_e32 v30, v9, v9
	v_mul_f32_e32 v31, v11, v11
	v_mul_f32_e32 v144, v13, v13
	v_mul_f32_e32 v145, v15, v15
	v_pk_mul_f32 v[4:5], v[10:11], s[26:27] op_sel_hi:[1,0]
	v_pk_mul_f32 v[16:17], v[8:9], s[26:27] op_sel_hi:[1,0]
	v_add_f32_e32 v9, v22, v23
	v_add_f32_e32 v11, v26, v27
	v_fmac_f32_e32 v30, v8, v8
	v_fmac_f32_e32 v31, v10, v10
	v_fmac_f32_e32 v144, v12, v12
	v_fmac_f32_e32 v145, v14, v14
	v_med3_f32 v8, v16, s63, v192
	v_add_f32_e32 v9, v9, v11
	v_add_f32_e32 v11, v30, v31
	v_add_f32_e32 v16, v144, v145
	v_add_f32_e32 v11, v11, v16
	v_add_f32_e32 v9, v28, v9
	v_add_f32_e32 v11, v29, v11
	v_med3_f32 v10, v17, s63, v192
	v_mov_b32_e32 v16, v9
	s_nop 1
	v_permlane16_swap_b32_e32 v9, v16
	v_mov_b32_e32 v17, v11
	s_nop 1
	v_permlane16_swap_b32_e32 v11, v17
	v_med3_f32 v4, v4, s63, v192
	v_med3_f32 v5, v5, s63, v192
	v_add_f32_e32 v8, 0x4b400000, v8
	v_add_f32_e32 v10, 0x4b400000, v10
	v_add_f32_e32 v4, 0x4b400000, v4
	v_add_f32_e32 v5, 0x4b400000, v5
	v_perm_b32 v8, v10, v8, s64
	v_perm_b32 v4, v5, v4, s65
	v_or_b32_e32 v10, v8, v4
	s_waitcnt lgkmcnt(0)
	v_add_f32_e32 v4, v9, v16
	s_waitcnt lgkmcnt(0)
	v_add_f32_e32 v8, v11, v17
	v_pk_mul_f32 v[18:19], v[14:15], s[26:27] op_sel_hi:[1,0]
	v_pk_mul_f32 v[20:21], v[12:13], s[26:27] op_sel_hi:[1,0]
	v_mov_b32_e32 v5, v4
	s_nop 1
	v_permlane32_swap_b32_e32 v4, v5
	v_mov_b32_e32 v9, v8
	s_nop 1
	v_permlane32_swap_b32_e32 v8, v9
	v_med3_f32 v12, v20, s63, v192
	v_med3_f32 v13, v21, s63, v192
	v_med3_f32 v14, v18, s63, v192
	v_med3_f32 v15, v19, s63, v192
	v_add_f32_e32 v12, 0x4b400000, v12
	v_add_f32_e32 v13, 0x4b400000, v13
	v_add_f32_e32 v14, 0x4b400000, v14
	v_add_f32_e32 v15, 0x4b400000, v15
	v_perm_b32 v11, v13, v12, s64
	v_perm_b32 v12, v15, v14, s65
	v_or_b32_e32 v11, v11, v12
	global_store_dwordx2 v[24:25], v[10:11], off offset:128
	s_and_saveexec_b64 s[40:41], s[2:3]
	s_cbranch_execz .LBB0_3691
	v_lshl_add_u64 v[10:11], v[2:3], 3, s[14:15]
	s_waitcnt lgkmcnt(0)
	v_add_f32_e32 v3, v4, v5
	s_waitcnt lgkmcnt(0)
	v_add_f32_e32 v4, v8, v9
	global_atomic_add_f32 v[10:11], v3, off
	global_atomic_add_f32 v[10:11], v4, off offset:4
; __device__ __forceinline__ u32x2 pack8i8(const f32x4 a, const f32x4 b) { return (u32x2){pack4i8(a), pack4i8(b)}; }
; __device__ __forceinline__ u32x4 pack8bf(const f32x4 a, const f32x4 b) { u32x4 w; w.x = cvt_pk_bf16(a[0], a[1]); w.y = cvt_pk_bf16(a[2], a[3]); w.z = cvt_pk_bf16(b[0], b[1]); w.w = cvt_pk_bf16(b[2], b[3]); return w; }
;     __device__ __forceinline__ void operator()(EPI_ARGS) const {
;     ...
;             for (int m = 0; m < 4; ++m) { const int row = row0 + ai * HALF + m * 16; const size_t off = (size_t)row * DM + col0;
;                 float mu = 0.f, rs = 1.f; if constexpr (RESLN) ln_stats(stin, row, mu, rs);
;                 float ss = 0.f, qq = 0.f;
; #pragma unroll
;                 for (int bj = 0; bj < 2; ++bj) { f32x4 r0 = __builtin_nontemporal_load((const f32x4*)(res + off + bj * HALF)), r1 = __builtin_nontemporal_load((const f32x4*)(res + off + bj * HALF + 4));
;                     if constexpr (RESLN) { r0 = (r0 - mu) * rs * gg[bj][0] + bb[bj][0]; r1 = (r1 - mu) * rs * gg[bj][1] + bb[bj][1]; }
;                     const f32x4 y0 = r0 * DN_ALPHA + acc[ai][bj][m][0] * ascale, y1 = r1 * DN_ALPHA + acc[ai][bj][m][1] * ascale;
;                     if constexpr (COPY != 4) { __builtin_nontemporal_store(y0, (f32x4*)(Y + off + bj * HALF)); __builtin_nontemporal_store(y1, (f32x4*)(Y + off + bj * HALF + 4)); }
;                     if constexpr (STATS) { ss += ((y0[0] + y0[1]) + (y0[2] + y0[3])) + ((y1[0] + y1[1]) + (y1[2] + y1[3]));
;                         qq += ((y0[0] * y0[0] + y0[1] * y0[1]) + (y0[2] * y0[2] + y0[3] * y0[3])) + ((y1[0] * y1[0] + y1[1] * y1[1]) + (y1[2] * y1[2] + y1[3] * y1[3])); }
;                     if constexpr (COPY == 1) *(u32x2*)((unsigned char*)copy + off + bj * HALF) = pack8fp8(y0 * cscale, y1 * cscale);
;                     if constexpr (COPY == 3) *(u32x2*)((unsigned char*)copy + off + bj * HALF) = pack8i8(y0 * cscale, y1 * cscale);
;                     if constexpr (COPY == 2 || COPY == 4) *(u32x4*)((bf16_t*)copy + off + bj * HALF) = pack8bf(y0, y1); }
;                 if constexpr (STATS) { ss += __shfl_xor(ss, 16); ss += __shfl_xor(ss, 32); qq += __shfl_xor(qq, 16); qq += __shfl_xor(qq, 32);
;                     if (fq == 0) { unsafeAtomicAdd(stout + 2 * (size_t)row, ss); unsafeAtomicAdd(stout + 2 * (size_t)row + 1, qq); } }
.LBB0_3691:
	s_or_b64 exec, exec, s[40:41]
	v_or_b32_e32 v4, 16, v2
	s_waitcnt lgkmcnt(1)
	v_ashrrev_i32_e32 v5, 31, v4
	s_waitcnt lgkmcnt(0)
	v_lshlrev_b64 v[8:9], 11, v[4:5]
	v_lshl_add_u64 v[16:17], v[8:9], 0, v[0:1]
	v_lshlrev_b64 v[18:19], 2, v[16:17]
	v_lshl_add_u64 v[20:21], s[6:7], 0, v[18:19]
	global_load_dwordx4 v[8:11], v[20:21], off nt
	global_load_dwordx4 v[12:15], v[20:21], off offset:16 nt
	v_lshl_add_u64 v[24:25], s[12:13], 0, v[16:17]
	v_lshl_add_u64 v[26:27], s[10:11], 0, v[18:19]
	s_waitcnt vmcnt(1)
	v_pk_mul_f32 v[10:11], v[10:11], s[20:21] op_sel_hi:[1,0]
	v_pk_mul_f32 v[8:9], v[8:9], s[20:21] op_sel_hi:[1,0]
	s_waitcnt vmcnt(0)
	v_pk_mul_f32 v[14:15], v[14:15], s[20:21] op_sel_hi:[1,0]
	v_pk_mul_f32 v[12:13], v[12:13], s[20:21] op_sel_hi:[1,0]
	v_pk_fma_f32 v[10:11], v[142:143], s[24:25], v[10:11] op_sel_hi:[1,0,1]
	v_pk_fma_f32 v[8:9], v[140:141], s[24:25], v[8:9] op_sel_hi:[1,0,1]
	v_pk_fma_f32 v[14:15], v[138:139], s[24:25], v[14:15] op_sel_hi:[1,0,1]
	v_pk_fma_f32 v[12:13], v[136:137], s[24:25], v[12:13] op_sel_hi:[1,0,1]
	v_pk_mul_f32 v[16:17], v[10:11], s[26:27] op_sel_hi:[1,0]
	v_pk_mul_f32 v[18:19], v[8:9], s[26:27] op_sel_hi:[1,0]
	v_pk_mul_f32 v[22:23], v[14:15], s[26:27] op_sel_hi:[1,0]
	v_pk_mul_f32 v[28:29], v[12:13], s[26:27] op_sel_hi:[1,0]
	v_med3_f32 v3, v18, s63, v192
	v_med3_f32 v18, v19, s63, v192
	v_med3_f32 v16, v16, s63, v192
	v_med3_f32 v17, v17, s63, v192
	v_med3_f32 v19, v28, s63, v192
	v_med3_f32 v28, v29, s63, v192
	v_med3_f32 v22, v22, s63, v192
	v_med3_f32 v23, v23, s63, v192
	v_add_f32_e32 v3, 0x4b400000, v3
	v_add_f32_e32 v18, 0x4b400000, v18
	v_add_f32_e32 v16, 0x4b400000, v16
	v_add_f32_e32 v17, 0x4b400000, v17
	v_add_f32_e32 v19, 0x4b400000, v19
	v_add_f32_e32 v28, 0x4b400000, v28
	v_add_f32_e32 v22, 0x4b400000, v22
	v_add_f32_e32 v23, 0x4b400000, v23
	v_perm_b32 v3, v18, v3, s64
	v_perm_b32 v16, v17, v16, s65
	v_perm_b32 v17, v28, v19, s64
	v_perm_b32 v18, v23, v22, s65
	v_or_b32_e32 v16, v3, v16
	v_or_b32_e32 v17, v17, v18
	global_store_dwordx4 v[26:27], v[8:11], off nt
	global_store_dwordx4 v[26:27], v[12:15], off offset:16 nt
	global_store_dwordx2 v[24:25], v[16:17], off
	global_load_dwordx4 v[16:19], v[20:21], off offset:512 nt
	s_nop 0
	global_load_dwordx4 v[20:23], v[20:21], off offset:528 nt
	v_add_f32_e32 v3, v8, v9
	v_add_f32_e32 v28, v10, v11
	v_add_f32_e32 v29, v12, v13
	v_add_f32_e32 v30, v14, v15
	v_mul_f32_e32 v9, v9, v9
	v_mul_f32_e32 v11, v11, v11
	v_mul_f32_e32 v13, v13, v13
	v_mul_f32_e32 v15, v15, v15
	v_fmac_f32_e32 v9, v8, v8
	v_fmac_f32_e32 v11, v10, v10
	v_fmac_f32_e32 v13, v12, v12
	v_fmac_f32_e32 v15, v14, v14
	v_add_f32_e32 v3, v3, v28
	v_add_f32_e32 v28, v29, v30
	v_add_f32_e32 v8, v9, v11
	v_add_f32_e32 v9, v13, v15
	v_add_f32_e32 v3, v3, v28
	v_add_f32_e32 v28, v8, v9
	v_add_f32_e32 v3, 0, v3
	s_waitcnt vmcnt(1)
	v_pk_mul_f32 v[8:9], v[18:19], s[20:21] op_sel_hi:[1,0]
	v_pk_mul_f32 v[12:13], v[16:17], s[20:21] op_sel_hi:[1,0]
	s_waitcnt vmcnt(0)
	v_pk_mul_f32 v[14:15], v[22:23], s[20:21] op_sel_hi:[1,0]
	v_pk_mul_f32 v[16:17], v[20:21], s[20:21] op_sel_hi:[1,0]
	v_pk_fma_f32 v[10:11], v[134:135], s[24:25], v[8:9] op_sel_hi:[1,0,1]
	v_pk_fma_f32 v[8:9], v[132:133], s[24:25], v[12:13] op_sel_hi:[1,0,1]
	v_pk_fma_f32 v[14:15], v[130:131], s[24:25], v[14:15] op_sel_hi:[1,0,1]
	v_pk_fma_f32 v[12:13], v[128:129], s[24:25], v[16:17] op_sel_hi:[1,0,1]
	global_store_dwordx4 v[26:27], v[8:11], off offset:512 nt
	global_store_dwordx4 v[26:27], v[12:15], off offset:528 nt
	v_add_f32_e32 v26, v8, v9
	v_add_f32_e32 v27, v10, v11
	v_add_f32_e32 v29, v12, v13
	v_add_f32_e32 v30, v14, v15
	v_mul_f32_e32 v31, v9, v9
	v_mul_f32_e32 v128, v11, v11
	v_mul_f32_e32 v129, v13, v13
	v_mul_f32_e32 v130, v15, v15
	v_pk_mul_f32 v[16:17], v[10:11], s[26:27] op_sel_hi:[1,0]
	v_pk_mul_f32 v[18:19], v[8:9], s[26:27] op_sel_hi:[1,0]
	v_add_f32_e32 v9, v26, v27
	v_add_f32_e32 v11, v29, v30
	v_fmac_f32_e32 v31, v8, v8
	v_fmac_f32_e32 v128, v10, v10
	v_fmac_f32_e32 v129, v12, v12
	v_fmac_f32_e32 v130, v14, v14
	v_med3_f32 v8, v18, s63, v192
	v_add_f32_e32 v9, v9, v11
	v_add_f32_e32 v11, v31, v128
	v_add_f32_e32 v18, v129, v130
	v_med3_f32 v10, v19, s63, v192
	v_add_f32_e32 v3, v3, v9
	v_add_f32_e32 v9, v11, v18
	v_add_f32_e32 v8, 0x4b400000, v8
	v_add_f32_e32 v10, 0x4b400000, v10
	v_add_f32_e32 v9, v28, v9
	v_perm_b32 v8, v10, v8, s64
	v_mov_b32_e32 v10, v3
	s_nop 1
	v_permlane16_swap_b32_e32 v3, v10
	v_mov_b32_e32 v11, v9
	s_nop 1
	v_permlane16_swap_b32_e32 v9, v11
	v_pk_mul_f32 v[22:23], v[12:13], s[26:27] op_sel_hi:[1,0]
	v_med3_f32 v12, v16, s63, v192
	v_med3_f32 v13, v17, s63, v192
	v_add_f32_e32 v12, 0x4b400000, v12
	v_add_f32_e32 v13, 0x4b400000, v13
	v_perm_b32 v12, v13, v12, s65
	s_waitcnt lgkmcnt(0)
	v_add_f32_e32 v3, v3, v10
	s_waitcnt lgkmcnt(0)
	v_add_f32_e32 v9, v9, v11
	v_pk_mul_f32 v[20:21], v[14:15], s[26:27] op_sel_hi:[1,0]
	v_or_b32_e32 v12, v8, v12
	v_mov_b32_e32 v8, v3
	s_nop 1
	v_permlane32_swap_b32_e32 v3, v8
	v_mov_b32_e32 v10, v9
	s_nop 1
	v_permlane32_swap_b32_e32 v9, v10
	v_med3_f32 v14, v22, s63, v192
	v_med3_f32 v15, v23, s63, v192
	v_med3_f32 v16, v20, s63, v192
	v_med3_f32 v17, v21, s63, v192
	v_add_f32_e32 v14, 0x4b400000, v14
	v_add_f32_e32 v15, 0x4b400000, v15
	v_add_f32_e32 v16, 0x4b400000, v16
	v_add_f32_e32 v17, 0x4b400000, v17
	v_perm_b32 v11, v15, v14, s64
	v_perm_b32 v13, v17, v16, s65
	v_or_b32_e32 v13, v11, v13
	global_store_dwordx2 v[24:25], v[12:13], off offset:128
	s_and_saveexec_b64 s[40:41], s[2:3]
	s_cbranch_execz .LBB0_3693
	v_lshl_add_u64 v[4:5], v[4:5], 3, s[14:15]
	s_waitcnt lgkmcnt(0)
	v_add_f32_e32 v3, v3, v8
	s_waitcnt lgkmcnt(0)
	v_add_f32_e32 v8, v9, v10
	global_atomic_add_f32 v[4:5], v3, off
	global_atomic_add_f32 v[4:5], v8, off offset:4
; __device__ __forceinline__ u32x2 pack8i8(const f32x4 a, const f32x4 b) { return (u32x2){pack4i8(a), pack4i8(b)}; }
; __device__ __forceinline__ u32x4 pack8bf(const f32x4 a, const f32x4 b) { u32x4 w; w.x = cvt_pk_bf16(a[0], a[1]); w.y = cvt_pk_bf16(a[2], a[3]); w.z = cvt_pk_bf16(b[0], b[1]); w.w = cvt_pk_bf16(b[2], b[3]); return w; }
;     __device__ __forceinline__ void operator()(EPI_ARGS) const {
;     ...
;             for (int m = 0; m < 4; ++m) { const int row = row0 + ai * HALF + m * 16; const size_t off = (size_t)row * DM + col0;
;                 float mu = 0.f, rs = 1.f; if constexpr (RESLN) ln_stats(stin, row, mu, rs);
;                 float ss = 0.f, qq = 0.f;
; #pragma unroll
;                 for (int bj = 0; bj < 2; ++bj) { f32x4 r0 = __builtin_nontemporal_load((const f32x4*)(res + off + bj * HALF)), r1 = __builtin_nontemporal_load((const f32x4*)(res + off + bj * HALF + 4));
;                     if constexpr (RESLN) { r0 = (r0 - mu) * rs * gg[bj][0] + bb[bj][0]; r1 = (r1 - mu) * rs * gg[bj][1] + bb[bj][1]; }
;                     const f32x4 y0 = r0 * DN_ALPHA + acc[ai][bj][m][0] * ascale, y1 = r1 * DN_ALPHA + acc[ai][bj][m][1] * ascale;
;                     if constexpr (COPY != 4) { __builtin_nontemporal_store(y0, (f32x4*)(Y + off + bj * HALF)); __builtin_nontemporal_store(y1, (f32x4*)(Y + off + bj * HALF + 4)); }
;                     if constexpr (STATS) { ss += ((y0[0] + y0[1]) + (y0[2] + y0[3])) + ((y1[0] + y1[1]) + (y1[2] + y1[3]));
;                         qq += ((y0[0] * y0[0] + y0[1] * y0[1]) + (y0[2] * y0[2] + y0[3] * y0[3])) + ((y1[0] * y1[0] + y1[1] * y1[1]) + (y1[2] * y1[2] + y1[3] * y1[3])); }
;                     if constexpr (COPY == 1) *(u32x2*)((unsigned char*)copy + off + bj * HALF) = pack8fp8(y0 * cscale, y1 * cscale);
;                     if constexpr (COPY == 3) *(u32x2*)((unsigned char*)copy + off + bj * HALF) = pack8i8(y0 * cscale, y1 * cscale);
;                     if constexpr (COPY == 2 || COPY == 4) *(u32x4*)((bf16_t*)copy + off + bj * HALF) = pack8bf(y0, y1); }
;                 if constexpr (STATS) { ss += __shfl_xor(ss, 16); ss += __shfl_xor(ss, 32); qq += __shfl_xor(qq, 16); qq += __shfl_xor(qq, 32);
;                     if (fq == 0) { unsafeAtomicAdd(stout + 2 * (size_t)row, ss); unsafeAtomicAdd(stout + 2 * (size_t)row + 1, qq); } }
.LBB0_3693:
	s_or_b64 exec, exec, s[40:41]
	v_or_b32_e32 v4, 32, v2
	v_ashrrev_i32_e32 v5, 31, v4
	s_waitcnt lgkmcnt(1)
	v_lshlrev_b64 v[8:9], 11, v[4:5]
	v_lshl_add_u64 v[16:17], v[8:9], 0, v[0:1]
	v_lshlrev_b64 v[18:19], 2, v[16:17]
	v_lshl_add_u64 v[20:21], s[6:7], 0, v[18:19]
	s_waitcnt lgkmcnt(0)
	global_load_dwordx4 v[8:11], v[20:21], off nt
	global_load_dwordx4 v[12:15], v[20:21], off offset:16 nt
	v_lshl_add_u64 v[24:25], s[12:13], 0, v[16:17]
	v_lshl_add_u64 v[26:27], s[10:11], 0, v[18:19]
	s_waitcnt vmcnt(1)
	v_pk_mul_f32 v[10:11], v[10:11], s[20:21] op_sel_hi:[1,0]
	v_pk_mul_f32 v[8:9], v[8:9], s[20:21] op_sel_hi:[1,0]
	s_waitcnt vmcnt(0)
	v_pk_mul_f32 v[14:15], v[14:15], s[20:21] op_sel_hi:[1,0]
	v_pk_mul_f32 v[12:13], v[12:13], s[20:21] op_sel_hi:[1,0]
	v_pk_fma_f32 v[10:11], v[126:127], s[24:25], v[10:11] op_sel_hi:[1,0,1]
	v_pk_fma_f32 v[8:9], v[124:125], s[24:25], v[8:9] op_sel_hi:[1,0,1]
	v_pk_fma_f32 v[14:15], v[122:123], s[24:25], v[14:15] op_sel_hi:[1,0,1]
	v_pk_fma_f32 v[12:13], v[120:121], s[24:25], v[12:13] op_sel_hi:[1,0,1]
	v_pk_mul_f32 v[16:17], v[10:11], s[26:27] op_sel_hi:[1,0]
	v_pk_mul_f32 v[18:19], v[8:9], s[26:27] op_sel_hi:[1,0]
	v_pk_mul_f32 v[22:23], v[14:15], s[26:27] op_sel_hi:[1,0]
	v_pk_mul_f32 v[28:29], v[12:13], s[26:27] op_sel_hi:[1,0]
	v_med3_f32 v3, v18, s63, v192
	v_med3_f32 v18, v19, s63, v192
	v_med3_f32 v16, v16, s63, v192
	v_med3_f32 v17, v17, s63, v192
	v_med3_f32 v19, v28, s63, v192
	v_med3_f32 v28, v29, s63, v192
	v_med3_f32 v22, v22, s63, v192
	v_med3_f32 v23, v23, s63, v192
	v_add_f32_e32 v3, 0x4b400000, v3
	v_add_f32_e32 v18, 0x4b400000, v18
	v_add_f32_e32 v16, 0x4b400000, v16
	v_add_f32_e32 v17, 0x4b400000, v17
	v_add_f32_e32 v19, 0x4b400000, v19
	v_add_f32_e32 v28, 0x4b400000, v28
	v_add_f32_e32 v22, 0x4b400000, v22
	v_add_f32_e32 v23, 0x4b400000, v23
	v_perm_b32 v3, v18, v3, s64
	v_perm_b32 v16, v17, v16, s65
	v_perm_b32 v17, v28, v19, s64
	v_perm_b32 v18, v23, v22, s65
	v_or_b32_e32 v16, v3, v16
	v_or_b32_e32 v17, v17, v18
	global_store_dwordx4 v[26:27], v[8:11], off nt
	global_store_dwordx4 v[26:27], v[12:15], off offset:16 nt
	global_store_dwordx2 v[24:25], v[16:17], off
	global_load_dwordx4 v[16:19], v[20:21], off offset:512 nt
	s_nop 0
	global_load_dwordx4 v[20:23], v[20:21], off offset:528 nt
	v_add_f32_e32 v3, v8, v9
	v_add_f32_e32 v28, v10, v11
	v_add_f32_e32 v29, v12, v13
	v_add_f32_e32 v30, v14, v15
	v_mul_f32_e32 v9, v9, v9
	v_mul_f32_e32 v11, v11, v11
	v_mul_f32_e32 v13, v13, v13
	v_mul_f32_e32 v15, v15, v15
	v_fmac_f32_e32 v9, v8, v8
	v_fmac_f32_e32 v11, v10, v10
	v_fmac_f32_e32 v13, v12, v12
	v_fmac_f32_e32 v15, v14, v14
	v_add_f32_e32 v3, v3, v28
	v_add_f32_e32 v28, v29, v30
	v_add_f32_e32 v8, v9, v11
	v_add_f32_e32 v9, v13, v15
	v_add_f32_e32 v3, v3, v28
	v_add_f32_e32 v28, v8, v9
	v_add_f32_e32 v3, 0, v3
	s_waitcnt vmcnt(1)
	v_pk_mul_f32 v[8:9], v[18:19], s[20:21] op_sel_hi:[1,0]
	v_pk_mul_f32 v[12:13], v[16:17], s[20:21] op_sel_hi:[1,0]
	s_waitcnt vmcnt(0)
	v_pk_mul_f32 v[14:15], v[22:23], s[20:21] op_sel_hi:[1,0]
	v_pk_mul_f32 v[16:17], v[20:21], s[20:21] op_sel_hi:[1,0]
	v_pk_fma_f32 v[10:11], v[118:119], s[24:25], v[8:9] op_sel_hi:[1,0,1]
	v_pk_fma_f32 v[8:9], v[116:117], s[24:25], v[12:13] op_sel_hi:[1,0,1]
	v_pk_fma_f32 v[14:15], v[114:115], s[24:25], v[14:15] op_sel_hi:[1,0,1]
	v_pk_fma_f32 v[12:13], v[112:113], s[24:25], v[16:17] op_sel_hi:[1,0,1]
	global_store_dwordx4 v[26:27], v[8:11], off offset:512 nt
	global_store_dwordx4 v[26:27], v[12:15], off offset:528 nt
	v_add_f32_e32 v26, v8, v9
	v_add_f32_e32 v27, v10, v11
	v_add_f32_e32 v29, v12, v13
	v_add_f32_e32 v30, v14, v15
	v_mul_f32_e32 v31, v9, v9
	v_mul_f32_e32 v112, v11, v11
	v_mul_f32_e32 v113, v13, v13
	v_mul_f32_e32 v114, v15, v15
	v_pk_mul_f32 v[16:17], v[10:11], s[26:27] op_sel_hi:[1,0]
	v_pk_mul_f32 v[18:19], v[8:9], s[26:27] op_sel_hi:[1,0]
	v_add_f32_e32 v9, v26, v27
	v_add_f32_e32 v11, v29, v30
	v_fmac_f32_e32 v31, v8, v8
	v_fmac_f32_e32 v112, v10, v10
	v_fmac_f32_e32 v113, v12, v12
	v_fmac_f32_e32 v114, v14, v14
	v_med3_f32 v8, v18, s63, v192
	v_add_f32_e32 v9, v9, v11
	v_add_f32_e32 v11, v31, v112
	v_add_f32_e32 v18, v113, v114
	v_med3_f32 v10, v19, s63, v192
	v_add_f32_e32 v3, v3, v9
	v_add_f32_e32 v9, v11, v18
	v_add_f32_e32 v8, 0x4b400000, v8
	v_add_f32_e32 v10, 0x4b400000, v10
	v_add_f32_e32 v9, v28, v9
	v_perm_b32 v8, v10, v8, s64
	v_mov_b32_e32 v10, v3
	s_nop 1
	v_permlane16_swap_b32_e32 v3, v10
	v_mov_b32_e32 v11, v9
	s_nop 1
	v_permlane16_swap_b32_e32 v9, v11
	v_pk_mul_f32 v[22:23], v[12:13], s[26:27] op_sel_hi:[1,0]
	v_med3_f32 v12, v16, s63, v192
	v_med3_f32 v13, v17, s63, v192
	v_add_f32_e32 v12, 0x4b400000, v12
	v_add_f32_e32 v13, 0x4b400000, v13
	v_perm_b32 v12, v13, v12, s65
	s_waitcnt lgkmcnt(0)
	v_add_f32_e32 v3, v3, v10
	s_waitcnt lgkmcnt(0)
	v_add_f32_e32 v9, v9, v11
	v_pk_mul_f32 v[20:21], v[14:15], s[26:27] op_sel_hi:[1,0]
	v_or_b32_e32 v12, v8, v12
	v_mov_b32_e32 v8, v3
	s_nop 1
	v_permlane32_swap_b32_e32 v3, v8
	v_mov_b32_e32 v10, v9
	s_nop 1
	v_permlane32_swap_b32_e32 v9, v10
	v_med3_f32 v14, v22, s63, v192
	v_med3_f32 v15, v23, s63, v192
	v_med3_f32 v16, v20, s63, v192
	v_med3_f32 v17, v21, s63, v192
	v_add_f32_e32 v14, 0x4b400000, v14
	v_add_f32_e32 v15, 0x4b400000, v15
	v_add_f32_e32 v16, 0x4b400000, v16
	v_add_f32_e32 v17, 0x4b400000, v17
	v_perm_b32 v11, v15, v14, s64
	v_perm_b32 v13, v17, v16, s65
	v_or_b32_e32 v13, v11, v13
	global_store_dwordx2 v[24:25], v[12:13], off offset:128
	s_and_saveexec_b64 s[40:41], s[2:3]
	s_cbranch_execz .LBB0_3695
	v_lshl_add_u64 v[4:5], v[4:5], 3, s[14:15]
	s_waitcnt lgkmcnt(0)
	v_add_f32_e32 v3, v3, v8
	s_waitcnt lgkmcnt(0)
	v_add_f32_e32 v8, v9, v10
	global_atomic_add_f32 v[4:5], v3, off
	global_atomic_add_f32 v[4:5], v8, off offset:4
; __device__ __forceinline__ u32x2 pack8i8(const f32x4 a, const f32x4 b) { return (u32x2){pack4i8(a), pack4i8(b)}; }
; __device__ __forceinline__ u32x4 pack8bf(const f32x4 a, const f32x4 b) { u32x4 w; w.x = cvt_pk_bf16(a[0], a[1]); w.y = cvt_pk_bf16(a[2], a[3]); w.z = cvt_pk_bf16(b[0], b[1]); w.w = cvt_pk_bf16(b[2], b[3]); return w; }
;     __device__ __forceinline__ void operator()(EPI_ARGS) const {
;     ...
;             for (int m = 0; m < 4; ++m) { const int row = row0 + ai * HALF + m * 16; const size_t off = (size_t)row * DM + col0;
;                 float mu = 0.f, rs = 1.f; if constexpr (RESLN) ln_stats(stin, row, mu, rs);
;                 float ss = 0.f, qq = 0.f;
; #pragma unroll
;                 for (int bj = 0; bj < 2; ++bj) { f32x4 r0 = __builtin_nontemporal_load((const f32x4*)(res + off + bj * HALF)), r1 = __builtin_nontemporal_load((const f32x4*)(res + off + bj * HALF + 4));
;                     if constexpr (RESLN) { r0 = (r0 - mu) * rs * gg[bj][0] + bb[bj][0]; r1 = (r1 - mu) * rs * gg[bj][1] + bb[bj][1]; }
;                     const f32x4 y0 = r0 * DN_ALPHA + acc[ai][bj][m][0] * ascale, y1 = r1 * DN_ALPHA + acc[ai][bj][m][1] * ascale;
;                     if constexpr (COPY != 4) { __builtin_nontemporal_store(y0, (f32x4*)(Y + off + bj * HALF)); __builtin_nontemporal_store(y1, (f32x4*)(Y + off + bj * HALF + 4)); }
;                     if constexpr (STATS) { ss += ((y0[0] + y0[1]) + (y0[2] + y0[3])) + ((y1[0] + y1[1]) + (y1[2] + y1[3]));
;                         qq += ((y0[0] * y0[0] + y0[1] * y0[1]) + (y0[2] * y0[2] + y0[3] * y0[3])) + ((y1[0] * y1[0] + y1[1] * y1[1]) + (y1[2] * y1[2] + y1[3] * y1[3])); }
;                     if constexpr (COPY == 1) *(u32x2*)((unsigned char*)copy + off + bj * HALF) = pack8fp8(y0 * cscale, y1 * cscale);
;                     if constexpr (COPY == 3) *(u32x2*)((unsigned char*)copy + off + bj * HALF) = pack8i8(y0 * cscale, y1 * cscale);
;                     if constexpr (COPY == 2 || COPY == 4) *(u32x4*)((bf16_t*)copy + off + bj * HALF) = pack8bf(y0, y1); }
;                 if constexpr (STATS) { ss += __shfl_xor(ss, 16); ss += __shfl_xor(ss, 32); qq += __shfl_xor(qq, 16); qq += __shfl_xor(qq, 32);
;                     if (fq == 0) { unsafeAtomicAdd(stout + 2 * (size_t)row, ss); unsafeAtomicAdd(stout + 2 * (size_t)row + 1, qq); } }
.LBB0_3695:
	s_or_b64 exec, exec, s[40:41]
	v_or_b32_e32 v4, 48, v2
	v_ashrrev_i32_e32 v5, 31, v4
	s_waitcnt lgkmcnt(1)
	v_lshlrev_b64 v[8:9], 11, v[4:5]
	v_lshl_add_u64 v[16:17], v[8:9], 0, v[0:1]
	v_lshlrev_b64 v[18:19], 2, v[16:17]
	v_lshl_add_u64 v[20:21], s[6:7], 0, v[18:19]
	s_waitcnt lgkmcnt(0)
	global_load_dwordx4 v[8:11], v[20:21], off nt
	global_load_dwordx4 v[12:15], v[20:21], off offset:16 nt
	v_lshl_add_u64 v[24:25], s[12:13], 0, v[16:17]
	v_lshl_add_u64 v[26:27], s[10:11], 0, v[18:19]
	s_waitcnt vmcnt(1)
	v_pk_mul_f32 v[10:11], v[10:11], s[20:21] op_sel_hi:[1,0]
	v_pk_mul_f32 v[8:9], v[8:9], s[20:21] op_sel_hi:[1,0]
	s_waitcnt vmcnt(0)
	v_pk_mul_f32 v[14:15], v[14:15], s[20:21] op_sel_hi:[1,0]
	v_pk_mul_f32 v[12:13], v[12:13], s[20:21] op_sel_hi:[1,0]
	v_pk_fma_f32 v[10:11], v[110:111], s[24:25], v[10:11] op_sel_hi:[1,0,1]
	v_pk_fma_f32 v[8:9], v[108:109], s[24:25], v[8:9] op_sel_hi:[1,0,1]
	v_pk_fma_f32 v[14:15], v[106:107], s[24:25], v[14:15] op_sel_hi:[1,0,1]
	v_pk_fma_f32 v[12:13], v[104:105], s[24:25], v[12:13] op_sel_hi:[1,0,1]
	v_pk_mul_f32 v[16:17], v[10:11], s[26:27] op_sel_hi:[1,0]
	v_pk_mul_f32 v[18:19], v[8:9], s[26:27] op_sel_hi:[1,0]
	v_pk_mul_f32 v[22:23], v[14:15], s[26:27] op_sel_hi:[1,0]
	v_pk_mul_f32 v[28:29], v[12:13], s[26:27] op_sel_hi:[1,0]
	v_med3_f32 v3, v18, s63, v192
	v_med3_f32 v18, v19, s63, v192
	v_med3_f32 v16, v16, s63, v192
	v_med3_f32 v17, v17, s63, v192
	v_med3_f32 v19, v28, s63, v192
	v_med3_f32 v28, v29, s63, v192
	v_med3_f32 v22, v22, s63, v192
	v_med3_f32 v23, v23, s63, v192
	v_add_f32_e32 v3, 0x4b400000, v3
	v_add_f32_e32 v18, 0x4b400000, v18
	v_add_f32_e32 v16, 0x4b400000, v16
	v_add_f32_e32 v17, 0x4b400000, v17
	v_add_f32_e32 v19, 0x4b400000, v19
	v_add_f32_e32 v28, 0x4b400000, v28
	v_add_f32_e32 v22, 0x4b400000, v22
	v_add_f32_e32 v23, 0x4b400000, v23
	v_perm_b32 v3, v18, v3, s64
	v_perm_b32 v16, v17, v16, s65
	v_perm_b32 v17, v28, v19, s64
	v_perm_b32 v18, v23, v22, s65
	v_or_b32_e32 v16, v3, v16
	v_or_b32_e32 v17, v17, v18
	global_store_dwordx4 v[26:27], v[8:11], off nt
	global_store_dwordx4 v[26:27], v[12:15], off offset:16 nt
	global_store_dwordx2 v[24:25], v[16:17], off
	global_load_dwordx4 v[16:19], v[20:21], off offset:512 nt
	s_nop 0
	global_load_dwordx4 v[20:23], v[20:21], off offset:528 nt
	v_add_f32_e32 v3, v8, v9
	v_add_f32_e32 v28, v10, v11
	v_add_f32_e32 v29, v12, v13
	v_add_f32_e32 v30, v14, v15
	v_mul_f32_e32 v9, v9, v9
	v_mul_f32_e32 v11, v11, v11
	v_mul_f32_e32 v13, v13, v13
	v_mul_f32_e32 v15, v15, v15
	v_fmac_f32_e32 v9, v8, v8
	v_fmac_f32_e32 v11, v10, v10
	v_fmac_f32_e32 v13, v12, v12
	v_fmac_f32_e32 v15, v14, v14
	v_add_f32_e32 v3, v3, v28
	v_add_f32_e32 v28, v29, v30
	v_add_f32_e32 v8, v9, v11
	v_add_f32_e32 v9, v13, v15
	v_add_f32_e32 v3, v3, v28
	v_add_f32_e32 v28, v8, v9
	v_add_f32_e32 v3, 0, v3
	s_waitcnt vmcnt(1)
	v_pk_mul_f32 v[8:9], v[18:19], s[20:21] op_sel_hi:[1,0]
	v_pk_mul_f32 v[12:13], v[16:17], s[20:21] op_sel_hi:[1,0]
	s_waitcnt vmcnt(0)
	v_pk_mul_f32 v[14:15], v[22:23], s[20:21] op_sel_hi:[1,0]
	v_pk_mul_f32 v[16:17], v[20:21], s[20:21] op_sel_hi:[1,0]
	v_pk_fma_f32 v[10:11], v[102:103], s[24:25], v[8:9] op_sel_hi:[1,0,1]
	v_pk_fma_f32 v[8:9], v[100:101], s[24:25], v[12:13] op_sel_hi:[1,0,1]
	v_pk_fma_f32 v[14:15], v[98:99], s[24:25], v[14:15] op_sel_hi:[1,0,1]
	v_pk_fma_f32 v[12:13], v[96:97], s[24:25], v[16:17] op_sel_hi:[1,0,1]
	global_store_dwordx4 v[26:27], v[8:11], off offset:512 nt
	global_store_dwordx4 v[26:27], v[12:15], off offset:528 nt
	v_add_f32_e32 v26, v8, v9
	v_add_f32_e32 v27, v10, v11
	v_add_f32_e32 v29, v12, v13
	v_add_f32_e32 v30, v14, v15
	v_mul_f32_e32 v31, v9, v9
	v_mul_f32_e32 v96, v11, v11
	v_mul_f32_e32 v97, v13, v13
	v_mul_f32_e32 v98, v15, v15
	v_pk_mul_f32 v[16:17], v[10:11], s[26:27] op_sel_hi:[1,0]
	v_pk_mul_f32 v[18:19], v[8:9], s[26:27] op_sel_hi:[1,0]
	v_add_f32_e32 v9, v26, v27
	v_add_f32_e32 v11, v29, v30
	v_fmac_f32_e32 v31, v8, v8
	v_fmac_f32_e32 v96, v10, v10
	v_fmac_f32_e32 v97, v12, v12
	v_fmac_f32_e32 v98, v14, v14
	v_med3_f32 v8, v18, s63, v192
	v_add_f32_e32 v9, v9, v11
	v_add_f32_e32 v11, v31, v96
	v_add_f32_e32 v18, v97, v98
	v_med3_f32 v10, v19, s63, v192
	v_add_f32_e32 v3, v3, v9
	v_add_f32_e32 v9, v11, v18
	v_add_f32_e32 v8, 0x4b400000, v8
	v_add_f32_e32 v10, 0x4b400000, v10
	v_add_f32_e32 v9, v28, v9
	v_perm_b32 v8, v10, v8, s64
	v_mov_b32_e32 v10, v3
	s_nop 1
	v_permlane16_swap_b32_e32 v3, v10
	v_mov_b32_e32 v11, v9
	s_nop 1
	v_permlane16_swap_b32_e32 v9, v11
	v_pk_mul_f32 v[22:23], v[12:13], s[26:27] op_sel_hi:[1,0]
	v_med3_f32 v12, v16, s63, v192
	v_med3_f32 v13, v17, s63, v192
	v_add_f32_e32 v12, 0x4b400000, v12
	v_add_f32_e32 v13, 0x4b400000, v13
	v_perm_b32 v12, v13, v12, s65
	s_waitcnt lgkmcnt(0)
	v_add_f32_e32 v3, v3, v10
	s_waitcnt lgkmcnt(0)
	v_add_f32_e32 v9, v9, v11
	v_pk_mul_f32 v[20:21], v[14:15], s[26:27] op_sel_hi:[1,0]
	v_or_b32_e32 v12, v8, v12
	v_mov_b32_e32 v8, v3
	s_nop 1
	v_permlane32_swap_b32_e32 v3, v8
	v_mov_b32_e32 v10, v9
	s_nop 1
	v_permlane32_swap_b32_e32 v9, v10
	v_med3_f32 v14, v22, s63, v192
	v_med3_f32 v15, v23, s63, v192
	v_med3_f32 v16, v20, s63, v192
	v_med3_f32 v17, v21, s63, v192
	v_add_f32_e32 v14, 0x4b400000, v14
	v_add_f32_e32 v15, 0x4b400000, v15
	v_add_f32_e32 v16, 0x4b400000, v16
	v_add_f32_e32 v17, 0x4b400000, v17
	v_perm_b32 v11, v15, v14, s64
	v_perm_b32 v13, v17, v16, s65
	v_or_b32_e32 v13, v11, v13
	global_store_dwordx2 v[24:25], v[12:13], off offset:128
	s_and_saveexec_b64 s[40:41], s[2:3]
	s_cbranch_execz .LBB0_3697
	v_lshl_add_u64 v[4:5], v[4:5], 3, s[14:15]
	s_waitcnt lgkmcnt(0)
	v_add_f32_e32 v3, v3, v8
	s_waitcnt lgkmcnt(0)
	v_add_f32_e32 v8, v9, v10
	global_atomic_add_f32 v[4:5], v3, off
	global_atomic_add_f32 v[4:5], v8, off offset:4
; __device__ __forceinline__ u32x2 pack8i8(const f32x4 a, const f32x4 b) { return (u32x2){pack4i8(a), pack4i8(b)}; }
; __device__ __forceinline__ u32x4 pack8bf(const f32x4 a, const f32x4 b) { u32x4 w; w.x = cvt_pk_bf16(a[0], a[1]); w.y = cvt_pk_bf16(a[2], a[3]); w.z = cvt_pk_bf16(b[0], b[1]); w.w = cvt_pk_bf16(b[2], b[3]); return w; }
;     __device__ __forceinline__ void operator()(EPI_ARGS) const {
;     ...
;             for (int m = 0; m < 4; ++m) { const int row = row0 + ai * HALF + m * 16; const size_t off = (size_t)row * DM + col0;
;                 float mu = 0.f, rs = 1.f; if constexpr (RESLN) ln_stats(stin, row, mu, rs);
;                 float ss = 0.f, qq = 0.f;
; #pragma unroll
;                 for (int bj = 0; bj < 2; ++bj) { f32x4 r0 = __builtin_nontemporal_load((const f32x4*)(res + off + bj * HALF)), r1 = __builtin_nontemporal_load((const f32x4*)(res + off + bj * HALF + 4));
;                     if constexpr (RESLN) { r0 = (r0 - mu) * rs * gg[bj][0] + bb[bj][0]; r1 = (r1 - mu) * rs * gg[bj][1] + bb[bj][1]; }
;                     const f32x4 y0 = r0 * DN_ALPHA + acc[ai][bj][m][0] * ascale, y1 = r1 * DN_ALPHA + acc[ai][bj][m][1] * ascale;
;                     if constexpr (COPY != 4) { __builtin_nontemporal_store(y0, (f32x4*)(Y + off + bj * HALF)); __builtin_nontemporal_store(y1, (f32x4*)(Y + off + bj * HALF + 4)); }
;                     if constexpr (STATS) { ss += ((y0[0] + y0[1]) + (y0[2] + y0[3])) + ((y1[0] + y1[1]) + (y1[2] + y1[3]));
;                         qq += ((y0[0] * y0[0] + y0[1] * y0[1]) + (y0[2] * y0[2] + y0[3] * y0[3])) + ((y1[0] * y1[0] + y1[1] * y1[1]) + (y1[2] * y1[2] + y1[3] * y1[3])); }
;                     if constexpr (COPY == 1) *(u32x2*)((unsigned char*)copy + off + bj * HALF) = pack8fp8(y0 * cscale, y1 * cscale);
;                     if constexpr (COPY == 3) *(u32x2*)((unsigned char*)copy + off + bj * HALF) = pack8i8(y0 * cscale, y1 * cscale);
;                     if constexpr (COPY == 2 || COPY == 4) *(u32x4*)((bf16_t*)copy + off + bj * HALF) = pack8bf(y0, y1); }
;                 if constexpr (STATS) { ss += __shfl_xor(ss, 16); ss += __shfl_xor(ss, 32); qq += __shfl_xor(qq, 16); qq += __shfl_xor(qq, 32);
;                     if (fq == 0) { unsafeAtomicAdd(stout + 2 * (size_t)row, ss); unsafeAtomicAdd(stout + 2 * (size_t)row + 1, qq); } }
.LBB0_3697:
	s_or_b64 exec, exec, s[40:41]
	v_add_u32_e32 v4, 0x80, v2
	v_ashrrev_i32_e32 v5, 31, v4
	s_waitcnt lgkmcnt(1)
	v_lshlrev_b64 v[8:9], 11, v[4:5]
	v_lshl_add_u64 v[16:17], v[8:9], 0, v[0:1]
	v_lshlrev_b64 v[18:19], 2, v[16:17]
	v_lshl_add_u64 v[20:21], s[6:7], 0, v[18:19]
	s_waitcnt lgkmcnt(0)
	global_load_dwordx4 v[8:11], v[20:21], off nt
	global_load_dwordx4 v[12:15], v[20:21], off offset:16 nt
	v_lshl_add_u64 v[24:25], s[12:13], 0, v[16:17]
	v_lshl_add_u64 v[26:27], s[10:11], 0, v[18:19]
	s_waitcnt vmcnt(1)
	v_pk_mul_f32 v[10:11], v[10:11], s[20:21] op_sel_hi:[1,0]
	v_pk_mul_f32 v[8:9], v[8:9], s[20:21] op_sel_hi:[1,0]
	s_waitcnt vmcnt(0)
	v_pk_mul_f32 v[14:15], v[14:15], s[20:21] op_sel_hi:[1,0]
	v_pk_mul_f32 v[12:13], v[12:13], s[20:21] op_sel_hi:[1,0]
	v_pk_fma_f32 v[10:11], v[94:95], s[24:25], v[10:11] op_sel_hi:[1,0,1]
	v_pk_fma_f32 v[8:9], v[92:93], s[24:25], v[8:9] op_sel_hi:[1,0,1]
	v_pk_fma_f32 v[14:15], v[90:91], s[24:25], v[14:15] op_sel_hi:[1,0,1]
	v_pk_fma_f32 v[12:13], v[88:89], s[24:25], v[12:13] op_sel_hi:[1,0,1]
	v_pk_mul_f32 v[16:17], v[10:11], s[26:27] op_sel_hi:[1,0]
	v_pk_mul_f32 v[18:19], v[8:9], s[26:27] op_sel_hi:[1,0]
	v_pk_mul_f32 v[22:23], v[14:15], s[26:27] op_sel_hi:[1,0]
	v_pk_mul_f32 v[28:29], v[12:13], s[26:27] op_sel_hi:[1,0]
	v_med3_f32 v3, v18, s63, v192
	v_med3_f32 v18, v19, s63, v192
	v_med3_f32 v16, v16, s63, v192
	v_med3_f32 v17, v17, s63, v192
	v_med3_f32 v19, v28, s63, v192
	v_med3_f32 v28, v29, s63, v192
	v_med3_f32 v22, v22, s63, v192
	v_med3_f32 v23, v23, s63, v192
	v_add_f32_e32 v3, 0x4b400000, v3
	v_add_f32_e32 v18, 0x4b400000, v18
	v_add_f32_e32 v16, 0x4b400000, v16
	v_add_f32_e32 v17, 0x4b400000, v17
	v_add_f32_e32 v19, 0x4b400000, v19
	v_add_f32_e32 v28, 0x4b400000, v28
	v_add_f32_e32 v22, 0x4b400000, v22
	v_add_f32_e32 v23, 0x4b400000, v23
	v_perm_b32 v3, v18, v3, s64
	v_perm_b32 v16, v17, v16, s65
	v_perm_b32 v17, v28, v19, s64
	v_perm_b32 v18, v23, v22, s65
	v_or_b32_e32 v16, v3, v16
	v_or_b32_e32 v17, v17, v18
	global_store_dwordx4 v[26:27], v[8:11], off nt
	global_store_dwordx4 v[26:27], v[12:15], off offset:16 nt
	global_store_dwordx2 v[24:25], v[16:17], off
	global_load_dwordx4 v[16:19], v[20:21], off offset:512 nt
	s_nop 0
	global_load_dwordx4 v[20:23], v[20:21], off offset:528 nt
	v_add_f32_e32 v3, v8, v9
	v_add_f32_e32 v28, v10, v11
	v_add_f32_e32 v29, v12, v13
	v_add_f32_e32 v30, v14, v15
	v_mul_f32_e32 v9, v9, v9
	v_mul_f32_e32 v11, v11, v11
	v_mul_f32_e32 v13, v13, v13
	v_mul_f32_e32 v15, v15, v15
	v_fmac_f32_e32 v9, v8, v8
	v_fmac_f32_e32 v11, v10, v10
	v_fmac_f32_e32 v13, v12, v12
	v_fmac_f32_e32 v15, v14, v14
	v_add_f32_e32 v3, v3, v28
	v_add_f32_e32 v28, v29, v30
	v_add_f32_e32 v8, v9, v11
	v_add_f32_e32 v9, v13, v15
	v_add_f32_e32 v3, v3, v28
	v_add_f32_e32 v28, v8, v9
	v_add_f32_e32 v3, 0, v3
	s_waitcnt vmcnt(1)
	v_pk_mul_f32 v[8:9], v[18:19], s[20:21] op_sel_hi:[1,0]
	v_pk_mul_f32 v[12:13], v[16:17], s[20:21] op_sel_hi:[1,0]
	s_waitcnt vmcnt(0)
	v_pk_mul_f32 v[14:15], v[22:23], s[20:21] op_sel_hi:[1,0]
	v_pk_mul_f32 v[16:17], v[20:21], s[20:21] op_sel_hi:[1,0]
	v_pk_fma_f32 v[10:11], v[86:87], s[24:25], v[8:9] op_sel_hi:[1,0,1]
	v_pk_fma_f32 v[8:9], v[84:85], s[24:25], v[12:13] op_sel_hi:[1,0,1]
	v_pk_fma_f32 v[14:15], v[82:83], s[24:25], v[14:15] op_sel_hi:[1,0,1]
	v_pk_fma_f32 v[12:13], v[80:81], s[24:25], v[16:17] op_sel_hi:[1,0,1]
	global_store_dwordx4 v[26:27], v[8:11], off offset:512 nt
	global_store_dwordx4 v[26:27], v[12:15], off offset:528 nt
	v_add_f32_e32 v26, v8, v9
	v_add_f32_e32 v27, v10, v11
	v_add_f32_e32 v29, v12, v13
	v_add_f32_e32 v30, v14, v15
	v_mul_f32_e32 v31, v9, v9
	v_mul_f32_e32 v80, v11, v11
	v_mul_f32_e32 v81, v13, v13
	v_mul_f32_e32 v82, v15, v15
	v_pk_mul_f32 v[16:17], v[10:11], s[26:27] op_sel_hi:[1,0]
	v_pk_mul_f32 v[18:19], v[8:9], s[26:27] op_sel_hi:[1,0]
	v_add_f32_e32 v9, v26, v27
	v_add_f32_e32 v11, v29, v30
	v_fmac_f32_e32 v31, v8, v8
	v_fmac_f32_e32 v80, v10, v10
	v_fmac_f32_e32 v81, v12, v12
	v_fmac_f32_e32 v82, v14, v14
	v_med3_f32 v8, v18, s63, v192
	v_add_f32_e32 v9, v9, v11
	v_add_f32_e32 v11, v31, v80
	v_add_f32_e32 v18, v81, v82
	v_med3_f32 v10, v19, s63, v192
	v_add_f32_e32 v3, v3, v9
	v_add_f32_e32 v9, v11, v18
	v_add_f32_e32 v8, 0x4b400000, v8
	v_add_f32_e32 v10, 0x4b400000, v10
	v_add_f32_e32 v9, v28, v9
	v_perm_b32 v8, v10, v8, s64
	v_mov_b32_e32 v10, v3
	s_nop 1
	v_permlane16_swap_b32_e32 v3, v10
	v_mov_b32_e32 v11, v9
	s_nop 1
	v_permlane16_swap_b32_e32 v9, v11
	v_pk_mul_f32 v[22:23], v[12:13], s[26:27] op_sel_hi:[1,0]
	v_med3_f32 v12, v16, s63, v192
	v_med3_f32 v13, v17, s63, v192
	v_add_f32_e32 v12, 0x4b400000, v12
	v_add_f32_e32 v13, 0x4b400000, v13
	v_perm_b32 v12, v13, v12, s65
	s_waitcnt lgkmcnt(0)
	v_add_f32_e32 v3, v3, v10
	s_waitcnt lgkmcnt(0)
	v_add_f32_e32 v9, v9, v11
	v_pk_mul_f32 v[20:21], v[14:15], s[26:27] op_sel_hi:[1,0]
	v_or_b32_e32 v12, v8, v12
	v_mov_b32_e32 v8, v3
	s_nop 1
	v_permlane32_swap_b32_e32 v3, v8
	v_mov_b32_e32 v10, v9
	s_nop 1
	v_permlane32_swap_b32_e32 v9, v10
	v_med3_f32 v14, v22, s63, v192
	v_med3_f32 v15, v23, s63, v192
	v_med3_f32 v16, v20, s63, v192
	v_med3_f32 v17, v21, s63, v192
	v_add_f32_e32 v14, 0x4b400000, v14
	v_add_f32_e32 v15, 0x4b400000, v15
	v_add_f32_e32 v16, 0x4b400000, v16
	v_add_f32_e32 v17, 0x4b400000, v17
	v_perm_b32 v11, v15, v14, s64
	v_perm_b32 v13, v17, v16, s65
	v_or_b32_e32 v13, v11, v13
	global_store_dwordx2 v[24:25], v[12:13], off offset:128
	s_and_saveexec_b64 s[40:41], s[2:3]
	s_cbranch_execz .LBB0_3699
	v_lshl_add_u64 v[4:5], v[4:5], 3, s[14:15]
	s_waitcnt lgkmcnt(0)
	v_add_f32_e32 v3, v3, v8
	s_waitcnt lgkmcnt(0)
	v_add_f32_e32 v8, v9, v10
	global_atomic_add_f32 v[4:5], v3, off
	global_atomic_add_f32 v[4:5], v8, off offset:4
; __device__ __forceinline__ u32x2 pack8i8(const f32x4 a, const f32x4 b) { return (u32x2){pack4i8(a), pack4i8(b)}; }
; __device__ __forceinline__ u32x4 pack8bf(const f32x4 a, const f32x4 b) { u32x4 w; w.x = cvt_pk_bf16(a[0], a[1]); w.y = cvt_pk_bf16(a[2], a[3]); w.z = cvt_pk_bf16(b[0], b[1]); w.w = cvt_pk_bf16(b[2], b[3]); return w; }
;     __device__ __forceinline__ void operator()(EPI_ARGS) const {
;     ...
;             for (int m = 0; m < 4; ++m) { const int row = row0 + ai * HALF + m * 16; const size_t off = (size_t)row * DM + col0;
;                 float mu = 0.f, rs = 1.f; if constexpr (RESLN) ln_stats(stin, row, mu, rs);
;                 float ss = 0.f, qq = 0.f;
; #pragma unroll
;                 for (int bj = 0; bj < 2; ++bj) { f32x4 r0 = __builtin_nontemporal_load((const f32x4*)(res + off + bj * HALF)), r1 = __builtin_nontemporal_load((const f32x4*)(res + off + bj * HALF + 4));
;                     if constexpr (RESLN) { r0 = (r0 - mu) * rs * gg[bj][0] + bb[bj][0]; r1 = (r1 - mu) * rs * gg[bj][1] + bb[bj][1]; }
;                     const f32x4 y0 = r0 * DN_ALPHA + acc[ai][bj][m][0] * ascale, y1 = r1 * DN_ALPHA + acc[ai][bj][m][1] * ascale;
;                     if constexpr (COPY != 4) { __builtin_nontemporal_store(y0, (f32x4*)(Y + off + bj * HALF)); __builtin_nontemporal_store(y1, (f32x4*)(Y + off + bj * HALF + 4)); }
;                     if constexpr (STATS) { ss += ((y0[0] + y0[1]) + (y0[2] + y0[3])) + ((y1[0] + y1[1]) + (y1[2] + y1[3]));
;                         qq += ((y0[0] * y0[0] + y0[1] * y0[1]) + (y0[2] * y0[2] + y0[3] * y0[3])) + ((y1[0] * y1[0] + y1[1] * y1[1]) + (y1[2] * y1[2] + y1[3] * y1[3])); }
;                     if constexpr (COPY == 1) *(u32x2*)((unsigned char*)copy + off + bj * HALF) = pack8fp8(y0 * cscale, y1 * cscale);
;                     if constexpr (COPY == 3) *(u32x2*)((unsigned char*)copy + off + bj * HALF) = pack8i8(y0 * cscale, y1 * cscale);
;                     if constexpr (COPY == 2 || COPY == 4) *(u32x4*)((bf16_t*)copy + off + bj * HALF) = pack8bf(y0, y1); }
;                 if constexpr (STATS) { ss += __shfl_xor(ss, 16); ss += __shfl_xor(ss, 32); qq += __shfl_xor(qq, 16); qq += __shfl_xor(qq, 32);
;                     if (fq == 0) { unsafeAtomicAdd(stout + 2 * (size_t)row, ss); unsafeAtomicAdd(stout + 2 * (size_t)row + 1, qq); } }
.LBB0_3699:
	s_or_b64 exec, exec, s[40:41]
	v_add_u32_e32 v4, 0x90, v2
	v_ashrrev_i32_e32 v5, 31, v4
	s_waitcnt lgkmcnt(1)
	v_lshlrev_b64 v[8:9], 11, v[4:5]
	v_lshl_add_u64 v[16:17], v[8:9], 0, v[0:1]
	v_lshlrev_b64 v[18:19], 2, v[16:17]
	v_lshl_add_u64 v[20:21], s[6:7], 0, v[18:19]
	s_waitcnt lgkmcnt(0)
	global_load_dwordx4 v[8:11], v[20:21], off nt
	global_load_dwordx4 v[12:15], v[20:21], off offset:16 nt
	v_lshl_add_u64 v[24:25], s[12:13], 0, v[16:17]
	v_lshl_add_u64 v[26:27], s[10:11], 0, v[18:19]
	s_waitcnt vmcnt(1)
	v_pk_mul_f32 v[10:11], v[10:11], s[20:21] op_sel_hi:[1,0]
	v_pk_mul_f32 v[8:9], v[8:9], s[20:21] op_sel_hi:[1,0]
	s_waitcnt vmcnt(0)
	v_pk_mul_f32 v[14:15], v[14:15], s[20:21] op_sel_hi:[1,0]
	v_pk_mul_f32 v[12:13], v[12:13], s[20:21] op_sel_hi:[1,0]
	v_pk_fma_f32 v[10:11], v[78:79], s[24:25], v[10:11] op_sel_hi:[1,0,1]
	v_pk_fma_f32 v[8:9], v[76:77], s[24:25], v[8:9] op_sel_hi:[1,0,1]
	v_pk_fma_f32 v[14:15], v[74:75], s[24:25], v[14:15] op_sel_hi:[1,0,1]
	v_pk_fma_f32 v[12:13], v[72:73], s[24:25], v[12:13] op_sel_hi:[1,0,1]
	v_pk_mul_f32 v[16:17], v[10:11], s[26:27] op_sel_hi:[1,0]
	v_pk_mul_f32 v[18:19], v[8:9], s[26:27] op_sel_hi:[1,0]
	v_pk_mul_f32 v[22:23], v[14:15], s[26:27] op_sel_hi:[1,0]
	v_pk_mul_f32 v[28:29], v[12:13], s[26:27] op_sel_hi:[1,0]
	v_med3_f32 v3, v18, s63, v192
	v_med3_f32 v18, v19, s63, v192
	v_med3_f32 v16, v16, s63, v192
	v_med3_f32 v17, v17, s63, v192
	v_med3_f32 v19, v28, s63, v192
	v_med3_f32 v28, v29, s63, v192
	v_med3_f32 v22, v22, s63, v192
	v_med3_f32 v23, v23, s63, v192
	v_add_f32_e32 v3, 0x4b400000, v3
	v_add_f32_e32 v18, 0x4b400000, v18
	v_add_f32_e32 v16, 0x4b400000, v16
	v_add_f32_e32 v17, 0x4b400000, v17
	v_add_f32_e32 v19, 0x4b400000, v19
	v_add_f32_e32 v28, 0x4b400000, v28
	v_add_f32_e32 v22, 0x4b400000, v22
	v_add_f32_e32 v23, 0x4b400000, v23
	v_perm_b32 v3, v18, v3, s64
	v_perm_b32 v16, v17, v16, s65
	v_perm_b32 v17, v28, v19, s64
	v_perm_b32 v18, v23, v22, s65
	v_or_b32_e32 v16, v3, v16
	v_or_b32_e32 v17, v17, v18
	global_store_dwordx4 v[26:27], v[8:11], off nt
	global_store_dwordx4 v[26:27], v[12:15], off offset:16 nt
	global_store_dwordx2 v[24:25], v[16:17], off
	global_load_dwordx4 v[16:19], v[20:21], off offset:512 nt
	s_nop 0
	global_load_dwordx4 v[20:23], v[20:21], off offset:528 nt
	v_add_f32_e32 v3, v8, v9
	v_add_f32_e32 v28, v10, v11
	v_add_f32_e32 v29, v12, v13
	v_add_f32_e32 v30, v14, v15
	v_mul_f32_e32 v9, v9, v9
	v_mul_f32_e32 v11, v11, v11
	v_mul_f32_e32 v13, v13, v13
	v_mul_f32_e32 v15, v15, v15
	v_fmac_f32_e32 v9, v8, v8
	v_fmac_f32_e32 v11, v10, v10
	v_fmac_f32_e32 v13, v12, v12
	v_fmac_f32_e32 v15, v14, v14
	v_add_f32_e32 v3, v3, v28
	v_add_f32_e32 v28, v29, v30
	v_add_f32_e32 v8, v9, v11
	v_add_f32_e32 v9, v13, v15
	v_add_f32_e32 v3, v3, v28
	v_add_f32_e32 v28, v8, v9
	v_add_f32_e32 v3, 0, v3
	s_waitcnt vmcnt(1)
	v_pk_mul_f32 v[8:9], v[18:19], s[20:21] op_sel_hi:[1,0]
	v_pk_mul_f32 v[12:13], v[16:17], s[20:21] op_sel_hi:[1,0]
	s_waitcnt vmcnt(0)
	v_pk_mul_f32 v[14:15], v[22:23], s[20:21] op_sel_hi:[1,0]
	v_pk_mul_f32 v[16:17], v[20:21], s[20:21] op_sel_hi:[1,0]
	v_pk_fma_f32 v[10:11], v[70:71], s[24:25], v[8:9] op_sel_hi:[1,0,1]
	v_pk_fma_f32 v[8:9], v[68:69], s[24:25], v[12:13] op_sel_hi:[1,0,1]
	v_pk_fma_f32 v[14:15], v[66:67], s[24:25], v[14:15] op_sel_hi:[1,0,1]
	v_pk_fma_f32 v[12:13], v[64:65], s[24:25], v[16:17] op_sel_hi:[1,0,1]
	global_store_dwordx4 v[26:27], v[8:11], off offset:512 nt
	global_store_dwordx4 v[26:27], v[12:15], off offset:528 nt
	v_add_f32_e32 v26, v8, v9
	v_add_f32_e32 v27, v10, v11
	v_add_f32_e32 v29, v12, v13
	v_add_f32_e32 v30, v14, v15
	v_mul_f32_e32 v31, v9, v9
	v_mul_f32_e32 v64, v11, v11
	v_mul_f32_e32 v65, v13, v13
	v_mul_f32_e32 v66, v15, v15
	v_pk_mul_f32 v[16:17], v[10:11], s[26:27] op_sel_hi:[1,0]
	v_pk_mul_f32 v[18:19], v[8:9], s[26:27] op_sel_hi:[1,0]
	v_add_f32_e32 v9, v26, v27
	v_add_f32_e32 v11, v29, v30
	v_fmac_f32_e32 v31, v8, v8
	v_fmac_f32_e32 v64, v10, v10
	v_fmac_f32_e32 v65, v12, v12
	v_fmac_f32_e32 v66, v14, v14
	v_med3_f32 v8, v18, s63, v192
	v_add_f32_e32 v9, v9, v11
	v_add_f32_e32 v11, v31, v64
	v_add_f32_e32 v18, v65, v66
	v_med3_f32 v10, v19, s63, v192
	v_add_f32_e32 v3, v3, v9
	v_add_f32_e32 v9, v11, v18
	v_add_f32_e32 v8, 0x4b400000, v8
	v_add_f32_e32 v10, 0x4b400000, v10
	v_add_f32_e32 v9, v28, v9
	v_perm_b32 v8, v10, v8, s64
	v_mov_b32_e32 v10, v3
	s_nop 1
	v_permlane16_swap_b32_e32 v3, v10
	v_mov_b32_e32 v11, v9
	s_nop 1
	v_permlane16_swap_b32_e32 v9, v11
	v_pk_mul_f32 v[22:23], v[12:13], s[26:27] op_sel_hi:[1,0]
	v_med3_f32 v12, v16, s63, v192
	v_med3_f32 v13, v17, s63, v192
	v_add_f32_e32 v12, 0x4b400000, v12
	v_add_f32_e32 v13, 0x4b400000, v13
	v_perm_b32 v12, v13, v12, s65
	s_waitcnt lgkmcnt(0)
	v_add_f32_e32 v3, v3, v10
	s_waitcnt lgkmcnt(0)
	v_add_f32_e32 v9, v9, v11
	v_pk_mul_f32 v[20:21], v[14:15], s[26:27] op_sel_hi:[1,0]
	v_or_b32_e32 v12, v8, v12
	v_mov_b32_e32 v8, v3
	s_nop 1
	v_permlane32_swap_b32_e32 v3, v8
	v_mov_b32_e32 v10, v9
	s_nop 1
	v_permlane32_swap_b32_e32 v9, v10
	v_med3_f32 v14, v22, s63, v192
	v_med3_f32 v15, v23, s63, v192
	v_med3_f32 v16, v20, s63, v192
	v_med3_f32 v17, v21, s63, v192
	v_add_f32_e32 v14, 0x4b400000, v14
	v_add_f32_e32 v15, 0x4b400000, v15
	v_add_f32_e32 v16, 0x4b400000, v16
	v_add_f32_e32 v17, 0x4b400000, v17
	v_perm_b32 v11, v15, v14, s64
	v_perm_b32 v13, v17, v16, s65
	v_or_b32_e32 v13, v11, v13
	global_store_dwordx2 v[24:25], v[12:13], off offset:128
	s_and_saveexec_b64 s[40:41], s[2:3]
	s_cbranch_execz .LBB0_3701
	v_lshl_add_u64 v[4:5], v[4:5], 3, s[14:15]
	s_waitcnt lgkmcnt(0)
	v_add_f32_e32 v3, v3, v8
	s_waitcnt lgkmcnt(0)
	v_add_f32_e32 v8, v9, v10
	global_atomic_add_f32 v[4:5], v3, off
	global_atomic_add_f32 v[4:5], v8, off offset:4
; __device__ __forceinline__ u32x2 pack8i8(const f32x4 a, const f32x4 b) { return (u32x2){pack4i8(a), pack4i8(b)}; }
; __device__ __forceinline__ u32x4 pack8bf(const f32x4 a, const f32x4 b) { u32x4 w; w.x = cvt_pk_bf16(a[0], a[1]); w.y = cvt_pk_bf16(a[2], a[3]); w.z = cvt_pk_bf16(b[0], b[1]); w.w = cvt_pk_bf16(b[2], b[3]); return w; }
;     __device__ __forceinline__ void operator()(EPI_ARGS) const {
;     ...
;             for (int m = 0; m < 4; ++m) { const int row = row0 + ai * HALF + m * 16; const size_t off = (size_t)row * DM + col0;
;                 float mu = 0.f, rs = 1.f; if constexpr (RESLN) ln_stats(stin, row, mu, rs);
;                 float ss = 0.f, qq = 0.f;
; #pragma unroll
;                 for (int bj = 0; bj < 2; ++bj) { f32x4 r0 = __builtin_nontemporal_load((const f32x4*)(res + off + bj * HALF)), r1 = __builtin_nontemporal_load((const f32x4*)(res + off + bj * HALF + 4));
;                     if constexpr (RESLN) { r0 = (r0 - mu) * rs * gg[bj][0] + bb[bj][0]; r1 = (r1 - mu) * rs * gg[bj][1] + bb[bj][1]; }
;                     const f32x4 y0 = r0 * DN_ALPHA + acc[ai][bj][m][0] * ascale, y1 = r1 * DN_ALPHA + acc[ai][bj][m][1] * ascale;
;                     if constexpr (COPY != 4) { __builtin_nontemporal_store(y0, (f32x4*)(Y + off + bj * HALF)); __builtin_nontemporal_store(y1, (f32x4*)(Y + off + bj * HALF + 4)); }
;                     if constexpr (STATS) { ss += ((y0[0] + y0[1]) + (y0[2] + y0[3])) + ((y1[0] + y1[1]) + (y1[2] + y1[3]));
;                         qq += ((y0[0] * y0[0] + y0[1] * y0[1]) + (y0[2] * y0[2] + y0[3] * y0[3])) + ((y1[0] * y1[0] + y1[1] * y1[1]) + (y1[2] * y1[2] + y1[3] * y1[3])); }
;                     if constexpr (COPY == 1) *(u32x2*)((unsigned char*)copy + off + bj * HALF) = pack8fp8(y0 * cscale, y1 * cscale);
;                     if constexpr (COPY == 3) *(u32x2*)((unsigned char*)copy + off + bj * HALF) = pack8i8(y0 * cscale, y1 * cscale);
;                     if constexpr (COPY == 2 || COPY == 4) *(u32x4*)((bf16_t*)copy + off + bj * HALF) = pack8bf(y0, y1); }
;                 if constexpr (STATS) { ss += __shfl_xor(ss, 16); ss += __shfl_xor(ss, 32); qq += __shfl_xor(qq, 16); qq += __shfl_xor(qq, 32);
;                     if (fq == 0) { unsafeAtomicAdd(stout + 2 * (size_t)row, ss); unsafeAtomicAdd(stout + 2 * (size_t)row + 1, qq); } }
.LBB0_3701:
	s_or_b64 exec, exec, s[40:41]
	v_add_u32_e32 v4, 0xa0, v2
	v_ashrrev_i32_e32 v5, 31, v4
	s_waitcnt lgkmcnt(1)
	v_lshlrev_b64 v[8:9], 11, v[4:5]
	v_lshl_add_u64 v[16:17], v[8:9], 0, v[0:1]
	v_lshlrev_b64 v[18:19], 2, v[16:17]
	v_lshl_add_u64 v[20:21], s[6:7], 0, v[18:19]
	s_waitcnt lgkmcnt(0)
	global_load_dwordx4 v[8:11], v[20:21], off nt
	global_load_dwordx4 v[12:15], v[20:21], off offset:16 nt
	v_lshl_add_u64 v[24:25], s[12:13], 0, v[16:17]
	v_lshl_add_u64 v[26:27], s[10:11], 0, v[18:19]
	s_waitcnt vmcnt(1)
	v_pk_mul_f32 v[10:11], v[10:11], s[20:21] op_sel_hi:[1,0]
	v_pk_mul_f32 v[8:9], v[8:9], s[20:21] op_sel_hi:[1,0]
	s_waitcnt vmcnt(0)
	v_pk_mul_f32 v[14:15], v[14:15], s[20:21] op_sel_hi:[1,0]
	v_pk_mul_f32 v[12:13], v[12:13], s[20:21] op_sel_hi:[1,0]
	v_pk_fma_f32 v[10:11], v[62:63], s[24:25], v[10:11] op_sel_hi:[1,0,1]
	v_pk_fma_f32 v[8:9], v[60:61], s[24:25], v[8:9] op_sel_hi:[1,0,1]
	v_pk_fma_f32 v[14:15], v[58:59], s[24:25], v[14:15] op_sel_hi:[1,0,1]
	v_pk_fma_f32 v[12:13], v[56:57], s[24:25], v[12:13] op_sel_hi:[1,0,1]
	v_pk_mul_f32 v[16:17], v[10:11], s[26:27] op_sel_hi:[1,0]
	v_pk_mul_f32 v[18:19], v[8:9], s[26:27] op_sel_hi:[1,0]
	v_pk_mul_f32 v[22:23], v[14:15], s[26:27] op_sel_hi:[1,0]
	v_pk_mul_f32 v[28:29], v[12:13], s[26:27] op_sel_hi:[1,0]
	v_med3_f32 v3, v18, s63, v192
	v_med3_f32 v18, v19, s63, v192
	v_med3_f32 v16, v16, s63, v192
	v_med3_f32 v17, v17, s63, v192
	v_med3_f32 v19, v28, s63, v192
	v_med3_f32 v28, v29, s63, v192
	v_med3_f32 v22, v22, s63, v192
	v_med3_f32 v23, v23, s63, v192
	v_add_f32_e32 v3, 0x4b400000, v3
	v_add_f32_e32 v18, 0x4b400000, v18
	v_add_f32_e32 v16, 0x4b400000, v16
	v_add_f32_e32 v17, 0x4b400000, v17
	v_add_f32_e32 v19, 0x4b400000, v19
	v_add_f32_e32 v28, 0x4b400000, v28
	v_add_f32_e32 v22, 0x4b400000, v22
	v_add_f32_e32 v23, 0x4b400000, v23
	v_perm_b32 v3, v18, v3, s64
	v_perm_b32 v16, v17, v16, s65
	v_perm_b32 v17, v28, v19, s64
	v_perm_b32 v18, v23, v22, s65
	v_or_b32_e32 v16, v3, v16
	v_or_b32_e32 v17, v17, v18
	global_store_dwordx4 v[26:27], v[8:11], off nt
	global_store_dwordx4 v[26:27], v[12:15], off offset:16 nt
	global_store_dwordx2 v[24:25], v[16:17], off
	global_load_dwordx4 v[16:19], v[20:21], off offset:512 nt
	s_nop 0
	global_load_dwordx4 v[20:23], v[20:21], off offset:528 nt
	v_add_f32_e32 v3, v8, v9
	v_add_f32_e32 v28, v10, v11
	v_add_f32_e32 v29, v12, v13
	v_add_f32_e32 v30, v14, v15
	v_mul_f32_e32 v9, v9, v9
	v_mul_f32_e32 v11, v11, v11
	v_mul_f32_e32 v13, v13, v13
	v_mul_f32_e32 v15, v15, v15
	v_fmac_f32_e32 v9, v8, v8
	v_fmac_f32_e32 v11, v10, v10
	v_fmac_f32_e32 v13, v12, v12
	v_fmac_f32_e32 v15, v14, v14
	v_add_f32_e32 v3, v3, v28
	v_add_f32_e32 v28, v29, v30
	v_add_f32_e32 v8, v9, v11
	v_add_f32_e32 v9, v13, v15
	v_add_f32_e32 v3, v3, v28
	v_add_f32_e32 v28, v8, v9
	v_add_f32_e32 v3, 0, v3
	s_waitcnt vmcnt(1)
	v_pk_mul_f32 v[8:9], v[18:19], s[20:21] op_sel_hi:[1,0]
	v_pk_mul_f32 v[12:13], v[16:17], s[20:21] op_sel_hi:[1,0]
	s_waitcnt vmcnt(0)
	v_pk_mul_f32 v[14:15], v[22:23], s[20:21] op_sel_hi:[1,0]
	v_pk_mul_f32 v[16:17], v[20:21], s[20:21] op_sel_hi:[1,0]
	v_pk_fma_f32 v[10:11], v[54:55], s[24:25], v[8:9] op_sel_hi:[1,0,1]
	v_pk_fma_f32 v[8:9], v[52:53], s[24:25], v[12:13] op_sel_hi:[1,0,1]
	v_pk_fma_f32 v[14:15], v[50:51], s[24:25], v[14:15] op_sel_hi:[1,0,1]
	v_pk_fma_f32 v[12:13], v[48:49], s[24:25], v[16:17] op_sel_hi:[1,0,1]
	global_store_dwordx4 v[26:27], v[8:11], off offset:512 nt
	global_store_dwordx4 v[26:27], v[12:15], off offset:528 nt
	v_add_f32_e32 v26, v8, v9
	v_add_f32_e32 v27, v10, v11
	v_add_f32_e32 v29, v12, v13
	v_add_f32_e32 v30, v14, v15
	v_mul_f32_e32 v31, v9, v9
	v_mul_f32_e32 v48, v11, v11
	v_mul_f32_e32 v49, v13, v13
	v_mul_f32_e32 v50, v15, v15
	v_pk_mul_f32 v[16:17], v[10:11], s[26:27] op_sel_hi:[1,0]
	v_pk_mul_f32 v[18:19], v[8:9], s[26:27] op_sel_hi:[1,0]
	v_add_f32_e32 v9, v26, v27
	v_add_f32_e32 v11, v29, v30
	v_fmac_f32_e32 v31, v8, v8
	v_fmac_f32_e32 v48, v10, v10
	v_fmac_f32_e32 v49, v12, v12
	v_fmac_f32_e32 v50, v14, v14
	v_med3_f32 v8, v18, s63, v192
	v_add_f32_e32 v9, v9, v11
	v_add_f32_e32 v11, v31, v48
	v_add_f32_e32 v18, v49, v50
	v_med3_f32 v10, v19, s63, v192
	v_add_f32_e32 v3, v3, v9
	v_add_f32_e32 v9, v11, v18
	v_add_f32_e32 v8, 0x4b400000, v8
	v_add_f32_e32 v10, 0x4b400000, v10
	v_add_f32_e32 v9, v28, v9
	v_perm_b32 v8, v10, v8, s64
	v_mov_b32_e32 v10, v3
	s_nop 1
	v_permlane16_swap_b32_e32 v3, v10
	v_mov_b32_e32 v11, v9
	s_nop 1
	v_permlane16_swap_b32_e32 v9, v11
	v_pk_mul_f32 v[22:23], v[12:13], s[26:27] op_sel_hi:[1,0]
	v_med3_f32 v12, v16, s63, v192
	v_med3_f32 v13, v17, s63, v192
	v_add_f32_e32 v12, 0x4b400000, v12
	v_add_f32_e32 v13, 0x4b400000, v13
	v_perm_b32 v12, v13, v12, s65
	s_waitcnt lgkmcnt(0)
	v_add_f32_e32 v3, v3, v10
	s_waitcnt lgkmcnt(0)
	v_add_f32_e32 v9, v9, v11
	v_pk_mul_f32 v[20:21], v[14:15], s[26:27] op_sel_hi:[1,0]
	v_or_b32_e32 v12, v8, v12
	v_mov_b32_e32 v8, v3
	s_nop 1
	v_permlane32_swap_b32_e32 v3, v8
	v_mov_b32_e32 v10, v9
	s_nop 1
	v_permlane32_swap_b32_e32 v9, v10
	v_med3_f32 v14, v22, s63, v192
	v_med3_f32 v15, v23, s63, v192
	v_med3_f32 v16, v20, s63, v192
	v_med3_f32 v17, v21, s63, v192
	v_add_f32_e32 v14, 0x4b400000, v14
	v_add_f32_e32 v15, 0x4b400000, v15
	v_add_f32_e32 v16, 0x4b400000, v16
	v_add_f32_e32 v17, 0x4b400000, v17
	v_perm_b32 v11, v15, v14, s64
	v_perm_b32 v13, v17, v16, s65
	v_or_b32_e32 v13, v11, v13
	global_store_dwordx2 v[24:25], v[12:13], off offset:128
	s_and_saveexec_b64 s[40:41], s[2:3]
	s_cbranch_execz .LBB0_3703
	v_lshl_add_u64 v[4:5], v[4:5], 3, s[14:15]
	s_waitcnt lgkmcnt(0)
	v_add_f32_e32 v3, v3, v8
	s_waitcnt lgkmcnt(0)
	v_add_f32_e32 v8, v9, v10
	global_atomic_add_f32 v[4:5], v3, off
	global_atomic_add_f32 v[4:5], v8, off offset:4
; __device__ __forceinline__ u32x2 pack8i8(const f32x4 a, const f32x4 b) { return (u32x2){pack4i8(a), pack4i8(b)}; }
; __device__ __forceinline__ u32x4 pack8bf(const f32x4 a, const f32x4 b) { u32x4 w; w.x = cvt_pk_bf16(a[0], a[1]); w.y = cvt_pk_bf16(a[2], a[3]); w.z = cvt_pk_bf16(b[0], b[1]); w.w = cvt_pk_bf16(b[2], b[3]); return w; }
;     __device__ __forceinline__ void operator()(EPI_ARGS) const {
;     ...
;             for (int m = 0; m < 4; ++m) { const int row = row0 + ai * HALF + m * 16; const size_t off = (size_t)row * DM + col0;
;                 float mu = 0.f, rs = 1.f; if constexpr (RESLN) ln_stats(stin, row, mu, rs);
;                 float ss = 0.f, qq = 0.f;
; #pragma unroll
;                 for (int bj = 0; bj < 2; ++bj) { f32x4 r0 = __builtin_nontemporal_load((const f32x4*)(res + off + bj * HALF)), r1 = __builtin_nontemporal_load((const f32x4*)(res + off + bj * HALF + 4));
;                     if constexpr (RESLN) { r0 = (r0 - mu) * rs * gg[bj][0] + bb[bj][0]; r1 = (r1 - mu) * rs * gg[bj][1] + bb[bj][1]; }
;                     const f32x4 y0 = r0 * DN_ALPHA + acc[ai][bj][m][0] * ascale, y1 = r1 * DN_ALPHA + acc[ai][bj][m][1] * ascale;
;                     if constexpr (COPY != 4) { __builtin_nontemporal_store(y0, (f32x4*)(Y + off + bj * HALF)); __builtin_nontemporal_store(y1, (f32x4*)(Y + off + bj * HALF + 4)); }
;                     if constexpr (STATS) { ss += ((y0[0] + y0[1]) + (y0[2] + y0[3])) + ((y1[0] + y1[1]) + (y1[2] + y1[3]));
;                         qq += ((y0[0] * y0[0] + y0[1] * y0[1]) + (y0[2] * y0[2] + y0[3] * y0[3])) + ((y1[0] * y1[0] + y1[1] * y1[1]) + (y1[2] * y1[2] + y1[3] * y1[3])); }
;                     if constexpr (COPY == 1) *(u32x2*)((unsigned char*)copy + off + bj * HALF) = pack8fp8(y0 * cscale, y1 * cscale);
;                     if constexpr (COPY == 3) *(u32x2*)((unsigned char*)copy + off + bj * HALF) = pack8i8(y0 * cscale, y1 * cscale);
;                     if constexpr (COPY == 2 || COPY == 4) *(u32x4*)((bf16_t*)copy + off + bj * HALF) = pack8bf(y0, y1); }
;                 if constexpr (STATS) { ss += __shfl_xor(ss, 16); ss += __shfl_xor(ss, 32); qq += __shfl_xor(qq, 16); qq += __shfl_xor(qq, 32);
;                     if (fq == 0) { unsafeAtomicAdd(stout + 2 * (size_t)row, ss); unsafeAtomicAdd(stout + 2 * (size_t)row + 1, qq); } }
.LBB0_3703:
	s_or_b64 exec, exec, s[40:41]
	v_add_u32_e32 v2, 0xb0, v2
	v_ashrrev_i32_e32 v3, 31, v2
	v_lshlrev_b64 v[4:5], 11, v[2:3]
	v_lshl_add_u64 v[0:1], v[4:5], 0, v[0:1]
	v_lshlrev_b64 v[4:5], 2, v[0:1]
	v_lshl_add_u64 v[20:21], s[6:7], 0, v[4:5]
	s_waitcnt lgkmcnt(0)
	global_load_dwordx4 v[8:11], v[20:21], off nt
	global_load_dwordx4 v[12:15], v[20:21], off offset:16 nt
	v_lshl_add_u64 v[24:25], s[12:13], 0, v[0:1]
	v_lshl_add_u64 v[0:1], s[10:11], 0, v[4:5]
	s_waitcnt vmcnt(1)
	v_pk_mul_f32 v[4:5], v[10:11], s[20:21] op_sel_hi:[1,0]
	v_pk_mul_f32 v[8:9], v[8:9], s[20:21] op_sel_hi:[1,0]
	s_waitcnt vmcnt(0)
	v_pk_mul_f32 v[14:15], v[14:15], s[20:21] op_sel_hi:[1,0]
	v_pk_mul_f32 v[12:13], v[12:13], s[20:21] op_sel_hi:[1,0]
	v_pk_fma_f32 v[10:11], v[46:47], s[24:25], v[4:5] op_sel_hi:[1,0,1]
	v_pk_fma_f32 v[8:9], v[44:45], s[24:25], v[8:9] op_sel_hi:[1,0,1]
	v_pk_fma_f32 v[14:15], v[42:43], s[24:25], v[14:15] op_sel_hi:[1,0,1]
	v_pk_fma_f32 v[12:13], v[40:41], s[24:25], v[12:13] op_sel_hi:[1,0,1]
	v_pk_mul_f32 v[4:5], v[10:11], s[26:27] op_sel_hi:[1,0]
	v_pk_mul_f32 v[16:17], v[8:9], s[26:27] op_sel_hi:[1,0]
	v_pk_mul_f32 v[18:19], v[14:15], s[26:27] op_sel_hi:[1,0]
	v_pk_mul_f32 v[22:23], v[12:13], s[26:27] op_sel_hi:[1,0]
	v_med3_f32 v16, v16, s63, v192
	v_med3_f32 v17, v17, s63, v192
	v_med3_f32 v4, v4, s63, v192
	v_med3_f32 v5, v5, s63, v192
	v_med3_f32 v22, v22, s63, v192
	v_med3_f32 v23, v23, s63, v192
	v_med3_f32 v18, v18, s63, v192
	v_med3_f32 v19, v19, s63, v192
	v_add_f32_e32 v16, 0x4b400000, v16
	v_add_f32_e32 v17, 0x4b400000, v17
	v_add_f32_e32 v4, 0x4b400000, v4
	v_add_f32_e32 v5, 0x4b400000, v5
	v_add_f32_e32 v22, 0x4b400000, v22
	v_add_f32_e32 v23, 0x4b400000, v23
	v_add_f32_e32 v18, 0x4b400000, v18
	v_add_f32_e32 v19, 0x4b400000, v19
	v_perm_b32 v16, v17, v16, s64
	v_perm_b32 v4, v5, v4, s65
	v_perm_b32 v5, v23, v22, s64
	v_perm_b32 v17, v19, v18, s65
	v_or_b32_e32 v4, v16, v4
	v_or_b32_e32 v5, v5, v17
	global_store_dwordx4 v[0:1], v[8:11], off nt
	global_store_dwordx4 v[0:1], v[12:15], off offset:16 nt
	global_store_dwordx2 v[24:25], v[4:5], off
	global_load_dwordx4 v[16:19], v[20:21], off offset:512 nt
	s_nop 0
	global_load_dwordx4 v[20:23], v[20:21], off offset:528 nt
	v_add_f32_e32 v4, v8, v9
	v_add_f32_e32 v5, v10, v11
	v_add_f32_e32 v26, v12, v13
	v_add_f32_e32 v27, v14, v15
	v_mul_f32_e32 v9, v9, v9
	v_mul_f32_e32 v11, v11, v11
	v_mul_f32_e32 v13, v13, v13
	v_mul_f32_e32 v15, v15, v15
	v_add_f32_e32 v4, v4, v5
	v_add_f32_e32 v5, v26, v27
	v_fmac_f32_e32 v9, v8, v8
	v_fmac_f32_e32 v11, v10, v10
	v_fmac_f32_e32 v13, v12, v12
	v_fmac_f32_e32 v15, v14, v14
	v_add_f32_e32 v4, v4, v5
	v_add_f32_e32 v5, v9, v11
	v_add_f32_e32 v8, v13, v15
	v_add_f32_e32 v26, 0, v4
	v_add_f32_e32 v27, v5, v8
	s_waitcnt vmcnt(1)
	v_pk_mul_f32 v[4:5], v[18:19], s[20:21] op_sel_hi:[1,0]
	v_pk_mul_f32 v[8:9], v[16:17], s[20:21] op_sel_hi:[1,0]
	s_waitcnt vmcnt(0)
	v_pk_mul_f32 v[12:13], v[22:23], s[20:21] op_sel_hi:[1,0]
	v_pk_mul_f32 v[16:17], v[20:21], s[20:21] op_sel_hi:[1,0]
	v_pk_fma_f32 v[10:11], v[38:39], s[24:25], v[4:5] op_sel_hi:[1,0,1]
	v_pk_fma_f32 v[8:9], v[36:37], s[24:25], v[8:9] op_sel_hi:[1,0,1]
	v_pk_fma_f32 v[14:15], v[34:35], s[24:25], v[12:13] op_sel_hi:[1,0,1]
	v_pk_fma_f32 v[12:13], v[32:33], s[24:25], v[16:17] op_sel_hi:[1,0,1]
	v_add_f32_e32 v20, v8, v9
	v_add_f32_e32 v21, v10, v11
	v_add_f32_e32 v22, v12, v13
	v_add_f32_e32 v23, v14, v15
	v_mul_f32_e32 v28, v9, v9
	v_mul_f32_e32 v29, v11, v11
	v_mul_f32_e32 v30, v13, v13
	v_mul_f32_e32 v31, v15, v15
	global_store_dwordx4 v[0:1], v[8:11], off offset:512 nt
	global_store_dwordx4 v[0:1], v[12:15], off offset:528 nt
	v_pk_mul_f32 v[0:1], v[10:11], s[26:27] op_sel_hi:[1,0]
	v_pk_mul_f32 v[4:5], v[8:9], s[26:27] op_sel_hi:[1,0]
	v_pk_mul_f32 v[18:19], v[12:13], s[26:27] op_sel_hi:[1,0]
	v_add_f32_e32 v9, v20, v21
	v_add_f32_e32 v11, v22, v23
	v_fmac_f32_e32 v28, v8, v8
	v_fmac_f32_e32 v29, v10, v10
	v_fmac_f32_e32 v30, v12, v12
	v_fmac_f32_e32 v31, v14, v14
	v_pk_mul_f32 v[16:17], v[14:15], s[26:27] op_sel_hi:[1,0]
	v_med3_f32 v8, v18, s63, v192
	v_add_f32_e32 v9, v9, v11
	v_add_f32_e32 v11, v28, v29
	v_add_f32_e32 v14, v30, v31
	v_med3_f32 v4, v4, s63, v192
	v_med3_f32 v5, v5, s63, v192
	v_add_f32_e32 v15, 0x4b400000, v8
	v_add_f32_e32 v8, v11, v14
	v_add_f32_e32 v4, 0x4b400000, v4
	v_add_f32_e32 v5, 0x4b400000, v5
	v_add_f32_e32 v9, v26, v9
	v_add_f32_e32 v11, v27, v8
	v_perm_b32 v4, v5, v4, s64
	v_mov_b32_e32 v5, v9
	s_nop 1
	v_permlane16_swap_b32_e32 v9, v5
	v_mov_b32_e32 v7, v11
	s_nop 1
	v_permlane16_swap_b32_e32 v11, v7
	v_med3_f32 v0, v0, s63, v192
	v_med3_f32 v1, v1, s63, v192
	v_add_f32_e32 v0, 0x4b400000, v0
	v_add_f32_e32 v1, 0x4b400000, v1
	v_perm_b32 v0, v1, v0, s65
	v_or_b32_e32 v8, v4, v0
	s_waitcnt lgkmcnt(0)
	v_add_f32_e32 v0, v9, v5
	s_waitcnt lgkmcnt(0)
	v_add_f32_e32 v4, v11, v7
	v_mov_b32_e32 v1, v0
	s_nop 1
	v_permlane32_swap_b32_e32 v0, v1
	v_mov_b32_e32 v5, v4
	s_nop 1
	v_permlane32_swap_b32_e32 v4, v5
	v_med3_f32 v10, v19, s63, v192
	v_med3_f32 v12, v16, s63, v192
	v_med3_f32 v13, v17, s63, v192
	v_add_f32_e32 v10, 0x4b400000, v10
	v_add_f32_e32 v12, 0x4b400000, v12
	v_add_f32_e32 v13, 0x4b400000, v13
	v_perm_b32 v6, v10, v15, s64
	v_perm_b32 v7, v13, v12, s65
	v_or_b32_e32 v9, v6, v7
	global_store_dwordx2 v[24:25], v[8:9], off offset:128
	s_and_saveexec_b64 s[40:41], s[2:3]
	s_cbranch_execz .LBB0_3705
	v_lshl_add_u64 v[2:3], v[2:3], 3, s[14:15]
	s_waitcnt lgkmcnt(0)
	v_add_f32_e32 v0, v0, v1
	s_waitcnt lgkmcnt(0)
	v_add_f32_e32 v1, v4, v5
	global_atomic_add_f32 v[2:3], v0, off
	global_atomic_add_f32 v[2:3], v1, off offset:4

;     __device__ __forceinline__ void operator()(EPI_ARGS) const {
;         const int row0 = u.pm * BM + wr * 64 + fr, col0 = u.pn * BM + wc * 32 + 8 * fq;
;         f32x4 gg[2][2], bb[2][2];
;         if constexpr (RESLN) {
; #pragma unroll
;             for (int bj = 0; bj < 2; ++bj)
; #pragma unroll
;                 for (int n = 0; n < 2; ++n) { gg[bj][n] = *(const f32x4*)(lg + col0 + bj * HALF + 4 * n); bb[bj][n] = *(const f32x4*)(lb + col0 + bj * HALF + 4 * n); } }
; #pragma unroll
;         for (int ai = 0; ai < 2; ++ai)
; #pragma unroll
;             for (int m = 0; m < 4; ++m) { const int row = row0 + ai * HALF + m * 16; const size_t off = (size_t)row * DM + col0;
;                 float mu = 0.f, rs = 1.f; if constexpr (RESLN) ln_stats(stin, row, mu, rs);
;                 float ss = 0.f, qq = 0.f;
; #pragma unroll
;                 for (int bj = 0; bj < 2; ++bj) { f32x4 r0 = __builtin_nontemporal_load((const f32x4*)(res + off + bj * HALF)), r1 = __builtin_nontemporal_load((const f32x4*)(res + off + bj * HALF + 4));
;                     if constexpr (RESLN) { r0 = (r0 - mu) * rs * gg[bj][0] + bb[bj][0]; r1 = (r1 - mu) * rs * gg[bj][1] + bb[bj][1]; }
;                     const f32x4 y0 = r0 * DN_ALPHA + acc[ai][bj][m][0] * ascale, y1 = r1 * DN_ALPHA + acc[ai][bj][m][1] * ascale;
;                     if constexpr (COPY != 4) { __builtin_nontemporal_store(y0, (f32x4*)(Y + off + bj * HALF)); __builtin_nontemporal_store(y1, (f32x4*)(Y + off + bj * HALF + 4)); }
;                     if constexpr (STATS) { ss += ((y0[0] + y0[1]) + (y0[2] + y0[3])) + ((y1[0] + y1[1]) + (y1[2] + y1[3]));
;                         qq += ((y0[0] * y0[0] + y0[1] * y0[1]) + (y0[2] * y0[2] + y0[3] * y0[3])) + ((y1[0] * y1[0] + y1[1] * y1[1]) + (y1[2] * y1[2] + y1[3] * y1[3])); }
;                     if constexpr (COPY == 1) *(u32x2*)((unsigned char*)copy + off + bj * HALF) = pack8fp8(y0 * cscale, y1 * cscale);
;                     if constexpr (COPY == 3) *(u32x2*)((unsigned char*)copy + off + bj * HALF) = pack8i8(y0 * cscale, y1 * cscale);
;                     if constexpr (COPY == 2 || COPY == 4) *(u32x4*)((bf16_t*)copy + off + bj * HALF) = pack8bf(y0, y1); }
;                 if constexpr (STATS) { ss += __shfl_xor(ss, 16); ss += __shfl_xor(ss, 32); qq += __shfl_xor(qq, 16); qq += __shfl_xor(qq, 32);
.LBB0_3861:
	v_lshl_add_u32 v178, s69, 8, v186
	v_lshl_or_b32 v176, s70, 8, v188
	v_ashrrev_i32_e32 v179, 31, v178
	v_ashrrev_i32_e32 v177, 31, v176
	v_lshlrev_b64 v[0:1], 11, v[178:179]
	v_lshlrev_b64 v[180:181], 3, v[178:179]
	v_lshl_add_u64 v[184:185], v[0:1], 0, v[176:177]
	v_lshl_add_u64 v[0:1], s[14:15], 0, v[180:181]
	global_load_dwordx2 v[204:205], v[0:1], off
	v_lshl_add_u64 v[182:183], v[184:185], 2, s[18:19]
	global_load_dwordx4 v[196:199], v[182:183], off nt
	global_load_dwordx4 v[200:203], v[182:183], off offset:16 nt
	v_lshlrev_b64 v[0:1], 2, v[176:177]
	v_lshl_add_u64 v[4:5], s[8:9], 0, v[0:1]
	v_lshl_add_u64 v[12:13], s[10:11], 0, v[0:1]
	global_load_dwordx4 v[16:19], v[12:13], off
	global_load_dwordx4 v[28:31], v[4:5], off
	global_load_dwordx4 v[20:23], v[4:5], off offset:16
	global_load_dwordx4 v[24:27], v[12:13], off offset:16
	global_load_dwordx4 v[0:3], v[4:5], off offset:528
	global_load_dwordx4 v[8:11], v[4:5], off offset:512
	s_nop 0
	global_load_dwordx4 v[4:7], v[12:13], off offset:528
	s_nop 0
	global_load_dwordx4 v[12:15], v[12:13], off offset:512
	v_lshl_add_u64 v[184:185], s[20:21], 0, v[184:185]
	s_waitcnt vmcnt(0)
	v_pk_mul_f32 v[208:209], v[204:205], s[28:29] op_sel_hi:[1,0]
	s_nop 0
	v_fma_f32 v179, -v208, v208, v209
	v_add_f32_e32 v179, 0x3727c5ac, v179
	v_rsq_f32_e32 v254, v179
	v_sub_f32_e32 v199, v199, v208
	v_sub_f32_e32 v198, v198, v208
	v_sub_f32_e32 v197, v197, v208
	v_sub_f32_e32 v196, v196, v208
	v_sub_f32_e32 v203, v203, v208
	v_sub_f32_e32 v202, v202, v208
	v_sub_f32_e32 v201, v201, v208
	v_sub_f32_e32 v200, v200, v208
	s_nop 0
	s_nop 1
	v_mov_b32_e32 v210, v254
	v_pk_mul_f32 v[196:197], v[196:197], v[210:211] op_sel_hi:[1,0]
	v_pk_mul_f32 v[198:199], v[198:199], v[210:211] op_sel_hi:[1,0]
	v_pk_mul_f32 v[200:201], v[200:201], v[210:211] op_sel_hi:[1,0]
	v_pk_mul_f32 v[202:203], v[202:203], v[210:211] op_sel_hi:[1,0]
	v_pk_fma_f32 v[198:199], v[30:31], v[198:199], v[18:19]
	v_pk_fma_f32 v[196:197], v[28:29], v[196:197], v[16:17]
	v_pk_fma_f32 v[202:203], v[22:23], v[202:203], v[26:27]
	v_pk_fma_f32 v[200:201], v[20:21], v[200:201], v[24:25]
	v_pk_mul_f32 v[196:197], v[196:197], s[30:31] op_sel_hi:[1,0]
	v_pk_mul_f32 v[198:199], v[198:199], s[30:31] op_sel_hi:[1,0]
	v_pk_mul_f32 v[200:201], v[200:201], s[30:31] op_sel_hi:[1,0]
	v_pk_mul_f32 v[202:203], v[202:203], s[30:31] op_sel_hi:[1,0]
	v_pk_fma_f32 v[158:159], v[158:159], s[36:37], v[198:199] op_sel_hi:[1,0,1]
	v_pk_fma_f32 v[156:157], v[156:157], s[36:37], v[196:197] op_sel_hi:[1,0,1]
	v_pk_fma_f32 v[198:199], v[154:155], s[36:37], v[202:203] op_sel_hi:[1,0,1]
	v_pk_fma_f32 v[196:197], v[152:153], s[36:37], v[200:201] op_sel_hi:[1,0,1]
	v_pk_mul_f32 v[152:153], v[158:159], s[38:39] op_sel_hi:[1,0]
	v_pk_mul_f32 v[154:155], v[156:157], s[38:39] op_sel_hi:[1,0]
	v_pk_mul_f32 v[200:201], v[198:199], s[38:39] op_sel_hi:[1,0]
	v_pk_mul_f32 v[202:203], v[196:197], s[38:39] op_sel_hi:[1,0]
	v_med3_f32 v154, v154, s64, v195
	v_med3_f32 v155, v155, s64, v195
	v_med3_f32 v152, v152, s64, v195
	v_med3_f32 v153, v153, s64, v195
	v_med3_f32 v179, v202, s64, v195
	v_med3_f32 v202, v203, s64, v195
	v_med3_f32 v200, v200, s64, v195
	v_med3_f32 v201, v201, s64, v195
	v_add_f32_e32 v154, 0x4b400000, v154
	v_add_f32_e32 v155, 0x4b400000, v155
	v_add_f32_e32 v152, 0x4b400000, v152
	v_add_f32_e32 v153, 0x4b400000, v153
	v_add_f32_e32 v179, 0x4b400000, v179
	v_add_f32_e32 v202, 0x4b400000, v202
	v_add_f32_e32 v200, 0x4b400000, v200
	v_add_f32_e32 v201, 0x4b400000, v201
	v_perm_b32 v154, v155, v154, s65
	v_perm_b32 v152, v153, v152, s66
	v_perm_b32 v153, v202, v179, s65
	v_perm_b32 v155, v201, v200, s66
	v_or_b32_e32 v152, v154, v152
	v_or_b32_e32 v153, v153, v155
	global_store_dwordx4 v[182:183], v[156:159], off nt
	global_store_dwordx4 v[182:183], v[196:199], off offset:16 nt
	global_store_dwordx2 v[184:185], v[152:153], off
	global_load_dwordx4 v[200:203], v[182:183], off offset:512 nt
	global_load_dwordx4 v[204:207], v[182:183], off offset:528 nt
	v_and_b32_e32 v153, 64, v193
	v_xor_b32_e32 v152, 16, v193
	v_add_u32_e32 v153, 64, v153
	v_xor_b32_e32 v154, 32, v193
	v_cmp_lt_i32_e32 vcc, v152, v153
	v_add_f32_e32 v155, v158, v159
	v_add_f32_e32 v179, v196, v197
	v_cndmask_b32_e32 v152, v193, v152, vcc
	v_cmp_lt_i32_e32 vcc, v154, v153
	v_lshlrev_b32_e32 v153, 2, v152
	v_add_f32_e32 v209, v198, v199
	v_cndmask_b32_e32 v154, v193, v154, vcc
	v_lshlrev_b32_e32 v152, 2, v154
	v_add_f32_e32 v154, v156, v157
	v_mul_f32_e32 v157, v157, v157
	v_mul_f32_e32 v159, v159, v159
	v_mul_f32_e32 v197, v197, v197
	v_mul_f32_e32 v199, v199, v199
	v_add_f32_e32 v154, v154, v155
	v_add_f32_e32 v155, v179, v209
	v_fmac_f32_e32 v157, v156, v156
	v_fmac_f32_e32 v159, v158, v158
	v_fmac_f32_e32 v197, v196, v196
	v_fmac_f32_e32 v199, v198, v198
	v_add_f32_e32 v154, v154, v155
	v_add_f32_e32 v155, v157, v159
	v_add_f32_e32 v156, v197, v199
	v_add_f32_e32 v179, 0, v154
	v_add_f32_e32 v198, v155, v156
	s_waitcnt vmcnt(1)
	v_sub_f32_e32 v155, v203, v208
	v_sub_f32_e32 v154, v202, v208
	v_sub_f32_e32 v157, v201, v208
	v_sub_f32_e32 v156, v200, v208
	s_waitcnt vmcnt(0)
;     __device__ __forceinline__ void operator()(EPI_ARGS) const {
;         const int row0 = u.pm * BM + wr * 64 + fr, col0 = u.pn * BM + wc * 32 + 8 * fq;
;         f32x4 gg[2][2], bb[2][2];
;         if constexpr (RESLN) {
; #pragma unroll
;             for (int bj = 0; bj < 2; ++bj)
; #pragma unroll
;                 for (int n = 0; n < 2; ++n) { gg[bj][n] = *(const f32x4*)(lg + col0 + bj * HALF + 4 * n); bb[bj][n] = *(const f32x4*)(lb + col0 + bj * HALF + 4 * n); } }
; #pragma unroll
;         for (int ai = 0; ai < 2; ++ai)
; #pragma unroll
;             for (int m = 0; m < 4; ++m) { const int row = row0 + ai * HALF + m * 16; const size_t off = (size_t)row * DM + col0;
;                 float mu = 0.f, rs = 1.f; if constexpr (RESLN) ln_stats(stin, row, mu, rs);
;                 float ss = 0.f, qq = 0.f;
; #pragma unroll
;                 for (int bj = 0; bj < 2; ++bj) { f32x4 r0 = __builtin_nontemporal_load((const f32x4*)(res + off + bj * HALF)), r1 = __builtin_nontemporal_load((const f32x4*)(res + off + bj * HALF + 4));
;                     if constexpr (RESLN) { r0 = (r0 - mu) * rs * gg[bj][0] + bb[bj][0]; r1 = (r1 - mu) * rs * gg[bj][1] + bb[bj][1]; }
;                     const f32x4 y0 = r0 * DN_ALPHA + acc[ai][bj][m][0] * ascale, y1 = r1 * DN_ALPHA + acc[ai][bj][m][1] * ascale;
;                     if constexpr (COPY != 4) { __builtin_nontemporal_store(y0, (f32x4*)(Y + off + bj * HALF)); __builtin_nontemporal_store(y1, (f32x4*)(Y + off + bj * HALF + 4)); }
;                     if constexpr (STATS) { ss += ((y0[0] + y0[1]) + (y0[2] + y0[3])) + ((y1[0] + y1[1]) + (y1[2] + y1[3]));
;                         qq += ((y0[0] * y0[0] + y0[1] * y0[1]) + (y0[2] * y0[2] + y0[3] * y0[3])) + ((y1[0] * y1[0] + y1[1] * y1[1]) + (y1[2] * y1[2] + y1[3] * y1[3])); }
;                     if constexpr (COPY == 1) *(u32x2*)((unsigned char*)copy + off + bj * HALF) = pack8fp8(y0 * cscale, y1 * cscale);
;                     if constexpr (COPY == 3) *(u32x2*)((unsigned char*)copy + off + bj * HALF) = pack8i8(y0 * cscale, y1 * cscale);
;                     if constexpr (COPY == 2 || COPY == 4) *(u32x4*)((bf16_t*)copy + off + bj * HALF) = pack8bf(y0, y1); }
;                 if constexpr (STATS) { ss += __shfl_xor(ss, 16); ss += __shfl_xor(ss, 32); qq += __shfl_xor(qq, 16); qq += __shfl_xor(qq, 32);
	v_sub_f32_e32 v159, v207, v208
	v_sub_f32_e32 v158, v206, v208
	v_sub_f32_e32 v197, v205, v208
	v_sub_f32_e32 v196, v204, v208
	v_pk_mul_f32 v[156:157], v[156:157], v[210:211] op_sel_hi:[1,0]
	v_pk_mul_f32 v[154:155], v[154:155], v[210:211] op_sel_hi:[1,0]
	v_pk_mul_f32 v[196:197], v[196:197], v[210:211] op_sel_hi:[1,0]
	v_pk_mul_f32 v[158:159], v[158:159], v[210:211] op_sel_hi:[1,0]
	v_pk_fma_f32 v[154:155], v[10:11], v[154:155], v[14:15]
	v_pk_fma_f32 v[156:157], v[8:9], v[156:157], v[12:13]
	v_pk_fma_f32 v[158:159], v[2:3], v[158:159], v[6:7]
	v_pk_fma_f32 v[196:197], v[0:1], v[196:197], v[4:5]
	v_pk_mul_f32 v[156:157], v[156:157], s[30:31] op_sel_hi:[1,0]
	v_pk_mul_f32 v[154:155], v[154:155], s[30:31] op_sel_hi:[1,0]
	v_pk_mul_f32 v[196:197], v[196:197], s[30:31] op_sel_hi:[1,0]
	v_pk_mul_f32 v[158:159], v[158:159], s[30:31] op_sel_hi:[1,0]
	v_pk_fma_f32 v[150:151], v[150:151], s[36:37], v[154:155] op_sel_hi:[1,0,1]
	v_pk_fma_f32 v[148:149], v[148:149], s[36:37], v[156:157] op_sel_hi:[1,0,1]
	v_pk_fma_f32 v[146:147], v[146:147], s[36:37], v[158:159] op_sel_hi:[1,0,1]
	v_pk_fma_f32 v[144:145], v[144:145], s[36:37], v[196:197] op_sel_hi:[1,0,1]
	v_add_f32_e32 v196, v148, v149
	v_add_f32_e32 v197, v150, v151
	v_add_f32_e32 v199, v144, v145
	v_add_f32_e32 v200, v146, v147
	v_mul_f32_e32 v201, v149, v149
	v_mul_f32_e32 v202, v151, v151
	v_mul_f32_e32 v203, v145, v145
	v_mul_f32_e32 v204, v147, v147
	global_store_dwordx4 v[182:183], v[148:151], off offset:512 nt
	global_store_dwordx4 v[182:183], v[144:147], off offset:528 nt
	v_pk_mul_f32 v[156:157], v[148:149], s[38:39] op_sel_hi:[1,0]
	v_pk_mul_f32 v[158:159], v[146:147], s[38:39] op_sel_hi:[1,0]
	v_pk_mul_f32 v[182:183], v[144:145], s[38:39] op_sel_hi:[1,0]
	v_add_f32_e32 v145, v196, v197
	v_add_f32_e32 v147, v199, v200
	v_fmac_f32_e32 v201, v148, v148
	v_fmac_f32_e32 v202, v150, v150
	v_fmac_f32_e32 v203, v144, v144
	v_fmac_f32_e32 v204, v146, v146
	v_med3_f32 v144, v156, s64, v195
	v_add_f32_e32 v145, v145, v147
	v_add_f32_e32 v147, v201, v202
	v_add_f32_e32 v156, v203, v204
	v_med3_f32 v146, v157, s64, v195
	v_add_f32_e32 v147, v147, v156
	v_add_f32_e32 v144, 0x4b400000, v144
	v_add_f32_e32 v146, 0x4b400000, v146
	v_add_f32_e32 v145, v145, v179
	v_add_f32_e32 v147, v198, v147
	v_perm_b32 v144, v146, v144, s65
	v_mov_b32_e32 v146, v145
	s_nop 1
	v_permlane16_swap_b32_e32 v145, v146
	v_mov_b32_e32 v156, v147
	s_nop 1
	v_permlane16_swap_b32_e32 v147, v156
	v_pk_mul_f32 v[154:155], v[150:151], s[38:39] op_sel_hi:[1,0]
	v_med3_f32 v150, v182, s64, v195
	v_med3_f32 v148, v154, s64, v195
	v_med3_f32 v149, v155, s64, v195
	v_add_f32_e32 v148, 0x4b400000, v148
	v_add_f32_e32 v149, 0x4b400000, v149
	v_perm_b32 v148, v149, v148, s66
	v_or_b32_e32 v148, v144, v148
	s_waitcnt lgkmcnt(0)
	v_add_f32_e32 v144, v145, v146
	s_waitcnt lgkmcnt(0)
	v_add_f32_e32 v146, v147, v156
	v_mov_b32_e32 v145, v144
	s_nop 1
	v_permlane32_swap_b32_e32 v144, v145
	v_mov_b32_e32 v147, v146
	s_nop 1
	v_permlane32_swap_b32_e32 v146, v147
	v_med3_f32 v151, v183, s64, v195
	v_med3_f32 v154, v158, s64, v195
	v_med3_f32 v155, v159, s64, v195
	v_add_f32_e32 v150, 0x4b400000, v150
	v_add_f32_e32 v151, 0x4b400000, v151
	v_add_f32_e32 v154, 0x4b400000, v154
	v_add_f32_e32 v155, 0x4b400000, v155
	v_perm_b32 v149, v151, v150, s65
	v_perm_b32 v150, v155, v154, s66
	v_or_b32_e32 v149, v149, v150
	global_store_dwordx2 v[184:185], v[148:149], off offset:128
	s_and_saveexec_b64 s[6:7], s[2:3]
	s_cbranch_execz .LBB0_3863
	v_lshl_add_u64 v[148:149], s[12:13], 0, v[180:181]
	s_waitcnt lgkmcnt(0)
	v_add_f32_e32 v144, v144, v145
	s_waitcnt lgkmcnt(0)
	v_add_f32_e32 v145, v146, v147
	global_atomic_add_f32 v[148:149], v144, off
	global_atomic_add_f32 v[148:149], v145, off offset:4
.LBB0_3863:
	s_or_b64 exec, exec, s[6:7]
	v_or_b32_e32 v144, 16, v178
	s_waitcnt lgkmcnt(1)
	v_ashrrev_i32_e32 v145, 31, v144
	s_waitcnt lgkmcnt(0)
	v_lshlrev_b64 v[146:147], 11, v[144:145]
	v_lshlrev_b64 v[144:145], 3, v[144:145]
	v_lshl_add_u64 v[158:159], v[146:147], 0, v[176:177]
	v_lshl_add_u64 v[146:147], s[14:15], 0, v[144:145]
	global_load_dwordx2 v[180:181], v[146:147], off
	v_lshl_add_u64 v[146:147], v[158:159], 2, s[18:19]
	global_load_dwordx4 v[148:151], v[146:147], off nt
	global_load_dwordx4 v[154:157], v[146:147], off offset:16 nt
	v_lshl_add_u64 v[158:159], s[20:21], 0, v[158:159]
	s_waitcnt vmcnt(2)
	v_pk_mul_f32 v[180:181], v[180:181], s[28:29] op_sel_hi:[1,0]
	s_nop 0
	v_fma_f32 v179, -v180, v180, v181
	v_add_f32_e32 v179, 0x3727c5ac, v179
	v_rsq_f32_e32 v254, v179
	s_waitcnt vmcnt(1)
	v_sub_f32_e32 v151, v151, v180
	v_sub_f32_e32 v150, v150, v180
	v_sub_f32_e32 v149, v149, v180
	v_sub_f32_e32 v148, v148, v180
	s_waitcnt vmcnt(0)
;     __device__ __forceinline__ void operator()(EPI_ARGS) const {
;         const int row0 = u.pm * BM + wr * 64 + fr, col0 = u.pn * BM + wc * 32 + 8 * fq;
;         f32x4 gg[2][2], bb[2][2];
;         if constexpr (RESLN) {
; #pragma unroll
;             for (int bj = 0; bj < 2; ++bj)
; #pragma unroll
;                 for (int n = 0; n < 2; ++n) { gg[bj][n] = *(const f32x4*)(lg + col0 + bj * HALF + 4 * n); bb[bj][n] = *(const f32x4*)(lb + col0 + bj * HALF + 4 * n); } }
; #pragma unroll
;         for (int ai = 0; ai < 2; ++ai)
; #pragma unroll
;             for (int m = 0; m < 4; ++m) { const int row = row0 + ai * HALF + m * 16; const size_t off = (size_t)row * DM + col0;
;                 float mu = 0.f, rs = 1.f; if constexpr (RESLN) ln_stats(stin, row, mu, rs);
;                 float ss = 0.f, qq = 0.f;
; #pragma unroll
;                 for (int bj = 0; bj < 2; ++bj) { f32x4 r0 = __builtin_nontemporal_load((const f32x4*)(res + off + bj * HALF)), r1 = __builtin_nontemporal_load((const f32x4*)(res + off + bj * HALF + 4));
;                     if constexpr (RESLN) { r0 = (r0 - mu) * rs * gg[bj][0] + bb[bj][0]; r1 = (r1 - mu) * rs * gg[bj][1] + bb[bj][1]; }
;                     const f32x4 y0 = r0 * DN_ALPHA + acc[ai][bj][m][0] * ascale, y1 = r1 * DN_ALPHA + acc[ai][bj][m][1] * ascale;
;                     if constexpr (COPY != 4) { __builtin_nontemporal_store(y0, (f32x4*)(Y + off + bj * HALF)); __builtin_nontemporal_store(y1, (f32x4*)(Y + off + bj * HALF + 4)); }
;                     if constexpr (STATS) { ss += ((y0[0] + y0[1]) + (y0[2] + y0[3])) + ((y1[0] + y1[1]) + (y1[2] + y1[3]));
;                         qq += ((y0[0] * y0[0] + y0[1] * y0[1]) + (y0[2] * y0[2] + y0[3] * y0[3])) + ((y1[0] * y1[0] + y1[1] * y1[1]) + (y1[2] * y1[2] + y1[3] * y1[3])); }
;                     if constexpr (COPY == 1) *(u32x2*)((unsigned char*)copy + off + bj * HALF) = pack8fp8(y0 * cscale, y1 * cscale);
;                     if constexpr (COPY == 3) *(u32x2*)((unsigned char*)copy + off + bj * HALF) = pack8i8(y0 * cscale, y1 * cscale);
;                     if constexpr (COPY == 2 || COPY == 4) *(u32x4*)((bf16_t*)copy + off + bj * HALF) = pack8bf(y0, y1); }
;                 if constexpr (STATS) { ss += __shfl_xor(ss, 16); ss += __shfl_xor(ss, 32); qq += __shfl_xor(qq, 16); qq += __shfl_xor(qq, 32);
	v_sub_f32_e32 v157, v157, v180
	v_sub_f32_e32 v156, v156, v180
	v_sub_f32_e32 v155, v155, v180
	v_sub_f32_e32 v154, v154, v180
	s_nop 0
	s_nop 1
	v_mov_b32_e32 v182, v254
	v_pk_mul_f32 v[148:149], v[148:149], v[182:183] op_sel_hi:[1,0]
	v_pk_mul_f32 v[150:151], v[150:151], v[182:183] op_sel_hi:[1,0]
	v_pk_mul_f32 v[154:155], v[154:155], v[182:183] op_sel_hi:[1,0]
	v_pk_mul_f32 v[156:157], v[156:157], v[182:183] op_sel_hi:[1,0]
	v_pk_fma_f32 v[150:151], v[30:31], v[150:151], v[18:19]
	v_pk_fma_f32 v[148:149], v[28:29], v[148:149], v[16:17]
	v_pk_fma_f32 v[156:157], v[22:23], v[156:157], v[26:27]
	v_pk_fma_f32 v[154:155], v[20:21], v[154:155], v[24:25]
	v_pk_mul_f32 v[148:149], v[148:149], s[30:31] op_sel_hi:[1,0]
	v_pk_mul_f32 v[150:151], v[150:151], s[30:31] op_sel_hi:[1,0]
	v_pk_mul_f32 v[154:155], v[154:155], s[30:31] op_sel_hi:[1,0]
	v_pk_mul_f32 v[156:157], v[156:157], s[30:31] op_sel_hi:[1,0]
	v_pk_fma_f32 v[142:143], v[142:143], s[36:37], v[150:151] op_sel_hi:[1,0,1]
	v_pk_fma_f32 v[140:141], v[140:141], s[36:37], v[148:149] op_sel_hi:[1,0,1]
	v_pk_fma_f32 v[138:139], v[138:139], s[36:37], v[156:157] op_sel_hi:[1,0,1]
	v_pk_fma_f32 v[136:137], v[136:137], s[36:37], v[154:155] op_sel_hi:[1,0,1]
	v_pk_mul_f32 v[148:149], v[142:143], s[38:39] op_sel_hi:[1,0]
	v_pk_mul_f32 v[150:151], v[140:141], s[38:39] op_sel_hi:[1,0]
	v_pk_mul_f32 v[154:155], v[138:139], s[38:39] op_sel_hi:[1,0]
	v_pk_mul_f32 v[156:157], v[136:137], s[38:39] op_sel_hi:[1,0]
	v_med3_f32 v150, v150, s64, v195
	v_med3_f32 v151, v151, s64, v195
	v_med3_f32 v148, v148, s64, v195
	v_med3_f32 v149, v149, s64, v195
	v_med3_f32 v156, v156, s64, v195
	v_med3_f32 v157, v157, s64, v195
	v_med3_f32 v154, v154, s64, v195
	v_med3_f32 v155, v155, s64, v195
	v_add_f32_e32 v150, 0x4b400000, v150
	v_add_f32_e32 v151, 0x4b400000, v151
	v_add_f32_e32 v148, 0x4b400000, v148
	v_add_f32_e32 v149, 0x4b400000, v149
	v_add_f32_e32 v156, 0x4b400000, v156
	v_add_f32_e32 v157, 0x4b400000, v157
	v_add_f32_e32 v154, 0x4b400000, v154
	v_add_f32_e32 v155, 0x4b400000, v155
	v_perm_b32 v150, v151, v150, s65
	v_perm_b32 v148, v149, v148, s66
	v_perm_b32 v149, v157, v156, s65
	v_perm_b32 v151, v155, v154, s66
	v_or_b32_e32 v148, v150, v148
	v_or_b32_e32 v149, v149, v151
	global_store_dwordx4 v[146:147], v[140:143], off nt
	global_store_dwordx4 v[146:147], v[136:139], off offset:16 nt
	global_store_dwordx2 v[158:159], v[148:149], off
	global_load_dwordx4 v[148:151], v[146:147], off offset:512 nt
	s_nop 0
	global_load_dwordx4 v[154:157], v[146:147], off offset:528 nt
	v_add_f32_e32 v179, v140, v141
	v_add_f32_e32 v181, v142, v143
	v_add_f32_e32 v183, v136, v137
	v_add_f32_e32 v184, v138, v139
	v_mul_f32_e32 v141, v141, v141
	v_mul_f32_e32 v143, v143, v143
	v_mul_f32_e32 v137, v137, v137
	v_mul_f32_e32 v139, v139, v139
	v_add_f32_e32 v179, v179, v181
	v_add_f32_e32 v181, v183, v184
	v_fmac_f32_e32 v141, v140, v140
	v_fmac_f32_e32 v143, v142, v142
	v_fmac_f32_e32 v137, v136, v136
	v_fmac_f32_e32 v139, v138, v138
	v_add_f32_e32 v136, v179, v181
	v_add_f32_e32 v138, v141, v143
	v_add_f32_e32 v137, v137, v139
	v_add_f32_e32 v179, 0, v136
	v_add_f32_e32 v181, v138, v137
	s_waitcnt vmcnt(1)
	v_sub_f32_e32 v137, v151, v180
	v_sub_f32_e32 v136, v150, v180
	v_sub_f32_e32 v139, v149, v180
	v_sub_f32_e32 v138, v148, v180
	s_waitcnt vmcnt(0)
	v_sub_f32_e32 v141, v157, v180
	v_sub_f32_e32 v140, v156, v180
	v_sub_f32_e32 v143, v155, v180
	v_sub_f32_e32 v142, v154, v180
	v_pk_mul_f32 v[138:139], v[138:139], v[182:183] op_sel_hi:[1,0]
	v_pk_mul_f32 v[136:137], v[136:137], v[182:183] op_sel_hi:[1,0]
	v_pk_mul_f32 v[142:143], v[142:143], v[182:183] op_sel_hi:[1,0]
	v_pk_mul_f32 v[140:141], v[140:141], v[182:183] op_sel_hi:[1,0]
	v_pk_fma_f32 v[136:137], v[10:11], v[136:137], v[14:15]
	v_pk_fma_f32 v[138:139], v[8:9], v[138:139], v[12:13]
	v_pk_fma_f32 v[140:141], v[2:3], v[140:141], v[6:7]
	v_pk_fma_f32 v[142:143], v[0:1], v[142:143], v[4:5]
	v_pk_mul_f32 v[138:139], v[138:139], s[30:31] op_sel_hi:[1,0]
	v_pk_mul_f32 v[136:137], v[136:137], s[30:31] op_sel_hi:[1,0]
	v_pk_mul_f32 v[142:143], v[142:143], s[30:31] op_sel_hi:[1,0]
	v_pk_mul_f32 v[140:141], v[140:141], s[30:31] op_sel_hi:[1,0]
	v_pk_fma_f32 v[134:135], v[134:135], s[36:37], v[136:137] op_sel_hi:[1,0,1]
	v_pk_fma_f32 v[132:133], v[132:133], s[36:37], v[138:139] op_sel_hi:[1,0,1]
	v_pk_fma_f32 v[130:131], v[130:131], s[36:37], v[140:141] op_sel_hi:[1,0,1]
	v_pk_fma_f32 v[128:129], v[128:129], s[36:37], v[142:143] op_sel_hi:[1,0,1]
	global_store_dwordx4 v[146:147], v[132:135], off offset:512 nt
	global_store_dwordx4 v[146:147], v[128:131], off offset:528 nt
	v_add_f32_e32 v146, v132, v133
	v_add_f32_e32 v147, v134, v135
	v_add_f32_e32 v148, v128, v129
	v_add_f32_e32 v149, v130, v131
	v_mul_f32_e32 v150, v133, v133
	v_mul_f32_e32 v151, v135, v135
	v_mul_f32_e32 v154, v129, v129
	v_mul_f32_e32 v155, v131, v131
	v_pk_mul_f32 v[138:139], v[132:133], s[38:39] op_sel_hi:[1,0]
	v_pk_mul_f32 v[140:141], v[130:131], s[38:39] op_sel_hi:[1,0]
	v_pk_mul_f32 v[142:143], v[128:129], s[38:39] op_sel_hi:[1,0]
	v_add_f32_e32 v129, v146, v147
	v_add_f32_e32 v131, v148, v149
	v_fmac_f32_e32 v150, v132, v132
	v_fmac_f32_e32 v151, v134, v134
	v_fmac_f32_e32 v154, v128, v128
	v_fmac_f32_e32 v155, v130, v130
	v_med3_f32 v128, v138, s64, v195
	v_add_f32_e32 v129, v129, v131
	v_add_f32_e32 v131, v150, v151
	v_add_f32_e32 v138, v154, v155
	v_med3_f32 v130, v139, s64, v195
	v_add_f32_e32 v131, v131, v138
	v_add_f32_e32 v128, 0x4b400000, v128
	v_add_f32_e32 v130, 0x4b400000, v130
	v_add_f32_e32 v129, v129, v179
	v_add_f32_e32 v131, v181, v131
	v_perm_b32 v128, v130, v128, s65
	v_mov_b32_e32 v130, v129
	s_nop 1
	v_permlane16_swap_b32_e32 v129, v130
	v_mov_b32_e32 v138, v131
	s_nop 1
	v_permlane16_swap_b32_e32 v131, v138
	v_pk_mul_f32 v[136:137], v[134:135], s[38:39] op_sel_hi:[1,0]
	v_med3_f32 v134, v142, s64, v195
	v_med3_f32 v132, v136, s64, v195
	v_med3_f32 v133, v137, s64, v195
	v_add_f32_e32 v132, 0x4b400000, v132
	v_add_f32_e32 v133, 0x4b400000, v133
	v_perm_b32 v132, v133, v132, s66
	v_or_b32_e32 v132, v128, v132
	s_waitcnt lgkmcnt(0)
	v_add_f32_e32 v128, v129, v130
	s_waitcnt lgkmcnt(0)
	v_add_f32_e32 v130, v131, v138
	v_mov_b32_e32 v129, v128
	s_nop 1
	v_permlane32_swap_b32_e32 v128, v129
	v_mov_b32_e32 v131, v130
	s_nop 1
	v_permlane32_swap_b32_e32 v130, v131
	v_med3_f32 v135, v143, s64, v195
	v_med3_f32 v136, v140, s64, v195
	v_med3_f32 v137, v141, s64, v195
	v_add_f32_e32 v134, 0x4b400000, v134
	v_add_f32_e32 v135, 0x4b400000, v135
	v_add_f32_e32 v136, 0x4b400000, v136
	v_add_f32_e32 v137, 0x4b400000, v137
	v_perm_b32 v133, v135, v134, s65
	v_perm_b32 v134, v137, v136, s66
	v_or_b32_e32 v133, v133, v134
	global_store_dwordx2 v[158:159], v[132:133], off offset:128
	s_and_saveexec_b64 s[6:7], s[2:3]
	s_cbranch_execz .LBB0_3865
;     __device__ __forceinline__ void operator()(EPI_ARGS) const {
;         const int row0 = u.pm * BM + wr * 64 + fr, col0 = u.pn * BM + wc * 32 + 8 * fq;
;         f32x4 gg[2][2], bb[2][2];
;         if constexpr (RESLN) {
; #pragma unroll
;             for (int bj = 0; bj < 2; ++bj)
; #pragma unroll
;                 for (int n = 0; n < 2; ++n) { gg[bj][n] = *(const f32x4*)(lg + col0 + bj * HALF + 4 * n); bb[bj][n] = *(const f32x4*)(lb + col0 + bj * HALF + 4 * n); } }
; #pragma unroll
;         for (int ai = 0; ai < 2; ++ai)
; #pragma unroll
;             for (int m = 0; m < 4; ++m) { const int row = row0 + ai * HALF + m * 16; const size_t off = (size_t)row * DM + col0;
;                 float mu = 0.f, rs = 1.f; if constexpr (RESLN) ln_stats(stin, row, mu, rs);
;                 float ss = 0.f, qq = 0.f;
; #pragma unroll
;                 for (int bj = 0; bj < 2; ++bj) { f32x4 r0 = __builtin_nontemporal_load((const f32x4*)(res + off + bj * HALF)), r1 = __builtin_nontemporal_load((const f32x4*)(res + off + bj * HALF + 4));
;                     if constexpr (RESLN) { r0 = (r0 - mu) * rs * gg[bj][0] + bb[bj][0]; r1 = (r1 - mu) * rs * gg[bj][1] + bb[bj][1]; }
;                     const f32x4 y0 = r0 * DN_ALPHA + acc[ai][bj][m][0] * ascale, y1 = r1 * DN_ALPHA + acc[ai][bj][m][1] * ascale;
;                     if constexpr (COPY != 4) { __builtin_nontemporal_store(y0, (f32x4*)(Y + off + bj * HALF)); __builtin_nontemporal_store(y1, (f32x4*)(Y + off + bj * HALF + 4)); }
;                     if constexpr (STATS) { ss += ((y0[0] + y0[1]) + (y0[2] + y0[3])) + ((y1[0] + y1[1]) + (y1[2] + y1[3]));
;                         qq += ((y0[0] * y0[0] + y0[1] * y0[1]) + (y0[2] * y0[2] + y0[3] * y0[3])) + ((y1[0] * y1[0] + y1[1] * y1[1]) + (y1[2] * y1[2] + y1[3] * y1[3])); }
;                     if constexpr (COPY == 1) *(u32x2*)((unsigned char*)copy + off + bj * HALF) = pack8fp8(y0 * cscale, y1 * cscale);
;                     if constexpr (COPY == 3) *(u32x2*)((unsigned char*)copy + off + bj * HALF) = pack8i8(y0 * cscale, y1 * cscale);
;                     if constexpr (COPY == 2 || COPY == 4) *(u32x4*)((bf16_t*)copy + off + bj * HALF) = pack8bf(y0, y1); }
;                 if constexpr (STATS) { ss += __shfl_xor(ss, 16); ss += __shfl_xor(ss, 32); qq += __shfl_xor(qq, 16); qq += __shfl_xor(qq, 32);
	v_lshl_add_u64 v[132:133], s[12:13], 0, v[144:145]
	s_waitcnt lgkmcnt(0)
	v_add_f32_e32 v128, v128, v129
	s_waitcnt lgkmcnt(0)
	v_add_f32_e32 v129, v130, v131
	global_atomic_add_f32 v[132:133], v128, off
	global_atomic_add_f32 v[132:133], v129, off offset:4
.LBB0_3865:
	s_or_b64 exec, exec, s[6:7]
	v_or_b32_e32 v128, 32, v178
	s_waitcnt lgkmcnt(1)
	v_ashrrev_i32_e32 v129, 31, v128
	s_waitcnt lgkmcnt(0)
	v_lshlrev_b64 v[130:131], 11, v[128:129]
	v_lshlrev_b64 v[128:129], 3, v[128:129]
	v_lshl_add_u64 v[140:141], v[130:131], 0, v[176:177]
	v_lshl_add_u64 v[130:131], s[14:15], 0, v[128:129]
	global_load_dwordx2 v[142:143], v[130:131], off
	v_lshl_add_u64 v[130:131], v[140:141], 2, s[18:19]
	global_load_dwordx4 v[132:135], v[130:131], off nt
	global_load_dwordx4 v[136:139], v[130:131], off offset:16 nt
	v_lshl_add_u64 v[140:141], s[20:21], 0, v[140:141]
	s_waitcnt vmcnt(2)
	v_pk_mul_f32 v[142:143], v[142:143], s[28:29] op_sel_hi:[1,0]
	s_nop 0
	v_fma_f32 v143, -v142, v142, v143
	v_add_f32_e32 v143, 0x3727c5ac, v143
	v_rsq_f32_e32 v254, v143
	s_waitcnt vmcnt(1)
	v_sub_f32_e32 v135, v135, v142
	v_sub_f32_e32 v134, v134, v142
	v_sub_f32_e32 v133, v133, v142
	v_sub_f32_e32 v132, v132, v142
	s_waitcnt vmcnt(0)
	v_sub_f32_e32 v139, v139, v142
	v_sub_f32_e32 v138, v138, v142
	v_sub_f32_e32 v137, v137, v142
	v_sub_f32_e32 v136, v136, v142
	s_nop 0
	s_nop 1
	v_mov_b32_e32 v144, v254
	v_pk_mul_f32 v[132:133], v[132:133], v[144:145] op_sel_hi:[1,0]
	v_pk_mul_f32 v[134:135], v[134:135], v[144:145] op_sel_hi:[1,0]
	v_pk_mul_f32 v[136:137], v[136:137], v[144:145] op_sel_hi:[1,0]
	v_pk_mul_f32 v[138:139], v[138:139], v[144:145] op_sel_hi:[1,0]
	v_pk_fma_f32 v[134:135], v[30:31], v[134:135], v[18:19]
	v_pk_fma_f32 v[132:133], v[28:29], v[132:133], v[16:17]
	v_pk_fma_f32 v[138:139], v[22:23], v[138:139], v[26:27]
	v_pk_fma_f32 v[136:137], v[20:21], v[136:137], v[24:25]
	v_pk_mul_f32 v[132:133], v[132:133], s[30:31] op_sel_hi:[1,0]
	v_pk_mul_f32 v[134:135], v[134:135], s[30:31] op_sel_hi:[1,0]
	v_pk_mul_f32 v[136:137], v[136:137], s[30:31] op_sel_hi:[1,0]
	v_pk_mul_f32 v[138:139], v[138:139], s[30:31] op_sel_hi:[1,0]
	v_pk_fma_f32 v[126:127], v[126:127], s[36:37], v[134:135] op_sel_hi:[1,0,1]
	v_pk_fma_f32 v[124:125], v[124:125], s[36:37], v[132:133] op_sel_hi:[1,0,1]
	v_pk_fma_f32 v[122:123], v[122:123], s[36:37], v[138:139] op_sel_hi:[1,0,1]
	v_pk_fma_f32 v[120:121], v[120:121], s[36:37], v[136:137] op_sel_hi:[1,0,1]
	v_pk_mul_f32 v[132:133], v[126:127], s[38:39] op_sel_hi:[1,0]
	v_pk_mul_f32 v[134:135], v[124:125], s[38:39] op_sel_hi:[1,0]
	v_pk_mul_f32 v[136:137], v[122:123], s[38:39] op_sel_hi:[1,0]
	v_pk_mul_f32 v[138:139], v[120:121], s[38:39] op_sel_hi:[1,0]
	v_med3_f32 v134, v134, s64, v195
	v_med3_f32 v135, v135, s64, v195
	v_med3_f32 v132, v132, s64, v195
	v_med3_f32 v133, v133, s64, v195
	v_med3_f32 v138, v138, s64, v195
	v_med3_f32 v139, v139, s64, v195
	v_med3_f32 v136, v136, s64, v195
	v_med3_f32 v137, v137, s64, v195
	v_add_f32_e32 v134, 0x4b400000, v134
	v_add_f32_e32 v135, 0x4b400000, v135
	v_add_f32_e32 v132, 0x4b400000, v132
	v_add_f32_e32 v133, 0x4b400000, v133
	v_add_f32_e32 v138, 0x4b400000, v138
	v_add_f32_e32 v139, 0x4b400000, v139
	v_add_f32_e32 v136, 0x4b400000, v136
	v_add_f32_e32 v137, 0x4b400000, v137
	v_perm_b32 v134, v135, v134, s65
	v_perm_b32 v132, v133, v132, s66
	v_perm_b32 v133, v139, v138, s65
	v_perm_b32 v135, v137, v136, s66
	v_or_b32_e32 v132, v134, v132
	v_or_b32_e32 v133, v133, v135
	global_store_dwordx4 v[130:131], v[124:127], off nt
	global_store_dwordx4 v[130:131], v[120:123], off offset:16 nt
	global_store_dwordx2 v[140:141], v[132:133], off
	global_load_dwordx4 v[132:135], v[130:131], off offset:512 nt
	s_nop 0
	global_load_dwordx4 v[136:139], v[130:131], off offset:528 nt
	v_add_f32_e32 v143, v124, v125
	v_add_f32_e32 v145, v126, v127
	v_add_f32_e32 v146, v120, v121
	v_add_f32_e32 v147, v122, v123
	v_mul_f32_e32 v125, v125, v125
	v_mul_f32_e32 v127, v127, v127
	v_mul_f32_e32 v121, v121, v121
	v_mul_f32_e32 v123, v123, v123
	v_add_f32_e32 v143, v143, v145
	v_add_f32_e32 v145, v146, v147
	v_fmac_f32_e32 v125, v124, v124
	v_fmac_f32_e32 v127, v126, v126
	v_fmac_f32_e32 v121, v120, v120
	v_fmac_f32_e32 v123, v122, v122
	v_add_f32_e32 v120, v143, v145
	v_add_f32_e32 v122, v125, v127
	v_add_f32_e32 v121, v121, v123
	v_add_f32_e32 v143, 0, v120
	v_add_f32_e32 v145, v122, v121
	s_waitcnt vmcnt(1)
	v_sub_f32_e32 v121, v135, v142
	v_sub_f32_e32 v120, v134, v142
	v_sub_f32_e32 v123, v133, v142
	v_sub_f32_e32 v122, v132, v142
	s_waitcnt vmcnt(0)
;     __device__ __forceinline__ void operator()(EPI_ARGS) const {
;         const int row0 = u.pm * BM + wr * 64 + fr, col0 = u.pn * BM + wc * 32 + 8 * fq;
;         f32x4 gg[2][2], bb[2][2];
;         if constexpr (RESLN) {
; #pragma unroll
;             for (int bj = 0; bj < 2; ++bj)
; #pragma unroll
;                 for (int n = 0; n < 2; ++n) { gg[bj][n] = *(const f32x4*)(lg + col0 + bj * HALF + 4 * n); bb[bj][n] = *(const f32x4*)(lb + col0 + bj * HALF + 4 * n); } }
; #pragma unroll
;         for (int ai = 0; ai < 2; ++ai)
; #pragma unroll
;             for (int m = 0; m < 4; ++m) { const int row = row0 + ai * HALF + m * 16; const size_t off = (size_t)row * DM + col0;
;                 float mu = 0.f, rs = 1.f; if constexpr (RESLN) ln_stats(stin, row, mu, rs);
;                 float ss = 0.f, qq = 0.f;
; #pragma unroll
;                 for (int bj = 0; bj < 2; ++bj) { f32x4 r0 = __builtin_nontemporal_load((const f32x4*)(res + off + bj * HALF)), r1 = __builtin_nontemporal_load((const f32x4*)(res + off + bj * HALF + 4));
;                     if constexpr (RESLN) { r0 = (r0 - mu) * rs * gg[bj][0] + bb[bj][0]; r1 = (r1 - mu) * rs * gg[bj][1] + bb[bj][1]; }
;                     const f32x4 y0 = r0 * DN_ALPHA + acc[ai][bj][m][0] * ascale, y1 = r1 * DN_ALPHA + acc[ai][bj][m][1] * ascale;
;                     if constexpr (COPY != 4) { __builtin_nontemporal_store(y0, (f32x4*)(Y + off + bj * HALF)); __builtin_nontemporal_store(y1, (f32x4*)(Y + off + bj * HALF + 4)); }
;                     if constexpr (STATS) { ss += ((y0[0] + y0[1]) + (y0[2] + y0[3])) + ((y1[0] + y1[1]) + (y1[2] + y1[3]));
;                         qq += ((y0[0] * y0[0] + y0[1] * y0[1]) + (y0[2] * y0[2] + y0[3] * y0[3])) + ((y1[0] * y1[0] + y1[1] * y1[1]) + (y1[2] * y1[2] + y1[3] * y1[3])); }
;                     if constexpr (COPY == 1) *(u32x2*)((unsigned char*)copy + off + bj * HALF) = pack8fp8(y0 * cscale, y1 * cscale);
;                     if constexpr (COPY == 3) *(u32x2*)((unsigned char*)copy + off + bj * HALF) = pack8i8(y0 * cscale, y1 * cscale);
;                     if constexpr (COPY == 2 || COPY == 4) *(u32x4*)((bf16_t*)copy + off + bj * HALF) = pack8bf(y0, y1); }
;                 if constexpr (STATS) { ss += __shfl_xor(ss, 16); ss += __shfl_xor(ss, 32); qq += __shfl_xor(qq, 16); qq += __shfl_xor(qq, 32);
	v_sub_f32_e32 v125, v139, v142
	v_sub_f32_e32 v124, v138, v142
	v_sub_f32_e32 v127, v137, v142
	v_sub_f32_e32 v126, v136, v142
	v_pk_mul_f32 v[122:123], v[122:123], v[144:145] op_sel_hi:[1,0]
	v_pk_mul_f32 v[120:121], v[120:121], v[144:145] op_sel_hi:[1,0]
	v_pk_mul_f32 v[126:127], v[126:127], v[144:145] op_sel_hi:[1,0]
	v_pk_mul_f32 v[124:125], v[124:125], v[144:145] op_sel_hi:[1,0]
	v_pk_fma_f32 v[120:121], v[10:11], v[120:121], v[14:15]
	v_pk_fma_f32 v[122:123], v[8:9], v[122:123], v[12:13]
	v_pk_fma_f32 v[124:125], v[2:3], v[124:125], v[6:7]
	v_pk_fma_f32 v[126:127], v[0:1], v[126:127], v[4:5]
	v_pk_mul_f32 v[122:123], v[122:123], s[30:31] op_sel_hi:[1,0]
	v_pk_mul_f32 v[120:121], v[120:121], s[30:31] op_sel_hi:[1,0]
	v_pk_mul_f32 v[126:127], v[126:127], s[30:31] op_sel_hi:[1,0]
	v_pk_mul_f32 v[124:125], v[124:125], s[30:31] op_sel_hi:[1,0]
	v_pk_fma_f32 v[118:119], v[118:119], s[36:37], v[120:121] op_sel_hi:[1,0,1]
	v_pk_fma_f32 v[116:117], v[116:117], s[36:37], v[122:123] op_sel_hi:[1,0,1]
	v_pk_fma_f32 v[114:115], v[114:115], s[36:37], v[124:125] op_sel_hi:[1,0,1]
	v_pk_fma_f32 v[112:113], v[112:113], s[36:37], v[126:127] op_sel_hi:[1,0,1]
	global_store_dwordx4 v[130:131], v[116:119], off offset:512 nt
	global_store_dwordx4 v[130:131], v[112:115], off offset:528 nt
	v_add_f32_e32 v130, v116, v117
	v_add_f32_e32 v131, v118, v119
	v_add_f32_e32 v132, v112, v113
	v_add_f32_e32 v133, v114, v115
	v_mul_f32_e32 v134, v117, v117
	v_mul_f32_e32 v135, v119, v119
	v_mul_f32_e32 v136, v113, v113
	v_mul_f32_e32 v137, v115, v115
	v_pk_mul_f32 v[122:123], v[116:117], s[38:39] op_sel_hi:[1,0]
	v_pk_mul_f32 v[124:125], v[114:115], s[38:39] op_sel_hi:[1,0]
	v_pk_mul_f32 v[126:127], v[112:113], s[38:39] op_sel_hi:[1,0]
	v_add_f32_e32 v113, v130, v131
	v_add_f32_e32 v115, v132, v133
	v_fmac_f32_e32 v134, v116, v116
	v_fmac_f32_e32 v135, v118, v118
	v_fmac_f32_e32 v136, v112, v112
	v_fmac_f32_e32 v137, v114, v114
	v_med3_f32 v112, v122, s64, v195
	v_add_f32_e32 v113, v113, v115
	v_add_f32_e32 v115, v134, v135
	v_add_f32_e32 v122, v136, v137
	v_med3_f32 v114, v123, s64, v195
	v_add_f32_e32 v115, v115, v122
	v_add_f32_e32 v112, 0x4b400000, v112
	v_add_f32_e32 v114, 0x4b400000, v114
	v_add_f32_e32 v113, v113, v143
	v_add_f32_e32 v115, v145, v115
	v_perm_b32 v112, v114, v112, s65
	v_mov_b32_e32 v114, v113
	s_nop 1
	v_permlane16_swap_b32_e32 v113, v114
	v_mov_b32_e32 v122, v115
	s_nop 1
	v_permlane16_swap_b32_e32 v115, v122
	v_pk_mul_f32 v[120:121], v[118:119], s[38:39] op_sel_hi:[1,0]
	v_med3_f32 v118, v126, s64, v195
	v_med3_f32 v116, v120, s64, v195
	v_med3_f32 v117, v121, s64, v195
	v_add_f32_e32 v116, 0x4b400000, v116
	v_add_f32_e32 v117, 0x4b400000, v117
	v_perm_b32 v116, v117, v116, s66
	v_or_b32_e32 v116, v112, v116
	s_waitcnt lgkmcnt(0)
	v_add_f32_e32 v112, v113, v114
	s_waitcnt lgkmcnt(0)
	v_add_f32_e32 v114, v115, v122
	v_mov_b32_e32 v113, v112
	s_nop 1
	v_permlane32_swap_b32_e32 v112, v113
	v_mov_b32_e32 v115, v114
	s_nop 1
	v_permlane32_swap_b32_e32 v114, v115
	v_med3_f32 v119, v127, s64, v195
	v_med3_f32 v120, v124, s64, v195
	v_med3_f32 v121, v125, s64, v195
	v_add_f32_e32 v118, 0x4b400000, v118
	v_add_f32_e32 v119, 0x4b400000, v119
	v_add_f32_e32 v120, 0x4b400000, v120
	v_add_f32_e32 v121, 0x4b400000, v121
	v_perm_b32 v117, v119, v118, s65
	v_perm_b32 v118, v121, v120, s66
	v_or_b32_e32 v117, v117, v118
	global_store_dwordx2 v[140:141], v[116:117], off offset:128
	s_and_saveexec_b64 s[6:7], s[2:3]
	s_cbranch_execz .LBB0_3867
	v_lshl_add_u64 v[116:117], s[12:13], 0, v[128:129]
	s_waitcnt lgkmcnt(0)
	v_add_f32_e32 v112, v112, v113
	s_waitcnt lgkmcnt(0)
	v_add_f32_e32 v113, v114, v115
	global_atomic_add_f32 v[116:117], v112, off
	global_atomic_add_f32 v[116:117], v113, off offset:4
.LBB0_3867:
	s_or_b64 exec, exec, s[6:7]
	v_or_b32_e32 v112, 48, v178
	s_waitcnt lgkmcnt(1)
	v_ashrrev_i32_e32 v113, 31, v112
	s_waitcnt lgkmcnt(0)
	v_lshlrev_b64 v[114:115], 11, v[112:113]
	v_lshlrev_b64 v[112:113], 3, v[112:113]
	v_lshl_add_u64 v[124:125], v[114:115], 0, v[176:177]
	v_lshl_add_u64 v[114:115], s[14:15], 0, v[112:113]
	global_load_dwordx2 v[126:127], v[114:115], off
	v_lshl_add_u64 v[114:115], v[124:125], 2, s[18:19]
	global_load_dwordx4 v[116:119], v[114:115], off nt
	global_load_dwordx4 v[120:123], v[114:115], off offset:16 nt
	v_lshl_add_u64 v[124:125], s[20:21], 0, v[124:125]
	s_waitcnt vmcnt(2)
	v_pk_mul_f32 v[126:127], v[126:127], s[28:29] op_sel_hi:[1,0]
	s_nop 0
	v_fma_f32 v127, -v126, v126, v127
	v_add_f32_e32 v127, 0x3727c5ac, v127
	v_rsq_f32_e32 v254, v127
	s_waitcnt vmcnt(1)
	v_sub_f32_e32 v119, v119, v126
	v_sub_f32_e32 v118, v118, v126
	v_sub_f32_e32 v117, v117, v126
	v_sub_f32_e32 v116, v116, v126
	s_waitcnt vmcnt(0)
;     __device__ __forceinline__ void operator()(EPI_ARGS) const {
;         const int row0 = u.pm * BM + wr * 64 + fr, col0 = u.pn * BM + wc * 32 + 8 * fq;
;         f32x4 gg[2][2], bb[2][2];
;         if constexpr (RESLN) {
; #pragma unroll
;             for (int bj = 0; bj < 2; ++bj)
; #pragma unroll
;                 for (int n = 0; n < 2; ++n) { gg[bj][n] = *(const f32x4*)(lg + col0 + bj * HALF + 4 * n); bb[bj][n] = *(const f32x4*)(lb + col0 + bj * HALF + 4 * n); } }
; #pragma unroll
;         for (int ai = 0; ai < 2; ++ai)
; #pragma unroll
;             for (int m = 0; m < 4; ++m) { const int row = row0 + ai * HALF + m * 16; const size_t off = (size_t)row * DM + col0;
;                 float mu = 0.f, rs = 1.f; if constexpr (RESLN) ln_stats(stin, row, mu, rs);
;                 float ss = 0.f, qq = 0.f;
; #pragma unroll
;                 for (int bj = 0; bj < 2; ++bj) { f32x4 r0 = __builtin_nontemporal_load((const f32x4*)(res + off + bj * HALF)), r1 = __builtin_nontemporal_load((const f32x4*)(res + off + bj * HALF + 4));
;                     if constexpr (RESLN) { r0 = (r0 - mu) * rs * gg[bj][0] + bb[bj][0]; r1 = (r1 - mu) * rs * gg[bj][1] + bb[bj][1]; }
;                     const f32x4 y0 = r0 * DN_ALPHA + acc[ai][bj][m][0] * ascale, y1 = r1 * DN_ALPHA + acc[ai][bj][m][1] * ascale;
;                     if constexpr (COPY != 4) { __builtin_nontemporal_store(y0, (f32x4*)(Y + off + bj * HALF)); __builtin_nontemporal_store(y1, (f32x4*)(Y + off + bj * HALF + 4)); }
;                     if constexpr (STATS) { ss += ((y0[0] + y0[1]) + (y0[2] + y0[3])) + ((y1[0] + y1[1]) + (y1[2] + y1[3]));
;                         qq += ((y0[0] * y0[0] + y0[1] * y0[1]) + (y0[2] * y0[2] + y0[3] * y0[3])) + ((y1[0] * y1[0] + y1[1] * y1[1]) + (y1[2] * y1[2] + y1[3] * y1[3])); }
;                     if constexpr (COPY == 1) *(u32x2*)((unsigned char*)copy + off + bj * HALF) = pack8fp8(y0 * cscale, y1 * cscale);
;                     if constexpr (COPY == 3) *(u32x2*)((unsigned char*)copy + off + bj * HALF) = pack8i8(y0 * cscale, y1 * cscale);
;                     if constexpr (COPY == 2 || COPY == 4) *(u32x4*)((bf16_t*)copy + off + bj * HALF) = pack8bf(y0, y1); }
;                 if constexpr (STATS) { ss += __shfl_xor(ss, 16); ss += __shfl_xor(ss, 32); qq += __shfl_xor(qq, 16); qq += __shfl_xor(qq, 32);
	v_sub_f32_e32 v123, v123, v126
	v_sub_f32_e32 v122, v122, v126
	v_sub_f32_e32 v121, v121, v126
	v_sub_f32_e32 v120, v120, v126
	s_nop 0
	s_nop 1
	v_mov_b32_e32 v128, v254
	v_pk_mul_f32 v[116:117], v[116:117], v[128:129] op_sel_hi:[1,0]
	v_pk_mul_f32 v[118:119], v[118:119], v[128:129] op_sel_hi:[1,0]
	v_pk_mul_f32 v[120:121], v[120:121], v[128:129] op_sel_hi:[1,0]
	v_pk_mul_f32 v[122:123], v[122:123], v[128:129] op_sel_hi:[1,0]
	v_pk_fma_f32 v[118:119], v[30:31], v[118:119], v[18:19]
	v_pk_fma_f32 v[116:117], v[28:29], v[116:117], v[16:17]
	v_pk_fma_f32 v[122:123], v[22:23], v[122:123], v[26:27]
	v_pk_fma_f32 v[120:121], v[20:21], v[120:121], v[24:25]
	v_pk_mul_f32 v[116:117], v[116:117], s[30:31] op_sel_hi:[1,0]
	v_pk_mul_f32 v[118:119], v[118:119], s[30:31] op_sel_hi:[1,0]
	v_pk_mul_f32 v[120:121], v[120:121], s[30:31] op_sel_hi:[1,0]
	v_pk_mul_f32 v[122:123], v[122:123], s[30:31] op_sel_hi:[1,0]
	v_pk_fma_f32 v[110:111], v[110:111], s[36:37], v[118:119] op_sel_hi:[1,0,1]
	v_pk_fma_f32 v[108:109], v[108:109], s[36:37], v[116:117] op_sel_hi:[1,0,1]
	v_pk_fma_f32 v[106:107], v[106:107], s[36:37], v[122:123] op_sel_hi:[1,0,1]
	v_pk_fma_f32 v[104:105], v[104:105], s[36:37], v[120:121] op_sel_hi:[1,0,1]
	v_pk_mul_f32 v[116:117], v[110:111], s[38:39] op_sel_hi:[1,0]
	v_pk_mul_f32 v[118:119], v[108:109], s[38:39] op_sel_hi:[1,0]
	v_pk_mul_f32 v[120:121], v[106:107], s[38:39] op_sel_hi:[1,0]
	v_pk_mul_f32 v[122:123], v[104:105], s[38:39] op_sel_hi:[1,0]
	v_med3_f32 v118, v118, s64, v195
	v_med3_f32 v119, v119, s64, v195
	v_med3_f32 v116, v116, s64, v195
	v_med3_f32 v117, v117, s64, v195
	v_med3_f32 v122, v122, s64, v195
	v_med3_f32 v123, v123, s64, v195
	v_med3_f32 v120, v120, s64, v195
	v_med3_f32 v121, v121, s64, v195
	v_add_f32_e32 v118, 0x4b400000, v118
	v_add_f32_e32 v119, 0x4b400000, v119
	v_add_f32_e32 v116, 0x4b400000, v116
	v_add_f32_e32 v117, 0x4b400000, v117
	v_add_f32_e32 v122, 0x4b400000, v122
	v_add_f32_e32 v123, 0x4b400000, v123
	v_add_f32_e32 v120, 0x4b400000, v120
	v_add_f32_e32 v121, 0x4b400000, v121
	v_perm_b32 v118, v119, v118, s65
	v_perm_b32 v116, v117, v116, s66
	v_perm_b32 v117, v123, v122, s65
	v_perm_b32 v119, v121, v120, s66
	v_or_b32_e32 v116, v118, v116
	v_or_b32_e32 v117, v117, v119
	global_store_dwordx4 v[114:115], v[108:111], off nt
	global_store_dwordx4 v[114:115], v[104:107], off offset:16 nt
	global_store_dwordx2 v[124:125], v[116:117], off
	global_load_dwordx4 v[116:119], v[114:115], off offset:512 nt
	s_nop 0
	global_load_dwordx4 v[120:123], v[114:115], off offset:528 nt
	v_add_f32_e32 v127, v108, v109
	v_add_f32_e32 v129, v110, v111
	v_add_f32_e32 v130, v104, v105
	v_add_f32_e32 v131, v106, v107
	v_mul_f32_e32 v109, v109, v109
	v_mul_f32_e32 v111, v111, v111
	v_mul_f32_e32 v105, v105, v105
	v_mul_f32_e32 v107, v107, v107
	v_add_f32_e32 v127, v127, v129
	v_add_f32_e32 v129, v130, v131
	v_fmac_f32_e32 v109, v108, v108
	v_fmac_f32_e32 v111, v110, v110
	v_fmac_f32_e32 v105, v104, v104
	v_fmac_f32_e32 v107, v106, v106
	v_add_f32_e32 v104, v127, v129
	v_add_f32_e32 v106, v109, v111
	v_add_f32_e32 v105, v105, v107
	v_add_f32_e32 v127, 0, v104
	v_add_f32_e32 v129, v106, v105
	s_waitcnt vmcnt(1)
	v_sub_f32_e32 v105, v119, v126
	v_sub_f32_e32 v104, v118, v126
	v_sub_f32_e32 v107, v117, v126
	v_sub_f32_e32 v106, v116, v126
	s_waitcnt vmcnt(0)
	v_sub_f32_e32 v109, v123, v126
	v_sub_f32_e32 v108, v122, v126
	v_sub_f32_e32 v111, v121, v126
	v_sub_f32_e32 v110, v120, v126
	v_pk_mul_f32 v[106:107], v[106:107], v[128:129] op_sel_hi:[1,0]
	v_pk_mul_f32 v[104:105], v[104:105], v[128:129] op_sel_hi:[1,0]
	v_pk_mul_f32 v[110:111], v[110:111], v[128:129] op_sel_hi:[1,0]
	v_pk_mul_f32 v[108:109], v[108:109], v[128:129] op_sel_hi:[1,0]
	v_pk_fma_f32 v[104:105], v[10:11], v[104:105], v[14:15]
	v_pk_fma_f32 v[106:107], v[8:9], v[106:107], v[12:13]
	v_pk_fma_f32 v[108:109], v[2:3], v[108:109], v[6:7]
	v_pk_fma_f32 v[110:111], v[0:1], v[110:111], v[4:5]
	v_pk_mul_f32 v[106:107], v[106:107], s[30:31] op_sel_hi:[1,0]
	v_pk_mul_f32 v[104:105], v[104:105], s[30:31] op_sel_hi:[1,0]
	v_pk_mul_f32 v[110:111], v[110:111], s[30:31] op_sel_hi:[1,0]
	v_pk_mul_f32 v[108:109], v[108:109], s[30:31] op_sel_hi:[1,0]
	v_pk_fma_f32 v[102:103], v[102:103], s[36:37], v[104:105] op_sel_hi:[1,0,1]
	v_pk_fma_f32 v[100:101], v[100:101], s[36:37], v[106:107] op_sel_hi:[1,0,1]
	v_pk_fma_f32 v[98:99], v[98:99], s[36:37], v[108:109] op_sel_hi:[1,0,1]
	v_pk_fma_f32 v[96:97], v[96:97], s[36:37], v[110:111] op_sel_hi:[1,0,1]
	global_store_dwordx4 v[114:115], v[100:103], off offset:512 nt
	global_store_dwordx4 v[114:115], v[96:99], off offset:528 nt
	v_add_f32_e32 v114, v100, v101
	v_add_f32_e32 v115, v102, v103
	v_add_f32_e32 v116, v96, v97
	v_add_f32_e32 v117, v98, v99
	v_mul_f32_e32 v118, v101, v101
	v_mul_f32_e32 v119, v103, v103
	v_mul_f32_e32 v120, v97, v97
	v_mul_f32_e32 v121, v99, v99
	v_pk_mul_f32 v[106:107], v[100:101], s[38:39] op_sel_hi:[1,0]
	v_pk_mul_f32 v[108:109], v[98:99], s[38:39] op_sel_hi:[1,0]
	v_pk_mul_f32 v[110:111], v[96:97], s[38:39] op_sel_hi:[1,0]
	v_add_f32_e32 v97, v114, v115
	v_add_f32_e32 v99, v116, v117
	v_fmac_f32_e32 v118, v100, v100
	v_fmac_f32_e32 v119, v102, v102
	v_fmac_f32_e32 v120, v96, v96
	v_fmac_f32_e32 v121, v98, v98
	v_med3_f32 v96, v106, s64, v195
	v_add_f32_e32 v97, v97, v99
	v_add_f32_e32 v99, v118, v119
	v_add_f32_e32 v106, v120, v121
	v_med3_f32 v98, v107, s64, v195
	v_add_f32_e32 v99, v99, v106
	v_add_f32_e32 v96, 0x4b400000, v96
	v_add_f32_e32 v98, 0x4b400000, v98
	v_add_f32_e32 v97, v97, v127
	v_add_f32_e32 v99, v129, v99
	v_perm_b32 v96, v98, v96, s65
	v_mov_b32_e32 v98, v97
	s_nop 1
	v_permlane16_swap_b32_e32 v97, v98
	v_mov_b32_e32 v106, v99
	s_nop 1
	v_permlane16_swap_b32_e32 v99, v106
	v_pk_mul_f32 v[104:105], v[102:103], s[38:39] op_sel_hi:[1,0]
	v_med3_f32 v102, v110, s64, v195
	v_med3_f32 v100, v104, s64, v195
	v_med3_f32 v101, v105, s64, v195
	v_add_f32_e32 v100, 0x4b400000, v100
	v_add_f32_e32 v101, 0x4b400000, v101
	v_perm_b32 v100, v101, v100, s66
	v_or_b32_e32 v100, v96, v100
	s_waitcnt lgkmcnt(0)
	v_add_f32_e32 v96, v97, v98
	s_waitcnt lgkmcnt(0)
	v_add_f32_e32 v98, v99, v106
	v_mov_b32_e32 v97, v96
	s_nop 1
	v_permlane32_swap_b32_e32 v96, v97
	v_mov_b32_e32 v99, v98
	s_nop 1
	v_permlane32_swap_b32_e32 v98, v99
	v_med3_f32 v103, v111, s64, v195
	v_med3_f32 v104, v108, s64, v195
	v_med3_f32 v105, v109, s64, v195
	v_add_f32_e32 v102, 0x4b400000, v102
	v_add_f32_e32 v103, 0x4b400000, v103
	v_add_f32_e32 v104, 0x4b400000, v104
	v_add_f32_e32 v105, 0x4b400000, v105
	v_perm_b32 v101, v103, v102, s65
	v_perm_b32 v102, v105, v104, s66
	v_or_b32_e32 v101, v101, v102
	global_store_dwordx2 v[124:125], v[100:101], off offset:128
	s_and_saveexec_b64 s[6:7], s[2:3]
	s_cbranch_execz .LBB0_3869
	v_lshl_add_u64 v[100:101], s[12:13], 0, v[112:113]
	s_waitcnt lgkmcnt(0)
	v_add_f32_e32 v96, v96, v97
	s_waitcnt lgkmcnt(0)
	v_add_f32_e32 v97, v98, v99
	global_atomic_add_f32 v[100:101], v96, off
	global_atomic_add_f32 v[100:101], v97, off offset:4
;     __device__ __forceinline__ void operator()(EPI_ARGS) const {
;         const int row0 = u.pm * BM + wr * 64 + fr, col0 = u.pn * BM + wc * 32 + 8 * fq;
;         f32x4 gg[2][2], bb[2][2];
;         if constexpr (RESLN) {
; #pragma unroll
;             for (int bj = 0; bj < 2; ++bj)
; #pragma unroll
;                 for (int n = 0; n < 2; ++n) { gg[bj][n] = *(const f32x4*)(lg + col0 + bj * HALF + 4 * n); bb[bj][n] = *(const f32x4*)(lb + col0 + bj * HALF + 4 * n); } }
; #pragma unroll
;         for (int ai = 0; ai < 2; ++ai)
; #pragma unroll
;             for (int m = 0; m < 4; ++m) { const int row = row0 + ai * HALF + m * 16; const size_t off = (size_t)row * DM + col0;
;                 float mu = 0.f, rs = 1.f; if constexpr (RESLN) ln_stats(stin, row, mu, rs);
;                 float ss = 0.f, qq = 0.f;
; #pragma unroll
;                 for (int bj = 0; bj < 2; ++bj) { f32x4 r0 = __builtin_nontemporal_load((const f32x4*)(res + off + bj * HALF)), r1 = __builtin_nontemporal_load((const f32x4*)(res + off + bj * HALF + 4));
;                     if constexpr (RESLN) { r0 = (r0 - mu) * rs * gg[bj][0] + bb[bj][0]; r1 = (r1 - mu) * rs * gg[bj][1] + bb[bj][1]; }
;                     const f32x4 y0 = r0 * DN_ALPHA + acc[ai][bj][m][0] * ascale, y1 = r1 * DN_ALPHA + acc[ai][bj][m][1] * ascale;
;                     if constexpr (COPY != 4) { __builtin_nontemporal_store(y0, (f32x4*)(Y + off + bj * HALF)); __builtin_nontemporal_store(y1, (f32x4*)(Y + off + bj * HALF + 4)); }
;                     if constexpr (STATS) { ss += ((y0[0] + y0[1]) + (y0[2] + y0[3])) + ((y1[0] + y1[1]) + (y1[2] + y1[3]));
;                         qq += ((y0[0] * y0[0] + y0[1] * y0[1]) + (y0[2] * y0[2] + y0[3] * y0[3])) + ((y1[0] * y1[0] + y1[1] * y1[1]) + (y1[2] * y1[2] + y1[3] * y1[3])); }
;                     if constexpr (COPY == 1) *(u32x2*)((unsigned char*)copy + off + bj * HALF) = pack8fp8(y0 * cscale, y1 * cscale);
;                     if constexpr (COPY == 3) *(u32x2*)((unsigned char*)copy + off + bj * HALF) = pack8i8(y0 * cscale, y1 * cscale);
;                     if constexpr (COPY == 2 || COPY == 4) *(u32x4*)((bf16_t*)copy + off + bj * HALF) = pack8bf(y0, y1); }
;                 if constexpr (STATS) { ss += __shfl_xor(ss, 16); ss += __shfl_xor(ss, 32); qq += __shfl_xor(qq, 16); qq += __shfl_xor(qq, 32);
.LBB0_3869:
	s_or_b64 exec, exec, s[6:7]
	v_add_u32_e32 v96, 0x80, v178
	s_waitcnt lgkmcnt(1)
	v_ashrrev_i32_e32 v97, 31, v96
	s_waitcnt lgkmcnt(0)
	v_lshlrev_b64 v[98:99], 11, v[96:97]
	v_lshlrev_b64 v[96:97], 3, v[96:97]
	v_lshl_add_u64 v[108:109], v[98:99], 0, v[176:177]
	v_lshl_add_u64 v[98:99], s[14:15], 0, v[96:97]
	global_load_dwordx2 v[110:111], v[98:99], off
	v_lshl_add_u64 v[98:99], v[108:109], 2, s[18:19]
	global_load_dwordx4 v[100:103], v[98:99], off nt
	global_load_dwordx4 v[104:107], v[98:99], off offset:16 nt
	v_lshl_add_u64 v[108:109], s[20:21], 0, v[108:109]
	s_waitcnt vmcnt(2)
	v_pk_mul_f32 v[110:111], v[110:111], s[28:29] op_sel_hi:[1,0]
	s_nop 0
	v_fma_f32 v111, -v110, v110, v111
	v_add_f32_e32 v111, 0x3727c5ac, v111
	v_rsq_f32_e32 v254, v111
	s_waitcnt vmcnt(1)
	v_sub_f32_e32 v103, v103, v110
	v_sub_f32_e32 v102, v102, v110
	v_sub_f32_e32 v101, v101, v110
	v_sub_f32_e32 v100, v100, v110
	s_waitcnt vmcnt(0)
	v_sub_f32_e32 v107, v107, v110
	v_sub_f32_e32 v106, v106, v110
	v_sub_f32_e32 v105, v105, v110
	v_sub_f32_e32 v104, v104, v110
	s_nop 0
	s_nop 1
	v_mov_b32_e32 v112, v254
	v_pk_mul_f32 v[100:101], v[100:101], v[112:113] op_sel_hi:[1,0]
	v_pk_mul_f32 v[102:103], v[102:103], v[112:113] op_sel_hi:[1,0]
	v_pk_mul_f32 v[104:105], v[104:105], v[112:113] op_sel_hi:[1,0]
	v_pk_mul_f32 v[106:107], v[106:107], v[112:113] op_sel_hi:[1,0]
	v_pk_fma_f32 v[102:103], v[30:31], v[102:103], v[18:19]
	v_pk_fma_f32 v[100:101], v[28:29], v[100:101], v[16:17]
	v_pk_fma_f32 v[106:107], v[22:23], v[106:107], v[26:27]
	v_pk_fma_f32 v[104:105], v[20:21], v[104:105], v[24:25]
	v_pk_mul_f32 v[100:101], v[100:101], s[30:31] op_sel_hi:[1,0]
	v_pk_mul_f32 v[102:103], v[102:103], s[30:31] op_sel_hi:[1,0]
	v_pk_mul_f32 v[104:105], v[104:105], s[30:31] op_sel_hi:[1,0]
	v_pk_mul_f32 v[106:107], v[106:107], s[30:31] op_sel_hi:[1,0]
	v_pk_fma_f32 v[94:95], v[94:95], s[36:37], v[102:103] op_sel_hi:[1,0,1]
	v_pk_fma_f32 v[92:93], v[92:93], s[36:37], v[100:101] op_sel_hi:[1,0,1]
	v_pk_fma_f32 v[90:91], v[90:91], s[36:37], v[106:107] op_sel_hi:[1,0,1]
	v_pk_fma_f32 v[88:89], v[88:89], s[36:37], v[104:105] op_sel_hi:[1,0,1]
	v_pk_mul_f32 v[100:101], v[94:95], s[38:39] op_sel_hi:[1,0]
	v_pk_mul_f32 v[102:103], v[92:93], s[38:39] op_sel_hi:[1,0]
	v_pk_mul_f32 v[104:105], v[90:91], s[38:39] op_sel_hi:[1,0]
	v_pk_mul_f32 v[106:107], v[88:89], s[38:39] op_sel_hi:[1,0]
	v_med3_f32 v102, v102, s64, v195
	v_med3_f32 v103, v103, s64, v195
	v_med3_f32 v100, v100, s64, v195
	v_med3_f32 v101, v101, s64, v195
	v_med3_f32 v106, v106, s64, v195
	v_med3_f32 v107, v107, s64, v195
	v_med3_f32 v104, v104, s64, v195
	v_med3_f32 v105, v105, s64, v195
	v_add_f32_e32 v102, 0x4b400000, v102
	v_add_f32_e32 v103, 0x4b400000, v103
	v_add_f32_e32 v100, 0x4b400000, v100
	v_add_f32_e32 v101, 0x4b400000, v101
	v_add_f32_e32 v106, 0x4b400000, v106
	v_add_f32_e32 v107, 0x4b400000, v107
	v_add_f32_e32 v104, 0x4b400000, v104
	v_add_f32_e32 v105, 0x4b400000, v105
	v_perm_b32 v102, v103, v102, s65
	v_perm_b32 v100, v101, v100, s66
	v_perm_b32 v101, v107, v106, s65
	v_perm_b32 v103, v105, v104, s66
	v_or_b32_e32 v100, v102, v100
	v_or_b32_e32 v101, v101, v103
	global_store_dwordx4 v[98:99], v[92:95], off nt
	global_store_dwordx4 v[98:99], v[88:91], off offset:16 nt
	global_store_dwordx2 v[108:109], v[100:101], off
	global_load_dwordx4 v[100:103], v[98:99], off offset:512 nt
	s_nop 0
	global_load_dwordx4 v[104:107], v[98:99], off offset:528 nt
	v_add_f32_e32 v111, v92, v93
	v_add_f32_e32 v113, v94, v95
	v_add_f32_e32 v114, v88, v89
	v_add_f32_e32 v115, v90, v91
	v_mul_f32_e32 v93, v93, v93
	v_mul_f32_e32 v95, v95, v95
	v_mul_f32_e32 v89, v89, v89
	v_mul_f32_e32 v91, v91, v91
	v_add_f32_e32 v111, v111, v113
	v_add_f32_e32 v113, v114, v115
	v_fmac_f32_e32 v93, v92, v92
	v_fmac_f32_e32 v95, v94, v94
	v_fmac_f32_e32 v89, v88, v88
	v_fmac_f32_e32 v91, v90, v90
	v_add_f32_e32 v88, v111, v113
	v_add_f32_e32 v90, v93, v95
	v_add_f32_e32 v89, v89, v91
	v_add_f32_e32 v111, 0, v88
	v_add_f32_e32 v113, v90, v89
	s_waitcnt vmcnt(1)
	v_sub_f32_e32 v89, v103, v110
	v_sub_f32_e32 v88, v102, v110
	v_sub_f32_e32 v91, v101, v110
	v_sub_f32_e32 v90, v100, v110
	s_waitcnt vmcnt(0)
	v_sub_f32_e32 v93, v107, v110
	v_sub_f32_e32 v92, v106, v110
	v_sub_f32_e32 v95, v105, v110
	v_sub_f32_e32 v94, v104, v110
	v_pk_mul_f32 v[90:91], v[90:91], v[112:113] op_sel_hi:[1,0]
	v_pk_mul_f32 v[88:89], v[88:89], v[112:113] op_sel_hi:[1,0]
	v_pk_mul_f32 v[94:95], v[94:95], v[112:113] op_sel_hi:[1,0]
	v_pk_mul_f32 v[92:93], v[92:93], v[112:113] op_sel_hi:[1,0]
	v_pk_fma_f32 v[88:89], v[10:11], v[88:89], v[14:15]
	v_pk_fma_f32 v[90:91], v[8:9], v[90:91], v[12:13]
	v_pk_fma_f32 v[92:93], v[2:3], v[92:93], v[6:7]
	v_pk_fma_f32 v[94:95], v[0:1], v[94:95], v[4:5]
	v_pk_mul_f32 v[90:91], v[90:91], s[30:31] op_sel_hi:[1,0]
	v_pk_mul_f32 v[88:89], v[88:89], s[30:31] op_sel_hi:[1,0]
	v_pk_mul_f32 v[94:95], v[94:95], s[30:31] op_sel_hi:[1,0]
	v_pk_mul_f32 v[92:93], v[92:93], s[30:31] op_sel_hi:[1,0]
	v_pk_fma_f32 v[86:87], v[86:87], s[36:37], v[88:89] op_sel_hi:[1,0,1]
	v_pk_fma_f32 v[84:85], v[84:85], s[36:37], v[90:91] op_sel_hi:[1,0,1]
	v_pk_fma_f32 v[82:83], v[82:83], s[36:37], v[92:93] op_sel_hi:[1,0,1]
	v_pk_fma_f32 v[80:81], v[80:81], s[36:37], v[94:95] op_sel_hi:[1,0,1]
	global_store_dwordx4 v[98:99], v[84:87], off offset:512 nt
	global_store_dwordx4 v[98:99], v[80:83], off offset:528 nt
	v_add_f32_e32 v98, v84, v85
	v_add_f32_e32 v99, v86, v87
	v_add_f32_e32 v100, v80, v81
	v_add_f32_e32 v101, v82, v83
	v_mul_f32_e32 v102, v85, v85
	v_mul_f32_e32 v103, v87, v87
	v_mul_f32_e32 v104, v81, v81
	v_mul_f32_e32 v105, v83, v83
	v_pk_mul_f32 v[90:91], v[84:85], s[38:39] op_sel_hi:[1,0]
	v_pk_mul_f32 v[92:93], v[82:83], s[38:39] op_sel_hi:[1,0]
	v_pk_mul_f32 v[94:95], v[80:81], s[38:39] op_sel_hi:[1,0]
	v_add_f32_e32 v81, v98, v99
	v_add_f32_e32 v83, v100, v101
	v_fmac_f32_e32 v102, v84, v84
	v_fmac_f32_e32 v103, v86, v86
	v_fmac_f32_e32 v104, v80, v80
	v_fmac_f32_e32 v105, v82, v82
	v_med3_f32 v80, v90, s64, v195
	v_add_f32_e32 v81, v81, v83
	v_add_f32_e32 v83, v102, v103
	v_add_f32_e32 v90, v104, v105
	v_med3_f32 v82, v91, s64, v195
	v_add_f32_e32 v83, v83, v90
	v_add_f32_e32 v80, 0x4b400000, v80
	v_add_f32_e32 v82, 0x4b400000, v82
	v_add_f32_e32 v81, v81, v111
	v_add_f32_e32 v83, v113, v83
	v_perm_b32 v80, v82, v80, s65
	v_mov_b32_e32 v82, v81
	s_nop 1
	v_permlane16_swap_b32_e32 v81, v82
	v_mov_b32_e32 v90, v83
	s_nop 1
	v_permlane16_swap_b32_e32 v83, v90
	v_pk_mul_f32 v[88:89], v[86:87], s[38:39] op_sel_hi:[1,0]
	v_med3_f32 v86, v94, s64, v195
	v_med3_f32 v84, v88, s64, v195
	v_med3_f32 v85, v89, s64, v195
	v_add_f32_e32 v84, 0x4b400000, v84
	v_add_f32_e32 v85, 0x4b400000, v85
	v_perm_b32 v84, v85, v84, s66
	v_or_b32_e32 v84, v80, v84
	s_waitcnt lgkmcnt(0)
;     __device__ __forceinline__ void operator()(EPI_ARGS) const {
;         const int row0 = u.pm * BM + wr * 64 + fr, col0 = u.pn * BM + wc * 32 + 8 * fq;
;         f32x4 gg[2][2], bb[2][2];
;         if constexpr (RESLN) {
; #pragma unroll
;             for (int bj = 0; bj < 2; ++bj)
; #pragma unroll
;                 for (int n = 0; n < 2; ++n) { gg[bj][n] = *(const f32x4*)(lg + col0 + bj * HALF + 4 * n); bb[bj][n] = *(const f32x4*)(lb + col0 + bj * HALF + 4 * n); } }
; #pragma unroll
;         for (int ai = 0; ai < 2; ++ai)
; #pragma unroll
;             for (int m = 0; m < 4; ++m) { const int row = row0 + ai * HALF + m * 16; const size_t off = (size_t)row * DM + col0;
;                 float mu = 0.f, rs = 1.f; if constexpr (RESLN) ln_stats(stin, row, mu, rs);
;                 float ss = 0.f, qq = 0.f;
; #pragma unroll
;                 for (int bj = 0; bj < 2; ++bj) { f32x4 r0 = __builtin_nontemporal_load((const f32x4*)(res + off + bj * HALF)), r1 = __builtin_nontemporal_load((const f32x4*)(res + off + bj * HALF + 4));
;                     if constexpr (RESLN) { r0 = (r0 - mu) * rs * gg[bj][0] + bb[bj][0]; r1 = (r1 - mu) * rs * gg[bj][1] + bb[bj][1]; }
;                     const f32x4 y0 = r0 * DN_ALPHA + acc[ai][bj][m][0] * ascale, y1 = r1 * DN_ALPHA + acc[ai][bj][m][1] * ascale;
;                     if constexpr (COPY != 4) { __builtin_nontemporal_store(y0, (f32x4*)(Y + off + bj * HALF)); __builtin_nontemporal_store(y1, (f32x4*)(Y + off + bj * HALF + 4)); }
;                     if constexpr (STATS) { ss += ((y0[0] + y0[1]) + (y0[2] + y0[3])) + ((y1[0] + y1[1]) + (y1[2] + y1[3]));
;                         qq += ((y0[0] * y0[0] + y0[1] * y0[1]) + (y0[2] * y0[2] + y0[3] * y0[3])) + ((y1[0] * y1[0] + y1[1] * y1[1]) + (y1[2] * y1[2] + y1[3] * y1[3])); }
;                     if constexpr (COPY == 1) *(u32x2*)((unsigned char*)copy + off + bj * HALF) = pack8fp8(y0 * cscale, y1 * cscale);
;                     if constexpr (COPY == 3) *(u32x2*)((unsigned char*)copy + off + bj * HALF) = pack8i8(y0 * cscale, y1 * cscale);
;                     if constexpr (COPY == 2 || COPY == 4) *(u32x4*)((bf16_t*)copy + off + bj * HALF) = pack8bf(y0, y1); }
;                 if constexpr (STATS) { ss += __shfl_xor(ss, 16); ss += __shfl_xor(ss, 32); qq += __shfl_xor(qq, 16); qq += __shfl_xor(qq, 32);
	v_add_f32_e32 v80, v81, v82
	s_waitcnt lgkmcnt(0)
	v_add_f32_e32 v82, v83, v90
	v_mov_b32_e32 v81, v80
	s_nop 1
	v_permlane32_swap_b32_e32 v80, v81
	v_mov_b32_e32 v83, v82
	s_nop 1
	v_permlane32_swap_b32_e32 v82, v83
	v_med3_f32 v87, v95, s64, v195
	v_med3_f32 v88, v92, s64, v195
	v_med3_f32 v89, v93, s64, v195
	v_add_f32_e32 v86, 0x4b400000, v86
	v_add_f32_e32 v87, 0x4b400000, v87
	v_add_f32_e32 v88, 0x4b400000, v88
	v_add_f32_e32 v89, 0x4b400000, v89
	v_perm_b32 v85, v87, v86, s65
	v_perm_b32 v86, v89, v88, s66
	v_or_b32_e32 v85, v85, v86
	global_store_dwordx2 v[108:109], v[84:85], off offset:128
	s_and_saveexec_b64 s[6:7], s[2:3]
	s_cbranch_execz .LBB0_3871
	v_lshl_add_u64 v[84:85], s[12:13], 0, v[96:97]
	s_waitcnt lgkmcnt(0)
	v_add_f32_e32 v80, v80, v81
	s_waitcnt lgkmcnt(0)
	v_add_f32_e32 v81, v82, v83
	global_atomic_add_f32 v[84:85], v80, off
	global_atomic_add_f32 v[84:85], v81, off offset:4
.LBB0_3871:
	s_or_b64 exec, exec, s[6:7]
	v_add_u32_e32 v80, 0x90, v178
	s_waitcnt lgkmcnt(1)
	v_ashrrev_i32_e32 v81, 31, v80
	s_waitcnt lgkmcnt(0)
	v_lshlrev_b64 v[82:83], 11, v[80:81]
	v_lshlrev_b64 v[80:81], 3, v[80:81]
	v_lshl_add_u64 v[92:93], v[82:83], 0, v[176:177]
	v_lshl_add_u64 v[82:83], s[14:15], 0, v[80:81]
	global_load_dwordx2 v[94:95], v[82:83], off
	v_lshl_add_u64 v[82:83], v[92:93], 2, s[18:19]
	global_load_dwordx4 v[84:87], v[82:83], off nt
	global_load_dwordx4 v[88:91], v[82:83], off offset:16 nt
	v_lshl_add_u64 v[92:93], s[20:21], 0, v[92:93]
	s_waitcnt vmcnt(2)
	v_pk_mul_f32 v[94:95], v[94:95], s[28:29] op_sel_hi:[1,0]
	s_nop 0
	v_fma_f32 v95, -v94, v94, v95
	v_add_f32_e32 v95, 0x3727c5ac, v95
	v_rsq_f32_e32 v254, v95
	s_waitcnt vmcnt(1)
	v_sub_f32_e32 v87, v87, v94
	v_sub_f32_e32 v86, v86, v94
	v_sub_f32_e32 v85, v85, v94
	v_sub_f32_e32 v84, v84, v94
	s_waitcnt vmcnt(0)
	v_sub_f32_e32 v91, v91, v94
	v_sub_f32_e32 v90, v90, v94
	v_sub_f32_e32 v89, v89, v94
	v_sub_f32_e32 v88, v88, v94
	s_nop 0
	s_nop 1
	v_mov_b32_e32 v96, v254
	v_pk_mul_f32 v[84:85], v[84:85], v[96:97] op_sel_hi:[1,0]
	v_pk_mul_f32 v[86:87], v[86:87], v[96:97] op_sel_hi:[1,0]
	v_pk_mul_f32 v[88:89], v[88:89], v[96:97] op_sel_hi:[1,0]
	v_pk_mul_f32 v[90:91], v[90:91], v[96:97] op_sel_hi:[1,0]
	v_pk_fma_f32 v[86:87], v[30:31], v[86:87], v[18:19]
	v_pk_fma_f32 v[84:85], v[28:29], v[84:85], v[16:17]
	v_pk_fma_f32 v[90:91], v[22:23], v[90:91], v[26:27]
	v_pk_fma_f32 v[88:89], v[20:21], v[88:89], v[24:25]
	v_pk_mul_f32 v[84:85], v[84:85], s[30:31] op_sel_hi:[1,0]
	v_pk_mul_f32 v[86:87], v[86:87], s[30:31] op_sel_hi:[1,0]
	v_pk_mul_f32 v[88:89], v[88:89], s[30:31] op_sel_hi:[1,0]
	v_pk_mul_f32 v[90:91], v[90:91], s[30:31] op_sel_hi:[1,0]
	v_pk_fma_f32 v[78:79], v[78:79], s[36:37], v[86:87] op_sel_hi:[1,0,1]
	v_pk_fma_f32 v[76:77], v[76:77], s[36:37], v[84:85] op_sel_hi:[1,0,1]
	v_pk_fma_f32 v[74:75], v[74:75], s[36:37], v[90:91] op_sel_hi:[1,0,1]
	v_pk_fma_f32 v[72:73], v[72:73], s[36:37], v[88:89] op_sel_hi:[1,0,1]
	v_pk_mul_f32 v[84:85], v[78:79], s[38:39] op_sel_hi:[1,0]
	v_pk_mul_f32 v[86:87], v[76:77], s[38:39] op_sel_hi:[1,0]
	v_pk_mul_f32 v[88:89], v[74:75], s[38:39] op_sel_hi:[1,0]
	v_pk_mul_f32 v[90:91], v[72:73], s[38:39] op_sel_hi:[1,0]
	v_med3_f32 v86, v86, s64, v195
	v_med3_f32 v87, v87, s64, v195
	v_med3_f32 v84, v84, s64, v195
	v_med3_f32 v85, v85, s64, v195
	v_med3_f32 v90, v90, s64, v195
	v_med3_f32 v91, v91, s64, v195
	v_med3_f32 v88, v88, s64, v195
	v_med3_f32 v89, v89, s64, v195
	v_add_f32_e32 v86, 0x4b400000, v86
	v_add_f32_e32 v87, 0x4b400000, v87
	v_add_f32_e32 v84, 0x4b400000, v84
	v_add_f32_e32 v85, 0x4b400000, v85
	v_add_f32_e32 v90, 0x4b400000, v90
	v_add_f32_e32 v91, 0x4b400000, v91
	v_add_f32_e32 v88, 0x4b400000, v88
	v_add_f32_e32 v89, 0x4b400000, v89
	v_perm_b32 v86, v87, v86, s65
	v_perm_b32 v84, v85, v84, s66
	v_perm_b32 v85, v91, v90, s65
	v_perm_b32 v87, v89, v88, s66
	v_or_b32_e32 v84, v86, v84
	v_or_b32_e32 v85, v85, v87
	global_store_dwordx4 v[82:83], v[76:79], off nt
	global_store_dwordx4 v[82:83], v[72:75], off offset:16 nt
	global_store_dwordx2 v[92:93], v[84:85], off
	global_load_dwordx4 v[84:87], v[82:83], off offset:512 nt
	s_nop 0
	global_load_dwordx4 v[88:91], v[82:83], off offset:528 nt
	v_add_f32_e32 v95, v76, v77
	v_add_f32_e32 v97, v78, v79
	v_add_f32_e32 v98, v72, v73
	v_add_f32_e32 v99, v74, v75
	v_mul_f32_e32 v77, v77, v77
	v_mul_f32_e32 v79, v79, v79
	v_mul_f32_e32 v73, v73, v73
	v_mul_f32_e32 v75, v75, v75
	v_add_f32_e32 v95, v95, v97
	v_add_f32_e32 v97, v98, v99
	v_fmac_f32_e32 v77, v76, v76
	v_fmac_f32_e32 v79, v78, v78
	v_fmac_f32_e32 v73, v72, v72
	v_fmac_f32_e32 v75, v74, v74
	v_add_f32_e32 v72, v95, v97
	v_add_f32_e32 v74, v77, v79
	v_add_f32_e32 v73, v73, v75
	v_add_f32_e32 v95, 0, v72
	v_add_f32_e32 v97, v74, v73
	s_waitcnt vmcnt(1)
	v_sub_f32_e32 v73, v87, v94
	v_sub_f32_e32 v72, v86, v94
	v_sub_f32_e32 v75, v85, v94
	v_sub_f32_e32 v74, v84, v94
	s_waitcnt vmcnt(0)
;     __device__ __forceinline__ void operator()(EPI_ARGS) const {
;         const int row0 = u.pm * BM + wr * 64 + fr, col0 = u.pn * BM + wc * 32 + 8 * fq;
;         f32x4 gg[2][2], bb[2][2];
;         if constexpr (RESLN) {
; #pragma unroll
;             for (int bj = 0; bj < 2; ++bj)
; #pragma unroll
;                 for (int n = 0; n < 2; ++n) { gg[bj][n] = *(const f32x4*)(lg + col0 + bj * HALF + 4 * n); bb[bj][n] = *(const f32x4*)(lb + col0 + bj * HALF + 4 * n); } }
; #pragma unroll
;         for (int ai = 0; ai < 2; ++ai)
; #pragma unroll
;             for (int m = 0; m < 4; ++m) { const int row = row0 + ai * HALF + m * 16; const size_t off = (size_t)row * DM + col0;
;                 float mu = 0.f, rs = 1.f; if constexpr (RESLN) ln_stats(stin, row, mu, rs);
;                 float ss = 0.f, qq = 0.f;
; #pragma unroll
;                 for (int bj = 0; bj < 2; ++bj) { f32x4 r0 = __builtin_nontemporal_load((const f32x4*)(res + off + bj * HALF)), r1 = __builtin_nontemporal_load((const f32x4*)(res + off + bj * HALF + 4));
;                     if constexpr (RESLN) { r0 = (r0 - mu) * rs * gg[bj][0] + bb[bj][0]; r1 = (r1 - mu) * rs * gg[bj][1] + bb[bj][1]; }
;                     const f32x4 y0 = r0 * DN_ALPHA + acc[ai][bj][m][0] * ascale, y1 = r1 * DN_ALPHA + acc[ai][bj][m][1] * ascale;
;                     if constexpr (COPY != 4) { __builtin_nontemporal_store(y0, (f32x4*)(Y + off + bj * HALF)); __builtin_nontemporal_store(y1, (f32x4*)(Y + off + bj * HALF + 4)); }
;                     if constexpr (STATS) { ss += ((y0[0] + y0[1]) + (y0[2] + y0[3])) + ((y1[0] + y1[1]) + (y1[2] + y1[3]));
;                         qq += ((y0[0] * y0[0] + y0[1] * y0[1]) + (y0[2] * y0[2] + y0[3] * y0[3])) + ((y1[0] * y1[0] + y1[1] * y1[1]) + (y1[2] * y1[2] + y1[3] * y1[3])); }
;                     if constexpr (COPY == 1) *(u32x2*)((unsigned char*)copy + off + bj * HALF) = pack8fp8(y0 * cscale, y1 * cscale);
;                     if constexpr (COPY == 3) *(u32x2*)((unsigned char*)copy + off + bj * HALF) = pack8i8(y0 * cscale, y1 * cscale);
;                     if constexpr (COPY == 2 || COPY == 4) *(u32x4*)((bf16_t*)copy + off + bj * HALF) = pack8bf(y0, y1); }
;                 if constexpr (STATS) { ss += __shfl_xor(ss, 16); ss += __shfl_xor(ss, 32); qq += __shfl_xor(qq, 16); qq += __shfl_xor(qq, 32);
	v_sub_f32_e32 v77, v91, v94
	v_sub_f32_e32 v76, v90, v94
	v_sub_f32_e32 v79, v89, v94
	v_sub_f32_e32 v78, v88, v94
	v_pk_mul_f32 v[74:75], v[74:75], v[96:97] op_sel_hi:[1,0]
	v_pk_mul_f32 v[72:73], v[72:73], v[96:97] op_sel_hi:[1,0]
	v_pk_mul_f32 v[78:79], v[78:79], v[96:97] op_sel_hi:[1,0]
	v_pk_mul_f32 v[76:77], v[76:77], v[96:97] op_sel_hi:[1,0]
	v_pk_fma_f32 v[72:73], v[10:11], v[72:73], v[14:15]
	v_pk_fma_f32 v[74:75], v[8:9], v[74:75], v[12:13]
	v_pk_fma_f32 v[76:77], v[2:3], v[76:77], v[6:7]
	v_pk_fma_f32 v[78:79], v[0:1], v[78:79], v[4:5]
	v_pk_mul_f32 v[74:75], v[74:75], s[30:31] op_sel_hi:[1,0]
	v_pk_mul_f32 v[72:73], v[72:73], s[30:31] op_sel_hi:[1,0]
	v_pk_mul_f32 v[78:79], v[78:79], s[30:31] op_sel_hi:[1,0]
	v_pk_mul_f32 v[76:77], v[76:77], s[30:31] op_sel_hi:[1,0]
	v_pk_fma_f32 v[70:71], v[70:71], s[36:37], v[72:73] op_sel_hi:[1,0,1]
	v_pk_fma_f32 v[68:69], v[68:69], s[36:37], v[74:75] op_sel_hi:[1,0,1]
	v_pk_fma_f32 v[66:67], v[66:67], s[36:37], v[76:77] op_sel_hi:[1,0,1]
	v_pk_fma_f32 v[64:65], v[64:65], s[36:37], v[78:79] op_sel_hi:[1,0,1]
	global_store_dwordx4 v[82:83], v[68:71], off offset:512 nt
	global_store_dwordx4 v[82:83], v[64:67], off offset:528 nt
	v_add_f32_e32 v82, v68, v69
	v_add_f32_e32 v83, v70, v71
	v_add_f32_e32 v84, v64, v65
	v_add_f32_e32 v85, v66, v67
	v_mul_f32_e32 v86, v69, v69
	v_mul_f32_e32 v87, v71, v71
	v_mul_f32_e32 v88, v65, v65
	v_mul_f32_e32 v89, v67, v67
	v_pk_mul_f32 v[74:75], v[68:69], s[38:39] op_sel_hi:[1,0]
	v_pk_mul_f32 v[76:77], v[66:67], s[38:39] op_sel_hi:[1,0]
	v_pk_mul_f32 v[78:79], v[64:65], s[38:39] op_sel_hi:[1,0]
	v_add_f32_e32 v65, v82, v83
	v_add_f32_e32 v67, v84, v85
	v_fmac_f32_e32 v86, v68, v68
	v_fmac_f32_e32 v87, v70, v70
	v_fmac_f32_e32 v88, v64, v64
	v_fmac_f32_e32 v89, v66, v66
	v_med3_f32 v64, v74, s64, v195
	v_add_f32_e32 v65, v65, v67
	v_add_f32_e32 v67, v86, v87
	v_add_f32_e32 v74, v88, v89
	v_med3_f32 v66, v75, s64, v195
	v_add_f32_e32 v67, v67, v74
	v_add_f32_e32 v64, 0x4b400000, v64
	v_add_f32_e32 v66, 0x4b400000, v66
	v_add_f32_e32 v65, v65, v95
	v_add_f32_e32 v67, v97, v67
	v_perm_b32 v64, v66, v64, s65
	v_mov_b32_e32 v66, v65
	s_nop 1
	v_permlane16_swap_b32_e32 v65, v66
	v_mov_b32_e32 v74, v67
	s_nop 1
	v_permlane16_swap_b32_e32 v67, v74
	v_pk_mul_f32 v[72:73], v[70:71], s[38:39] op_sel_hi:[1,0]
	v_med3_f32 v70, v78, s64, v195
	v_med3_f32 v68, v72, s64, v195
	v_med3_f32 v69, v73, s64, v195
	v_add_f32_e32 v68, 0x4b400000, v68
	v_add_f32_e32 v69, 0x4b400000, v69
	v_perm_b32 v68, v69, v68, s66
	v_or_b32_e32 v68, v64, v68
	s_waitcnt lgkmcnt(0)
	v_add_f32_e32 v64, v65, v66
	s_waitcnt lgkmcnt(0)
	v_add_f32_e32 v66, v67, v74
	v_mov_b32_e32 v65, v64
	s_nop 1
	v_permlane32_swap_b32_e32 v64, v65
	v_mov_b32_e32 v67, v66
	s_nop 1
	v_permlane32_swap_b32_e32 v66, v67
	v_med3_f32 v71, v79, s64, v195
	v_med3_f32 v72, v76, s64, v195
	v_med3_f32 v73, v77, s64, v195
	v_add_f32_e32 v70, 0x4b400000, v70
	v_add_f32_e32 v71, 0x4b400000, v71
	v_add_f32_e32 v72, 0x4b400000, v72
	v_add_f32_e32 v73, 0x4b400000, v73
	v_perm_b32 v69, v71, v70, s65
	v_perm_b32 v70, v73, v72, s66
	v_or_b32_e32 v69, v69, v70
	global_store_dwordx2 v[92:93], v[68:69], off offset:128
	s_and_saveexec_b64 s[6:7], s[2:3]
	s_cbranch_execz .LBB0_3873
	v_lshl_add_u64 v[68:69], s[12:13], 0, v[80:81]
	s_waitcnt lgkmcnt(0)
	v_add_f32_e32 v64, v64, v65
	s_waitcnt lgkmcnt(0)
	v_add_f32_e32 v65, v66, v67
	global_atomic_add_f32 v[68:69], v64, off
	global_atomic_add_f32 v[68:69], v65, off offset:4
.LBB0_3873:
	s_or_b64 exec, exec, s[6:7]
	v_add_u32_e32 v64, 0xa0, v178
	s_waitcnt lgkmcnt(1)
	v_ashrrev_i32_e32 v65, 31, v64
	s_waitcnt lgkmcnt(0)
	v_lshlrev_b64 v[66:67], 11, v[64:65]
	v_lshlrev_b64 v[64:65], 3, v[64:65]
	v_lshl_add_u64 v[76:77], v[66:67], 0, v[176:177]
	v_lshl_add_u64 v[66:67], s[14:15], 0, v[64:65]
	global_load_dwordx2 v[78:79], v[66:67], off
	v_lshl_add_u64 v[66:67], v[76:77], 2, s[18:19]
	global_load_dwordx4 v[68:71], v[66:67], off nt
	global_load_dwordx4 v[72:75], v[66:67], off offset:16 nt
	v_lshl_add_u64 v[76:77], s[20:21], 0, v[76:77]
	s_waitcnt vmcnt(2)
	v_pk_mul_f32 v[78:79], v[78:79], s[28:29] op_sel_hi:[1,0]
	s_nop 0
	v_fma_f32 v79, -v78, v78, v79
	v_add_f32_e32 v79, 0x3727c5ac, v79
	v_rsq_f32_e32 v254, v79
	s_waitcnt vmcnt(1)
	v_sub_f32_e32 v71, v71, v78
	v_sub_f32_e32 v70, v70, v78
	v_sub_f32_e32 v69, v69, v78
	v_sub_f32_e32 v68, v68, v78
	s_waitcnt vmcnt(0)
;     __device__ __forceinline__ void operator()(EPI_ARGS) const {
;         const int row0 = u.pm * BM + wr * 64 + fr, col0 = u.pn * BM + wc * 32 + 8 * fq;
;         f32x4 gg[2][2], bb[2][2];
;         if constexpr (RESLN) {
; #pragma unroll
;             for (int bj = 0; bj < 2; ++bj)
; #pragma unroll
;                 for (int n = 0; n < 2; ++n) { gg[bj][n] = *(const f32x4*)(lg + col0 + bj * HALF + 4 * n); bb[bj][n] = *(const f32x4*)(lb + col0 + bj * HALF + 4 * n); } }
; #pragma unroll
;         for (int ai = 0; ai < 2; ++ai)
; #pragma unroll
;             for (int m = 0; m < 4; ++m) { const int row = row0 + ai * HALF + m * 16; const size_t off = (size_t)row * DM + col0;
;                 float mu = 0.f, rs = 1.f; if constexpr (RESLN) ln_stats(stin, row, mu, rs);
;                 float ss = 0.f, qq = 0.f;
; #pragma unroll
;                 for (int bj = 0; bj < 2; ++bj) { f32x4 r0 = __builtin_nontemporal_load((const f32x4*)(res + off + bj * HALF)), r1 = __builtin_nontemporal_load((const f32x4*)(res + off + bj * HALF + 4));
;                     if constexpr (RESLN) { r0 = (r0 - mu) * rs * gg[bj][0] + bb[bj][0]; r1 = (r1 - mu) * rs * gg[bj][1] + bb[bj][1]; }
;                     const f32x4 y0 = r0 * DN_ALPHA + acc[ai][bj][m][0] * ascale, y1 = r1 * DN_ALPHA + acc[ai][bj][m][1] * ascale;
;                     if constexpr (COPY != 4) { __builtin_nontemporal_store(y0, (f32x4*)(Y + off + bj * HALF)); __builtin_nontemporal_store(y1, (f32x4*)(Y + off + bj * HALF + 4)); }
;                     if constexpr (STATS) { ss += ((y0[0] + y0[1]) + (y0[2] + y0[3])) + ((y1[0] + y1[1]) + (y1[2] + y1[3]));
;                         qq += ((y0[0] * y0[0] + y0[1] * y0[1]) + (y0[2] * y0[2] + y0[3] * y0[3])) + ((y1[0] * y1[0] + y1[1] * y1[1]) + (y1[2] * y1[2] + y1[3] * y1[3])); }
;                     if constexpr (COPY == 1) *(u32x2*)((unsigned char*)copy + off + bj * HALF) = pack8fp8(y0 * cscale, y1 * cscale);
;                     if constexpr (COPY == 3) *(u32x2*)((unsigned char*)copy + off + bj * HALF) = pack8i8(y0 * cscale, y1 * cscale);
;                     if constexpr (COPY == 2 || COPY == 4) *(u32x4*)((bf16_t*)copy + off + bj * HALF) = pack8bf(y0, y1); }
;                 if constexpr (STATS) { ss += __shfl_xor(ss, 16); ss += __shfl_xor(ss, 32); qq += __shfl_xor(qq, 16); qq += __shfl_xor(qq, 32);
	v_sub_f32_e32 v75, v75, v78
	v_sub_f32_e32 v74, v74, v78
	v_sub_f32_e32 v73, v73, v78
	v_sub_f32_e32 v72, v72, v78
	s_nop 0
	s_nop 1
	v_mov_b32_e32 v80, v254
	v_pk_mul_f32 v[68:69], v[68:69], v[80:81] op_sel_hi:[1,0]
	v_pk_mul_f32 v[70:71], v[70:71], v[80:81] op_sel_hi:[1,0]
	v_pk_mul_f32 v[72:73], v[72:73], v[80:81] op_sel_hi:[1,0]
	v_pk_mul_f32 v[74:75], v[74:75], v[80:81] op_sel_hi:[1,0]
	v_pk_fma_f32 v[70:71], v[30:31], v[70:71], v[18:19]
	v_pk_fma_f32 v[68:69], v[28:29], v[68:69], v[16:17]
	v_pk_fma_f32 v[74:75], v[22:23], v[74:75], v[26:27]
	v_pk_fma_f32 v[72:73], v[20:21], v[72:73], v[24:25]
	v_pk_mul_f32 v[68:69], v[68:69], s[30:31] op_sel_hi:[1,0]
	v_pk_mul_f32 v[70:71], v[70:71], s[30:31] op_sel_hi:[1,0]
	v_pk_mul_f32 v[72:73], v[72:73], s[30:31] op_sel_hi:[1,0]
	v_pk_mul_f32 v[74:75], v[74:75], s[30:31] op_sel_hi:[1,0]
	v_pk_fma_f32 v[62:63], v[62:63], s[36:37], v[70:71] op_sel_hi:[1,0,1]
	v_pk_fma_f32 v[60:61], v[60:61], s[36:37], v[68:69] op_sel_hi:[1,0,1]
	v_pk_fma_f32 v[58:59], v[58:59], s[36:37], v[74:75] op_sel_hi:[1,0,1]
	v_pk_fma_f32 v[56:57], v[56:57], s[36:37], v[72:73] op_sel_hi:[1,0,1]
	v_pk_mul_f32 v[68:69], v[62:63], s[38:39] op_sel_hi:[1,0]
	v_pk_mul_f32 v[70:71], v[60:61], s[38:39] op_sel_hi:[1,0]
	v_pk_mul_f32 v[72:73], v[58:59], s[38:39] op_sel_hi:[1,0]
	v_pk_mul_f32 v[74:75], v[56:57], s[38:39] op_sel_hi:[1,0]
	v_med3_f32 v70, v70, s64, v195
	v_med3_f32 v71, v71, s64, v195
	v_med3_f32 v68, v68, s64, v195
	v_med3_f32 v69, v69, s64, v195
	v_med3_f32 v74, v74, s64, v195
	v_med3_f32 v75, v75, s64, v195
	v_med3_f32 v72, v72, s64, v195
	v_med3_f32 v73, v73, s64, v195
	v_add_f32_e32 v70, 0x4b400000, v70
	v_add_f32_e32 v71, 0x4b400000, v71
	v_add_f32_e32 v68, 0x4b400000, v68
	v_add_f32_e32 v69, 0x4b400000, v69
	v_add_f32_e32 v74, 0x4b400000, v74
	v_add_f32_e32 v75, 0x4b400000, v75
	v_add_f32_e32 v72, 0x4b400000, v72
	v_add_f32_e32 v73, 0x4b400000, v73
	v_perm_b32 v70, v71, v70, s65
	v_perm_b32 v68, v69, v68, s66
	v_perm_b32 v69, v75, v74, s65
	v_perm_b32 v71, v73, v72, s66
	v_or_b32_e32 v68, v70, v68
	v_or_b32_e32 v69, v69, v71
	global_store_dwordx4 v[66:67], v[60:63], off nt
	global_store_dwordx4 v[66:67], v[56:59], off offset:16 nt
	global_store_dwordx2 v[76:77], v[68:69], off
	global_load_dwordx4 v[68:71], v[66:67], off offset:512 nt
	s_nop 0
	global_load_dwordx4 v[72:75], v[66:67], off offset:528 nt
	v_add_f32_e32 v79, v60, v61
	v_add_f32_e32 v81, v62, v63
	v_add_f32_e32 v82, v56, v57
	v_add_f32_e32 v83, v58, v59
	v_mul_f32_e32 v61, v61, v61
	v_mul_f32_e32 v63, v63, v63
	v_mul_f32_e32 v57, v57, v57
	v_mul_f32_e32 v59, v59, v59
	v_add_f32_e32 v79, v79, v81
	v_add_f32_e32 v81, v82, v83
	v_fmac_f32_e32 v61, v60, v60
	v_fmac_f32_e32 v63, v62, v62
	v_fmac_f32_e32 v57, v56, v56
	v_fmac_f32_e32 v59, v58, v58
	v_add_f32_e32 v56, v79, v81
	v_add_f32_e32 v58, v61, v63
	v_add_f32_e32 v57, v57, v59
	v_add_f32_e32 v79, 0, v56
	v_add_f32_e32 v81, v58, v57
	s_waitcnt vmcnt(1)
	v_sub_f32_e32 v57, v71, v78
	v_sub_f32_e32 v56, v70, v78
	v_sub_f32_e32 v59, v69, v78
	v_sub_f32_e32 v58, v68, v78
	s_waitcnt vmcnt(0)
	v_sub_f32_e32 v61, v75, v78
	v_sub_f32_e32 v60, v74, v78
	v_sub_f32_e32 v63, v73, v78
	v_sub_f32_e32 v62, v72, v78
	v_pk_mul_f32 v[58:59], v[58:59], v[80:81] op_sel_hi:[1,0]
	v_pk_mul_f32 v[56:57], v[56:57], v[80:81] op_sel_hi:[1,0]
	v_pk_mul_f32 v[62:63], v[62:63], v[80:81] op_sel_hi:[1,0]
	v_pk_mul_f32 v[60:61], v[60:61], v[80:81] op_sel_hi:[1,0]
	v_pk_fma_f32 v[56:57], v[10:11], v[56:57], v[14:15]
	v_pk_fma_f32 v[58:59], v[8:9], v[58:59], v[12:13]
	v_pk_fma_f32 v[60:61], v[2:3], v[60:61], v[6:7]
	v_pk_fma_f32 v[62:63], v[0:1], v[62:63], v[4:5]
	v_pk_mul_f32 v[58:59], v[58:59], s[30:31] op_sel_hi:[1,0]
	v_pk_mul_f32 v[56:57], v[56:57], s[30:31] op_sel_hi:[1,0]
	v_pk_mul_f32 v[62:63], v[62:63], s[30:31] op_sel_hi:[1,0]
	v_pk_mul_f32 v[60:61], v[60:61], s[30:31] op_sel_hi:[1,0]
	v_pk_fma_f32 v[54:55], v[54:55], s[36:37], v[56:57] op_sel_hi:[1,0,1]
	v_pk_fma_f32 v[52:53], v[52:53], s[36:37], v[58:59] op_sel_hi:[1,0,1]
	v_pk_fma_f32 v[50:51], v[50:51], s[36:37], v[60:61] op_sel_hi:[1,0,1]
	v_pk_fma_f32 v[48:49], v[48:49], s[36:37], v[62:63] op_sel_hi:[1,0,1]
	global_store_dwordx4 v[66:67], v[52:55], off offset:512 nt
	global_store_dwordx4 v[66:67], v[48:51], off offset:528 nt
	v_add_f32_e32 v66, v52, v53
	v_add_f32_e32 v67, v54, v55
	v_add_f32_e32 v68, v48, v49
	v_add_f32_e32 v69, v50, v51
	v_mul_f32_e32 v70, v53, v53
	v_mul_f32_e32 v71, v55, v55
	v_mul_f32_e32 v72, v49, v49
	v_mul_f32_e32 v73, v51, v51
	v_pk_mul_f32 v[58:59], v[52:53], s[38:39] op_sel_hi:[1,0]
	v_pk_mul_f32 v[60:61], v[50:51], s[38:39] op_sel_hi:[1,0]
	v_pk_mul_f32 v[62:63], v[48:49], s[38:39] op_sel_hi:[1,0]
	v_add_f32_e32 v49, v66, v67
	v_add_f32_e32 v51, v68, v69
	v_fmac_f32_e32 v70, v52, v52
	v_fmac_f32_e32 v71, v54, v54
	v_fmac_f32_e32 v72, v48, v48
	v_fmac_f32_e32 v73, v50, v50
	v_med3_f32 v48, v58, s64, v195
	v_add_f32_e32 v49, v49, v51
	v_add_f32_e32 v51, v70, v71
	v_add_f32_e32 v58, v72, v73
	v_med3_f32 v50, v59, s64, v195
	v_add_f32_e32 v51, v51, v58
	v_add_f32_e32 v48, 0x4b400000, v48
	v_add_f32_e32 v50, 0x4b400000, v50
	v_add_f32_e32 v49, v49, v79
	v_add_f32_e32 v51, v81, v51
	v_perm_b32 v48, v50, v48, s65
	v_mov_b32_e32 v50, v49
	s_nop 1
	v_permlane16_swap_b32_e32 v49, v50
	v_mov_b32_e32 v58, v51
	s_nop 1
	v_permlane16_swap_b32_e32 v51, v58
	v_pk_mul_f32 v[56:57], v[54:55], s[38:39] op_sel_hi:[1,0]
	v_med3_f32 v54, v62, s64, v195
	v_med3_f32 v52, v56, s64, v195
	v_med3_f32 v53, v57, s64, v195
	v_add_f32_e32 v52, 0x4b400000, v52
	v_add_f32_e32 v53, 0x4b400000, v53
	v_perm_b32 v52, v53, v52, s66
	v_or_b32_e32 v52, v48, v52
	s_waitcnt lgkmcnt(0)
	v_add_f32_e32 v48, v49, v50
	s_waitcnt lgkmcnt(0)
	v_add_f32_e32 v50, v51, v58
	v_mov_b32_e32 v49, v48
	s_nop 1
	v_permlane32_swap_b32_e32 v48, v49
	v_mov_b32_e32 v51, v50
	s_nop 1
	v_permlane32_swap_b32_e32 v50, v51
	v_med3_f32 v55, v63, s64, v195
	v_med3_f32 v56, v60, s64, v195
	v_med3_f32 v57, v61, s64, v195
	v_add_f32_e32 v54, 0x4b400000, v54
	v_add_f32_e32 v55, 0x4b400000, v55
	v_add_f32_e32 v56, 0x4b400000, v56
	v_add_f32_e32 v57, 0x4b400000, v57
	v_perm_b32 v53, v55, v54, s65
	v_perm_b32 v54, v57, v56, s66
	v_or_b32_e32 v53, v53, v54
	global_store_dwordx2 v[76:77], v[52:53], off offset:128
	s_and_saveexec_b64 s[6:7], s[2:3]
	s_cbranch_execz .LBB0_3875
	v_lshl_add_u64 v[52:53], s[12:13], 0, v[64:65]
	s_waitcnt lgkmcnt(0)
	v_add_f32_e32 v48, v48, v49
	s_waitcnt lgkmcnt(0)
	v_add_f32_e32 v49, v50, v51
	global_atomic_add_f32 v[52:53], v48, off
	global_atomic_add_f32 v[52:53], v49, off offset:4
;     __device__ __forceinline__ void operator()(EPI_ARGS) const {
;         const int row0 = u.pm * BM + wr * 64 + fr, col0 = u.pn * BM + wc * 32 + 8 * fq;
;         f32x4 gg[2][2], bb[2][2];
;         if constexpr (RESLN) {
; #pragma unroll
;             for (int bj = 0; bj < 2; ++bj)
; #pragma unroll
;                 for (int n = 0; n < 2; ++n) { gg[bj][n] = *(const f32x4*)(lg + col0 + bj * HALF + 4 * n); bb[bj][n] = *(const f32x4*)(lb + col0 + bj * HALF + 4 * n); } }
; #pragma unroll
;         for (int ai = 0; ai < 2; ++ai)
; #pragma unroll
;             for (int m = 0; m < 4; ++m) { const int row = row0 + ai * HALF + m * 16; const size_t off = (size_t)row * DM + col0;
;                 float mu = 0.f, rs = 1.f; if constexpr (RESLN) ln_stats(stin, row, mu, rs);
;                 float ss = 0.f, qq = 0.f;
; #pragma unroll
;                 for (int bj = 0; bj < 2; ++bj) { f32x4 r0 = __builtin_nontemporal_load((const f32x4*)(res + off + bj * HALF)), r1 = __builtin_nontemporal_load((const f32x4*)(res + off + bj * HALF + 4));
;                     if constexpr (RESLN) { r0 = (r0 - mu) * rs * gg[bj][0] + bb[bj][0]; r1 = (r1 - mu) * rs * gg[bj][1] + bb[bj][1]; }
;                     const f32x4 y0 = r0 * DN_ALPHA + acc[ai][bj][m][0] * ascale, y1 = r1 * DN_ALPHA + acc[ai][bj][m][1] * ascale;
;                     if constexpr (COPY != 4) { __builtin_nontemporal_store(y0, (f32x4*)(Y + off + bj * HALF)); __builtin_nontemporal_store(y1, (f32x4*)(Y + off + bj * HALF + 4)); }
;                     if constexpr (STATS) { ss += ((y0[0] + y0[1]) + (y0[2] + y0[3])) + ((y1[0] + y1[1]) + (y1[2] + y1[3]));
;                         qq += ((y0[0] * y0[0] + y0[1] * y0[1]) + (y0[2] * y0[2] + y0[3] * y0[3])) + ((y1[0] * y1[0] + y1[1] * y1[1]) + (y1[2] * y1[2] + y1[3] * y1[3])); }
;                     if constexpr (COPY == 1) *(u32x2*)((unsigned char*)copy + off + bj * HALF) = pack8fp8(y0 * cscale, y1 * cscale);
;                     if constexpr (COPY == 3) *(u32x2*)((unsigned char*)copy + off + bj * HALF) = pack8i8(y0 * cscale, y1 * cscale);
;                     if constexpr (COPY == 2 || COPY == 4) *(u32x4*)((bf16_t*)copy + off + bj * HALF) = pack8bf(y0, y1); }
;                 if constexpr (STATS) { ss += __shfl_xor(ss, 16); ss += __shfl_xor(ss, 32); qq += __shfl_xor(qq, 16); qq += __shfl_xor(qq, 32);
.LBB0_3875:
	s_or_b64 exec, exec, s[6:7]
	v_add_u32_e32 v48, 0xb0, v178
	s_waitcnt lgkmcnt(1)
	v_ashrrev_i32_e32 v49, 31, v48
	s_waitcnt lgkmcnt(0)
	v_lshlrev_b64 v[50:51], 11, v[48:49]
	v_lshlrev_b64 v[48:49], 3, v[48:49]
	v_lshl_add_u64 v[60:61], v[50:51], 0, v[176:177]
	v_lshl_add_u64 v[50:51], s[14:15], 0, v[48:49]
	global_load_dwordx2 v[62:63], v[50:51], off
	v_lshl_add_u64 v[50:51], v[60:61], 2, s[18:19]
	global_load_dwordx4 v[52:55], v[50:51], off nt
	global_load_dwordx4 v[56:59], v[50:51], off offset:16 nt
	v_lshl_add_u64 v[60:61], s[20:21], 0, v[60:61]
	s_waitcnt vmcnt(2)
	v_pk_mul_f32 v[62:63], v[62:63], s[28:29] op_sel_hi:[1,0]
	s_nop 0
	v_fma_f32 v63, -v62, v62, v63
	v_add_f32_e32 v63, 0x3727c5ac, v63
	v_rsq_f32_e32 v254, v63
	s_waitcnt vmcnt(1)
	v_sub_f32_e32 v55, v55, v62
	v_sub_f32_e32 v54, v54, v62
	v_sub_f32_e32 v53, v53, v62
	v_sub_f32_e32 v52, v52, v62
	s_waitcnt vmcnt(0)
	v_sub_f32_e32 v59, v59, v62
	v_sub_f32_e32 v58, v58, v62
	v_sub_f32_e32 v57, v57, v62
	v_sub_f32_e32 v56, v56, v62
	s_nop 0
	s_nop 1
	v_mov_b32_e32 v64, v254
	v_pk_mul_f32 v[52:53], v[52:53], v[64:65] op_sel_hi:[1,0]
	v_pk_mul_f32 v[54:55], v[54:55], v[64:65] op_sel_hi:[1,0]
	v_pk_mul_f32 v[56:57], v[56:57], v[64:65] op_sel_hi:[1,0]
	v_pk_mul_f32 v[58:59], v[58:59], v[64:65] op_sel_hi:[1,0]
	v_pk_fma_f32 v[18:19], v[30:31], v[54:55], v[18:19]
	v_pk_fma_f32 v[16:17], v[28:29], v[52:53], v[16:17]
	v_pk_fma_f32 v[22:23], v[22:23], v[58:59], v[26:27]
	v_pk_fma_f32 v[20:21], v[20:21], v[56:57], v[24:25]
	v_pk_mul_f32 v[16:17], v[16:17], s[30:31] op_sel_hi:[1,0]
	v_pk_mul_f32 v[18:19], v[18:19], s[30:31] op_sel_hi:[1,0]
	v_pk_mul_f32 v[20:21], v[20:21], s[30:31] op_sel_hi:[1,0]
	v_pk_mul_f32 v[22:23], v[22:23], s[30:31] op_sel_hi:[1,0]
	v_pk_fma_f32 v[18:19], v[46:47], s[36:37], v[18:19] op_sel_hi:[1,0,1]
	v_pk_fma_f32 v[16:17], v[44:45], s[36:37], v[16:17] op_sel_hi:[1,0,1]
	v_pk_fma_f32 v[22:23], v[42:43], s[36:37], v[22:23] op_sel_hi:[1,0,1]
	v_pk_fma_f32 v[20:21], v[40:41], s[36:37], v[20:21] op_sel_hi:[1,0,1]
	v_pk_mul_f32 v[24:25], v[18:19], s[38:39] op_sel_hi:[1,0]
	v_pk_mul_f32 v[26:27], v[16:17], s[38:39] op_sel_hi:[1,0]
	v_pk_mul_f32 v[28:29], v[22:23], s[38:39] op_sel_hi:[1,0]
	v_pk_mul_f32 v[30:31], v[20:21], s[38:39] op_sel_hi:[1,0]
	v_med3_f32 v26, v26, s64, v195
	v_med3_f32 v27, v27, s64, v195
	v_med3_f32 v24, v24, s64, v195
	v_med3_f32 v25, v25, s64, v195
	v_med3_f32 v30, v30, s64, v195
	v_med3_f32 v31, v31, s64, v195
	v_med3_f32 v28, v28, s64, v195
	v_med3_f32 v29, v29, s64, v195
	v_add_f32_e32 v26, 0x4b400000, v26
	v_add_f32_e32 v27, 0x4b400000, v27
	v_add_f32_e32 v24, 0x4b400000, v24
	v_add_f32_e32 v25, 0x4b400000, v25
	v_add_f32_e32 v30, 0x4b400000, v30
	v_add_f32_e32 v31, 0x4b400000, v31
	v_add_f32_e32 v28, 0x4b400000, v28
	v_add_f32_e32 v29, 0x4b400000, v29
	v_perm_b32 v26, v27, v26, s65
	v_perm_b32 v24, v25, v24, s66
	v_perm_b32 v25, v31, v30, s65
	v_perm_b32 v27, v29, v28, s66
	v_or_b32_e32 v24, v26, v24
	v_or_b32_e32 v25, v25, v27
	global_store_dwordx4 v[50:51], v[16:19], off nt
	global_store_dwordx4 v[50:51], v[20:23], off offset:16 nt
	global_store_dwordx2 v[60:61], v[24:25], off
	global_load_dwordx4 v[24:27], v[50:51], off offset:512 nt
	s_nop 0
	global_load_dwordx4 v[28:31], v[50:51], off offset:528 nt
	v_add_f32_e32 v40, v16, v17
	v_add_f32_e32 v41, v18, v19
	v_add_f32_e32 v42, v20, v21
	v_add_f32_e32 v43, v22, v23
	v_mul_f32_e32 v17, v17, v17
	v_mul_f32_e32 v19, v19, v19
	v_mul_f32_e32 v21, v21, v21
	v_mul_f32_e32 v23, v23, v23
	v_add_f32_e32 v40, v40, v41
	v_add_f32_e32 v41, v42, v43
	v_fmac_f32_e32 v17, v16, v16
	v_fmac_f32_e32 v19, v18, v18
	v_fmac_f32_e32 v21, v20, v20
	v_fmac_f32_e32 v23, v22, v22
	v_add_f32_e32 v16, v40, v41
	v_add_f32_e32 v17, v17, v19
	v_add_f32_e32 v18, v21, v23
	v_add_f32_e32 v40, 0, v16
	v_add_f32_e32 v41, v17, v18
	s_waitcnt vmcnt(1)
; __device__ __forceinline__ u32x2 pack8i8(const f32x4 a, const f32x4 b) { return (u32x2){pack4i8(a), pack4i8(b)}; }
; __device__ __forceinline__ u32x4 pack8bf(const f32x4 a, const f32x4 b) { u32x4 w; w.x = cvt_pk_bf16(a[0], a[1]); w.y = cvt_pk_bf16(a[2], a[3]); w.z = cvt_pk_bf16(b[0], b[1]); w.w = cvt_pk_bf16(b[2], b[3]); return w; }
;     __device__ __forceinline__ void operator()(EPI_ARGS) const {
;     ...
;                 for (int bj = 0; bj < 2; ++bj) { f32x4 r0 = __builtin_nontemporal_load((const f32x4*)(res + off + bj * HALF)), r1 = __builtin_nontemporal_load((const f32x4*)(res + off + bj * HALF + 4));
;                     if constexpr (RESLN) { r0 = (r0 - mu) * rs * gg[bj][0] + bb[bj][0]; r1 = (r1 - mu) * rs * gg[bj][1] + bb[bj][1]; }
;                     const f32x4 y0 = r0 * DN_ALPHA + acc[ai][bj][m][0] * ascale, y1 = r1 * DN_ALPHA + acc[ai][bj][m][1] * ascale;
;                     if constexpr (COPY != 4) { __builtin_nontemporal_store(y0, (f32x4*)(Y + off + bj * HALF)); __builtin_nontemporal_store(y1, (f32x4*)(Y + off + bj * HALF + 4)); }
;                     if constexpr (STATS) { ss += ((y0[0] + y0[1]) + (y0[2] + y0[3])) + ((y1[0] + y1[1]) + (y1[2] + y1[3]));
;                         qq += ((y0[0] * y0[0] + y0[1] * y0[1]) + (y0[2] * y0[2] + y0[3] * y0[3])) + ((y1[0] * y1[0] + y1[1] * y1[1]) + (y1[2] * y1[2] + y1[3] * y1[3])); }
;                     if constexpr (COPY == 1) *(u32x2*)((unsigned char*)copy + off + bj * HALF) = pack8fp8(y0 * cscale, y1 * cscale);
;                     if constexpr (COPY == 3) *(u32x2*)((unsigned char*)copy + off + bj * HALF) = pack8i8(y0 * cscale, y1 * cscale);
;                     if constexpr (COPY == 2 || COPY == 4) *(u32x4*)((bf16_t*)copy + off + bj * HALF) = pack8bf(y0, y1); }
;                 if constexpr (STATS) { ss += __shfl_xor(ss, 16); ss += __shfl_xor(ss, 32); qq += __shfl_xor(qq, 16); qq += __shfl_xor(qq, 32);
;                     if (fq == 0) { unsafeAtomicAdd(stout + 2 * (size_t)row, ss); unsafeAtomicAdd(stout + 2 * (size_t)row + 1, qq); } }
	v_sub_f32_e32 v17, v27, v62
	v_sub_f32_e32 v16, v26, v62
	v_sub_f32_e32 v19, v25, v62
	v_sub_f32_e32 v18, v24, v62
	s_waitcnt vmcnt(0)
	v_sub_f32_e32 v21, v31, v62
	v_sub_f32_e32 v20, v30, v62
	v_sub_f32_e32 v23, v29, v62
	v_sub_f32_e32 v22, v28, v62
	v_pk_mul_f32 v[18:19], v[18:19], v[64:65] op_sel_hi:[1,0]
	v_pk_mul_f32 v[16:17], v[16:17], v[64:65] op_sel_hi:[1,0]
	v_pk_mul_f32 v[22:23], v[22:23], v[64:65] op_sel_hi:[1,0]
	v_pk_mul_f32 v[20:21], v[20:21], v[64:65] op_sel_hi:[1,0]
	v_pk_fma_f32 v[10:11], v[10:11], v[16:17], v[14:15]
	v_pk_fma_f32 v[8:9], v[8:9], v[18:19], v[12:13]
	v_pk_fma_f32 v[2:3], v[2:3], v[20:21], v[6:7]
	v_pk_fma_f32 v[0:1], v[0:1], v[22:23], v[4:5]
	v_pk_mul_f32 v[4:5], v[8:9], s[30:31] op_sel_hi:[1,0]
	v_pk_mul_f32 v[6:7], v[10:11], s[30:31] op_sel_hi:[1,0]
	v_pk_mul_f32 v[8:9], v[0:1], s[30:31] op_sel_hi:[1,0]
	v_pk_mul_f32 v[10:11], v[2:3], s[30:31] op_sel_hi:[1,0]
	v_pk_fma_f32 v[2:3], v[38:39], s[36:37], v[6:7] op_sel_hi:[1,0,1]
	v_pk_fma_f32 v[0:1], v[36:37], s[36:37], v[4:5] op_sel_hi:[1,0,1]
	v_pk_fma_f32 v[6:7], v[34:35], s[36:37], v[10:11] op_sel_hi:[1,0,1]
	v_pk_fma_f32 v[4:5], v[32:33], s[36:37], v[8:9] op_sel_hi:[1,0,1]
	v_add_f32_e32 v16, v0, v1
	v_add_f32_e32 v17, v2, v3
	v_add_f32_e32 v18, v4, v5
	v_add_f32_e32 v19, v6, v7
	v_mul_f32_e32 v20, v1, v1
	v_mul_f32_e32 v21, v3, v3
	v_mul_f32_e32 v22, v5, v5
	v_mul_f32_e32 v23, v7, v7
	global_store_dwordx4 v[50:51], v[0:3], off offset:512 nt
	global_store_dwordx4 v[50:51], v[4:7], off offset:528 nt
	v_pk_mul_f32 v[8:9], v[2:3], s[38:39] op_sel_hi:[1,0]
	v_pk_mul_f32 v[10:11], v[0:1], s[38:39] op_sel_hi:[1,0]
	v_add_f32_e32 v1, v16, v17
	v_add_f32_e32 v3, v18, v19
	v_fmac_f32_e32 v20, v0, v0
	v_fmac_f32_e32 v21, v2, v2
	v_fmac_f32_e32 v22, v4, v4
	v_fmac_f32_e32 v23, v6, v6
	v_med3_f32 v0, v10, s64, v195
	v_add_f32_e32 v1, v1, v3
	v_add_f32_e32 v3, v20, v21
	v_add_f32_e32 v10, v22, v23
	v_med3_f32 v2, v11, s64, v195
	v_add_f32_e32 v3, v3, v10
	v_add_f32_e32 v0, 0x4b400000, v0
	v_add_f32_e32 v2, 0x4b400000, v2
	v_add_f32_e32 v1, v1, v40
	v_add_f32_e32 v3, v41, v3
	v_perm_b32 v0, v2, v0, s65
	v_mov_b32_e32 v2, v1
	s_nop 1
	v_permlane16_swap_b32_e32 v1, v2
	v_mov_b32_e32 v10, v3
	s_nop 1
	v_permlane16_swap_b32_e32 v3, v10
	v_pk_mul_f32 v[14:15], v[4:5], s[38:39] op_sel_hi:[1,0]
	v_med3_f32 v4, v8, s64, v195
	v_med3_f32 v5, v9, s64, v195
	v_add_f32_e32 v4, 0x4b400000, v4
	v_add_f32_e32 v5, 0x4b400000, v5
	v_perm_b32 v4, v5, v4, s66
	v_or_b32_e32 v4, v0, v4
	s_waitcnt lgkmcnt(0)
	v_add_f32_e32 v0, v1, v2
	s_waitcnt lgkmcnt(0)
	v_add_f32_e32 v2, v3, v10
	v_pk_mul_f32 v[12:13], v[6:7], s[38:39] op_sel_hi:[1,0]
	v_mov_b32_e32 v1, v0
	s_nop 1
	v_permlane32_swap_b32_e32 v0, v1
	v_mov_b32_e32 v3, v2
	s_nop 1
	v_permlane32_swap_b32_e32 v2, v3
	v_med3_f32 v6, v14, s64, v195
	v_med3_f32 v7, v15, s64, v195
	v_med3_f32 v8, v12, s64, v195
	v_med3_f32 v9, v13, s64, v195
	v_add_f32_e32 v6, 0x4b400000, v6
	v_add_f32_e32 v7, 0x4b400000, v7
	v_add_f32_e32 v8, 0x4b400000, v8
	v_add_f32_e32 v9, 0x4b400000, v9
	v_perm_b32 v5, v7, v6, s65
	v_perm_b32 v6, v9, v8, s66
	v_or_b32_e32 v5, v5, v6
	global_store_dwordx2 v[60:61], v[4:5], off offset:128
	s_and_saveexec_b64 s[6:7], s[2:3]
	s_cbranch_execz .LBB0_3877
	v_lshl_add_u64 v[4:5], s[12:13], 0, v[48:49]
	s_waitcnt lgkmcnt(0)
	v_add_f32_e32 v0, v0, v1
	s_waitcnt lgkmcnt(0)
	v_add_f32_e32 v1, v2, v3
	global_atomic_add_f32 v[4:5], v0, off
	global_atomic_add_f32 v[4:5], v1, off offset:4

; __device__ __forceinline__ u32x2 pack8i8(const f32x4 a, const f32x4 b) { return (u32x2){pack4i8(a), pack4i8(b)}; }
; __device__ __forceinline__ void ln_stats(const float* st, int row, float& mu, float& rs) { const f32x2 s = *(const f32x2*)(st + 2 * (size_t)row); mu = s[0] * (1.0f / DM); rs = 1.0f / sqrtf(s[1] * (1.0f / DM) - mu * mu + LN_EPS); }
;     __device__ __forceinline__ void operator()(EPI_ARGS) const {
;     ...
;             bf16_t* dst = (u.pn < 2) ? CQ : CKV; const int col0 = (u.pn & 1) * BM + wc * 32 + 8 * fq; const int slot = (u.pn >> 1) * 8 + (u.pn & 1) * 4 + wc;
;             f32x4 cc[2][2], dd[2][2];
; #pragma unroll
;             for (int bj = 0; bj < 2; ++bj)
; #pragma unroll
;                 for (int n = 0; n < 2; ++n) { cc[bj][n] = *(const f32x4*)(C + n0 + bj * HALF + 4 * n); dd[bj][n] = *(const f32x4*)(D + n0 + bj * HALF + 4 * n); }
; #pragma unroll
;             for (int ai = 0; ai < 2; ++ai)
; #pragma unroll
;                 for (int m = 0; m < 4; ++m) { const int row = row0 + ai * HALF + m * 16; float s = 0.f; float mu, rs; ln_stats(st, row, mu, rs);
; #pragma unroll
;                     for (int bj = 0; bj < 2; ++bj) { const f32x4 a = (acc[ai][bj][m][0] - cc[bj][0] * mu) * rs + dd[bj][0], b = (acc[ai][bj][m][1] - cc[bj][1] * mu) * rs + dd[bj][1];
;                         s += (a[0] * a[0] + a[1] * a[1]) + (a[2] * a[2] + a[3] * a[3]) + (b[0] * b[0] + b[1] * b[1]) + (b[2] * b[2] + b[3] * b[3]);
;                         *(u32x2*)((unsigned char*)dst + (size_t)row * 512 + col0 + bj * HALF) = pack8i8(a * lsc, b * lsc); }
;                     s += __shfl_xor(s, 16); s += __shfl_xor(s, 32);
;                     if (fq == 0) ssq[(size_t)row * 16 + slot] = s; }
.LBB0_3964:
	v_ashrrev_i32_e32 v97, 31, v96
	v_lshl_add_u64 v[66:67], v[96:97], 3, s[12:13]
	global_load_dwordx2 v[192:193], v[66:67], off
	v_ashrrev_i32_e32 v81, 31, v80
	v_lshlrev_b64 v[64:65], 2, v[80:81]
	v_lshl_add_u64 v[84:85], s[14:15], 0, v[64:65]
	global_load_dwordx4 v[80:83], v[84:85], off
	global_load_dwordx4 v[72:75], v[84:85], off offset:16
	v_lshl_add_u64 v[162:163], s[16:17], 0, v[64:65]
	global_load_dwordx4 v[68:71], v[162:163], off
	global_load_dwordx4 v[64:67], v[162:163], off offset:16
	v_cvt_f32_i32_e32 v199, v57
	v_and_b32_e32 v57, 64, v188
	v_cvt_f32_i32_e32 v198, v56
	v_xor_b32_e32 v56, 16, v188
	v_add_u32_e32 v57, 64, v57
	v_cvt_f32_i32_e32 v200, v58
	v_xor_b32_e32 v58, 32, v188
	v_cmp_lt_i32_e32 vcc, v56, v57
	v_cvt_f32_i32_e32 v195, v61
	v_cvt_f32_i32_e32 v194, v60
	v_cndmask_b32_e32 v136, v188, v56, vcc
	v_cmp_lt_i32_e32 vcc, v58, v57
	v_cvt_f32_i32_e32 v197, v63
	v_cvt_f32_i32_e32 v196, v62
	v_cvt_f32_i32_e32 v201, v59
	v_cndmask_b32_e32 v190, v188, v58, vcc
	global_load_dwordx4 v[76:79], v[84:85], off offset:528
	s_nop 0
	global_load_dwordx4 v[84:87], v[84:85], off offset:512
	s_nop 0
	global_load_dwordx4 v[56:59], v[162:163], off offset:528
	global_load_dwordx4 v[60:63], v[162:163], off offset:512
	s_cmp_lt_i32 s44, 2
	s_cselect_b32 s6, s69, 0x64000000
	s_add_u32 s6, s56, s6
	s_addc_u32 s7, s57, 0
	s_and_b32 s37, s37, 0x100
	v_lshlrev_b32_e32 v191, 2, v136
	v_or_b32_e32 v136, s37, v182
	v_lshl_add_u64 v[162:163], s[6:7], 0, v[136:137]
	v_lshlrev_b64 v[202:203], 9, v[96:97]
	v_lshl_add_u64 v[202:203], v[162:163], 0, v[202:203]
	v_lshlrev_b32_e32 v190, 2, v190
	s_lshl_b32 s39, s44, 2
	s_or_b32 s44, s39, s60
	s_ashr_i32 s45, s44, 31
	s_waitcnt vmcnt(0)
	v_pk_mul_f32 v[192:193], v[192:193], s[28:29] op_sel_hi:[1,0]
	s_nop 0
	v_fma_f32 v136, -v192, v192, v193
	v_add_f32_e32 v136, 0x3727c5ac, v136
	v_rsq_f32_e32 v254, v136
	v_xor_b32_e32 v83, 0x80000000, v83
	v_xor_b32_e32 v82, 0x80000000, v82
	v_xor_b32_e32 v75, 0x80000000, v75
	v_xor_b32_e32 v74, 0x80000000, v74
	v_pk_fma_f32 v[178:179], v[80:81], v[192:193], v[178:179] op_sel_hi:[1,0,1] neg_lo:[1,0,0] neg_hi:[1,0,0]
	v_pk_fma_f32 v[174:175], v[82:83], v[192:193], v[174:175] op_sel_hi:[1,0,1]
	v_pk_fma_f32 v[172:173], v[74:75], v[192:193], v[172:173] op_sel_hi:[1,0,1]
	v_pk_fma_f32 v[176:177], v[72:73], v[192:193], v[176:177] op_sel_hi:[1,0,1] neg_lo:[1,0,0] neg_hi:[1,0,0]
	s_nop 0
	s_nop 1
	v_mov_b32_e32 v136, v254
	v_pk_fma_f32 v[174:175], v[174:175], v[136:137], v[70:71] op_sel_hi:[1,0,1]
	v_pk_fma_f32 v[178:179], v[178:179], v[136:137], v[68:69] op_sel_hi:[1,0,1]
	v_pk_fma_f32 v[172:173], v[172:173], v[136:137], v[66:67] op_sel_hi:[1,0,1]
	v_mul_f32_e32 v213, v175, v175
	v_mul_f32_e32 v215, v173, v173
	v_pk_mul_f32 v[204:205], v[174:175], s[30:31] op_sel_hi:[1,0]
	v_pk_mul_f32 v[206:207], v[178:179], s[30:31] op_sel_hi:[1,0]
	v_pk_fma_f32 v[176:177], v[176:177], v[136:137], v[64:65] op_sel_hi:[1,0,1]
	v_pk_mul_f32 v[208:209], v[172:173], s[30:31] op_sel_hi:[1,0]
	v_fmac_f32_e32 v213, v174, v174
	v_fmac_f32_e32 v215, v172, v172
	v_med3_f32 v172, v206, s70, v189
	v_med3_f32 v173, v207, s70, v189
	v_med3_f32 v174, v204, s70, v189
	v_med3_f32 v175, v205, s70, v189
	v_mul_f32_e32 v214, v177, v177
	v_pk_mul_f32 v[210:211], v[176:177], s[30:31] op_sel_hi:[1,0]
	v_add_f32_e32 v172, 0x4b400000, v172
	v_add_f32_e32 v173, 0x4b400000, v173
	v_add_f32_e32 v174, 0x4b400000, v174
	v_add_f32_e32 v175, 0x4b400000, v175
	v_fmac_f32_e32 v214, v176, v176
	v_med3_f32 v176, v210, s70, v189
	v_perm_b32 v172, v173, v172, s71
	v_perm_b32 v173, v175, v174, s72
	v_or_b32_e32 v172, v172, v173
	v_add_f32_e32 v173, 0x4b400000, v176
	v_med3_f32 v174, v211, s70, v189
	v_med3_f32 v175, v208, s70, v189
	v_med3_f32 v176, v209, s70, v189
	v_mul_f32_e32 v212, v179, v179
	v_add_f32_e32 v174, 0x4b400000, v174
	v_add_f32_e32 v175, 0x4b400000, v175
	v_add_f32_e32 v176, 0x4b400000, v176
	v_fmac_f32_e32 v212, v178, v178
	v_perm_b32 v173, v174, v173, s71
	v_perm_b32 v174, v176, v175, s72
	v_add_f32_e32 v177, v212, v213
	v_or_b32_e32 v173, v173, v174
	v_add_f32_e32 v177, v214, v177
	global_store_dwordx2 v[202:203], v[172:173], off
	v_pk_mul_f32 v[172:173], v[86:87], v[192:193] op_sel_hi:[1,0]
	v_pk_mul_f32 v[174:175], v[84:85], v[192:193] op_sel_hi:[1,0]
	v_add_f32_e32 v204, v215, v177
	v_pk_fma_f32 v[172:173], v[196:197], s[26:27], v[172:173] op_sel_hi:[1,0,1] neg_lo:[0,0,1] neg_hi:[0,0,1]
	v_pk_fma_f32 v[174:175], v[194:195], s[26:27], v[174:175] op_sel_hi:[1,0,1] neg_lo:[0,0,1] neg_hi:[0,0,1]
	v_pk_mul_f32 v[176:177], v[78:79], v[192:193] op_sel_hi:[1,0]
	v_pk_mul_f32 v[178:179], v[76:77], v[192:193] op_sel_hi:[1,0]
	v_pk_fma_f32 v[172:173], v[172:173], v[136:137], v[62:63] op_sel_hi:[1,0,1]
	v_pk_fma_f32 v[174:175], v[174:175], v[136:137], v[60:61] op_sel_hi:[1,0,1]
	v_pk_fma_f32 v[176:177], v[200:201], s[26:27], v[176:177] op_sel_hi:[1,0,1] neg_lo:[0,0,1] neg_hi:[0,0,1]
	v_pk_fma_f32 v[178:179], v[198:199], s[26:27], v[178:179] op_sel_hi:[1,0,1] neg_lo:[0,0,1] neg_hi:[0,0,1]
	v_pk_fma_f32 v[176:177], v[176:177], v[136:137], v[58:59] op_sel_hi:[1,0,1]
	v_pk_fma_f32 v[178:179], v[178:179], v[136:137], v[56:57] op_sel_hi:[1,0,1]
	v_mul_f32_e32 v136, v175, v175
	v_mul_f32_e32 v192, v173, v173
	v_fmac_f32_e32 v136, v174, v174
	v_fmac_f32_e32 v192, v172, v172
	v_add_f32_e32 v136, v136, v192
	v_mul_f32_e32 v192, v179, v179
	v_pk_mul_f32 v[172:173], v[172:173], s[30:31] op_sel_hi:[1,0]
	v_pk_mul_f32 v[174:175], v[174:175], s[30:31] op_sel_hi:[1,0]
	v_fmac_f32_e32 v192, v178, v178
	v_med3_f32 v174, v174, s70, v189
	v_med3_f32 v175, v175, s70, v189
	v_med3_f32 v172, v172, s70, v189
	v_med3_f32 v173, v173, s70, v189
	v_add_f32_e32 v136, v192, v136
	v_mul_f32_e32 v192, v177, v177
	v_add_f32_e32 v174, 0x4b400000, v174
	v_add_f32_e32 v175, 0x4b400000, v175
	v_add_f32_e32 v172, 0x4b400000, v172
	v_add_f32_e32 v173, 0x4b400000, v173
	v_fmac_f32_e32 v192, v176, v176
	v_pk_mul_f32 v[178:179], v[178:179], s[30:31] op_sel_hi:[1,0]
	v_perm_b32 v174, v175, v174, s71
	v_perm_b32 v172, v173, v172, s72
	v_add_f32_e32 v136, v192, v136
	v_or_b32_e32 v174, v174, v172
	v_med3_f32 v172, v178, s70, v189
	v_add_f32_e32 v136, v204, v136
	v_add_f32_e32 v173, 0x4b400000, v172
	v_med3_f32 v172, v179, s70, v189
	v_add_f32_e32 v175, 0x4b400000, v172
	v_mov_b32_e32 v172, v136
	s_nop 1
	v_permlane16_swap_b32_e32 v136, v172
	v_pk_mul_f32 v[176:177], v[176:177], s[30:31] op_sel_hi:[1,0]
	v_perm_b32 v173, v175, v173, s71
	v_med3_f32 v176, v176, s70, v189
	v_med3_f32 v177, v177, s70, v189
	s_waitcnt lgkmcnt(0)
	v_add_f32_e32 v136, v136, v172
	v_mov_b32_e32 v172, v136
	s_nop 1
	v_permlane32_swap_b32_e32 v136, v172
	v_add_f32_e32 v176, 0x4b400000, v176
	v_add_f32_e32 v177, 0x4b400000, v177
	v_perm_b32 v175, v177, v176, s72
	v_or_b32_e32 v175, v173, v175
	global_store_dwordx2 v[202:203], v[174:175], off offset:128
	s_and_saveexec_b64 s[6:7], s[2:3]
	s_cbranch_execz .LBB0_3966
; __device__ __forceinline__ u32x2 pack8i8(const f32x4 a, const f32x4 b) { return (u32x2){pack4i8(a), pack4i8(b)}; }
; __device__ __forceinline__ void ln_stats(const float* st, int row, float& mu, float& rs) { const f32x2 s = *(const f32x2*)(st + 2 * (size_t)row); mu = s[0] * (1.0f / DM); rs = 1.0f / sqrtf(s[1] * (1.0f / DM) - mu * mu + LN_EPS); }
;     __device__ __forceinline__ void operator()(EPI_ARGS) const {
;     ...
;                 for (int m = 0; m < 4; ++m) { const int row = row0 + ai * HALF + m * 16; float s = 0.f; float mu, rs; ln_stats(st, row, mu, rs);
; #pragma unroll
;                     for (int bj = 0; bj < 2; ++bj) { const f32x4 a = (acc[ai][bj][m][0] - cc[bj][0] * mu) * rs + dd[bj][0], b = (acc[ai][bj][m][1] - cc[bj][1] * mu) * rs + dd[bj][1];
;                         s += (a[0] * a[0] + a[1] * a[1]) + (a[2] * a[2] + a[3] * a[3]) + (b[0] * b[0] + b[1] * b[1]) + (b[2] * b[2] + b[3] * b[3]);
;                         *(u32x2*)((unsigned char*)dst + (size_t)row * 512 + col0 + bj * HALF) = pack8i8(a * lsc, b * lsc); }
;                     s += __shfl_xor(s, 16); s += __shfl_xor(s, 32);
;                     if (fq == 0) ssq[(size_t)row * 16 + slot] = s; }
	v_lshlrev_b64 v[174:175], 6, v[96:97]
	v_lshl_add_u64 v[174:175], s[10:11], 0, v[174:175]
	v_lshl_add_u64 v[174:175], s[44:45], 2, v[174:175]
	s_waitcnt lgkmcnt(0)
	v_add_f32_e32 v97, v136, v172
	global_store_dword v[174:175], v97, off
.LBB0_3966:
	s_or_b64 exec, exec, s[6:7]
	s_waitcnt lgkmcnt(0)
	v_or_b32_e32 v172, 16, v96
	v_ashrrev_i32_e32 v173, 31, v172
	v_lshl_add_u64 v[174:175], v[172:173], 3, s[12:13]
	global_load_dwordx2 v[174:175], v[174:175], off
	v_cvt_f32_i32_e32 v49, v49
	v_cvt_f32_i32_e32 v48, v48
	v_cvt_f32_i32_e32 v55, v55
	v_cvt_f32_i32_e32 v54, v54
	v_cvt_f32_i32_e32 v53, v53
	v_cvt_f32_i32_e32 v52, v52
	v_cvt_f32_i32_e32 v51, v51
	v_cvt_f32_i32_e32 v50, v50
	v_lshlrev_b64 v[176:177], 9, v[172:173]
	v_lshl_add_u64 v[176:177], v[162:163], 0, v[176:177]
	s_waitcnt vmcnt(0)
	v_pk_mul_f32 v[174:175], v[174:175], s[28:29] op_sel_hi:[1,0]
	s_nop 0
	v_fma_f32 v97, -v174, v174, v175
	v_add_f32_e32 v97, 0x3727c5ac, v97
	v_rsq_f32_e32 v254, v97
	v_pk_fma_f32 v[168:169], v[82:83], v[174:175], v[168:169] op_sel_hi:[1,0,1]
	v_pk_fma_f32 v[170:171], v[80:81], v[174:175], v[170:171] op_sel_hi:[1,0,1] neg_lo:[1,0,0] neg_hi:[1,0,0]
	v_pk_fma_f32 v[164:165], v[74:75], v[174:175], v[164:165] op_sel_hi:[1,0,1]
	v_pk_fma_f32 v[166:167], v[72:73], v[174:175], v[166:167] op_sel_hi:[1,0,1] neg_lo:[1,0,0] neg_hi:[1,0,0]
	v_pk_mul_f32 v[178:179], v[86:87], v[174:175] op_sel_hi:[1,0]
	v_pk_mul_f32 v[192:193], v[84:85], v[174:175] op_sel_hi:[1,0]
	v_pk_mul_f32 v[194:195], v[78:79], v[174:175] op_sel_hi:[1,0]
	v_pk_mul_f32 v[174:175], v[76:77], v[174:175] op_sel_hi:[1,0]
	v_pk_fma_f32 v[54:55], v[54:55], s[26:27], v[178:179] op_sel_hi:[1,0,1] neg_lo:[0,0,1] neg_hi:[0,0,1]
	v_pk_fma_f32 v[48:49], v[48:49], s[26:27], v[174:175] op_sel_hi:[1,0,1] neg_lo:[0,0,1] neg_hi:[0,0,1]
	v_pk_fma_f32 v[52:53], v[52:53], s[26:27], v[192:193] op_sel_hi:[1,0,1] neg_lo:[0,0,1] neg_hi:[0,0,1]
	v_pk_fma_f32 v[50:51], v[50:51], s[26:27], v[194:195] op_sel_hi:[1,0,1] neg_lo:[0,0,1] neg_hi:[0,0,1]
	s_nop 1
	s_nop 1
	v_mov_b32_e32 v136, v254
	v_pk_fma_f32 v[168:169], v[168:169], v[136:137], v[70:71] op_sel_hi:[1,0,1]
	v_pk_fma_f32 v[170:171], v[170:171], v[136:137], v[68:69] op_sel_hi:[1,0,1]
	v_pk_fma_f32 v[164:165], v[164:165], v[136:137], v[66:67] op_sel_hi:[1,0,1]
	v_pk_fma_f32 v[166:167], v[166:167], v[136:137], v[64:65] op_sel_hi:[1,0,1]
	v_pk_fma_f32 v[54:55], v[54:55], v[136:137], v[62:63] op_sel_hi:[1,0,1]
	v_pk_fma_f32 v[52:53], v[52:53], v[136:137], v[60:61] op_sel_hi:[1,0,1]
	v_pk_fma_f32 v[50:51], v[50:51], v[136:137], v[58:59] op_sel_hi:[1,0,1]
	v_pk_fma_f32 v[48:49], v[48:49], v[136:137], v[56:57] op_sel_hi:[1,0,1]
	v_mul_f32_e32 v97, v171, v171
	v_mul_f32_e32 v136, v169, v169
	v_mul_f32_e32 v200, v167, v167
	v_mul_f32_e32 v201, v165, v165
	v_pk_mul_f32 v[174:175], v[168:169], s[30:31] op_sel_hi:[1,0]
	v_pk_mul_f32 v[178:179], v[170:171], s[30:31] op_sel_hi:[1,0]
	v_pk_mul_f32 v[192:193], v[164:165], s[30:31] op_sel_hi:[1,0]
	v_pk_mul_f32 v[194:195], v[166:167], s[30:31] op_sel_hi:[1,0]
	v_mul_f32_e32 v165, v53, v53
	v_mul_f32_e32 v167, v55, v55
	v_mul_f32_e32 v169, v49, v49
	v_pk_mul_f32 v[196:197], v[54:55], s[30:31] op_sel_hi:[1,0]
	v_pk_mul_f32 v[198:199], v[52:53], s[30:31] op_sel_hi:[1,0]
	v_fmac_f32_e32 v97, v170, v170
	v_fmac_f32_e32 v136, v168, v168
	v_fmac_f32_e32 v200, v166, v166
	v_fmac_f32_e32 v201, v164, v164
	v_med3_f32 v53, v178, s70, v189
	v_med3_f32 v55, v179, s70, v189
	v_med3_f32 v164, v174, s70, v189
	v_med3_f32 v166, v175, s70, v189
	v_med3_f32 v168, v194, s70, v189
	v_med3_f32 v170, v195, s70, v189
	v_med3_f32 v174, v192, s70, v189
	v_med3_f32 v175, v193, s70, v189
	v_fmac_f32_e32 v165, v52, v52
	v_fmac_f32_e32 v167, v54, v54
	v_mul_f32_e32 v171, v51, v51
	v_fmac_f32_e32 v169, v48, v48
	v_add_f32_e32 v52, v97, v136
	v_add_f32_e32 v53, 0x4b400000, v53
	v_add_f32_e32 v54, 0x4b400000, v55
	v_add_f32_e32 v55, 0x4b400000, v164
	v_add_f32_e32 v97, 0x4b400000, v166
	v_add_f32_e32 v136, 0x4b400000, v168
	v_add_f32_e32 v164, 0x4b400000, v170
	v_add_f32_e32 v166, 0x4b400000, v174
	v_add_f32_e32 v168, 0x4b400000, v175
	v_add_f32_e32 v165, v165, v167
	v_fmac_f32_e32 v171, v50, v50
	v_add_f32_e32 v52, v200, v52
	v_perm_b32 v53, v54, v53, s71
	v_perm_b32 v54, v97, v55, s72
	v_perm_b32 v55, v164, v136, s71
	v_perm_b32 v97, v168, v166, s72
	v_add_f32_e32 v136, v169, v165
	v_add_f32_e32 v164, v201, v52
	v_or_b32_e32 v52, v53, v54
	v_or_b32_e32 v53, v55, v97
	v_add_f32_e32 v54, v171, v136
	global_store_dwordx2 v[176:177], v[52:53], off
	v_add_f32_e32 v53, v164, v54
	v_med3_f32 v52, v198, s70, v189
	v_med3_f32 v54, v199, s70, v189
	v_med3_f32 v55, v196, s70, v189
	v_med3_f32 v97, v197, s70, v189
	v_pk_mul_f32 v[48:49], v[48:49], s[30:31] op_sel_hi:[1,0]
	v_add_f32_e32 v52, 0x4b400000, v52
	v_add_f32_e32 v54, 0x4b400000, v54
	v_add_f32_e32 v55, 0x4b400000, v55
	v_add_f32_e32 v97, 0x4b400000, v97
	v_perm_b32 v52, v54, v52, s71
	v_perm_b32 v54, v97, v55, s72
	v_med3_f32 v48, v48, s70, v189
	v_or_b32_e32 v52, v52, v54
	v_add_f32_e32 v54, 0x4b400000, v48
	v_med3_f32 v48, v49, s70, v189
	v_add_f32_e32 v55, 0x4b400000, v48
	v_mov_b32_e32 v48, v53
	s_nop 1
	v_permlane16_swap_b32_e32 v53, v48
	v_pk_mul_f32 v[50:51], v[50:51], s[30:31] op_sel_hi:[1,0]
	s_waitcnt lgkmcnt(0)
	v_add_f32_e32 v48, v53, v48
	v_med3_f32 v49, v50, s70, v189
	v_add_f32_e32 v50, 0x4b400000, v49
	v_med3_f32 v49, v51, s70, v189
	v_add_f32_e32 v51, 0x4b400000, v49
	v_mov_b32_e32 v49, v48
	s_nop 1
	v_permlane32_swap_b32_e32 v48, v49
	v_perm_b32 v53, v55, v54, s71
	v_perm_b32 v50, v51, v50, s72
	v_or_b32_e32 v53, v53, v50
	global_store_dwordx2 v[176:177], v[52:53], off offset:128
	s_and_saveexec_b64 s[6:7], s[2:3]
	s_cbranch_execz .LBB0_3968
	v_lshlrev_b64 v[50:51], 6, v[172:173]
	v_lshl_add_u64 v[50:51], s[10:11], 0, v[50:51]
	v_lshl_add_u64 v[50:51], s[44:45], 2, v[50:51]
	s_waitcnt lgkmcnt(0)
	v_add_f32_e32 v48, v48, v49
	global_store_dword v[50:51], v48, off
; __device__ __forceinline__ u32x2 pack8i8(const f32x4 a, const f32x4 b) { return (u32x2){pack4i8(a), pack4i8(b)}; }
; __device__ __forceinline__ void ln_stats(const float* st, int row, float& mu, float& rs) { const f32x2 s = *(const f32x2*)(st + 2 * (size_t)row); mu = s[0] * (1.0f / DM); rs = 1.0f / sqrtf(s[1] * (1.0f / DM) - mu * mu + LN_EPS); }
;     __device__ __forceinline__ void operator()(EPI_ARGS) const {
;     ...
;                 for (int m = 0; m < 4; ++m) { const int row = row0 + ai * HALF + m * 16; float s = 0.f; float mu, rs; ln_stats(st, row, mu, rs);
; #pragma unroll
;                     for (int bj = 0; bj < 2; ++bj) { const f32x4 a = (acc[ai][bj][m][0] - cc[bj][0] * mu) * rs + dd[bj][0], b = (acc[ai][bj][m][1] - cc[bj][1] * mu) * rs + dd[bj][1];
;                         s += (a[0] * a[0] + a[1] * a[1]) + (a[2] * a[2] + a[3] * a[3]) + (b[0] * b[0] + b[1] * b[1]) + (b[2] * b[2] + b[3] * b[3]);
;                         *(u32x2*)((unsigned char*)dst + (size_t)row * 512 + col0 + bj * HALF) = pack8i8(a * lsc, b * lsc); }
;                     s += __shfl_xor(s, 16); s += __shfl_xor(s, 32);
;                     if (fq == 0) ssq[(size_t)row * 16 + slot] = s; }
.LBB0_3968:
	s_or_b64 exec, exec, s[6:7]
	v_or_b32_e32 v48, 32, v96
	s_waitcnt lgkmcnt(0)
	v_ashrrev_i32_e32 v49, 31, v48
	v_lshl_add_u64 v[50:51], v[48:49], 3, s[12:13]
	global_load_dwordx2 v[50:51], v[50:51], off
	v_cvt_f32_i32_e32 v41, v41
	v_cvt_f32_i32_e32 v40, v40
	v_cvt_f32_i32_e32 v47, v47
	v_cvt_f32_i32_e32 v46, v46
	v_cvt_f32_i32_e32 v45, v45
	v_cvt_f32_i32_e32 v44, v44
	v_cvt_f32_i32_e32 v43, v43
	v_cvt_f32_i32_e32 v42, v42
	v_lshlrev_b64 v[52:53], 9, v[48:49]
	v_lshl_add_u64 v[52:53], v[162:163], 0, v[52:53]
	s_waitcnt vmcnt(0)
	v_pk_mul_f32 v[50:51], v[50:51], s[28:29] op_sel_hi:[1,0]
	s_nop 0
	v_fma_f32 v97, -v50, v50, v51
	v_add_f32_e32 v97, 0x3727c5ac, v97
	v_rsq_f32_e32 v254, v97
	v_pk_fma_f32 v[54:55], v[82:83], v[50:51], v[158:159] op_sel_hi:[1,0,1]
	v_pk_fma_f32 v[158:159], v[80:81], v[50:51], v[160:161] op_sel_hi:[1,0,1] neg_lo:[1,0,0] neg_hi:[1,0,0]
	v_pk_fma_f32 v[154:155], v[74:75], v[50:51], v[154:155] op_sel_hi:[1,0,1]
	v_pk_fma_f32 v[156:157], v[72:73], v[50:51], v[156:157] op_sel_hi:[1,0,1] neg_lo:[1,0,0] neg_hi:[1,0,0]
	v_pk_mul_f32 v[160:161], v[86:87], v[50:51] op_sel_hi:[1,0]
	v_pk_mul_f32 v[164:165], v[84:85], v[50:51] op_sel_hi:[1,0]
	v_pk_mul_f32 v[166:167], v[78:79], v[50:51] op_sel_hi:[1,0]
	v_pk_mul_f32 v[50:51], v[76:77], v[50:51] op_sel_hi:[1,0]
	v_pk_fma_f32 v[46:47], v[46:47], s[26:27], v[160:161] op_sel_hi:[1,0,1] neg_lo:[0,0,1] neg_hi:[0,0,1]
	v_pk_fma_f32 v[40:41], v[40:41], s[26:27], v[50:51] op_sel_hi:[1,0,1] neg_lo:[0,0,1] neg_hi:[0,0,1]
	v_pk_fma_f32 v[44:45], v[44:45], s[26:27], v[164:165] op_sel_hi:[1,0,1] neg_lo:[0,0,1] neg_hi:[0,0,1]
	v_pk_fma_f32 v[42:43], v[42:43], s[26:27], v[166:167] op_sel_hi:[1,0,1] neg_lo:[0,0,1] neg_hi:[0,0,1]
	s_nop 1
	s_nop 1
	v_mov_b32_e32 v50, v254
	v_pk_fma_f32 v[54:55], v[54:55], v[50:51], v[70:71] op_sel_hi:[1,0,1]
	v_pk_fma_f32 v[158:159], v[158:159], v[50:51], v[68:69] op_sel_hi:[1,0,1]
	v_pk_fma_f32 v[154:155], v[154:155], v[50:51], v[66:67] op_sel_hi:[1,0,1]
	v_pk_fma_f32 v[156:157], v[156:157], v[50:51], v[64:65] op_sel_hi:[1,0,1]
	v_pk_fma_f32 v[46:47], v[46:47], v[50:51], v[62:63] op_sel_hi:[1,0,1]
	v_pk_fma_f32 v[44:45], v[44:45], v[50:51], v[60:61] op_sel_hi:[1,0,1]
	v_pk_fma_f32 v[42:43], v[42:43], v[50:51], v[58:59] op_sel_hi:[1,0,1]
	v_pk_fma_f32 v[40:41], v[40:41], v[50:51], v[56:57] op_sel_hi:[1,0,1]
	v_mul_f32_e32 v97, v159, v159
	v_mul_f32_e32 v136, v55, v55
	v_mul_f32_e32 v172, v157, v157
	v_mul_f32_e32 v173, v155, v155
	v_pk_mul_f32 v[50:51], v[54:55], s[30:31] op_sel_hi:[1,0]
	v_pk_mul_f32 v[160:161], v[158:159], s[30:31] op_sel_hi:[1,0]
	v_pk_mul_f32 v[164:165], v[154:155], s[30:31] op_sel_hi:[1,0]
	v_pk_mul_f32 v[166:167], v[156:157], s[30:31] op_sel_hi:[1,0]
	v_mul_f32_e32 v55, v45, v45
	v_mul_f32_e32 v155, v47, v47
	v_mul_f32_e32 v157, v41, v41
	v_pk_mul_f32 v[168:169], v[46:47], s[30:31] op_sel_hi:[1,0]
	v_pk_mul_f32 v[170:171], v[44:45], s[30:31] op_sel_hi:[1,0]
	v_fmac_f32_e32 v97, v158, v158
	v_fmac_f32_e32 v136, v54, v54
	v_fmac_f32_e32 v172, v156, v156
	v_fmac_f32_e32 v173, v154, v154
	v_med3_f32 v45, v160, s70, v189
	v_med3_f32 v47, v161, s70, v189
	v_med3_f32 v50, v50, s70, v189
	v_med3_f32 v51, v51, s70, v189
	v_med3_f32 v54, v166, s70, v189
	v_med3_f32 v154, v167, s70, v189
	v_med3_f32 v156, v164, s70, v189
	v_med3_f32 v158, v165, s70, v189
	v_fmac_f32_e32 v55, v44, v44
	v_fmac_f32_e32 v155, v46, v46
	v_mul_f32_e32 v159, v43, v43
	v_fmac_f32_e32 v157, v40, v40
	v_add_f32_e32 v44, v97, v136
	v_add_f32_e32 v45, 0x4b400000, v45
	v_add_f32_e32 v46, 0x4b400000, v47
	v_add_f32_e32 v47, 0x4b400000, v50
	v_add_f32_e32 v50, 0x4b400000, v51
	v_add_f32_e32 v51, 0x4b400000, v54
	v_add_f32_e32 v54, 0x4b400000, v154
	v_add_f32_e32 v97, 0x4b400000, v156
	v_add_f32_e32 v136, 0x4b400000, v158
	v_add_f32_e32 v55, v55, v155
	v_fmac_f32_e32 v159, v42, v42
	v_add_f32_e32 v44, v172, v44
	v_perm_b32 v45, v46, v45, s71
	v_perm_b32 v46, v50, v47, s72
	v_perm_b32 v47, v54, v51, s71
	v_perm_b32 v50, v136, v97, s72
	v_add_f32_e32 v51, v157, v55
	v_add_f32_e32 v54, v173, v44
	v_or_b32_e32 v44, v45, v46
	v_or_b32_e32 v45, v47, v50
	v_add_f32_e32 v46, v159, v51
	global_store_dwordx2 v[52:53], v[44:45], off
	v_add_f32_e32 v45, v54, v46
	v_med3_f32 v44, v170, s70, v189
	v_med3_f32 v46, v171, s70, v189
	v_med3_f32 v47, v168, s70, v189
	v_med3_f32 v50, v169, s70, v189
	v_pk_mul_f32 v[40:41], v[40:41], s[30:31] op_sel_hi:[1,0]
	v_add_f32_e32 v44, 0x4b400000, v44
	v_add_f32_e32 v46, 0x4b400000, v46
	v_add_f32_e32 v47, 0x4b400000, v47
	v_add_f32_e32 v50, 0x4b400000, v50
	v_perm_b32 v44, v46, v44, s71
	v_perm_b32 v46, v50, v47, s72
	v_med3_f32 v40, v40, s70, v189
	v_or_b32_e32 v44, v44, v46
	v_add_f32_e32 v46, 0x4b400000, v40
	v_med3_f32 v40, v41, s70, v189
	v_add_f32_e32 v47, 0x4b400000, v40
	v_mov_b32_e32 v40, v45
	s_nop 1
	v_permlane16_swap_b32_e32 v45, v40
	v_pk_mul_f32 v[42:43], v[42:43], s[30:31] op_sel_hi:[1,0]
	s_waitcnt lgkmcnt(0)
	v_add_f32_e32 v40, v45, v40
	v_med3_f32 v41, v42, s70, v189
	v_add_f32_e32 v42, 0x4b400000, v41
	v_med3_f32 v41, v43, s70, v189
	v_add_f32_e32 v43, 0x4b400000, v41
	v_mov_b32_e32 v41, v40
	s_nop 1
	v_permlane32_swap_b32_e32 v40, v41
	v_perm_b32 v45, v47, v46, s71
	v_perm_b32 v42, v43, v42, s72
	v_or_b32_e32 v45, v45, v42
	global_store_dwordx2 v[52:53], v[44:45], off offset:128
	s_and_saveexec_b64 s[6:7], s[2:3]
	s_cbranch_execz .LBB0_3970
	v_lshlrev_b64 v[42:43], 6, v[48:49]
	v_lshl_add_u64 v[42:43], s[10:11], 0, v[42:43]
	v_lshl_add_u64 v[42:43], s[44:45], 2, v[42:43]
	s_waitcnt lgkmcnt(0)
	v_add_f32_e32 v40, v40, v41
	global_store_dword v[42:43], v40, off
; __device__ __forceinline__ u32x2 pack8i8(const f32x4 a, const f32x4 b) { return (u32x2){pack4i8(a), pack4i8(b)}; }
; __device__ __forceinline__ void ln_stats(const float* st, int row, float& mu, float& rs) { const f32x2 s = *(const f32x2*)(st + 2 * (size_t)row); mu = s[0] * (1.0f / DM); rs = 1.0f / sqrtf(s[1] * (1.0f / DM) - mu * mu + LN_EPS); }
;     __device__ __forceinline__ void operator()(EPI_ARGS) const {
;     ...
;                 for (int m = 0; m < 4; ++m) { const int row = row0 + ai * HALF + m * 16; float s = 0.f; float mu, rs; ln_stats(st, row, mu, rs);
; #pragma unroll
;                     for (int bj = 0; bj < 2; ++bj) { const f32x4 a = (acc[ai][bj][m][0] - cc[bj][0] * mu) * rs + dd[bj][0], b = (acc[ai][bj][m][1] - cc[bj][1] * mu) * rs + dd[bj][1];
;                         s += (a[0] * a[0] + a[1] * a[1]) + (a[2] * a[2] + a[3] * a[3]) + (b[0] * b[0] + b[1] * b[1]) + (b[2] * b[2] + b[3] * b[3]);
;                         *(u32x2*)((unsigned char*)dst + (size_t)row * 512 + col0 + bj * HALF) = pack8i8(a * lsc, b * lsc); }
;                     s += __shfl_xor(s, 16); s += __shfl_xor(s, 32);
;                     if (fq == 0) ssq[(size_t)row * 16 + slot] = s; }
.LBB0_3970:
	s_or_b64 exec, exec, s[6:7]
	v_or_b32_e32 v40, 48, v96
	s_waitcnt lgkmcnt(0)
	v_ashrrev_i32_e32 v41, 31, v40
	v_lshl_add_u64 v[42:43], v[40:41], 3, s[12:13]
	global_load_dwordx2 v[42:43], v[42:43], off
	v_cvt_f32_i32_e32 v33, v33
	v_cvt_f32_i32_e32 v32, v32
	v_cvt_f32_i32_e32 v39, v39
	v_cvt_f32_i32_e32 v38, v38
	v_cvt_f32_i32_e32 v37, v37
	v_cvt_f32_i32_e32 v36, v36
	v_cvt_f32_i32_e32 v35, v35
	v_cvt_f32_i32_e32 v34, v34
	v_lshlrev_b64 v[44:45], 9, v[40:41]
	v_lshl_add_u64 v[44:45], v[162:163], 0, v[44:45]
	s_waitcnt vmcnt(0)
	v_pk_mul_f32 v[42:43], v[42:43], s[28:29] op_sel_hi:[1,0]
	s_nop 0
	v_fma_f32 v97, -v42, v42, v43
	v_add_f32_e32 v97, 0x3727c5ac, v97
	v_rsq_f32_e32 v254, v97
	v_pk_fma_f32 v[46:47], v[82:83], v[42:43], v[126:127] op_sel_hi:[1,0,1]
	v_pk_fma_f32 v[48:49], v[80:81], v[42:43], v[152:153] op_sel_hi:[1,0,1] neg_lo:[1,0,0] neg_hi:[1,0,0]
	v_pk_fma_f32 v[50:51], v[74:75], v[42:43], v[122:123] op_sel_hi:[1,0,1]
	v_pk_fma_f32 v[52:53], v[72:73], v[42:43], v[124:125] op_sel_hi:[1,0,1] neg_lo:[1,0,0] neg_hi:[1,0,0]
	v_pk_mul_f32 v[54:55], v[86:87], v[42:43] op_sel_hi:[1,0]
	v_pk_mul_f32 v[122:123], v[84:85], v[42:43] op_sel_hi:[1,0]
	v_pk_mul_f32 v[124:125], v[78:79], v[42:43] op_sel_hi:[1,0]
	v_pk_mul_f32 v[42:43], v[76:77], v[42:43] op_sel_hi:[1,0]
	v_pk_fma_f32 v[38:39], v[38:39], s[26:27], v[54:55] op_sel_hi:[1,0,1] neg_lo:[0,0,1] neg_hi:[0,0,1]
	v_pk_fma_f32 v[32:33], v[32:33], s[26:27], v[42:43] op_sel_hi:[1,0,1] neg_lo:[0,0,1] neg_hi:[0,0,1]
	v_pk_fma_f32 v[36:37], v[36:37], s[26:27], v[122:123] op_sel_hi:[1,0,1] neg_lo:[0,0,1] neg_hi:[0,0,1]
	v_pk_fma_f32 v[34:35], v[34:35], s[26:27], v[124:125] op_sel_hi:[1,0,1] neg_lo:[0,0,1] neg_hi:[0,0,1]
	s_nop 1
	s_nop 1
	v_mov_b32_e32 v42, v254
	v_pk_fma_f32 v[46:47], v[46:47], v[42:43], v[70:71] op_sel_hi:[1,0,1]
	v_pk_fma_f32 v[48:49], v[48:49], v[42:43], v[68:69] op_sel_hi:[1,0,1]
	v_pk_fma_f32 v[50:51], v[50:51], v[42:43], v[66:67] op_sel_hi:[1,0,1]
	v_pk_fma_f32 v[52:53], v[52:53], v[42:43], v[64:65] op_sel_hi:[1,0,1]
	v_pk_fma_f32 v[38:39], v[38:39], v[42:43], v[62:63] op_sel_hi:[1,0,1]
	v_pk_fma_f32 v[36:37], v[36:37], v[42:43], v[60:61] op_sel_hi:[1,0,1]
	v_pk_fma_f32 v[34:35], v[34:35], v[42:43], v[58:59] op_sel_hi:[1,0,1]
	v_pk_fma_f32 v[32:33], v[32:33], v[42:43], v[56:57] op_sel_hi:[1,0,1]
	v_mul_f32_e32 v97, v49, v49
	v_mul_f32_e32 v136, v47, v47
	v_mul_f32_e32 v154, v53, v53
	v_mul_f32_e32 v155, v51, v51
	v_pk_mul_f32 v[42:43], v[46:47], s[30:31] op_sel_hi:[1,0]
	v_pk_mul_f32 v[54:55], v[48:49], s[30:31] op_sel_hi:[1,0]
	v_pk_mul_f32 v[122:123], v[50:51], s[30:31] op_sel_hi:[1,0]
	v_pk_mul_f32 v[124:125], v[52:53], s[30:31] op_sel_hi:[1,0]
	v_mul_f32_e32 v47, v37, v37
	v_mul_f32_e32 v49, v39, v39
	v_mul_f32_e32 v51, v33, v33
	v_pk_mul_f32 v[126:127], v[38:39], s[30:31] op_sel_hi:[1,0]
	v_pk_mul_f32 v[152:153], v[36:37], s[30:31] op_sel_hi:[1,0]
	v_fmac_f32_e32 v97, v48, v48
	v_fmac_f32_e32 v136, v46, v46
	v_fmac_f32_e32 v154, v52, v52
	v_fmac_f32_e32 v155, v50, v50
	v_med3_f32 v37, v54, s70, v189
	v_med3_f32 v39, v55, s70, v189
	v_med3_f32 v42, v42, s70, v189
	v_med3_f32 v43, v43, s70, v189
	v_med3_f32 v46, v124, s70, v189
	v_med3_f32 v48, v125, s70, v189
	v_med3_f32 v50, v122, s70, v189
	v_med3_f32 v52, v123, s70, v189
	v_fmac_f32_e32 v47, v36, v36
	v_fmac_f32_e32 v49, v38, v38
	v_mul_f32_e32 v53, v35, v35
	v_fmac_f32_e32 v51, v32, v32
	v_add_f32_e32 v36, v97, v136
	v_add_f32_e32 v37, 0x4b400000, v37
	v_add_f32_e32 v38, 0x4b400000, v39
	v_add_f32_e32 v39, 0x4b400000, v42
	v_add_f32_e32 v42, 0x4b400000, v43
	v_add_f32_e32 v43, 0x4b400000, v46
	v_add_f32_e32 v46, 0x4b400000, v48
	v_add_f32_e32 v48, 0x4b400000, v50
	v_add_f32_e32 v50, 0x4b400000, v52
	v_add_f32_e32 v47, v47, v49
	v_fmac_f32_e32 v53, v34, v34
	v_add_f32_e32 v36, v154, v36
	v_perm_b32 v37, v38, v37, s71
	v_perm_b32 v38, v42, v39, s72
	v_perm_b32 v39, v46, v43, s71
	v_perm_b32 v42, v50, v48, s72
	v_add_f32_e32 v43, v51, v47
	v_add_f32_e32 v46, v155, v36
	v_or_b32_e32 v36, v37, v38
	v_or_b32_e32 v37, v39, v42
	v_add_f32_e32 v38, v53, v43
	global_store_dwordx2 v[44:45], v[36:37], off
	v_add_f32_e32 v37, v46, v38
	v_med3_f32 v36, v152, s70, v189
	v_med3_f32 v38, v153, s70, v189
	v_med3_f32 v39, v126, s70, v189
	v_med3_f32 v42, v127, s70, v189
	v_pk_mul_f32 v[32:33], v[32:33], s[30:31] op_sel_hi:[1,0]
	v_add_f32_e32 v36, 0x4b400000, v36
	v_add_f32_e32 v38, 0x4b400000, v38
	v_add_f32_e32 v39, 0x4b400000, v39
	v_add_f32_e32 v42, 0x4b400000, v42
	v_perm_b32 v36, v38, v36, s71
	v_perm_b32 v38, v42, v39, s72
	v_med3_f32 v32, v32, s70, v189
	v_or_b32_e32 v36, v36, v38
	v_add_f32_e32 v38, 0x4b400000, v32
	v_med3_f32 v32, v33, s70, v189
	v_add_f32_e32 v39, 0x4b400000, v32
	v_mov_b32_e32 v32, v37
	s_nop 1
	v_permlane16_swap_b32_e32 v37, v32
	v_pk_mul_f32 v[34:35], v[34:35], s[30:31] op_sel_hi:[1,0]
	s_waitcnt lgkmcnt(0)
	v_add_f32_e32 v32, v37, v32
	v_med3_f32 v33, v34, s70, v189
	v_add_f32_e32 v34, 0x4b400000, v33
	v_med3_f32 v33, v35, s70, v189
	v_add_f32_e32 v35, 0x4b400000, v33
	v_mov_b32_e32 v33, v32
	s_nop 1
	v_permlane32_swap_b32_e32 v32, v33
	v_perm_b32 v37, v39, v38, s71
	v_perm_b32 v34, v35, v34, s72
	v_or_b32_e32 v37, v37, v34
	global_store_dwordx2 v[44:45], v[36:37], off offset:128
	s_and_saveexec_b64 s[6:7], s[2:3]
	s_cbranch_execz .LBB0_3972
	v_lshlrev_b64 v[34:35], 6, v[40:41]
	v_lshl_add_u64 v[34:35], s[10:11], 0, v[34:35]
	v_lshl_add_u64 v[34:35], s[44:45], 2, v[34:35]
	s_waitcnt lgkmcnt(0)
	v_add_f32_e32 v32, v32, v33
	global_store_dword v[34:35], v32, off
; __device__ __forceinline__ u32x2 pack8i8(const f32x4 a, const f32x4 b) { return (u32x2){pack4i8(a), pack4i8(b)}; }
; __device__ __forceinline__ void ln_stats(const float* st, int row, float& mu, float& rs) { const f32x2 s = *(const f32x2*)(st + 2 * (size_t)row); mu = s[0] * (1.0f / DM); rs = 1.0f / sqrtf(s[1] * (1.0f / DM) - mu * mu + LN_EPS); }
;     __device__ __forceinline__ void operator()(EPI_ARGS) const {
;     ...
;                 for (int m = 0; m < 4; ++m) { const int row = row0 + ai * HALF + m * 16; float s = 0.f; float mu, rs; ln_stats(st, row, mu, rs);
; #pragma unroll
;                     for (int bj = 0; bj < 2; ++bj) { const f32x4 a = (acc[ai][bj][m][0] - cc[bj][0] * mu) * rs + dd[bj][0], b = (acc[ai][bj][m][1] - cc[bj][1] * mu) * rs + dd[bj][1];
;                         s += (a[0] * a[0] + a[1] * a[1]) + (a[2] * a[2] + a[3] * a[3]) + (b[0] * b[0] + b[1] * b[1]) + (b[2] * b[2] + b[3] * b[3]);
;                         *(u32x2*)((unsigned char*)dst + (size_t)row * 512 + col0 + bj * HALF) = pack8i8(a * lsc, b * lsc); }
;                     s += __shfl_xor(s, 16); s += __shfl_xor(s, 32);
;                     if (fq == 0) ssq[(size_t)row * 16 + slot] = s; }
.LBB0_3972:
	s_or_b64 exec, exec, s[6:7]
	v_add_u32_e32 v32, 0x80, v96
	s_waitcnt lgkmcnt(0)
	v_ashrrev_i32_e32 v33, 31, v32
	v_lshl_add_u64 v[34:35], v[32:33], 3, s[12:13]
	global_load_dwordx2 v[34:35], v[34:35], off
	v_cvt_f32_i32_e32 v25, v25
	v_cvt_f32_i32_e32 v24, v24
	v_cvt_f32_i32_e32 v31, v31
	v_cvt_f32_i32_e32 v30, v30
	v_cvt_f32_i32_e32 v29, v29
	v_cvt_f32_i32_e32 v28, v28
	v_cvt_f32_i32_e32 v27, v27
	v_cvt_f32_i32_e32 v26, v26
	v_lshlrev_b64 v[36:37], 9, v[32:33]
	v_lshl_add_u64 v[36:37], v[162:163], 0, v[36:37]
	s_waitcnt vmcnt(0)
	v_pk_mul_f32 v[34:35], v[34:35], s[28:29] op_sel_hi:[1,0]
	s_nop 0
	v_fma_f32 v52, -v34, v34, v35
	v_add_f32_e32 v52, 0x3727c5ac, v52
	v_rsq_f32_e32 v254, v52
	v_pk_fma_f32 v[38:39], v[82:83], v[34:35], v[118:119] op_sel_hi:[1,0,1]
	v_pk_fma_f32 v[40:41], v[80:81], v[34:35], v[120:121] op_sel_hi:[1,0,1] neg_lo:[1,0,0] neg_hi:[1,0,0]
	v_pk_fma_f32 v[42:43], v[74:75], v[34:35], v[114:115] op_sel_hi:[1,0,1]
	v_pk_fma_f32 v[44:45], v[72:73], v[34:35], v[116:117] op_sel_hi:[1,0,1] neg_lo:[1,0,0] neg_hi:[1,0,0]
	v_pk_mul_f32 v[46:47], v[86:87], v[34:35] op_sel_hi:[1,0]
	v_pk_mul_f32 v[48:49], v[84:85], v[34:35] op_sel_hi:[1,0]
	v_pk_mul_f32 v[50:51], v[78:79], v[34:35] op_sel_hi:[1,0]
	v_pk_mul_f32 v[34:35], v[76:77], v[34:35] op_sel_hi:[1,0]
	v_pk_fma_f32 v[30:31], v[30:31], s[26:27], v[46:47] op_sel_hi:[1,0,1] neg_lo:[0,0,1] neg_hi:[0,0,1]
	v_pk_fma_f32 v[24:25], v[24:25], s[26:27], v[34:35] op_sel_hi:[1,0,1] neg_lo:[0,0,1] neg_hi:[0,0,1]
	v_pk_fma_f32 v[28:29], v[28:29], s[26:27], v[48:49] op_sel_hi:[1,0,1] neg_lo:[0,0,1] neg_hi:[0,0,1]
	v_pk_fma_f32 v[26:27], v[26:27], s[26:27], v[50:51] op_sel_hi:[1,0,1] neg_lo:[0,0,1] neg_hi:[0,0,1]
	s_nop 1
	s_nop 1
	v_mov_b32_e32 v34, v254
	v_pk_fma_f32 v[38:39], v[38:39], v[34:35], v[70:71] op_sel_hi:[1,0,1]
	v_pk_fma_f32 v[40:41], v[40:41], v[34:35], v[68:69] op_sel_hi:[1,0,1]
	v_pk_fma_f32 v[42:43], v[42:43], v[34:35], v[66:67] op_sel_hi:[1,0,1]
	v_pk_fma_f32 v[44:45], v[44:45], v[34:35], v[64:65] op_sel_hi:[1,0,1]
	v_pk_fma_f32 v[30:31], v[30:31], v[34:35], v[62:63] op_sel_hi:[1,0,1]
	v_pk_fma_f32 v[28:29], v[28:29], v[34:35], v[60:61] op_sel_hi:[1,0,1]
	v_pk_fma_f32 v[26:27], v[26:27], v[34:35], v[58:59] op_sel_hi:[1,0,1]
	v_pk_fma_f32 v[24:25], v[24:25], v[34:35], v[56:57] op_sel_hi:[1,0,1]
	v_mul_f32_e32 v97, v41, v41
	v_mul_f32_e32 v114, v39, v39
	v_mul_f32_e32 v115, v45, v45
	v_mul_f32_e32 v116, v43, v43
	v_pk_mul_f32 v[34:35], v[38:39], s[30:31] op_sel_hi:[1,0]
	v_pk_mul_f32 v[46:47], v[40:41], s[30:31] op_sel_hi:[1,0]
	v_pk_mul_f32 v[48:49], v[42:43], s[30:31] op_sel_hi:[1,0]
	v_pk_mul_f32 v[50:51], v[44:45], s[30:31] op_sel_hi:[1,0]
	v_mul_f32_e32 v39, v29, v29
	v_mul_f32_e32 v41, v31, v31
	v_mul_f32_e32 v43, v25, v25
	v_pk_mul_f32 v[52:53], v[30:31], s[30:31] op_sel_hi:[1,0]
	v_pk_mul_f32 v[54:55], v[28:29], s[30:31] op_sel_hi:[1,0]
	v_fmac_f32_e32 v97, v40, v40
	v_fmac_f32_e32 v114, v38, v38
	v_fmac_f32_e32 v115, v44, v44
	v_fmac_f32_e32 v116, v42, v42
	v_med3_f32 v29, v46, s70, v189
	v_med3_f32 v31, v47, s70, v189
	v_med3_f32 v34, v34, s70, v189
	v_med3_f32 v35, v35, s70, v189
	v_med3_f32 v38, v50, s70, v189
	v_med3_f32 v40, v51, s70, v189
	v_med3_f32 v42, v48, s70, v189
	v_med3_f32 v44, v49, s70, v189
	v_fmac_f32_e32 v39, v28, v28
	v_fmac_f32_e32 v41, v30, v30
	v_mul_f32_e32 v45, v27, v27
	v_fmac_f32_e32 v43, v24, v24
	v_add_f32_e32 v28, v97, v114
	v_add_f32_e32 v29, 0x4b400000, v29
	v_add_f32_e32 v30, 0x4b400000, v31
	v_add_f32_e32 v31, 0x4b400000, v34
	v_add_f32_e32 v34, 0x4b400000, v35
	v_add_f32_e32 v35, 0x4b400000, v38
	v_add_f32_e32 v38, 0x4b400000, v40
	v_add_f32_e32 v40, 0x4b400000, v42
	v_add_f32_e32 v42, 0x4b400000, v44
	v_add_f32_e32 v39, v39, v41
	v_fmac_f32_e32 v45, v26, v26
	v_add_f32_e32 v28, v115, v28
	v_perm_b32 v29, v30, v29, s71
	v_perm_b32 v30, v34, v31, s72
	v_perm_b32 v31, v38, v35, s71
	v_perm_b32 v34, v42, v40, s72
	v_add_f32_e32 v35, v43, v39
	v_add_f32_e32 v38, v116, v28
	v_or_b32_e32 v28, v29, v30
	v_or_b32_e32 v29, v31, v34
	v_add_f32_e32 v30, v45, v35
	global_store_dwordx2 v[36:37], v[28:29], off
	v_add_f32_e32 v29, v38, v30
	v_med3_f32 v28, v54, s70, v189
	v_med3_f32 v30, v55, s70, v189
	v_med3_f32 v31, v52, s70, v189
	v_med3_f32 v34, v53, s70, v189
	v_pk_mul_f32 v[24:25], v[24:25], s[30:31] op_sel_hi:[1,0]
	v_add_f32_e32 v28, 0x4b400000, v28
	v_add_f32_e32 v30, 0x4b400000, v30
	v_add_f32_e32 v31, 0x4b400000, v31
	v_add_f32_e32 v34, 0x4b400000, v34
	v_perm_b32 v28, v30, v28, s71
	v_perm_b32 v30, v34, v31, s72
	v_med3_f32 v24, v24, s70, v189
	v_or_b32_e32 v28, v28, v30
	v_add_f32_e32 v30, 0x4b400000, v24
	v_med3_f32 v24, v25, s70, v189
	v_add_f32_e32 v31, 0x4b400000, v24
	v_mov_b32_e32 v24, v29
	s_nop 1
	v_permlane16_swap_b32_e32 v29, v24
	v_pk_mul_f32 v[26:27], v[26:27], s[30:31] op_sel_hi:[1,0]
	s_waitcnt lgkmcnt(0)
	v_add_f32_e32 v24, v29, v24
	v_med3_f32 v25, v26, s70, v189
	v_add_f32_e32 v26, 0x4b400000, v25
	v_med3_f32 v25, v27, s70, v189
	v_add_f32_e32 v27, 0x4b400000, v25
	v_mov_b32_e32 v25, v24
	s_nop 1
	v_permlane32_swap_b32_e32 v24, v25
	v_perm_b32 v29, v31, v30, s71
	v_perm_b32 v26, v27, v26, s72
	v_or_b32_e32 v29, v29, v26
	global_store_dwordx2 v[36:37], v[28:29], off offset:128
	s_and_saveexec_b64 s[6:7], s[2:3]
	s_cbranch_execz .LBB0_3974
	v_lshlrev_b64 v[26:27], 6, v[32:33]
	v_lshl_add_u64 v[26:27], s[10:11], 0, v[26:27]
	v_lshl_add_u64 v[26:27], s[44:45], 2, v[26:27]
	s_waitcnt lgkmcnt(0)
	v_add_f32_e32 v24, v24, v25
	global_store_dword v[26:27], v24, off
; __device__ __forceinline__ u32x2 pack8i8(const f32x4 a, const f32x4 b) { return (u32x2){pack4i8(a), pack4i8(b)}; }
; __device__ __forceinline__ void ln_stats(const float* st, int row, float& mu, float& rs) { const f32x2 s = *(const f32x2*)(st + 2 * (size_t)row); mu = s[0] * (1.0f / DM); rs = 1.0f / sqrtf(s[1] * (1.0f / DM) - mu * mu + LN_EPS); }
;     __device__ __forceinline__ void operator()(EPI_ARGS) const {
;     ...
;                 for (int m = 0; m < 4; ++m) { const int row = row0 + ai * HALF + m * 16; float s = 0.f; float mu, rs; ln_stats(st, row, mu, rs);
; #pragma unroll
;                     for (int bj = 0; bj < 2; ++bj) { const f32x4 a = (acc[ai][bj][m][0] - cc[bj][0] * mu) * rs + dd[bj][0], b = (acc[ai][bj][m][1] - cc[bj][1] * mu) * rs + dd[bj][1];
;                         s += (a[0] * a[0] + a[1] * a[1]) + (a[2] * a[2] + a[3] * a[3]) + (b[0] * b[0] + b[1] * b[1]) + (b[2] * b[2] + b[3] * b[3]);
;                         *(u32x2*)((unsigned char*)dst + (size_t)row * 512 + col0 + bj * HALF) = pack8i8(a * lsc, b * lsc); }
;                     s += __shfl_xor(s, 16); s += __shfl_xor(s, 32);
;                     if (fq == 0) ssq[(size_t)row * 16 + slot] = s; }
.LBB0_3974:
	s_or_b64 exec, exec, s[6:7]
	v_add_u32_e32 v24, 0x90, v96
	s_waitcnt lgkmcnt(0)
	v_ashrrev_i32_e32 v25, 31, v24
	v_lshl_add_u64 v[26:27], v[24:25], 3, s[12:13]
	global_load_dwordx2 v[26:27], v[26:27], off
	v_cvt_f32_i32_e32 v17, v17
	v_cvt_f32_i32_e32 v16, v16
	v_cvt_f32_i32_e32 v23, v23
	v_cvt_f32_i32_e32 v22, v22
	v_cvt_f32_i32_e32 v21, v21
	v_cvt_f32_i32_e32 v20, v20
	v_cvt_f32_i32_e32 v19, v19
	v_cvt_f32_i32_e32 v18, v18
	v_lshlrev_b64 v[28:29], 9, v[24:25]
	v_lshl_add_u64 v[28:29], v[162:163], 0, v[28:29]
	s_waitcnt vmcnt(0)
	v_pk_mul_f32 v[26:27], v[26:27], s[28:29] op_sel_hi:[1,0]
	s_nop 0
	v_fma_f32 v44, -v26, v26, v27
	v_add_f32_e32 v44, 0x3727c5ac, v44
	v_rsq_f32_e32 v254, v44
	v_pk_fma_f32 v[30:31], v[82:83], v[26:27], v[110:111] op_sel_hi:[1,0,1]
	v_pk_fma_f32 v[32:33], v[80:81], v[26:27], v[112:113] op_sel_hi:[1,0,1] neg_lo:[1,0,0] neg_hi:[1,0,0]
	v_pk_fma_f32 v[34:35], v[74:75], v[26:27], v[106:107] op_sel_hi:[1,0,1]
	v_pk_fma_f32 v[36:37], v[72:73], v[26:27], v[108:109] op_sel_hi:[1,0,1] neg_lo:[1,0,0] neg_hi:[1,0,0]
	v_pk_mul_f32 v[38:39], v[86:87], v[26:27] op_sel_hi:[1,0]
	v_pk_mul_f32 v[40:41], v[84:85], v[26:27] op_sel_hi:[1,0]
	v_pk_mul_f32 v[42:43], v[78:79], v[26:27] op_sel_hi:[1,0]
	v_pk_mul_f32 v[26:27], v[76:77], v[26:27] op_sel_hi:[1,0]
	v_pk_fma_f32 v[22:23], v[22:23], s[26:27], v[38:39] op_sel_hi:[1,0,1] neg_lo:[0,0,1] neg_hi:[0,0,1]
	v_pk_fma_f32 v[16:17], v[16:17], s[26:27], v[26:27] op_sel_hi:[1,0,1] neg_lo:[0,0,1] neg_hi:[0,0,1]
	v_pk_fma_f32 v[20:21], v[20:21], s[26:27], v[40:41] op_sel_hi:[1,0,1] neg_lo:[0,0,1] neg_hi:[0,0,1]
	v_pk_fma_f32 v[18:19], v[18:19], s[26:27], v[42:43] op_sel_hi:[1,0,1] neg_lo:[0,0,1] neg_hi:[0,0,1]
	s_nop 1
	s_nop 1
	v_mov_b32_e32 v26, v254
	v_pk_fma_f32 v[30:31], v[30:31], v[26:27], v[70:71] op_sel_hi:[1,0,1]
	v_pk_fma_f32 v[32:33], v[32:33], v[26:27], v[68:69] op_sel_hi:[1,0,1]
	v_pk_fma_f32 v[34:35], v[34:35], v[26:27], v[66:67] op_sel_hi:[1,0,1]
	v_pk_fma_f32 v[36:37], v[36:37], v[26:27], v[64:65] op_sel_hi:[1,0,1]
	v_pk_fma_f32 v[22:23], v[22:23], v[26:27], v[62:63] op_sel_hi:[1,0,1]
	v_pk_fma_f32 v[20:21], v[20:21], v[26:27], v[60:61] op_sel_hi:[1,0,1]
	v_pk_fma_f32 v[18:19], v[18:19], v[26:27], v[58:59] op_sel_hi:[1,0,1]
	v_pk_fma_f32 v[16:17], v[16:17], v[26:27], v[56:57] op_sel_hi:[1,0,1]
	v_mul_f32_e32 v48, v33, v33
	v_mul_f32_e32 v49, v31, v31
	v_mul_f32_e32 v50, v37, v37
	v_mul_f32_e32 v51, v35, v35
	v_pk_mul_f32 v[26:27], v[30:31], s[30:31] op_sel_hi:[1,0]
	v_pk_mul_f32 v[38:39], v[32:33], s[30:31] op_sel_hi:[1,0]
	v_pk_mul_f32 v[40:41], v[34:35], s[30:31] op_sel_hi:[1,0]
	v_pk_mul_f32 v[42:43], v[36:37], s[30:31] op_sel_hi:[1,0]
	v_mul_f32_e32 v31, v21, v21
	v_mul_f32_e32 v33, v23, v23
	v_mul_f32_e32 v35, v17, v17
	v_pk_mul_f32 v[44:45], v[22:23], s[30:31] op_sel_hi:[1,0]
	v_pk_mul_f32 v[46:47], v[20:21], s[30:31] op_sel_hi:[1,0]
	v_fmac_f32_e32 v48, v32, v32
	v_fmac_f32_e32 v49, v30, v30
	v_fmac_f32_e32 v50, v36, v36
	v_fmac_f32_e32 v51, v34, v34
	v_med3_f32 v21, v38, s70, v189
	v_med3_f32 v23, v39, s70, v189
	v_med3_f32 v26, v26, s70, v189
	v_med3_f32 v27, v27, s70, v189
	v_med3_f32 v30, v42, s70, v189
	v_med3_f32 v32, v43, s70, v189
	v_med3_f32 v34, v40, s70, v189
	v_med3_f32 v36, v41, s70, v189
	v_fmac_f32_e32 v31, v20, v20
	v_fmac_f32_e32 v33, v22, v22
	v_mul_f32_e32 v37, v19, v19
	v_fmac_f32_e32 v35, v16, v16
	v_add_f32_e32 v20, v48, v49
	v_add_f32_e32 v21, 0x4b400000, v21
	v_add_f32_e32 v22, 0x4b400000, v23
	v_add_f32_e32 v23, 0x4b400000, v26
	v_add_f32_e32 v26, 0x4b400000, v27
	v_add_f32_e32 v27, 0x4b400000, v30
	v_add_f32_e32 v30, 0x4b400000, v32
	v_add_f32_e32 v32, 0x4b400000, v34
	v_add_f32_e32 v34, 0x4b400000, v36
	v_add_f32_e32 v31, v31, v33
	v_fmac_f32_e32 v37, v18, v18
	v_add_f32_e32 v20, v50, v20
	v_perm_b32 v21, v22, v21, s71
	v_perm_b32 v22, v26, v23, s72
	v_perm_b32 v23, v30, v27, s71
	v_perm_b32 v26, v34, v32, s72
	v_add_f32_e32 v27, v35, v31
	v_add_f32_e32 v30, v51, v20
	v_or_b32_e32 v20, v21, v22
	v_or_b32_e32 v21, v23, v26
	v_add_f32_e32 v22, v37, v27
	global_store_dwordx2 v[28:29], v[20:21], off
	v_add_f32_e32 v21, v30, v22
	v_med3_f32 v20, v46, s70, v189
	v_med3_f32 v22, v47, s70, v189
	v_med3_f32 v23, v44, s70, v189
	v_med3_f32 v26, v45, s70, v189
	v_pk_mul_f32 v[16:17], v[16:17], s[30:31] op_sel_hi:[1,0]
	v_add_f32_e32 v20, 0x4b400000, v20
	v_add_f32_e32 v22, 0x4b400000, v22
	v_add_f32_e32 v23, 0x4b400000, v23
	v_add_f32_e32 v26, 0x4b400000, v26
	v_perm_b32 v20, v22, v20, s71
	v_perm_b32 v22, v26, v23, s72
	v_med3_f32 v16, v16, s70, v189
	v_or_b32_e32 v20, v20, v22
	v_add_f32_e32 v22, 0x4b400000, v16
	v_med3_f32 v16, v17, s70, v189
	v_add_f32_e32 v23, 0x4b400000, v16
	v_mov_b32_e32 v16, v21
	s_nop 1
	v_permlane16_swap_b32_e32 v21, v16
	v_pk_mul_f32 v[18:19], v[18:19], s[30:31] op_sel_hi:[1,0]
	s_waitcnt lgkmcnt(0)
	v_add_f32_e32 v16, v21, v16
	v_med3_f32 v17, v18, s70, v189
	v_add_f32_e32 v18, 0x4b400000, v17
	v_med3_f32 v17, v19, s70, v189
	v_add_f32_e32 v19, 0x4b400000, v17
	v_mov_b32_e32 v17, v16
	s_nop 1
	v_permlane32_swap_b32_e32 v16, v17
	v_perm_b32 v21, v23, v22, s71
	v_perm_b32 v18, v19, v18, s72
	v_or_b32_e32 v21, v21, v18
	global_store_dwordx2 v[28:29], v[20:21], off offset:128
	s_and_saveexec_b64 s[6:7], s[2:3]
	s_cbranch_execz .LBB0_3976
	v_lshlrev_b64 v[18:19], 6, v[24:25]
	v_lshl_add_u64 v[18:19], s[10:11], 0, v[18:19]
	v_lshl_add_u64 v[18:19], s[44:45], 2, v[18:19]
	s_waitcnt lgkmcnt(0)
	v_add_f32_e32 v16, v16, v17
	global_store_dword v[18:19], v16, off
; __device__ __forceinline__ u32x2 pack8i8(const f32x4 a, const f32x4 b) { return (u32x2){pack4i8(a), pack4i8(b)}; }
; __device__ __forceinline__ void ln_stats(const float* st, int row, float& mu, float& rs) { const f32x2 s = *(const f32x2*)(st + 2 * (size_t)row); mu = s[0] * (1.0f / DM); rs = 1.0f / sqrtf(s[1] * (1.0f / DM) - mu * mu + LN_EPS); }
;     __device__ __forceinline__ void operator()(EPI_ARGS) const {
;     ...
;                 for (int m = 0; m < 4; ++m) { const int row = row0 + ai * HALF + m * 16; float s = 0.f; float mu, rs; ln_stats(st, row, mu, rs);
; #pragma unroll
;                     for (int bj = 0; bj < 2; ++bj) { const f32x4 a = (acc[ai][bj][m][0] - cc[bj][0] * mu) * rs + dd[bj][0], b = (acc[ai][bj][m][1] - cc[bj][1] * mu) * rs + dd[bj][1];
;                         s += (a[0] * a[0] + a[1] * a[1]) + (a[2] * a[2] + a[3] * a[3]) + (b[0] * b[0] + b[1] * b[1]) + (b[2] * b[2] + b[3] * b[3]);
;                         *(u32x2*)((unsigned char*)dst + (size_t)row * 512 + col0 + bj * HALF) = pack8i8(a * lsc, b * lsc); }
;                     s += __shfl_xor(s, 16); s += __shfl_xor(s, 32);
;                     if (fq == 0) ssq[(size_t)row * 16 + slot] = s; }
.LBB0_3976:
	s_or_b64 exec, exec, s[6:7]
	v_add_u32_e32 v16, 0xa0, v96
	s_waitcnt lgkmcnt(0)
	v_ashrrev_i32_e32 v17, 31, v16
	v_lshl_add_u64 v[18:19], v[16:17], 3, s[12:13]
	global_load_dwordx2 v[18:19], v[18:19], off
	v_cvt_f32_i32_e32 v9, v9
	v_cvt_f32_i32_e32 v8, v8
	v_cvt_f32_i32_e32 v15, v15
	v_cvt_f32_i32_e32 v14, v14
	v_cvt_f32_i32_e32 v13, v13
	v_cvt_f32_i32_e32 v12, v12
	v_cvt_f32_i32_e32 v11, v11
	v_cvt_f32_i32_e32 v10, v10
	v_lshlrev_b64 v[20:21], 9, v[16:17]
	v_lshl_add_u64 v[20:21], v[162:163], 0, v[20:21]
	s_waitcnt vmcnt(0)
	v_pk_mul_f32 v[18:19], v[18:19], s[28:29] op_sel_hi:[1,0]
	s_nop 0
	v_fma_f32 v36, -v18, v18, v19
	v_add_f32_e32 v36, 0x3727c5ac, v36
	v_rsq_f32_e32 v254, v36
	v_pk_fma_f32 v[22:23], v[82:83], v[18:19], v[102:103] op_sel_hi:[1,0,1]
	v_pk_fma_f32 v[24:25], v[80:81], v[18:19], v[104:105] op_sel_hi:[1,0,1] neg_lo:[1,0,0] neg_hi:[1,0,0]
	v_pk_fma_f32 v[26:27], v[74:75], v[18:19], v[98:99] op_sel_hi:[1,0,1]
	v_pk_fma_f32 v[28:29], v[72:73], v[18:19], v[100:101] op_sel_hi:[1,0,1] neg_lo:[1,0,0] neg_hi:[1,0,0]
	v_pk_mul_f32 v[30:31], v[86:87], v[18:19] op_sel_hi:[1,0]
	v_pk_mul_f32 v[32:33], v[84:85], v[18:19] op_sel_hi:[1,0]
	v_pk_mul_f32 v[34:35], v[78:79], v[18:19] op_sel_hi:[1,0]
	v_pk_mul_f32 v[18:19], v[76:77], v[18:19] op_sel_hi:[1,0]
	v_pk_fma_f32 v[14:15], v[14:15], s[26:27], v[30:31] op_sel_hi:[1,0,1] neg_lo:[0,0,1] neg_hi:[0,0,1]
	v_pk_fma_f32 v[8:9], v[8:9], s[26:27], v[18:19] op_sel_hi:[1,0,1] neg_lo:[0,0,1] neg_hi:[0,0,1]
	v_pk_fma_f32 v[12:13], v[12:13], s[26:27], v[32:33] op_sel_hi:[1,0,1] neg_lo:[0,0,1] neg_hi:[0,0,1]
	v_pk_fma_f32 v[10:11], v[10:11], s[26:27], v[34:35] op_sel_hi:[1,0,1] neg_lo:[0,0,1] neg_hi:[0,0,1]
	s_nop 1
	s_nop 1
	v_mov_b32_e32 v18, v254
	v_pk_fma_f32 v[22:23], v[22:23], v[18:19], v[70:71] op_sel_hi:[1,0,1]
	v_pk_fma_f32 v[24:25], v[24:25], v[18:19], v[68:69] op_sel_hi:[1,0,1]
	v_pk_fma_f32 v[26:27], v[26:27], v[18:19], v[66:67] op_sel_hi:[1,0,1]
	v_pk_fma_f32 v[28:29], v[28:29], v[18:19], v[64:65] op_sel_hi:[1,0,1]
	v_pk_fma_f32 v[14:15], v[14:15], v[18:19], v[62:63] op_sel_hi:[1,0,1]
	v_pk_fma_f32 v[12:13], v[12:13], v[18:19], v[60:61] op_sel_hi:[1,0,1]
	v_pk_fma_f32 v[10:11], v[10:11], v[18:19], v[58:59] op_sel_hi:[1,0,1]
	v_pk_fma_f32 v[8:9], v[8:9], v[18:19], v[56:57] op_sel_hi:[1,0,1]
	v_mul_f32_e32 v40, v25, v25
	v_mul_f32_e32 v41, v23, v23
	v_mul_f32_e32 v42, v29, v29
	v_mul_f32_e32 v43, v27, v27
	v_pk_mul_f32 v[18:19], v[22:23], s[30:31] op_sel_hi:[1,0]
	v_pk_mul_f32 v[30:31], v[24:25], s[30:31] op_sel_hi:[1,0]
	v_pk_mul_f32 v[32:33], v[26:27], s[30:31] op_sel_hi:[1,0]
	v_pk_mul_f32 v[34:35], v[28:29], s[30:31] op_sel_hi:[1,0]
	v_mul_f32_e32 v23, v13, v13
	v_mul_f32_e32 v25, v15, v15
	v_mul_f32_e32 v27, v9, v9
	v_pk_mul_f32 v[36:37], v[14:15], s[30:31] op_sel_hi:[1,0]
	v_pk_mul_f32 v[38:39], v[12:13], s[30:31] op_sel_hi:[1,0]
	v_fmac_f32_e32 v40, v24, v24
	v_fmac_f32_e32 v41, v22, v22
	v_fmac_f32_e32 v42, v28, v28
	v_fmac_f32_e32 v43, v26, v26
	v_med3_f32 v13, v30, s70, v189
	v_med3_f32 v15, v31, s70, v189
	v_med3_f32 v18, v18, s70, v189
	v_med3_f32 v19, v19, s70, v189
	v_med3_f32 v22, v34, s70, v189
	v_med3_f32 v24, v35, s70, v189
	v_med3_f32 v26, v32, s70, v189
	v_med3_f32 v28, v33, s70, v189
	v_fmac_f32_e32 v23, v12, v12
	v_fmac_f32_e32 v25, v14, v14
	v_mul_f32_e32 v29, v11, v11
	v_fmac_f32_e32 v27, v8, v8
	v_add_f32_e32 v12, v40, v41
	v_add_f32_e32 v13, 0x4b400000, v13
	v_add_f32_e32 v14, 0x4b400000, v15
	v_add_f32_e32 v15, 0x4b400000, v18
	v_add_f32_e32 v18, 0x4b400000, v19
	v_add_f32_e32 v19, 0x4b400000, v22
	v_add_f32_e32 v22, 0x4b400000, v24
	v_add_f32_e32 v24, 0x4b400000, v26
	v_add_f32_e32 v26, 0x4b400000, v28
	v_add_f32_e32 v23, v23, v25
	v_fmac_f32_e32 v29, v10, v10
	v_add_f32_e32 v12, v42, v12
	v_perm_b32 v13, v14, v13, s71
	v_perm_b32 v14, v18, v15, s72
	v_perm_b32 v15, v22, v19, s71
	v_perm_b32 v18, v26, v24, s72
	v_add_f32_e32 v19, v27, v23
	v_add_f32_e32 v22, v43, v12
	v_or_b32_e32 v12, v13, v14
	v_or_b32_e32 v13, v15, v18
	v_add_f32_e32 v14, v29, v19
	global_store_dwordx2 v[20:21], v[12:13], off
	v_add_f32_e32 v13, v22, v14
	v_med3_f32 v12, v38, s70, v189
	v_med3_f32 v14, v39, s70, v189
	v_med3_f32 v15, v36, s70, v189
	v_med3_f32 v18, v37, s70, v189
	v_pk_mul_f32 v[8:9], v[8:9], s[30:31] op_sel_hi:[1,0]
	v_add_f32_e32 v12, 0x4b400000, v12
	v_add_f32_e32 v14, 0x4b400000, v14
	v_add_f32_e32 v15, 0x4b400000, v15
	v_add_f32_e32 v18, 0x4b400000, v18
	v_perm_b32 v12, v14, v12, s71
	v_perm_b32 v14, v18, v15, s72
	v_med3_f32 v8, v8, s70, v189
	v_or_b32_e32 v12, v12, v14
	v_add_f32_e32 v14, 0x4b400000, v8
	v_med3_f32 v8, v9, s70, v189
	v_add_f32_e32 v15, 0x4b400000, v8
	v_mov_b32_e32 v8, v13
	s_nop 1
	v_permlane16_swap_b32_e32 v13, v8
	v_pk_mul_f32 v[10:11], v[10:11], s[30:31] op_sel_hi:[1,0]
	s_waitcnt lgkmcnt(0)
	v_add_f32_e32 v8, v13, v8
	v_med3_f32 v9, v10, s70, v189
	v_add_f32_e32 v10, 0x4b400000, v9
	v_med3_f32 v9, v11, s70, v189
	v_add_f32_e32 v11, 0x4b400000, v9
	v_mov_b32_e32 v9, v8
	s_nop 1
	v_permlane32_swap_b32_e32 v8, v9
	v_perm_b32 v13, v15, v14, s71
	v_perm_b32 v10, v11, v10, s72
	v_or_b32_e32 v13, v13, v10
	global_store_dwordx2 v[20:21], v[12:13], off offset:128
	s_and_saveexec_b64 s[6:7], s[2:3]
	s_cbranch_execz .LBB0_3978
	v_lshlrev_b64 v[10:11], 6, v[16:17]
	v_lshl_add_u64 v[10:11], s[10:11], 0, v[10:11]
	v_lshl_add_u64 v[10:11], s[44:45], 2, v[10:11]
	s_waitcnt lgkmcnt(0)
	v_add_f32_e32 v8, v8, v9
	global_store_dword v[10:11], v8, off
; __device__ __forceinline__ u32x2 pack8i8(const f32x4 a, const f32x4 b) { return (u32x2){pack4i8(a), pack4i8(b)}; }
; __device__ __forceinline__ void ln_stats(const float* st, int row, float& mu, float& rs) { const f32x2 s = *(const f32x2*)(st + 2 * (size_t)row); mu = s[0] * (1.0f / DM); rs = 1.0f / sqrtf(s[1] * (1.0f / DM) - mu * mu + LN_EPS); }
;     __device__ __forceinline__ void operator()(EPI_ARGS) const {
;     ...
;                 for (int m = 0; m < 4; ++m) { const int row = row0 + ai * HALF + m * 16; float s = 0.f; float mu, rs; ln_stats(st, row, mu, rs);
; #pragma unroll
;                     for (int bj = 0; bj < 2; ++bj) { const f32x4 a = (acc[ai][bj][m][0] - cc[bj][0] * mu) * rs + dd[bj][0], b = (acc[ai][bj][m][1] - cc[bj][1] * mu) * rs + dd[bj][1];
;                         s += (a[0] * a[0] + a[1] * a[1]) + (a[2] * a[2] + a[3] * a[3]) + (b[0] * b[0] + b[1] * b[1]) + (b[2] * b[2] + b[3] * b[3]);
;                         *(u32x2*)((unsigned char*)dst + (size_t)row * 512 + col0 + bj * HALF) = pack8i8(a * lsc, b * lsc); }
;                     s += __shfl_xor(s, 16); s += __shfl_xor(s, 32);
;                     if (fq == 0) ssq[(size_t)row * 16 + slot] = s; }
.LBB0_3978:
	s_or_b64 exec, exec, s[6:7]
	v_add_u32_e32 v8, 0xb0, v96
	s_waitcnt lgkmcnt(0)
	v_ashrrev_i32_e32 v9, 31, v8
	v_lshl_add_u64 v[10:11], v[8:9], 3, s[12:13]
	global_load_dwordx2 v[10:11], v[10:11], off
	v_cvt_f32_i32_e32 v1, v1
	v_cvt_f32_i32_e32 v0, v0
	v_cvt_f32_i32_e32 v7, v7
	v_cvt_f32_i32_e32 v6, v6
	v_cvt_f32_i32_e32 v5, v5
	v_cvt_f32_i32_e32 v4, v4
	v_cvt_f32_i32_e32 v3, v3
	v_cvt_f32_i32_e32 v2, v2
	v_lshlrev_b64 v[12:13], 9, v[8:9]
	v_lshl_add_u64 v[12:13], v[162:163], 0, v[12:13]
	s_waitcnt vmcnt(0)
	v_pk_mul_f32 v[10:11], v[10:11], s[28:29] op_sel_hi:[1,0]
	s_nop 0
	v_fma_f32 v28, -v10, v10, v11
	v_add_f32_e32 v28, 0x3727c5ac, v28
	v_rsq_f32_e32 v254, v28
	v_pk_fma_f32 v[14:15], v[82:83], v[10:11], v[92:93] op_sel_hi:[1,0,1]
	v_pk_fma_f32 v[16:17], v[80:81], v[10:11], v[94:95] op_sel_hi:[1,0,1] neg_lo:[1,0,0] neg_hi:[1,0,0]
	v_pk_fma_f32 v[18:19], v[74:75], v[10:11], v[88:89] op_sel_hi:[1,0,1]
	v_pk_fma_f32 v[20:21], v[72:73], v[10:11], v[90:91] op_sel_hi:[1,0,1] neg_lo:[1,0,0] neg_hi:[1,0,0]
	v_pk_mul_f32 v[22:23], v[86:87], v[10:11] op_sel_hi:[1,0]
	v_pk_mul_f32 v[24:25], v[84:85], v[10:11] op_sel_hi:[1,0]
	v_pk_mul_f32 v[26:27], v[78:79], v[10:11] op_sel_hi:[1,0]
	v_pk_mul_f32 v[10:11], v[76:77], v[10:11] op_sel_hi:[1,0]
	v_pk_fma_f32 v[6:7], v[6:7], s[26:27], v[22:23] op_sel_hi:[1,0,1] neg_lo:[0,0,1] neg_hi:[0,0,1]
	v_pk_fma_f32 v[0:1], v[0:1], s[26:27], v[10:11] op_sel_hi:[1,0,1] neg_lo:[0,0,1] neg_hi:[0,0,1]
	v_pk_fma_f32 v[4:5], v[4:5], s[26:27], v[24:25] op_sel_hi:[1,0,1] neg_lo:[0,0,1] neg_hi:[0,0,1]
	v_pk_fma_f32 v[2:3], v[2:3], s[26:27], v[26:27] op_sel_hi:[1,0,1] neg_lo:[0,0,1] neg_hi:[0,0,1]
	s_nop 1
	s_nop 1
	v_mov_b32_e32 v10, v254
	v_pk_fma_f32 v[14:15], v[14:15], v[10:11], v[70:71] op_sel_hi:[1,0,1]
	v_pk_fma_f32 v[16:17], v[16:17], v[10:11], v[68:69] op_sel_hi:[1,0,1]
	v_pk_fma_f32 v[18:19], v[18:19], v[10:11], v[66:67] op_sel_hi:[1,0,1]
	v_pk_fma_f32 v[20:21], v[20:21], v[10:11], v[64:65] op_sel_hi:[1,0,1]
	v_pk_fma_f32 v[6:7], v[6:7], v[10:11], v[62:63] op_sel_hi:[1,0,1]
	v_pk_fma_f32 v[4:5], v[4:5], v[10:11], v[60:61] op_sel_hi:[1,0,1]
	v_pk_fma_f32 v[2:3], v[2:3], v[10:11], v[58:59] op_sel_hi:[1,0,1]
	v_pk_fma_f32 v[0:1], v[0:1], v[10:11], v[56:57] op_sel_hi:[1,0,1]
	v_mul_f32_e32 v32, v17, v17
	v_mul_f32_e32 v33, v15, v15
	v_mul_f32_e32 v34, v21, v21
	v_mul_f32_e32 v35, v19, v19
	v_pk_mul_f32 v[10:11], v[14:15], s[30:31] op_sel_hi:[1,0]
	v_pk_mul_f32 v[22:23], v[16:17], s[30:31] op_sel_hi:[1,0]
	v_pk_mul_f32 v[24:25], v[18:19], s[30:31] op_sel_hi:[1,0]
	v_pk_mul_f32 v[26:27], v[20:21], s[30:31] op_sel_hi:[1,0]
	v_mul_f32_e32 v15, v5, v5
	v_mul_f32_e32 v17, v7, v7
	v_mul_f32_e32 v19, v1, v1
	v_pk_mul_f32 v[28:29], v[6:7], s[30:31] op_sel_hi:[1,0]
	v_pk_mul_f32 v[30:31], v[4:5], s[30:31] op_sel_hi:[1,0]
	v_fmac_f32_e32 v32, v16, v16
	v_fmac_f32_e32 v33, v14, v14
	v_fmac_f32_e32 v34, v20, v20
	v_fmac_f32_e32 v35, v18, v18
	v_med3_f32 v5, v22, s70, v189
	v_med3_f32 v7, v23, s70, v189
	v_med3_f32 v10, v10, s70, v189
	v_med3_f32 v11, v11, s70, v189
	v_med3_f32 v14, v26, s70, v189
	v_med3_f32 v16, v27, s70, v189
	v_med3_f32 v18, v24, s70, v189
	v_med3_f32 v20, v25, s70, v189
	v_fmac_f32_e32 v15, v4, v4
	v_fmac_f32_e32 v17, v6, v6
	v_mul_f32_e32 v21, v3, v3
	v_fmac_f32_e32 v19, v0, v0
	v_add_f32_e32 v4, v32, v33
	v_add_f32_e32 v5, 0x4b400000, v5
	v_add_f32_e32 v6, 0x4b400000, v7
	v_add_f32_e32 v7, 0x4b400000, v10
	v_add_f32_e32 v10, 0x4b400000, v11
	v_add_f32_e32 v11, 0x4b400000, v14
	v_add_f32_e32 v14, 0x4b400000, v16
	v_add_f32_e32 v16, 0x4b400000, v18
	v_add_f32_e32 v18, 0x4b400000, v20
	v_add_f32_e32 v15, v15, v17
	v_fmac_f32_e32 v21, v2, v2
	v_add_f32_e32 v4, v34, v4
	v_perm_b32 v5, v6, v5, s71
	v_perm_b32 v6, v10, v7, s72
	v_perm_b32 v7, v14, v11, s71
	v_perm_b32 v10, v18, v16, s72
	v_add_f32_e32 v11, v19, v15
	v_add_f32_e32 v14, v35, v4
	v_or_b32_e32 v4, v5, v6
	v_or_b32_e32 v5, v7, v10
	v_add_f32_e32 v6, v21, v11
	global_store_dwordx2 v[12:13], v[4:5], off
	v_add_f32_e32 v5, v14, v6
	v_med3_f32 v4, v30, s70, v189
	v_med3_f32 v6, v31, s70, v189
	v_med3_f32 v7, v28, s70, v189
	v_med3_f32 v10, v29, s70, v189
	v_pk_mul_f32 v[0:1], v[0:1], s[30:31] op_sel_hi:[1,0]
	v_add_f32_e32 v4, 0x4b400000, v4
	v_add_f32_e32 v6, 0x4b400000, v6
	v_add_f32_e32 v7, 0x4b400000, v7
	v_add_f32_e32 v10, 0x4b400000, v10
	v_perm_b32 v4, v6, v4, s71
	v_perm_b32 v6, v10, v7, s72
	v_med3_f32 v0, v0, s70, v189
	v_or_b32_e32 v4, v4, v6
	v_add_f32_e32 v6, 0x4b400000, v0
	v_med3_f32 v0, v1, s70, v189
	v_add_f32_e32 v7, 0x4b400000, v0
	v_mov_b32_e32 v0, v5
	s_nop 1
	v_permlane16_swap_b32_e32 v5, v0
	v_pk_mul_f32 v[2:3], v[2:3], s[30:31] op_sel_hi:[1,0]
	s_waitcnt lgkmcnt(0)
	v_add_f32_e32 v0, v5, v0
	v_med3_f32 v1, v2, s70, v189
	v_add_f32_e32 v2, 0x4b400000, v1
	v_med3_f32 v1, v3, s70, v189
	v_add_f32_e32 v3, 0x4b400000, v1
	v_mov_b32_e32 v1, v0
	s_nop 1
	v_permlane32_swap_b32_e32 v0, v1
	v_perm_b32 v5, v7, v6, s71
	v_perm_b32 v2, v3, v2, s72
	v_or_b32_e32 v5, v5, v2
	global_store_dwordx2 v[12:13], v[4:5], off offset:128
	s_and_saveexec_b64 s[6:7], s[2:3]
	s_cbranch_execz .LBB0_3980
	v_lshlrev_b64 v[2:3], 6, v[8:9]
	v_lshl_add_u64 v[2:3], s[10:11], 0, v[2:3]
	v_lshl_add_u64 v[2:3], s[44:45], 2, v[2:3]
	s_waitcnt lgkmcnt(0)
	v_add_f32_e32 v0, v0, v1
	global_store_dword v[2:3], v0, off

; __device__ __forceinline__ f32x4 bf4x(const u32x2 a) { return (f32x4){__uint_as_float(a.x << 16), __uint_as_float(a.x & 0xffff0000u), __uint_as_float(a.y << 16), __uint_as_float(a.y & 0xffff0000u)}; }
; __device__ __forceinline__ void ln_norm2(f32x4 (&v)[8], const float* g, const float* b, int lane, float& mean_o, float& rstd_o) {
;     float s = 0.f;
; #pragma unroll
;     for (int j = 0; j < 8; ++j) s += (v[j][0] + v[j][1]) + (v[j][2] + v[j][3]);
;     const float mean = wave_sum(s) * (1.f / DM); float s2 = 0.f;
; #pragma unroll
;     for (int j = 0; j < 8; ++j) { v[j] = v[j] - mean; s2 += (v[j][0] * v[j][0] + v[j][1] * v[j][1]) + (v[j][2] * v[j][2] + v[j][3] * v[j][3]); }
;     const float rstd = 1.f / sqrtf(wave_sum(s2) * (1.f / DM) + LN_EPS);
; __device__ __forceinline__ void ln3_router_phase(const Params& P, LAS unsigned char* lds, const int tid) {
;     ...
;         for (int i = 0; i < 8; ++i) { const int m = c * 64 + wave * 8 + i; asm volatile("" ::: "memory");
;             const u32x2* yr = (const u32x2*)(Y + (size_t)m * DM) + lane; f32x4 v[8];
; #pragma unroll
;             for (int j = 0; j < 8; ++j) v[j] = bf4x(yr[64 * j]);
;             float mu3, rs3; ln_norm2(v, P.in[19], P.in[20], lane, mu3, rs3); ln_store(v, nullptr, H3B, (size_t)m, lane, -ASC_XI8);
.LBB0_4582:
	v_add_u32_e32 v68, s49, v85
	v_ashrrev_i32_e32 v69, 31, v68
	v_lshlrev_b64 v[36:37], 12, v[68:69]
	v_lshl_add_u64 v[36:37], v[10:11], 0, v[36:37]
	global_load_dwordx2 v[38:39], v[36:37], off offset:1536
	global_load_dwordx2 v[40:41], v[36:37], off offset:2048
	global_load_dwordx2 v[44:45], v[36:37], off offset:3072
	global_load_dwordx2 v[52:53], v[36:37], off offset:3584
	global_load_dwordx2 v[56:57], v[36:37], off
	global_load_dwordx2 v[62:63], v[36:37], off offset:512
	global_load_dwordx2 v[64:65], v[36:37], off offset:1024
	global_load_dwordx2 v[66:67], v[36:37], off offset:2560
	v_cmp_lt_i32_e32 vcc, v88, v87
	v_lshlrev_b64 v[68:69], 11, v[68:69]
	v_lshl_add_u64 v[68:69], v[12:13], 0, v[68:69]
	v_cndmask_b32_e32 v35, v86, v88, vcc
	v_lshlrev_b32_e32 v100, 2, v35
	v_cmp_lt_i32_e32 vcc, v89, v87
	s_waitcnt vmcnt(7)
	v_lshlrev_b32_e32 v48, 16, v38
	s_waitcnt vmcnt(6)
	v_lshlrev_b32_e32 v46, 16, v40
	v_and_b32_e32 v76, 0xffff0000, v40
	s_waitcnt vmcnt(5)
	v_lshlrev_b32_e32 v36, 16, v44
	s_waitcnt vmcnt(3)
	v_lshlrev_b32_e32 v59, 16, v56
	s_waitcnt vmcnt(2)
	v_lshlrev_b32_e32 v58, 16, v62
	v_and_b32_e32 v61, 0xffff0000, v56
	v_and_b32_e32 v60, 0xffff0000, v62
	v_lshlrev_b32_e32 v55, 16, v57
	v_lshlrev_b32_e32 v54, 16, v63
	v_and_b32_e32 v57, 0xffff0000, v57
	v_and_b32_e32 v56, 0xffff0000, v63
	v_and_b32_e32 v37, 0xffff0000, v44
	v_lshlrev_b32_e32 v44, 16, v52
	v_and_b32_e32 v72, 0xffff0000, v52
	v_lshlrev_b32_e32 v40, 16, v53
	v_and_b32_e32 v70, 0xffff0000, v53
	s_waitcnt vmcnt(1)
	v_lshlrev_b32_e32 v53, 16, v65
	v_lshlrev_b32_e32 v52, 16, v64
	v_and_b32_e32 v63, 0xffff0000, v65
	v_and_b32_e32 v62, 0xffff0000, v64
	s_waitcnt vmcnt(0)
	v_lshlrev_b32_e32 v79, 16, v67
	v_lshlrev_b32_e32 v78, 16, v66
	v_and_b32_e32 v65, 0xffff0000, v67
	v_and_b32_e32 v64, 0xffff0000, v66
	v_pk_add_f32 v[66:67], v[58:59], v[60:61]
	v_pk_add_f32 v[80:81], v[54:55], v[56:57]
	v_pk_add_f32 v[102:103], v[52:53], v[62:63]
	v_pk_add_f32 v[66:67], v[66:67], v[80:81]
	v_and_b32_e32 v49, 0xffff0000, v38
	v_lshlrev_b32_e32 v50, 16, v39
	v_and_b32_e32 v51, 0xffff0000, v39
	v_pk_add_f32 v[80:81], v[102:103], v[102:103] op_sel_hi:[0,1]
	v_add_f32_e32 v35, 0, v67
	v_lshlrev_b32_e32 v42, 16, v41
	v_and_b32_e32 v74, 0xffff0000, v41
	v_add_f32_e32 v47, v48, v49
	v_add_f32_e32 v77, v50, v51
	v_mov_b32_e32 v43, v81
	v_add_f32_e32 v75, v66, v35
	v_pk_add_f32 v[102:103], v[46:47], v[76:77]
	v_pk_add_f32 v[66:67], v[42:43], v[74:75]
	v_pk_add_f32 v[104:105], v[78:79], v[64:65]
	v_pk_add_f32 v[66:67], v[102:103], v[66:67]
	v_lshlrev_b32_e32 v38, 16, v45
	v_and_b32_e32 v39, 0xffff0000, v45
	v_pk_add_f32 v[104:105], v[104:105], v[104:105] op_sel_hi:[0,1]
	v_pk_add_f32 v[66:67], v[66:67], v[66:67] op_sel_hi:[0,1]
	v_add_f32_e32 v45, v36, v37
	v_add_f32_e32 v73, v38, v39
	v_mov_b32_e32 v41, v105
	v_mov_b32_e32 v71, v67
	v_pk_add_f32 v[106:107], v[44:45], v[72:73]
	v_pk_add_f32 v[66:67], v[40:41], v[70:71]
	v_cndmask_b32_e32 v43, v86, v89, vcc
	v_pk_add_f32 v[66:67], v[106:107], v[66:67]
	v_lshlrev_b32_e32 v71, 2, v43
	v_add_f32_e32 v35, v66, v67
	s_nop 1
	v_mov_b32_dpp v41, v35 quad_perm:[1,0,3,2] row_mask:0xf bank_mask:0xf
	v_cmp_lt_i32_e32 vcc, v90, v87
	s_waitcnt lgkmcnt(0)
	v_add_f32_e32 v35, v35, v41
	s_nop 1
	v_mov_b32_dpp v41, v35 quad_perm:[2,3,0,1] row_mask:0xf bank_mask:0xf
	v_cndmask_b32_e32 v43, v86, v90, vcc
	v_lshlrev_b32_e32 v73, 2, v43
	v_cmp_lt_i32_e32 vcc, v91, v87
	s_waitcnt lgkmcnt(0)
	v_add_f32_e32 v35, v35, v41
	s_nop 1
	v_mov_b32_dpp v41, v35 row_half_mirror row_mask:0xf bank_mask:0xf
	v_cndmask_b32_e32 v43, v86, v91, vcc
	v_lshlrev_b32_e32 v75, 2, v43
	v_cmp_lt_i32_e32 vcc, v92, v87
	s_waitcnt lgkmcnt(0)
	v_add_f32_e32 v35, v35, v41
	s_nop 1
	v_mov_b32_dpp v41, v35 row_mirror row_mask:0xf bank_mask:0xf
	v_cndmask_b32_e32 v43, v86, v92, vcc
	v_lshlrev_b32_e32 v77, 2, v43
	v_cmp_lt_i32_e32 vcc, v93, v87
	s_waitcnt lgkmcnt(0)
	v_add_f32_e32 v35, v35, v41
	v_mov_b32_e32 v41, v35
	s_nop 1
	v_permlane16_swap_b32_e32 v35, v41
	v_cndmask_b32_e32 v43, v86, v93, vcc
	v_lshlrev_b32_e32 v101, 2, v43
	s_waitcnt lgkmcnt(0)
	v_add_f32_e32 v35, v35, v41
	v_mov_b32_e32 v41, v35
	s_nop 1
	v_permlane32_swap_b32_e32 v35, v41
	s_waitcnt lgkmcnt(0)
	v_add_f32_e32 v102, v35, v41
	v_fmac_f32_e32 v57, 0xba000000, v102
	v_fmac_f32_e32 v61, 0xba000000, v102
	v_fmac_f32_e32 v56, 0xba000000, v102
	v_fmac_f32_e32 v60, 0xba000000, v102
	v_fmac_f32_e32 v55, 0xba000000, v102
	v_fmac_f32_e32 v59, 0xba000000, v102
	v_fmac_f32_e32 v54, 0xba000000, v102
	v_fmac_f32_e32 v58, 0xba000000, v102
	v_fmac_f32_e32 v62, 0xba000000, v102
	v_fmac_f32_e32 v63, 0xba000000, v102
	v_fmac_f32_e32 v53, 0xba000000, v102
	v_mov_b32_e32 v104, v61
	v_mov_b32_e32 v105, v60
	v_mov_b32_e32 v108, v57
	v_mov_b32_e32 v109, v56
	v_mov_b32_e32 v66, v59
	v_mov_b32_e32 v67, v58
	v_mov_b32_e32 v106, v55
	v_mov_b32_e32 v107, v54
	v_mov_b32_e32 v80, v53
	v_mov_b32_e32 v81, v63
	v_mov_b32_e32 v53, v62
	v_pk_mul_f32 v[62:63], v[104:105], v[104:105]
	v_pk_mul_f32 v[104:105], v[108:109], v[108:109]
	v_pk_fma_f32 v[62:63], v[66:67], v[66:67], v[62:63]
	v_pk_fma_f32 v[66:67], v[106:107], v[106:107], v[104:105]
	v_fmac_f32_e32 v52, 0xba000000, v102
	v_pk_add_f32 v[62:63], v[62:63], v[66:67]
	v_fmac_f32_e32 v48, 0xba000000, v102
	v_pk_mul_f32 v[108:109], v[80:81], v[80:81]
	v_pk_mul_f32 v[110:111], v[52:53], v[52:53]
	v_pk_add_f32 v[62:63], v[62:63], v[62:63] op_sel_hi:[0,1]
	v_fmac_f32_e32 v49, 0xba000000, v102
	v_fmac_f32_e32 v50, 0xba000000, v102
	v_pk_mov_b32 v[104:105], v[110:111], v[108:109] op_sel:[1,0]
	v_mov_b32_e32 v111, v109
	v_mul_f32_e32 v62, v48, v48
	v_fmac_f32_e32 v51, 0xba000000, v102
; __device__ __forceinline__ float clamp448(float x) { return __builtin_amdgcn_fmed3f(x, -448.0f, 448.0f); }
; __device__ __forceinline__ void ln_norm2(f32x4 (&v)[8], const float* g, const float* b, int lane, float& mean_o, float& rstd_o) {
;     ...
;     const float mean = wave_sum(s) * (1.f / DM); float s2 = 0.f;
; #pragma unroll
;     for (int j = 0; j < 8; ++j) { v[j] = v[j] - mean; s2 += (v[j][0] * v[j][0] + v[j][1] * v[j][1]) + (v[j][2] * v[j][2] + v[j][3] * v[j][3]); }
;     const float rstd = 1.f / sqrtf(wave_sum(s2) * (1.f / DM) + LN_EPS);
; #pragma unroll
;     for (int j = 0; j < 8; ++j) { const f32x4 gv = *((const f32x4*)g + lane + 64 * j), bv = *((const f32x4*)b + lane + 64 * j); v[j] = v[j] * rstd * gv + bv; }
;     mean_o = mean; rstd_o = rstd;
; }
; __device__ __forceinline__ void ln_norm(f32x4 (&v)[8], const float* g, const float* b, int lane) { float m_, r_; ln_norm2(v, g, b, lane, m_, r_); }
;     if (hf) { f32x4* o = (f32x4*)(hf + m * DM) + lane;
; #pragma unroll
;         for (int j = 0; j < 8; ++j) __builtin_nontemporal_store(v[j], o + 64 * j); }
;     if (hb && f8s != 0.f) { unsigned* o4 = (unsigned*)((unsigned char*)hb + m * DM) + lane;
; #pragma unroll
;         for (int j = 0; j < 8; ++j) { if (f8s < 0.f) { o4[64 * j] = pg8::pack4i8(v[j] * -f8s); continue; }
;             const f32x4 t = v[j] * f8s; int w = __builtin_amdgcn_cvt_pk_fp8_f32(pg8::clamp448(t[0]), pg8::clamp448(t[1]), 0, false); w = __builtin_amdgcn_cvt_pk_fp8_f32(pg8::clamp448(t[2]), pg8::clamp448(t[3]), w, true); o4[64 * j] = (unsigned)w; } }
	v_pk_add_f32 v[66:67], v[104:105], v[110:111]
	v_pk_fma_f32 v[104:105], v[48:49], v[48:49], v[62:63] op_sel_hi:[1,1,0]
	v_mul_f32_e32 v62, v50, v50
	v_pk_add_f32 v[66:67], v[66:67], v[66:67] op_sel_hi:[0,1]
	v_pk_fma_f32 v[106:107], v[50:51], v[50:51], v[62:63] op_sel_hi:[1,1,0]
	v_fmac_f32_e32 v74, 0xba000000, v102
	v_fmac_f32_e32 v42, 0xba000000, v102
	v_fmac_f32_e32 v76, 0xba000000, v102
	v_fmac_f32_e32 v46, 0xba000000, v102
	v_mul_f32_e32 v104, v46, v46
	v_mul_f32_e32 v106, v76, v76
	v_mul_f32_e32 v66, v42, v42
	v_mul_f32_e32 v62, v74, v74
	v_pk_add_f32 v[104:105], v[104:105], v[106:107]
	v_pk_add_f32 v[62:63], v[66:67], v[62:63]
	v_fmac_f32_e32 v64, 0xba000000, v102
	v_fmac_f32_e32 v65, 0xba000000, v102
	v_fmac_f32_e32 v79, 0xba000000, v102
	v_pk_add_f32 v[62:63], v[104:105], v[62:63]
	v_fmac_f32_e32 v78, 0xba000000, v102
	v_mov_b32_e32 v164, v79
	v_mov_b32_e32 v165, v65
	v_mov_b32_e32 v79, v64
	v_pk_add_f32 v[62:63], v[62:63], v[62:63] op_sel_hi:[0,1]
	v_pk_mul_f32 v[66:67], v[164:165], v[164:165]
	v_pk_mul_f32 v[64:65], v[78:79], v[78:79]
	v_fmac_f32_e32 v36, 0xba000000, v102
	v_pk_mov_b32 v[104:105], v[64:65], v[66:67] op_sel:[1,0]
	v_mov_b32_e32 v65, v67
	v_fmac_f32_e32 v37, 0xba000000, v102
	v_fmac_f32_e32 v38, 0xba000000, v102
	v_mul_f32_e32 v62, v36, v36
	v_pk_add_f32 v[64:65], v[104:105], v[64:65]
	v_fmac_f32_e32 v39, 0xba000000, v102
	v_pk_fma_f32 v[66:67], v[36:37], v[36:37], v[62:63] op_sel_hi:[1,1,0]
	v_mul_f32_e32 v62, v38, v38
	v_pk_add_f32 v[64:65], v[64:65], v[64:65] op_sel_hi:[0,1]
	v_pk_fma_f32 v[104:105], v[38:39], v[38:39], v[62:63] op_sel_hi:[1,1,0]
	v_fmac_f32_e32 v70, 0xba000000, v102
	v_fmac_f32_e32 v40, 0xba000000, v102
	v_fmac_f32_e32 v72, 0xba000000, v102
	v_fmac_f32_e32 v44, 0xba000000, v102
	v_mul_f32_e32 v66, v44, v44
	v_mul_f32_e32 v104, v72, v72
	v_mul_f32_e32 v64, v40, v40
	v_mul_f32_e32 v62, v70, v70
	v_pk_add_f32 v[66:67], v[66:67], v[104:105]
	v_pk_add_f32 v[62:63], v[64:65], v[62:63]
	v_mov_b32_e32 v166, v58
	v_pk_add_f32 v[62:63], v[66:67], v[62:63]
	v_mov_b32_e32 v58, v54
	v_add_f32_e32 v35, v62, v63
	global_load_dwordx4 v[62:65], v[14:15], off
	global_load_dwordx4 v[104:107], v[16:17], off
	global_load_dwordx4 v[108:111], v[14:15], off offset:1024
	global_load_dwordx4 v[112:115], v[16:17], off offset:1024
	global_load_dwordx4 v[116:119], v[14:15], off offset:2048
	global_load_dwordx4 v[120:123], v[16:17], off offset:2048
	global_load_dwordx4 v[124:127], v[14:15], off offset:3072
	global_load_dwordx4 v[128:131], v[16:17], off offset:3072
	global_load_dwordx4 v[132:135], v[18:19], off
	global_load_dwordx4 v[136:139], v[20:21], off
	global_load_dwordx4 v[140:143], v[22:23], off
	global_load_dwordx4 v[144:147], v[24:25], off
	global_load_dwordx4 v[148:151], v[26:27], off
	global_load_dwordx4 v[152:155], v[28:29], off
	s_nop 1
	v_mov_b32_dpp v41, v35 quad_perm:[1,0,3,2] row_mask:0xf bank_mask:0xf
	global_load_dwordx4 v[156:159], v[30:31], off
	global_load_dwordx4 v[160:163], v[32:33], off
	v_mov_b32_e32 v167, v60
	v_mov_b32_e32 v60, v59
	v_mov_b32_e32 v59, v56
	s_waitcnt lgkmcnt(0)
	v_add_f32_e32 v35, v35, v41
	s_nop 1
	v_mov_b32_dpp v41, v35 quad_perm:[2,3,0,1] row_mask:0xf bank_mask:0xf
	v_mov_b32_e32 v56, v55
	s_waitcnt lgkmcnt(0)
	v_add_f32_e32 v35, v35, v41
	s_nop 1
	v_mov_b32_dpp v41, v35 row_half_mirror row_mask:0xf bank_mask:0xf
	s_waitcnt lgkmcnt(0)
	v_add_f32_e32 v35, v35, v41
	s_nop 1
	v_mov_b32_dpp v41, v35 row_mirror row_mask:0xf bank_mask:0xf
	s_waitcnt lgkmcnt(0)
	v_add_f32_e32 v35, v35, v41
	v_mov_b32_e32 v41, v35
	s_nop 1
	v_permlane16_swap_b32_e32 v35, v41
	s_waitcnt lgkmcnt(0)
	v_add_f32_e32 v35, v35, v41
	v_mov_b32_e32 v41, v35
	s_nop 1
	v_permlane32_swap_b32_e32 v35, v41
	s_waitcnt lgkmcnt(0)
	v_add_f32_e32 v35, v35, v41
	v_fmamk_f32 v35, v35, 0x3a000000, v94
	v_rsq_f32_e32 v204, v35
	s_nop 1
	s_nop 0
	s_nop 0
	s_nop 1
	s_nop 1
	s_nop 0
	v_mov_b32_e32 v82, v204
	v_mov_b32_e32 v47, v76
	v_pk_mul_f32 v[54:55], v[60:61], v[82:83] op_sel_hi:[1,0]
	v_pk_mul_f32 v[56:57], v[56:57], v[82:83] op_sel_hi:[1,0]
	v_pk_mul_f32 v[52:53], v[52:53], v[82:83] op_sel_hi:[1,0]
	v_pk_mul_f32 v[50:51], v[50:51], v[82:83] op_sel_hi:[1,0]
	v_pk_mul_f32 v[46:47], v[46:47], v[82:83] op_sel_hi:[1,0]
	s_waitcnt vmcnt(14)
	v_pk_fma_f32 v[64:65], v[64:65], v[56:57], v[106:107]
	v_pk_fma_f32 v[66:67], v[62:63], v[54:55], v[104:105]
	v_pk_mul_f32 v[54:55], v[166:167], v[82:83] op_sel_hi:[1,0]
	v_pk_mul_f32 v[56:57], v[58:59], v[82:83] op_sel_hi:[1,0]
	s_waitcnt vmcnt(10)
	v_pk_fma_f32 v[58:59], v[116:117], v[52:53], v[120:121]
	s_waitcnt vmcnt(8)
	v_pk_fma_f32 v[52:53], v[126:127], v[50:51], v[130:131]
	s_waitcnt vmcnt(6)
	v_pk_fma_f32 v[50:51], v[132:133], v[46:47], v[136:137]
	v_pk_mul_f32 v[46:47], v[78:79], v[82:83] op_sel_hi:[1,0]
	v_pk_mul_f32 v[78:79], v[36:37], v[82:83] op_sel_hi:[1,0]
	v_pk_fma_f32 v[62:63], v[108:109], v[54:55], v[112:113]
	v_pk_mul_f32 v[54:55], v[80:81], v[82:83] op_sel_hi:[1,0]
	v_pk_mul_f32 v[36:37], v[38:39], v[82:83] op_sel_hi:[1,0]
	s_waitcnt vmcnt(2)
; __device__ __forceinline__ float clamp448(float x) { return __builtin_amdgcn_fmed3f(x, -448.0f, 448.0f); }
; __device__ __forceinline__ void ln_norm2(f32x4 (&v)[8], const float* g, const float* b, int lane, float& mean_o, float& rstd_o) {
;     ...
;     for (int j = 0; j < 8; ++j) { const f32x4 gv = *((const f32x4*)g + lane + 64 * j), bv = *((const f32x4*)b + lane + 64 * j); v[j] = v[j] * rstd * gv + bv; }
;     mean_o = mean; rstd_o = rstd;
; }
; __device__ __forceinline__ void ln_norm(f32x4 (&v)[8], const float* g, const float* b, int lane) { float m_, r_; ln_norm2(v, g, b, lane, m_, r_); }
;     if (hf) { f32x4* o = (f32x4*)(hf + m * DM) + lane;
; #pragma unroll
;         for (int j = 0; j < 8; ++j) __builtin_nontemporal_store(v[j], o + 64 * j); }
;     if (hb && f8s != 0.f) { unsigned* o4 = (unsigned*)((unsigned char*)hb + m * DM) + lane;
; #pragma unroll
;         for (int j = 0; j < 8; ++j) { if (f8s < 0.f) { o4[64 * j] = pg8::pack4i8(v[j] * -f8s); continue; }
;             const f32x4 t = v[j] * f8s; int w = __builtin_amdgcn_cvt_pk_fp8_f32(pg8::clamp448(t[0]), pg8::clamp448(t[1]), 0, false); w = __builtin_amdgcn_cvt_pk_fp8_f32(pg8::clamp448(t[2]), pg8::clamp448(t[3]), w, true); o4[64 * j] = (unsigned)w; } }
; __device__ __forceinline__ void ln3_router_phase(const Params& P, LAS unsigned char* lds, const int tid) {
;     ...
;             float mu3, rs3; ln_norm2(v, P.in[19], P.in[20], lane, mu3, rs3); ln_store(v, nullptr, H3B, (size_t)m, lane, -ASC_XI8);
;             if (lane == 0) { st3[2 * m] = mu3; st3[2 * m + 1] = rs3; }
	v_pk_fma_f32 v[38:39], v[148:149], v[78:79], v[152:153]
	v_pk_mul_f32 v[78:79], v[64:65], s[38:39] op_sel_hi:[1,0]
	v_pk_mul_f32 v[80:81], v[66:67], s[38:39] op_sel_hi:[1,0]
	v_mov_b32_e32 v43, v74
	v_mov_b32_e32 v45, v72
	v_mov_b32_e32 v41, v70
	v_med3_f32 v35, v80, s39, v96
	v_med3_f32 v70, v81, s39, v96
	v_med3_f32 v72, v78, s39, v96
	v_med3_f32 v74, v79, s39, v96
	v_add_f32_e32 v35, 0x4b400000, v35
	v_add_f32_e32 v70, 0x4b400000, v70
	v_add_f32_e32 v72, 0x4b400000, v72
	v_add_f32_e32 v74, 0x4b400000, v74
	v_pk_fma_f32 v[60:61], v[110:111], v[56:57], v[114:115]
	v_perm_b32 v35, v70, v35, s42
	v_perm_b32 v70, v74, v72, s43
	v_or_b32_e32 v35, v35, v70
	v_pk_mul_f32 v[78:79], v[60:61], s[38:39] op_sel_hi:[1,0]
	v_pk_mul_f32 v[80:81], v[62:63], s[38:39] op_sel_hi:[1,0]
	global_store_dword v[68:69], v35, off
	v_med3_f32 v35, v80, s39, v96
	v_med3_f32 v70, v81, s39, v96
	v_med3_f32 v72, v78, s39, v96
	v_med3_f32 v74, v79, s39, v96
	v_add_f32_e32 v35, 0x4b400000, v35
	v_add_f32_e32 v70, 0x4b400000, v70
	v_add_f32_e32 v72, 0x4b400000, v72
	v_add_f32_e32 v74, 0x4b400000, v74
	v_pk_fma_f32 v[56:57], v[118:119], v[54:55], v[122:123]
	v_perm_b32 v35, v70, v35, s42
	v_perm_b32 v70, v74, v72, s43
	v_or_b32_e32 v35, v35, v70
	v_pk_mul_f32 v[78:79], v[56:57], s[38:39] op_sel_hi:[1,0]
	v_pk_mul_f32 v[80:81], v[58:59], s[38:39] op_sel_hi:[1,0]
	global_store_dword v[68:69], v35, off offset:256
	v_med3_f32 v35, v80, s39, v96
	v_med3_f32 v70, v81, s39, v96
	v_med3_f32 v72, v78, s39, v96
	v_med3_f32 v74, v79, s39, v96
	v_pk_mul_f32 v[48:49], v[48:49], v[82:83] op_sel_hi:[1,0]
	v_add_f32_e32 v35, 0x4b400000, v35
	v_add_f32_e32 v70, 0x4b400000, v70
	v_add_f32_e32 v72, 0x4b400000, v72
	v_add_f32_e32 v74, 0x4b400000, v74
	v_pk_fma_f32 v[54:55], v[124:125], v[48:49], v[128:129]
	v_perm_b32 v35, v70, v35, s42
	v_perm_b32 v70, v74, v72, s43
	v_or_b32_e32 v35, v35, v70
	v_pk_mul_f32 v[78:79], v[52:53], s[38:39] op_sel_hi:[1,0]
	v_pk_mul_f32 v[80:81], v[54:55], s[38:39] op_sel_hi:[1,0]
	global_store_dword v[68:69], v35, off offset:512
	v_med3_f32 v35, v80, s39, v96
	v_med3_f32 v70, v81, s39, v96
	v_med3_f32 v72, v78, s39, v96
	v_med3_f32 v74, v79, s39, v96
	v_pk_mul_f32 v[42:43], v[42:43], v[82:83] op_sel_hi:[1,0]
	v_add_f32_e32 v35, 0x4b400000, v35
	v_add_f32_e32 v70, 0x4b400000, v70
	v_add_f32_e32 v72, 0x4b400000, v72
	v_add_f32_e32 v74, 0x4b400000, v74
	v_pk_fma_f32 v[48:49], v[134:135], v[42:43], v[138:139]
	v_perm_b32 v35, v70, v35, s42
	v_perm_b32 v70, v74, v72, s43
	v_or_b32_e32 v35, v35, v70
	v_pk_mul_f32 v[78:79], v[48:49], s[38:39] op_sel_hi:[1,0]
	v_pk_mul_f32 v[80:81], v[50:51], s[38:39] op_sel_hi:[1,0]
	global_store_dword v[68:69], v35, off offset:768
	v_med3_f32 v35, v80, s39, v96
	v_med3_f32 v70, v81, s39, v96
	v_med3_f32 v72, v78, s39, v96
	v_med3_f32 v74, v79, s39, v96
	v_pk_mul_f32 v[42:43], v[164:165], v[82:83] op_sel_hi:[1,0]
	v_add_f32_e32 v35, 0x4b400000, v35
	v_add_f32_e32 v70, 0x4b400000, v70
	v_add_f32_e32 v72, 0x4b400000, v72
	v_add_f32_e32 v74, 0x4b400000, v74
	v_pk_fma_f32 v[42:43], v[142:143], v[42:43], v[146:147]
	v_pk_fma_f32 v[46:47], v[140:141], v[46:47], v[144:145]
	v_perm_b32 v35, v70, v35, s42
	v_perm_b32 v70, v74, v72, s43
	v_or_b32_e32 v35, v35, v70
	v_pk_mul_f32 v[78:79], v[42:43], s[38:39] op_sel_hi:[1,0]
	v_pk_mul_f32 v[80:81], v[46:47], s[38:39] op_sel_hi:[1,0]
	global_store_dword v[68:69], v35, off offset:1024
	v_med3_f32 v35, v80, s39, v96
	v_med3_f32 v70, v81, s39, v96
	v_med3_f32 v72, v78, s39, v96
	v_med3_f32 v74, v79, s39, v96
	v_add_f32_e32 v35, 0x4b400000, v35
	v_add_f32_e32 v70, 0x4b400000, v70
	v_add_f32_e32 v72, 0x4b400000, v72
	v_add_f32_e32 v74, 0x4b400000, v74
	v_pk_fma_f32 v[36:37], v[150:151], v[36:37], v[154:155]
	v_perm_b32 v35, v70, v35, s42
	v_perm_b32 v70, v74, v72, s43
	v_or_b32_e32 v35, v35, v70
	v_pk_mul_f32 v[78:79], v[36:37], s[38:39] op_sel_hi:[1,0]
	v_pk_mul_f32 v[80:81], v[38:39], s[38:39] op_sel_hi:[1,0]
	global_store_dword v[68:69], v35, off offset:1280
	v_med3_f32 v35, v80, s39, v96
	v_med3_f32 v70, v81, s39, v96
	v_med3_f32 v72, v78, s39, v96
	v_med3_f32 v74, v79, s39, v96
	v_pk_mul_f32 v[44:45], v[44:45], v[82:83] op_sel_hi:[1,0]
	v_pk_mul_f32 v[40:41], v[40:41], v[82:83] op_sel_hi:[1,0]
	v_add_f32_e32 v35, 0x4b400000, v35
	v_add_f32_e32 v70, 0x4b400000, v70
	v_add_f32_e32 v72, 0x4b400000, v72
	v_add_f32_e32 v74, 0x4b400000, v74
	s_waitcnt vmcnt(6)
	v_pk_fma_f32 v[40:41], v[158:159], v[40:41], v[162:163]
	v_pk_fma_f32 v[44:45], v[156:157], v[44:45], v[160:161]
	v_perm_b32 v35, v70, v35, s42
	v_perm_b32 v70, v74, v72, s43
	v_or_b32_e32 v35, v35, v70
	v_pk_mul_f32 v[78:79], v[40:41], s[38:39] op_sel_hi:[1,0]
	v_pk_mul_f32 v[80:81], v[44:45], s[38:39] op_sel_hi:[1,0]
	global_store_dword v[68:69], v35, off offset:1536
	v_med3_f32 v35, v80, s39, v96
	v_med3_f32 v70, v81, s39, v96
	v_med3_f32 v72, v78, s39, v96
	v_med3_f32 v74, v79, s39, v96
	v_add_f32_e32 v35, 0x4b400000, v35
	v_add_f32_e32 v70, 0x4b400000, v70
	v_add_f32_e32 v72, 0x4b400000, v72
	v_add_f32_e32 v74, 0x4b400000, v74
	v_perm_b32 v35, v70, v35, s42
	v_perm_b32 v70, v74, v72, s43
	v_or_b32_e32 v35, v35, v70
	global_store_dword v[68:69], v35, off offset:1792
	v_ashrrev_i32_e32 v35, 31, v34
	s_and_saveexec_b64 s[6:7], s[2:3]
	s_cbranch_execz .LBB0_4584
	v_mul_f32_e32 v68, 0x3a000000, v102
	v_lshl_add_u64 v[78:79], v[34:35], 2, s[28:29]
	v_mov_b32_e32 v69, v82
	global_store_dwordx2 v[78:79], v[68:69], off
; #define LAS __attribute__((address_space(3)))
; __device__ __forceinline__ void ln3_router_phase(const Params& P, LAS unsigned char* lds, const int tid) {
;     ...
;             float l[8];
; #pragma unroll
;             for (int e = 0; e < 8; ++e) { float s = 0.f;
; #pragma unroll
;                 for (int j = 0; j < 8; ++j) { const f32x4 w = *(const LAS f32x4*)(wr + e * 2048 + 256 * j + 4 * lane); s = fmaf(v[j][0], w[0], s); s = fmaf(v[j][1], w[1], s); s = fmaf(v[j][2], w[2], s); s = fmaf(v[j][3], w[3], s); }
;                 l[e] = wave_sum(s); }
.LBB0_4584:
	s_or_b64 exec, exec, s[6:7]
	ds_read_b128 v[78:81], v9
	ds_read_b128 v[102:105], v9 offset:1024
	ds_read_b128 v[106:109], v9 offset:2048
	ds_read_b128 v[110:113], v9 offset:3072
	ds_read_b128 v[114:117], v9 offset:8192
	ds_read_b128 v[118:121], v9 offset:4096
	ds_read_b128 v[122:125], v9 offset:5120
	ds_read_b128 v[126:129], v9 offset:6144
	ds_read_b128 v[130:133], v9 offset:7168
	ds_read_b128 v[134:137], v9 offset:9216
	s_waitcnt lgkmcnt(5)
	v_mov_b32_e32 v68, v114
	v_mov_b32_e32 v69, v78
	v_pk_fma_f32 v[68:69], v[66:67], v[68:69], 0 op_sel_hi:[0,1,0]
	v_mov_b32_e32 v78, v115
	v_pk_fma_f32 v[68:69], v[66:67], v[78:79], v[68:69] op_sel:[1,0,0]
	v_mov_b32_e32 v78, v116
	v_mov_b32_e32 v79, v80
	v_pk_fma_f32 v[68:69], v[64:65], v[78:79], v[68:69] op_sel_hi:[0,1,1]
	v_mov_b32_e32 v70, v65
	v_mov_b32_e32 v80, v117
	v_pk_fma_f32 v[68:69], v[70:71], v[80:81], v[68:69] op_sel_hi:[0,1,1]
	ds_read_b128 v[78:81], v9 offset:10240
	ds_read_b128 v[114:117], v9 offset:11264
	s_waitcnt lgkmcnt(2)
	v_mov_b32_e32 v138, v134
	v_mov_b32_e32 v139, v102
	v_pk_fma_f32 v[68:69], v[62:63], v[138:139], v[68:69] op_sel_hi:[0,1,1]
	v_mov_b32_e32 v102, v135
	v_pk_fma_f32 v[68:69], v[62:63], v[102:103], v[68:69] op_sel:[1,0,0]
	v_mov_b32_e32 v102, v136
	v_mov_b32_e32 v103, v104
	v_pk_fma_f32 v[68:69], v[60:61], v[102:103], v[68:69] op_sel_hi:[0,1,1]
	v_mov_b32_e32 v70, v61
	v_mov_b32_e32 v104, v137
	v_pk_fma_f32 v[68:69], v[70:71], v[104:105], v[68:69] op_sel_hi:[0,1,1]
	s_waitcnt lgkmcnt(1)
	v_mov_b32_e32 v102, v78
	v_mov_b32_e32 v103, v106
	v_pk_fma_f32 v[68:69], v[58:59], v[102:103], v[68:69] op_sel_hi:[0,1,1]
	v_mov_b32_e32 v106, v79
	v_pk_fma_f32 v[68:69], v[58:59], v[106:107], v[68:69] op_sel:[1,0,0]
	v_mov_b32_e32 v78, v80
	v_mov_b32_e32 v79, v108
	v_pk_fma_f32 v[68:69], v[56:57], v[78:79], v[68:69] op_sel_hi:[0,1,1]
	v_mov_b32_e32 v70, v57
	v_mov_b32_e32 v108, v81
	v_pk_fma_f32 v[68:69], v[70:71], v[108:109], v[68:69] op_sel_hi:[0,1,1]
	s_waitcnt lgkmcnt(0)
	v_mov_b32_e32 v78, v114
	v_mov_b32_e32 v79, v110
	v_pk_fma_f32 v[68:69], v[54:55], v[78:79], v[68:69] op_sel_hi:[0,1,1]
	v_mov_b32_e32 v110, v115
	v_pk_fma_f32 v[68:69], v[54:55], v[110:111], v[68:69] op_sel:[1,0,0]
	v_mov_b32_e32 v78, v116
	v_mov_b32_e32 v79, v112
	v_pk_fma_f32 v[68:69], v[52:53], v[78:79], v[68:69] op_sel_hi:[0,1,1]
	ds_read_b128 v[78:81], v9 offset:12288
	ds_read_b128 v[102:105], v9 offset:13312
	ds_read_b128 v[106:109], v9 offset:14336
	v_mov_b32_e32 v70, v53
	v_mov_b32_e32 v112, v117
	v_pk_fma_f32 v[68:69], v[70:71], v[112:113], v[68:69] op_sel_hi:[0,1,1]
	s_waitcnt lgkmcnt(2)
	v_mov_b32_e32 v110, v78
	v_mov_b32_e32 v111, v118
	v_pk_fma_f32 v[68:69], v[50:51], v[110:111], v[68:69] op_sel_hi:[0,1,1]
	v_mov_b32_e32 v118, v79
	v_pk_fma_f32 v[68:69], v[50:51], v[118:119], v[68:69] op_sel:[1,0,0]
	v_mov_b32_e32 v78, v80
	v_mov_b32_e32 v79, v120
	v_pk_fma_f32 v[68:69], v[48:49], v[78:79], v[68:69] op_sel_hi:[0,1,1]
	v_mov_b32_e32 v70, v49
	v_mov_b32_e32 v120, v81
	v_pk_fma_f32 v[68:69], v[70:71], v[120:121], v[68:69] op_sel_hi:[0,1,1]
	s_waitcnt lgkmcnt(1)
	v_mov_b32_e32 v78, v102
	v_mov_b32_e32 v79, v122
	v_pk_fma_f32 v[68:69], v[46:47], v[78:79], v[68:69] op_sel_hi:[0,1,1]
	v_mov_b32_e32 v122, v103
	v_pk_fma_f32 v[68:69], v[46:47], v[122:123], v[68:69] op_sel:[1,0,0]
	v_mov_b32_e32 v78, v104
	v_mov_b32_e32 v79, v124
	v_pk_fma_f32 v[68:69], v[42:43], v[78:79], v[68:69] op_sel_hi:[0,1,1]
	v_mov_b32_e32 v70, v43
	v_mov_b32_e32 v124, v105
	ds_read_b128 v[78:81], v9 offset:15360
	v_pk_fma_f32 v[68:69], v[70:71], v[124:125], v[68:69] op_sel_hi:[0,1,1]
	s_waitcnt lgkmcnt(1)
	v_mov_b32_e32 v102, v106
	v_mov_b32_e32 v103, v126
	v_pk_fma_f32 v[68:69], v[38:39], v[102:103], v[68:69] op_sel_hi:[0,1,1]
	v_mov_b32_e32 v126, v107
	v_pk_fma_f32 v[68:69], v[38:39], v[126:127], v[68:69] op_sel:[1,0,0]
	v_mov_b32_e32 v102, v108
	v_mov_b32_e32 v103, v128
	v_pk_fma_f32 v[68:69], v[36:37], v[102:103], v[68:69] op_sel_hi:[0,1,1]
	v_mov_b32_e32 v70, v37
	v_mov_b32_e32 v128, v109
	v_pk_fma_f32 v[68:69], v[70:71], v[128:129], v[68:69] op_sel_hi:[0,1,1]
	s_waitcnt lgkmcnt(0)
	v_mov_b32_e32 v102, v78
	v_mov_b32_e32 v103, v130
	v_pk_fma_f32 v[68:69], v[44:45], v[102:103], v[68:69] op_sel_hi:[0,1,1]
	v_mov_b32_e32 v130, v79
	v_pk_fma_f32 v[68:69], v[44:45], v[130:131], v[68:69] op_sel:[1,0,0]
	v_mov_b32_e32 v78, v80
	v_mov_b32_e32 v79, v132
	v_pk_fma_f32 v[68:69], v[40:41], v[78:79], v[68:69] op_sel_hi:[0,1,1]
	v_mov_b32_e32 v70, v41
	v_mov_b32_e32 v132, v81
	v_pk_fma_f32 v[68:69], v[70:71], v[132:133], v[68:69] op_sel_hi:[0,1,1]
	s_nop 1
	v_mov_b32_dpp v79, v69 quad_perm:[1,0,3,2] row_mask:0xf bank_mask:0xf
	s_nop 1
	v_mov_b32_dpp v78, v68 quad_perm:[1,0,3,2] row_mask:0xf bank_mask:0xf
	s_waitcnt lgkmcnt(0)
	v_pk_add_f32 v[68:69], v[68:69], v[78:79]
	s_nop 1
	v_mov_b32_dpp v103, v69 quad_perm:[2,3,0,1] row_mask:0xf bank_mask:0xf
	s_nop 1
	v_mov_b32_dpp v102, v68 quad_perm:[2,3,0,1] row_mask:0xf bank_mask:0xf
	ds_read_b128 v[78:81], v9 offset:16384
	s_waitcnt lgkmcnt(0)
	v_pk_add_f32 v[68:69], v[68:69], v[102:103]
	ds_read_b128 v[102:105], v9 offset:17408
	s_waitcnt lgkmcnt(1)
	v_fma_f32 v70, v66, v78, 0
	v_fmac_f32_e32 v70, v67, v79
	v_fmac_f32_e32 v70, v64, v80
	v_fmac_f32_e32 v70, v65, v81
	ds_read_b128 v[78:81], v9 offset:18432
	s_waitcnt lgkmcnt(1)
	v_fmac_f32_e32 v70, v62, v102
	v_fmac_f32_e32 v70, v63, v103
	v_fmac_f32_e32 v70, v60, v104
	v_fmac_f32_e32 v70, v61, v105
	ds_read_b128 v[102:105], v9 offset:19456
	s_waitcnt lgkmcnt(1)
	v_fmac_f32_e32 v70, v58, v78
	v_fmac_f32_e32 v70, v59, v79
	v_fmac_f32_e32 v70, v56, v80
	v_fmac_f32_e32 v70, v57, v81
	ds_read_b128 v[78:81], v9 offset:20480
	s_waitcnt lgkmcnt(1)
; #define LAS __attribute__((address_space(3)))
; __device__ __forceinline__ float wave_sum(float v) {
; #pragma unroll
;     for (int o = 1; o < 64; o <<= 1) v += __shfl_xor(v, o);
;     return v;
; }
; __device__ __forceinline__ void ln3_router_phase(const Params& P, LAS unsigned char* lds, const int tid) {
;     ...
;             float l[8];
; #pragma unroll
;             for (int e = 0; e < 8; ++e) { float s = 0.f;
; #pragma unroll
;                 for (int j = 0; j < 8; ++j) { const f32x4 w = *(const LAS f32x4*)(wr + e * 2048 + 256 * j + 4 * lane); s = fmaf(v[j][0], w[0], s); s = fmaf(v[j][1], w[1], s); s = fmaf(v[j][2], w[2], s); s = fmaf(v[j][3], w[3], s); }
;                 l[e] = wave_sum(s); }
	v_fmac_f32_e32 v70, v54, v102
	v_fmac_f32_e32 v70, v55, v103
	v_fmac_f32_e32 v70, v52, v104
	v_fmac_f32_e32 v70, v53, v105
	ds_read_b128 v[102:105], v9 offset:21504
	s_waitcnt lgkmcnt(1)
	v_fmac_f32_e32 v70, v50, v78
	v_fmac_f32_e32 v70, v51, v79
	v_fmac_f32_e32 v70, v48, v80
	v_fmac_f32_e32 v70, v49, v81
	ds_read_b128 v[78:81], v9 offset:22528
	s_waitcnt lgkmcnt(1)
	v_fmac_f32_e32 v70, v46, v102
	v_fmac_f32_e32 v70, v47, v103
	v_fmac_f32_e32 v70, v42, v104
	v_fmac_f32_e32 v70, v43, v105
	ds_read_b128 v[102:105], v9 offset:23552
	s_waitcnt lgkmcnt(1)
	v_fmac_f32_e32 v70, v38, v78
	v_fmac_f32_e32 v70, v39, v79
	v_fmac_f32_e32 v70, v36, v80
	v_fmac_f32_e32 v70, v37, v81
	s_waitcnt lgkmcnt(0)
	v_fmac_f32_e32 v70, v44, v102
	v_fmac_f32_e32 v70, v45, v103
	v_fmac_f32_e32 v70, v40, v104
	s_nop 1
	v_mov_b32_dpp v107, v69 row_half_mirror row_mask:0xf bank_mask:0xf
	s_nop 1
	v_mov_b32_dpp v106, v68 row_half_mirror row_mask:0xf bank_mask:0xf
	v_fmac_f32_e32 v70, v41, v105
	s_nop 1
	v_mov_b32_dpp v72, v70 quad_perm:[1,0,3,2] row_mask:0xf bank_mask:0xf
	s_waitcnt lgkmcnt(0)
	v_pk_add_f32 v[68:69], v[68:69], v[106:107]
	s_nop 1
	v_mov_b32_dpp v79, v69 row_mirror row_mask:0xf bank_mask:0xf
	s_nop 1
	v_mov_b32_dpp v78, v68 row_mirror row_mask:0xf bank_mask:0xf
	s_waitcnt lgkmcnt(0)
	v_add_f32_e32 v70, v70, v72
	s_nop 1
	v_mov_b32_dpp v72, v70 quad_perm:[2,3,0,1] row_mask:0xf bank_mask:0xf
	s_waitcnt lgkmcnt(0)
	v_pk_add_f32 v[68:69], v[68:69], v[78:79]
	ds_bpermute_b32 v103, v77, v69
	ds_bpermute_b32 v102, v77, v68
	s_waitcnt lgkmcnt(2)
	v_add_f32_e32 v70, v70, v72
	s_nop 1
	v_mov_b32_dpp v72, v70 row_half_mirror row_mask:0xf bank_mask:0xf
	ds_read_b128 v[78:81], v9 offset:24576
	s_waitcnt lgkmcnt(1)
	v_pk_add_f32 v[68:69], v[68:69], v[102:103]
	ds_read_b128 v[102:105], v9 offset:25600
	s_waitcnt lgkmcnt(1)
	v_add_f32_e32 v70, v70, v72
	s_waitcnt lgkmcnt(0)
	v_fma_f32 v72, v66, v78, 0
	v_fmac_f32_e32 v72, v67, v79
	v_fmac_f32_e32 v72, v64, v80
	v_fmac_f32_e32 v72, v65, v81
	ds_read_b128 v[78:81], v9 offset:26624
	s_waitcnt lgkmcnt(1)
	v_fmac_f32_e32 v72, v62, v102
	v_fmac_f32_e32 v72, v63, v103
	v_fmac_f32_e32 v72, v60, v104
	v_fmac_f32_e32 v72, v61, v105
	ds_read_b128 v[102:105], v9 offset:27648
	s_waitcnt lgkmcnt(1)
	v_fmac_f32_e32 v72, v58, v78
	v_fmac_f32_e32 v72, v59, v79
	v_fmac_f32_e32 v72, v56, v80
	v_fmac_f32_e32 v72, v57, v81
	ds_read_b128 v[78:81], v9 offset:28672
	s_waitcnt lgkmcnt(1)
	v_fmac_f32_e32 v72, v54, v102
	v_fmac_f32_e32 v72, v55, v103
	v_fmac_f32_e32 v72, v52, v104
	v_fmac_f32_e32 v72, v53, v105
	ds_read_b128 v[102:105], v9 offset:29696
	s_waitcnt lgkmcnt(1)
	v_fmac_f32_e32 v72, v50, v78
	v_fmac_f32_e32 v72, v51, v79
	v_fmac_f32_e32 v72, v48, v80
	v_fmac_f32_e32 v72, v49, v81
	ds_read_b128 v[78:81], v9 offset:30720
	s_waitcnt lgkmcnt(1)
	v_fmac_f32_e32 v72, v46, v102
	v_fmac_f32_e32 v72, v47, v103
	v_fmac_f32_e32 v72, v42, v104
	v_fmac_f32_e32 v72, v43, v105
	ds_read_b128 v[102:105], v9 offset:31744
	s_waitcnt lgkmcnt(1)
	v_fmac_f32_e32 v72, v38, v78
	v_fmac_f32_e32 v72, v39, v79
	v_fmac_f32_e32 v72, v36, v80
	v_fmac_f32_e32 v72, v37, v81
	ds_read_b128 v[78:81], v9 offset:32768
	s_waitcnt lgkmcnt(1)
	v_fmac_f32_e32 v72, v44, v102
	v_fmac_f32_e32 v72, v45, v103
	v_fmac_f32_e32 v72, v40, v104
	v_fmac_f32_e32 v72, v41, v105
	ds_read_b128 v[102:105], v9 offset:33792
	s_waitcnt lgkmcnt(1)
	v_fma_f32 v76, v66, v78, 0
	v_fmac_f32_e32 v76, v67, v79
	v_fmac_f32_e32 v76, v64, v80
	v_fmac_f32_e32 v76, v65, v81
	ds_read_b128 v[78:81], v9 offset:34816
	s_waitcnt lgkmcnt(1)
	v_fmac_f32_e32 v76, v62, v102
	v_fmac_f32_e32 v76, v63, v103
	v_fmac_f32_e32 v76, v60, v104
	v_fmac_f32_e32 v76, v61, v105
	ds_read_b128 v[102:105], v9 offset:35840
	s_waitcnt lgkmcnt(1)
	v_fmac_f32_e32 v76, v58, v78
	v_fmac_f32_e32 v76, v59, v79
	v_fmac_f32_e32 v76, v56, v80
	v_fmac_f32_e32 v76, v57, v81
	ds_read_b128 v[78:81], v9 offset:36864
	s_waitcnt lgkmcnt(1)
	v_fmac_f32_e32 v76, v54, v102
	v_fmac_f32_e32 v76, v55, v103
	v_fmac_f32_e32 v76, v52, v104
	v_fmac_f32_e32 v76, v53, v105
	ds_read_b128 v[102:105], v9 offset:37888
	s_waitcnt lgkmcnt(1)
	v_fmac_f32_e32 v76, v50, v78
	v_fmac_f32_e32 v76, v51, v79
	v_fmac_f32_e32 v76, v48, v80
	v_fmac_f32_e32 v76, v49, v81
	ds_read_b128 v[78:81], v9 offset:38912
	s_waitcnt lgkmcnt(1)
	v_fmac_f32_e32 v76, v46, v102
	v_fmac_f32_e32 v76, v47, v103
	v_fmac_f32_e32 v76, v42, v104
	v_fmac_f32_e32 v76, v43, v105
	ds_read_b128 v[102:105], v9 offset:39936
	s_waitcnt lgkmcnt(1)
	v_fmac_f32_e32 v76, v38, v78
	v_fmac_f32_e32 v76, v39, v79
	v_fmac_f32_e32 v76, v36, v80
	v_fmac_f32_e32 v76, v37, v81
	s_waitcnt lgkmcnt(0)
	v_fmac_f32_e32 v76, v44, v102
	v_fmac_f32_e32 v76, v45, v103
	v_fmac_f32_e32 v76, v40, v104
	v_fmac_f32_e32 v76, v41, v105
	s_nop 1
	v_mov_b32_dpp v78, v76 quad_perm:[1,0,3,2] row_mask:0xf bank_mask:0xf
	s_nop 1
	v_mov_b32_dpp v80, v70 row_mirror row_mask:0xf bank_mask:0xf
	ds_bpermute_b32 v79, v101, v69
	ds_read_b128 v[102:105], v9 offset:41984
	s_nop 1
	v_mov_b32_dpp v74, v72 quad_perm:[1,0,3,2] row_mask:0xf bank_mask:0xf
	s_waitcnt lgkmcnt(1)
	v_add_f32_e32 v76, v76, v78
	s_nop 1
	v_mov_b32_dpp v78, v76 quad_perm:[2,3,0,1] row_mask:0xf bank_mask:0xf
	s_waitcnt lgkmcnt(0)
	v_add_f32_e32 v70, v70, v80
	v_mov_b32_e32 v80, v70
	s_nop 1
	v_permlane16_swap_b32_e32 v70, v80
	s_waitcnt lgkmcnt(1)
	v_add_f32_e32 v72, v72, v74
	s_nop 1
	v_mov_b32_dpp v74, v72 quad_perm:[2,3,0,1] row_mask:0xf bank_mask:0xf
	s_waitcnt lgkmcnt(0)
	v_add_f32_e32 v76, v76, v78
	s_nop 1
	v_mov_b32_dpp v81, v76 row_half_mirror row_mask:0xf bank_mask:0xf
	s_waitcnt lgkmcnt(0)
	v_add_f32_e32 v70, v70, v80
	ds_bpermute_b32 v78, v101, v68
	s_waitcnt lgkmcnt(2)
; #define LAS __attribute__((address_space(3)))
; __device__ __forceinline__ float wave_sum(float v) {
; #pragma unroll
;     for (int o = 1; o < 64; o <<= 1) v += __shfl_xor(v, o);
;     return v;
; }
; __device__ __forceinline__ void ln3_router_phase(const Params& P, LAS unsigned char* lds, const int tid) {
;     ...
;             float l[8];
; #pragma unroll
;             for (int e = 0; e < 8; ++e) { float s = 0.f;
; #pragma unroll
;                 for (int j = 0; j < 8; ++j) { const f32x4 w = *(const LAS f32x4*)(wr + e * 2048 + 256 * j + 4 * lane); s = fmaf(v[j][0], w[0], s); s = fmaf(v[j][1], w[1], s); s = fmaf(v[j][2], w[2], s); s = fmaf(v[j][3], w[3], s); }
;                 l[e] = wave_sum(s); }
	v_add_f32_e32 v72, v72, v74
	s_nop 1
	v_mov_b32_dpp v74, v72 row_half_mirror row_mask:0xf bank_mask:0xf
	s_waitcnt lgkmcnt(1)
	v_add_f32_e32 v76, v76, v81
	s_nop 1
	v_mov_b32_dpp v80, v76 row_mirror row_mask:0xf bank_mask:0xf
	v_mov_b32_e32 v81, v70
	s_nop 1
	v_permlane32_swap_b32_e32 v70, v81
	s_waitcnt lgkmcnt(0)
	v_pk_add_f32 v[68:69], v[68:69], v[78:79]
	s_waitcnt lgkmcnt(0)
	v_add_f32_e32 v72, v72, v74
	s_nop 1
	v_mov_b32_dpp v74, v72 row_mirror row_mask:0xf bank_mask:0xf
	s_waitcnt lgkmcnt(1)
	v_add_f32_e32 v76, v76, v80
	s_waitcnt lgkmcnt(0)
	v_add_f32_e32 v70, v70, v81
	ds_read_b128 v[78:81], v9 offset:40960
	ds_bpermute_b32 v82, v77, v76
	s_waitcnt lgkmcnt(2)
	v_add_f32_e32 v72, v72, v74
	ds_bpermute_b32 v74, v77, v72
	v_cmp_gt_f32_e32 vcc, v68, v69
	s_waitcnt lgkmcnt(2)
	v_fma_f32 v106, v66, v78, 0
	v_fmac_f32_e32 v106, v67, v79
	v_fmac_f32_e32 v106, v64, v80
	v_fmac_f32_e32 v106, v65, v81
	ds_read_b128 v[78:81], v9 offset:43008
	v_fmac_f32_e32 v106, v62, v102
	v_fmac_f32_e32 v106, v63, v103
	v_fmac_f32_e32 v106, v60, v104
	v_fmac_f32_e32 v106, v61, v105
	ds_read_b128 v[102:105], v9 offset:44032
	s_waitcnt lgkmcnt(1)
	v_fmac_f32_e32 v106, v58, v78
	v_fmac_f32_e32 v106, v59, v79
	v_fmac_f32_e32 v106, v56, v80
	v_fmac_f32_e32 v106, v57, v81
	ds_read_b128 v[78:81], v9 offset:45056
	s_waitcnt lgkmcnt(1)
	v_fmac_f32_e32 v106, v54, v102
	v_fmac_f32_e32 v106, v55, v103
	v_fmac_f32_e32 v106, v52, v104
	v_fmac_f32_e32 v106, v53, v105
	ds_read_b128 v[102:105], v9 offset:46080
	s_waitcnt lgkmcnt(1)
	v_fmac_f32_e32 v106, v50, v78
	v_fmac_f32_e32 v106, v51, v79
	v_fmac_f32_e32 v106, v48, v80
	v_fmac_f32_e32 v106, v49, v81
	ds_read_b128 v[78:81], v9 offset:47104
	s_waitcnt lgkmcnt(1)
	v_fmac_f32_e32 v106, v46, v102
	v_fmac_f32_e32 v106, v47, v103
	v_fmac_f32_e32 v106, v42, v104
	v_fmac_f32_e32 v106, v43, v105
	ds_read_b128 v[102:105], v9 offset:48128
	s_waitcnt lgkmcnt(1)
	v_fmac_f32_e32 v106, v38, v78
	v_fmac_f32_e32 v106, v39, v79
	v_fmac_f32_e32 v106, v36, v80
	v_fmac_f32_e32 v106, v37, v81
	ds_read_b128 v[78:81], v9 offset:49152
	s_waitcnt lgkmcnt(1)
	v_fmac_f32_e32 v106, v44, v102
	v_fmac_f32_e32 v106, v45, v103
	v_fmac_f32_e32 v106, v40, v104
	v_fmac_f32_e32 v106, v41, v105
	ds_read_b128 v[102:105], v9 offset:50176
	s_waitcnt lgkmcnt(1)
	v_fma_f32 v108, v66, v78, 0
	v_fmac_f32_e32 v108, v67, v79
	v_fmac_f32_e32 v108, v64, v80
	v_fmac_f32_e32 v108, v65, v81
	ds_read_b128 v[78:81], v9 offset:51200
	s_waitcnt lgkmcnt(1)
	v_fmac_f32_e32 v108, v62, v102
	v_fmac_f32_e32 v108, v63, v103
	v_fmac_f32_e32 v108, v60, v104
	v_fmac_f32_e32 v108, v61, v105
	ds_read_b128 v[102:105], v9 offset:52224
	s_waitcnt lgkmcnt(1)
	v_fmac_f32_e32 v108, v58, v78
	v_fmac_f32_e32 v108, v59, v79
	v_fmac_f32_e32 v108, v56, v80
	v_fmac_f32_e32 v108, v57, v81
	ds_read_b128 v[78:81], v9 offset:53248
	s_waitcnt lgkmcnt(1)
	v_fmac_f32_e32 v108, v54, v102
	v_fmac_f32_e32 v108, v55, v103
	v_fmac_f32_e32 v108, v52, v104
	v_fmac_f32_e32 v108, v53, v105
	ds_read_b128 v[102:105], v9 offset:54272
	s_waitcnt lgkmcnt(1)
	v_fmac_f32_e32 v108, v50, v78
	v_fmac_f32_e32 v108, v51, v79
	v_fmac_f32_e32 v108, v48, v80
	v_fmac_f32_e32 v108, v49, v81
	ds_read_b128 v[78:81], v9 offset:55296
	s_waitcnt lgkmcnt(1)
	v_fmac_f32_e32 v108, v46, v102
	v_fmac_f32_e32 v108, v47, v103
	v_fmac_f32_e32 v108, v42, v104
	v_fmac_f32_e32 v108, v43, v105
	ds_read_b128 v[102:105], v9 offset:56320
	s_waitcnt lgkmcnt(1)
	v_fmac_f32_e32 v108, v38, v78
	v_fmac_f32_e32 v108, v39, v79
	v_fmac_f32_e32 v108, v36, v80
	v_fmac_f32_e32 v108, v37, v81
	ds_read_b128 v[78:81], v9 offset:57344
	s_waitcnt lgkmcnt(1)
	v_fmac_f32_e32 v108, v44, v102
	v_fmac_f32_e32 v108, v45, v103
	v_fmac_f32_e32 v108, v40, v104
	v_fmac_f32_e32 v108, v41, v105
	ds_read_b128 v[102:105], v9 offset:58368
	s_waitcnt lgkmcnt(1)
	v_fma_f32 v78, v66, v78, 0
	v_fmac_f32_e32 v78, v67, v79
	v_fmac_f32_e32 v78, v64, v80
	v_fmac_f32_e32 v78, v65, v81
	ds_read_b128 v[64:67], v9 offset:59392
	s_waitcnt lgkmcnt(1)
	v_fmac_f32_e32 v78, v62, v102
	v_fmac_f32_e32 v78, v63, v103
	v_fmac_f32_e32 v78, v60, v104
	v_fmac_f32_e32 v78, v61, v105
	ds_read_b128 v[60:63], v9 offset:60416
	s_waitcnt lgkmcnt(1)
	v_fmac_f32_e32 v78, v58, v64
	v_fmac_f32_e32 v78, v59, v65
	v_fmac_f32_e32 v78, v56, v66
	v_fmac_f32_e32 v78, v57, v67
	ds_read_b128 v[56:59], v9 offset:61440
	s_waitcnt lgkmcnt(1)
	v_fmac_f32_e32 v78, v54, v60
	v_fmac_f32_e32 v78, v55, v61
	v_fmac_f32_e32 v78, v52, v62
	v_fmac_f32_e32 v78, v53, v63
	ds_read_b128 v[52:55], v9 offset:62464
	s_waitcnt lgkmcnt(1)
	v_fmac_f32_e32 v78, v50, v56
	v_fmac_f32_e32 v78, v51, v57
	v_fmac_f32_e32 v78, v48, v58
	v_fmac_f32_e32 v78, v49, v59
	ds_read_b128 v[48:51], v9 offset:63488
	s_waitcnt lgkmcnt(1)
	v_fmac_f32_e32 v78, v46, v52
	v_fmac_f32_e32 v78, v47, v53
	v_fmac_f32_e32 v78, v42, v54
	v_fmac_f32_e32 v78, v43, v55
	ds_read_b128 v[52:55], v9 offset:64512
	s_waitcnt lgkmcnt(1)
	v_fmac_f32_e32 v78, v38, v48
	v_fmac_f32_e32 v78, v39, v49
	v_fmac_f32_e32 v78, v36, v50
	v_fmac_f32_e32 v78, v37, v51
	s_waitcnt lgkmcnt(0)
	v_fmac_f32_e32 v78, v44, v52
	v_fmac_f32_e32 v78, v45, v53
	v_fmac_f32_e32 v78, v40, v54
	v_fmac_f32_e32 v78, v41, v55
	s_nop 1
	v_mov_b32_dpp v107, v106 quad_perm:[1,0,3,2] row_mask:0xf bank_mask:0xf
	s_nop 1
	v_mov_b32_dpp v36, v78 quad_perm:[1,0,3,2] row_mask:0xf bank_mask:0xf
	s_nop 1
	v_mov_b32_dpp v109, v108 quad_perm:[1,0,3,2] row_mask:0xf bank_mask:0xf
	v_add_f32_e32 v72, v72, v74
	v_mov_b32_e32 v74, v72
	s_nop 1
	v_permlane32_swap_b32_e32 v72, v74
	s_waitcnt lgkmcnt(0)
	v_add_f32_e32 v37, v106, v107
	s_waitcnt lgkmcnt(2)
	v_add_f32_e32 v36, v78, v36
	s_nop 1
	v_mov_b32_dpp v38, v37 quad_perm:[2,3,0,1] row_mask:0xf bank_mask:0xf
	s_waitcnt lgkmcnt(1)
; #define LAS __attribute__((address_space(3)))
; __device__ __forceinline__ void ln3_router_phase(const Params& P, LAS unsigned char* lds, const int tid) {
;     ...
;             float l[8];
; #pragma unroll
;             for (int e = 0; e < 8; ++e) { float s = 0.f;
; #pragma unroll
;                 for (int j = 0; j < 8; ++j) { const f32x4 w = *(const LAS f32x4*)(wr + e * 2048 + 256 * j + 4 * lane); s = fmaf(v[j][0], w[0], s); s = fmaf(v[j][1], w[1], s); s = fmaf(v[j][2], w[2], s); s = fmaf(v[j][3], w[3], s); }
;                 l[e] = wave_sum(s); }
;             float v1 = l[0]; int e1 = 0;
; #pragma unroll
;             for (int e = 1; e < 8; ++e) if (l[e] > v1) { v1 = l[e]; e1 = e; }
;             float v2 = -__builtin_inff(); int e2 = 0;
; #pragma unroll
;             for (int e = 0; e < 8; ++e) if (e != e1 && l[e] > v2) { v2 = l[e]; e2 = e; }
;             const float ex = expf(v2 - v1), g1 = 1.0f / (1.0f + ex), g2 = ex / (1.0f + ex);
;             if (lane == 0) { rte[2 * m] = e1; rte[2 * m + 1] = e2; rtg[2 * m] = g1; rtg[2 * m + 1] = g2; }
; #pragma unroll
;             for (int e = 0; e < 8; ++e) cnt[e] += (e1 == e) + (e2 == e);
	v_add_f32_e32 v39, v108, v109
	s_nop 1
	v_mov_b32_dpp v41, v36 quad_perm:[2,3,0,1] row_mask:0xf bank_mask:0xf
	s_nop 1
	v_mov_b32_dpp v40, v39 quad_perm:[2,3,0,1] row_mask:0xf bank_mask:0xf
	v_add_f32_e32 v76, v76, v82
	s_waitcnt lgkmcnt(0)
	v_add_f32_e32 v37, v37, v38
	s_nop 1
	v_mov_b32_dpp v38, v37 row_half_mirror row_mask:0xf bank_mask:0xf
	s_waitcnt lgkmcnt(1)
	v_add_f32_e32 v36, v36, v41
	s_waitcnt lgkmcnt(0)
	v_add_f32_e32 v39, v39, v40
	s_nop 1
	v_mov_b32_dpp v41, v36 row_half_mirror row_mask:0xf bank_mask:0xf
	s_nop 1
	v_mov_b32_dpp v40, v39 row_half_mirror row_mask:0xf bank_mask:0xf
	s_waitcnt lgkmcnt(0)
	v_add_f32_e32 v37, v37, v38
	s_nop 1
	v_mov_b32_dpp v38, v37 row_mirror row_mask:0xf bank_mask:0xf
	v_mov_b32_e32 v82, v76
	s_nop 1
	v_permlane32_swap_b32_e32 v76, v82
	s_waitcnt lgkmcnt(1)
	v_add_f32_e32 v36, v36, v41
	s_waitcnt lgkmcnt(0)
	v_add_f32_e32 v39, v39, v40
	s_nop 1
	v_mov_b32_dpp v41, v36 row_mirror row_mask:0xf bank_mask:0xf
	s_nop 1
	v_mov_b32_dpp v40, v39 row_mirror row_mask:0xf bank_mask:0xf
	s_waitcnt lgkmcnt(0)
	v_add_f32_e32 v37, v37, v38
	v_mov_b32_e32 v38, v37
	s_nop 1
	v_permlane16_swap_b32_e32 v37, v38
	v_add_f32_e32 v42, v72, v74
	s_waitcnt lgkmcnt(1)
	v_add_f32_e32 v36, v36, v41
	s_waitcnt lgkmcnt(0)
	v_add_f32_e32 v39, v39, v40
	v_mov_b32_e32 v41, v36
	s_nop 1
	v_permlane16_swap_b32_e32 v36, v41
	v_mov_b32_e32 v40, v39
	s_nop 1
	v_permlane16_swap_b32_e32 v39, v40
	s_waitcnt lgkmcnt(0)
	v_add_f32_e32 v37, v37, v38
	v_mov_b32_e32 v38, v37
	s_nop 1
	v_permlane32_swap_b32_e32 v37, v38
	v_add_f32_e32 v43, v76, v82
	s_waitcnt lgkmcnt(1)
	v_add_f32_e32 v36, v36, v41
	s_waitcnt lgkmcnt(0)
	v_add_f32_e32 v39, v39, v40
	v_mov_b32_e32 v41, v36
	s_nop 1
	v_permlane32_swap_b32_e32 v36, v41
	v_mov_b32_e32 v40, v39
	s_nop 1
	v_permlane32_swap_b32_e32 v39, v40
	s_waitcnt lgkmcnt(0)
	v_add_f32_e32 v37, v37, v38
	v_cmp_nlg_f32_e64 s[10:11], s44, v69
	s_waitcnt lgkmcnt(1)
	v_add_f32_e32 v38, v36, v41
	v_cndmask_b32_e32 v36, v69, v68, vcc
	s_waitcnt lgkmcnt(0)
	v_add_f32_e32 v40, v39, v40
	v_cndmask_b32_e64 v39, 0, 1, vcc
	v_cmp_gt_f32_e32 vcc, v70, v36
	s_nop 1
	v_cndmask_b32_e32 v36, v36, v70, vcc
	v_cndmask_b32_e64 v39, v39, 2, vcc
	v_cmp_gt_f32_e32 vcc, v42, v36
	s_nop 1
	v_cndmask_b32_e32 v36, v36, v42, vcc
	v_cndmask_b32_e64 v39, v39, 3, vcc
	v_cmp_gt_f32_e32 vcc, v43, v36
	s_nop 1
	v_cndmask_b32_e32 v36, v36, v43, vcc
	v_cndmask_b32_e64 v39, v39, 4, vcc
	v_cmp_gt_f32_e32 vcc, v37, v36
	s_nop 1
	v_cndmask_b32_e32 v36, v36, v37, vcc
	v_cndmask_b32_e64 v41, v39, 5, vcc
	v_cmp_gt_f32_e32 vcc, v40, v36
	s_nop 1
	v_cndmask_b32_e32 v39, v36, v40, vcc
	v_cndmask_b32_e64 v36, v41, 6, vcc
	v_cmp_gt_f32_e64 s[6:7], v38, v39
	v_cmp_ngt_f32_e64 s[20:21], v38, v39
	s_nop 0
	v_cndmask_b32_e64 v36, v36, 7, s[6:7]
	v_cmp_eq_u32_e64 s[8:9], 0, v36
	s_or_b64 s[10:11], s[8:9], s[10:11]
	v_cndmask_b32_e64 v41, v69, v98, s[10:11]
	v_cmp_eq_u32_e64 s[10:11], 1, v36
	v_cmp_ngt_f32_e64 s[12:13], v68, v41
	s_or_b64 s[12:13], s[10:11], s[12:13]
	s_nop 0
	v_cndmask_b32_e64 v41, v68, v41, s[12:13]
	s_xor_b64 s[12:13], s[12:13], -1
	v_cndmask_b32_e64 v44, 0, 1, s[12:13]
	v_cmp_eq_u32_e64 s[12:13], 2, v36
	v_cmp_ngt_f32_e64 s[14:15], v70, v41
	s_or_b64 s[14:15], s[12:13], s[14:15]
	s_nop 0
	v_cndmask_b32_e64 v41, v70, v41, s[14:15]
	v_cndmask_b32_e64 v44, 2, v44, s[14:15]
	v_cmp_eq_u32_e64 s[14:15], 3, v36
	v_cmp_ngt_f32_e64 s[16:17], v42, v41
	s_or_b64 s[16:17], s[14:15], s[16:17]
	s_nop 0
	v_cndmask_b32_e64 v41, v42, v41, s[16:17]
	v_cndmask_b32_e64 v42, 3, v44, s[16:17]
	v_cmp_eq_u32_e64 s[16:17], 4, v36
	v_cmp_ngt_f32_e64 s[18:19], v43, v41
	s_or_b64 s[18:19], s[16:17], s[18:19]
	s_nop 0
	v_cndmask_b32_e64 v41, v43, v41, s[18:19]
	v_cndmask_b32_e64 v42, 4, v42, s[18:19]
	v_cmp_eq_u32_e64 s[18:19], 5, v36
	v_cmp_ngt_f32_e64 s[24:25], v37, v41
	s_or_b64 s[24:25], s[18:19], s[24:25]
	s_nop 0
	v_cndmask_b32_e64 v37, v37, v41, s[24:25]
	v_cndmask_b32_e64 v41, 5, v42, s[24:25]
	s_and_b64 s[24:25], vcc, s[20:21]
	v_cmp_ngt_f32_e32 vcc, v40, v37
	s_or_b64 vcc, s[24:25], vcc
	s_nop 0
	v_cndmask_b32_e32 v40, v40, v37, vcc
	v_cndmask_b32_e32 v37, 6, v41, vcc
	v_cmp_ngt_f32_e32 vcc, v38, v40
	s_or_b64 s[20:21], s[6:7], vcc
	v_cndmask_b32_e64 v37, 7, v37, s[20:21]
	s_and_saveexec_b64 s[40:41], s[2:3]
	s_cbranch_execz .LBB0_4581
	v_cndmask_b32_e64 v40, v38, v40, s[20:21]
	v_cndmask_b32_e64 v38, v39, v38, s[6:7]
	v_sub_f32_e32 v38, v40, v38
	v_mul_f32_e32 v39, 0x3fb8aa3b, v38
	v_fma_f32 v40, v38, s45, -v39
	v_rndne_f32_e32 v41, v39
	v_fmac_f32_e32 v40, 0x32a5705f, v38
	v_sub_f32_e32 v39, v39, v41
	v_add_f32_e32 v39, v39, v40
	v_exp_f32_e32 v39, v39
	v_cvt_i32_f32_e32 v40, v41
	v_cmp_ngt_f32_e32 vcc, s46, v38
	v_ldexp_f32 v39, v39, v40
	s_nop 0
	v_cndmask_b32_e32 v39, 0, v39, vcc
	v_cmp_nlt_f32_e32 vcc, s47, v38
	s_nop 1
	v_cndmask_b32_e32 v38, v99, v39, vcc
	v_add_f32_e32 v39, 1.0, v38
	v_div_scale_f32 v40, s[50:51], v39, v39, v38
	v_rcp_f32_e32 v41, v40
	s_nop 0
	v_fma_f32 v42, -v40, v41, 1.0
	v_fmac_f32_e32 v41, v42, v41
	v_div_scale_f32 v42, vcc, v38, v39, v38
	v_mul_f32_e32 v43, v42, v41
	v_fma_f32 v44, -v40, v43, v42
	v_fmac_f32_e32 v43, v44, v41
	v_fma_f32 v40, -v40, v43, v42
	v_div_scale_f32 v42, s[50:51], v39, v39, 1.0
	v_rcp_f32_e32 v44, v42
	v_div_fmas_f32 v40, v40, v41, v43
	v_div_fixup_f32 v45, v40, v39, v38
	v_fma_f32 v38, -v42, v44, 1.0
	v_fmac_f32_e32 v44, v38, v44
	v_div_scale_f32 v38, vcc, 1.0, v39, 1.0
	v_mul_f32_e32 v40, v38, v44
	v_fma_f32 v41, -v42, v40, v38
	v_fmac_f32_e32 v40, v41, v44
	v_fma_f32 v38, -v42, v40, v38
	v_div_fmas_f32 v38, v38, v44, v40
	v_div_fixup_f32 v44, v38, v39, 1.0
	v_lshlrev_b64 v[38:39], 2, v[34:35]
	v_add_u32_e32 v42, 1, v34
	v_lshl_add_u64 v[40:41], s[26:27], 0, v[38:39]
	v_ashrrev_i32_e32 v43, 31, v42
	v_lshl_add_u64 v[38:39], s[30:31], 0, v[38:39]
	global_store_dword v[38:39], v44, off
	v_lshl_add_u64 v[38:39], v[42:43], 2, s[30:31]
	global_store_dwordx2 v[40:41], v[36:37], off
	global_store_dword v[38:39], v45, off
	s_branch .LBB0_4581

.LBB0_4900:
	global_load_dwordx4 v[0:3], v[14:15], off
	global_load_dwordx4 v[4:7], v[12:13], off
	global_load_dwordx4 v[184:187], v[12:13], off offset:1024
	global_load_dwordx4 v[188:191], v[14:15], off offset:1024
	global_load_dwordx4 v[192:195], v[14:15], off offset:2048
	global_load_dwordx4 v[196:199], v[12:13], off offset:2048
	global_load_dwordx4 v[200:203], v[12:13], off offset:3072
	global_load_dwordx4 v[204:207], v[14:15], off offset:3072
	global_load_dwordx4 v[208:211], v[16:17], off
	global_load_dwordx4 v[212:215], v[18:19], off
	global_load_dwordx4 v[216:219], v[20:21], off
	global_load_dwordx4 v[220:223], v[22:23], off
	global_load_dwordx4 v[224:227], v[24:25], off
	global_load_dwordx4 v[228:231], v[26:27], off
	global_load_dwordx4 v[232:235], v[28:29], off
	global_load_dwordx4 v[236:239], v[30:31], off
	v_mul_f32_e32 v162, 0x3b23d70a, v112
	v_mul_f32_e32 v112, 0x3b23d70a, v113
	v_lshlrev_b32_e32 v113, 16, v100
	v_and_b32_e32 v100, 0xffff0000, v100
	v_lshlrev_b32_e32 v183, 16, v101
	v_and_b32_e32 v101, 0xffff0000, v101
	v_lshlrev_b32_e32 v240, 16, v96
	v_and_b32_e32 v96, 0xffff0000, v96
	v_lshlrev_b32_e32 v241, 16, v97
	v_and_b32_e32 v242, 0xffff0000, v97
	v_lshlrev_b32_e32 v243, 16, v90
	v_and_b32_e32 v244, 0xffff0000, v90
	v_lshlrev_b32_e32 v245, 16, v91
	v_and_b32_e32 v246, 0xffff0000, v91
	v_lshlrev_b32_e32 v247, 16, v88
	v_and_b32_e32 v248, 0xffff0000, v88
	v_lshlrev_b32_e32 v249, 16, v89
	v_and_b32_e32 v250, 0xffff0000, v89
	v_sub_f32_e32 v89, v100, v81
	v_sub_f32_e32 v88, v113, v81
	v_sub_f32_e32 v91, v101, v81
	v_sub_f32_e32 v90, v183, v81
	v_sub_f32_e32 v97, v96, v81
	v_sub_f32_e32 v96, v240, v81
	v_sub_f32_e32 v101, v242, v81
	v_sub_f32_e32 v100, v241, v81
	v_sub_f32_e32 v241, v244, v81
	v_sub_f32_e32 v240, v243, v81
	v_sub_f32_e32 v243, v246, v81
	v_sub_f32_e32 v242, v245, v81
	v_sub_f32_e32 v245, v248, v81
	v_sub_f32_e32 v244, v247, v81
	v_sub_f32_e32 v247, v250, v81
	v_sub_f32_e32 v246, v249, v81
	v_pk_mul_f32 v[90:91], v[80:81], v[90:91] op_sel_hi:[0,1]
	v_pk_mul_f32 v[88:89], v[80:81], v[88:89] op_sel_hi:[0,1]
	v_pk_mul_f32 v[100:101], v[80:81], v[100:101] op_sel_hi:[0,1]
	v_pk_mul_f32 v[96:97], v[80:81], v[96:97] op_sel_hi:[0,1]
	v_pk_mul_f32 v[242:243], v[80:81], v[242:243] op_sel_hi:[0,1]
	v_pk_mul_f32 v[240:241], v[80:81], v[240:241] op_sel_hi:[0,1]
	v_pk_mul_f32 v[246:247], v[80:81], v[246:247] op_sel_hi:[0,1]
	v_pk_mul_f32 v[244:245], v[80:81], v[244:245] op_sel_hi:[0,1]
	s_waitcnt vmcnt(14)
	v_pk_fma_f32 v[0:1], v[88:89], v[4:5], v[0:1]
	v_pk_fma_f32 v[2:3], v[90:91], v[6:7], v[2:3]
	s_waitcnt vmcnt(12)
	v_pk_fma_f32 v[4:5], v[96:97], v[184:185], v[188:189]
	v_pk_fma_f32 v[6:7], v[100:101], v[186:187], v[190:191]
	s_waitcnt vmcnt(10)
	v_pk_fma_f32 v[88:89], v[240:241], v[196:197], v[192:193]
	v_pk_fma_f32 v[90:91], v[242:243], v[198:199], v[194:195]
	s_waitcnt vmcnt(8)
	v_pk_fma_f32 v[96:97], v[244:245], v[200:201], v[204:205]
	v_pk_fma_f32 v[100:101], v[246:247], v[202:203], v[206:207]
	v_pk_mul_f32 v[2:3], v[2:3], s[22:23] op_sel_hi:[1,0]
	v_pk_mul_f32 v[0:1], v[0:1], s[22:23] op_sel_hi:[1,0]
	v_pk_mul_f32 v[6:7], v[6:7], s[22:23] op_sel_hi:[1,0]
	v_pk_mul_f32 v[4:5], v[4:5], s[22:23] op_sel_hi:[1,0]
	v_pk_mul_f32 v[90:91], v[90:91], s[22:23] op_sel_hi:[1,0]
	v_pk_mul_f32 v[88:89], v[88:89], s[22:23] op_sel_hi:[1,0]
	v_pk_mul_f32 v[100:101], v[100:101], s[22:23] op_sel_hi:[1,0]
	v_pk_mul_f32 v[96:97], v[96:97], s[22:23] op_sel_hi:[1,0]
	v_pk_fma_f32 v[118:119], v[162:163], v[118:119], v[0:1] op_sel_hi:[0,1,1]
	v_pk_fma_f32 v[0:1], v[162:163], v[120:121], v[2:3] op_sel_hi:[0,1,1]
	v_pk_fma_f32 v[120:121], v[162:163], v[122:123], v[4:5] op_sel_hi:[0,1,1]
	v_pk_fma_f32 v[4:5], v[162:163], v[124:125], v[6:7] op_sel_hi:[0,1,1]
	v_pk_fma_f32 v[122:123], v[162:163], v[126:127], v[88:89] op_sel_hi:[0,1,1]
	v_pk_fma_f32 v[88:89], v[162:163], v[128:129], v[90:91] op_sel_hi:[0,1,1]
	v_pk_fma_f32 v[114:115], v[162:163], v[114:115], v[96:97] op_sel_hi:[0,1,1]
	v_pk_fma_f32 v[96:97], v[162:163], v[116:117], v[100:101] op_sel_hi:[0,1,1]
	v_pk_fma_f32 v[0:1], v[112:113], v[134:135], v[0:1] op_sel_hi:[0,1,1]
	v_pk_fma_f32 v[2:3], v[112:113], v[130:131], v[118:119] op_sel_hi:[0,1,1]
	v_pk_fma_f32 v[4:5], v[112:113], v[142:143], v[4:5] op_sel_hi:[0,1,1]
	v_pk_fma_f32 v[6:7], v[112:113], v[138:139], v[120:121] op_sel_hi:[0,1,1]
	v_pk_fma_f32 v[88:89], v[112:113], v[154:155], v[88:89] op_sel_hi:[0,1,1]
	v_pk_fma_f32 v[90:91], v[112:113], v[148:149], v[122:123] op_sel_hi:[0,1,1]
	v_pk_fma_f32 v[96:97], v[112:113], v[160:161], v[96:97] op_sel_hi:[0,1,1]
	v_pk_fma_f32 v[100:101], v[112:113], v[158:159], v[114:115] op_sel_hi:[0,1,1]
	v_lshlrev_b32_e32 v113, 16, v86
	v_and_b32_e32 v86, 0xffff0000, v86
	v_lshlrev_b32_e32 v114, 16, v87
	v_and_b32_e32 v115, 0xffff0000, v87
	v_sub_f32_e32 v87, v86, v81
	v_sub_f32_e32 v86, v113, v81
	v_sub_f32_e32 v115, v115, v81
	v_sub_f32_e32 v114, v114, v81
	v_pk_mul_f32 v[114:115], v[80:81], v[114:115] op_sel_hi:[0,1]
	v_pk_mul_f32 v[86:87], v[80:81], v[86:87] op_sel_hi:[0,1]
	s_waitcnt vmcnt(6)
	v_pk_fma_f32 v[86:87], v[86:87], v[208:209], v[212:213]
	v_pk_fma_f32 v[114:115], v[114:115], v[210:211], v[214:215]
	v_pk_mul_f32 v[86:87], v[86:87], s[22:23] op_sel_hi:[1,0]
	v_pk_mul_f32 v[114:115], v[114:115], s[22:23] op_sel_hi:[1,0]
	v_pk_fma_f32 v[106:107], v[162:163], v[106:107], v[86:87] op_sel_hi:[0,1,1]
	v_pk_fma_f32 v[86:87], v[162:163], v[110:111], v[114:115] op_sel_hi:[0,1,1]
	v_pk_fma_f32 v[86:87], v[112:113], v[156:157], v[86:87] op_sel_hi:[0,1,1]
	v_pk_fma_f32 v[106:107], v[112:113], v[152:153], v[106:107] op_sel_hi:[0,1,1]
	v_lshlrev_b32_e32 v110, 16, v84
	v_and_b32_e32 v84, 0xffff0000, v84
	v_lshlrev_b32_e32 v113, 16, v85
	v_and_b32_e32 v111, 0xffff0000, v85
	v_sub_f32_e32 v85, v84, v81
	v_sub_f32_e32 v84, v110, v81
	v_sub_f32_e32 v111, v111, v81
	v_sub_f32_e32 v110, v113, v81
	v_pk_mul_f32 v[110:111], v[80:81], v[110:111] op_sel_hi:[0,1]
	v_pk_mul_f32 v[84:85], v[80:81], v[84:85] op_sel_hi:[0,1]
	s_waitcnt vmcnt(4)
; __device__ __forceinline__ void ln_norm2(f32x4 (&v)[8], const float* g, const float* b, int lane, float& mean_o, float& rstd_o) {
;     float s = 0.f;
; #pragma unroll
;     for (int j = 0; j < 8; ++j) s += (v[j][0] + v[j][1]) + (v[j][2] + v[j][3]);
;     const float mean = wave_sum(s) * (1.f / DM); float s2 = 0.f;
; #pragma unroll
;     for (int j = 0; j < 8; ++j) { v[j] = v[j] - mean; s2 += (v[j][0] * v[j][0] + v[j][1] * v[j][1]) + (v[j][2] * v[j][2] + v[j][3] * v[j][3]); }
	v_pk_fma_f32 v[84:85], v[84:85], v[216:217], v[220:221]
	v_pk_fma_f32 v[110:111], v[110:111], v[218:219], v[222:223]
	v_pk_mul_f32 v[84:85], v[84:85], s[22:23] op_sel_hi:[1,0]
	v_pk_mul_f32 v[110:111], v[110:111], s[22:23] op_sel_hi:[1,0]
	v_pk_fma_f32 v[104:105], v[162:163], v[104:105], v[84:85] op_sel_hi:[0,1,1]
	v_pk_fma_f32 v[84:85], v[162:163], v[108:109], v[110:111] op_sel_hi:[0,1,1]
	v_lshlrev_b32_e32 v108, 16, v82
	v_and_b32_e32 v82, 0xffff0000, v82
	v_lshlrev_b32_e32 v110, 16, v83
	v_and_b32_e32 v109, 0xffff0000, v83
	v_sub_f32_e32 v83, v82, v81
	v_sub_f32_e32 v82, v108, v81
	v_sub_f32_e32 v109, v109, v81
	v_sub_f32_e32 v108, v110, v81
	v_pk_mul_f32 v[108:109], v[80:81], v[108:109] op_sel_hi:[0,1]
	v_pk_mul_f32 v[82:83], v[80:81], v[82:83] op_sel_hi:[0,1]
	s_waitcnt vmcnt(2)
	v_pk_fma_f32 v[82:83], v[82:83], v[224:225], v[228:229]
	v_pk_fma_f32 v[108:109], v[108:109], v[226:227], v[230:231]
	v_pk_mul_f32 v[82:83], v[82:83], s[22:23] op_sel_hi:[1,0]
	v_pk_mul_f32 v[108:109], v[108:109], s[22:23] op_sel_hi:[1,0]
	v_pk_fma_f32 v[98:99], v[162:163], v[98:99], v[82:83] op_sel_hi:[0,1,1]
	v_pk_fma_f32 v[82:83], v[162:163], v[102:103], v[108:109] op_sel_hi:[0,1,1]
	v_lshlrev_b32_e32 v102, 16, v78
	v_and_b32_e32 v78, 0xffff0000, v78
	v_lshlrev_b32_e32 v108, 16, v79
	v_and_b32_e32 v103, 0xffff0000, v79
	v_sub_f32_e32 v79, v78, v81
	v_sub_f32_e32 v78, v102, v81
	v_sub_f32_e32 v103, v103, v81
	v_sub_f32_e32 v102, v108, v81
	v_pk_mul_f32 v[78:79], v[80:81], v[78:79] op_sel_hi:[0,1]
	v_pk_mul_f32 v[102:103], v[80:81], v[102:103] op_sel_hi:[0,1]
	s_waitcnt vmcnt(0)
	v_pk_fma_f32 v[78:79], v[78:79], v[232:233], v[236:237]
	v_pk_fma_f32 v[80:81], v[102:103], v[234:235], v[238:239]
	v_pk_mul_f32 v[78:79], v[78:79], s[22:23] op_sel_hi:[1,0]
	v_pk_mul_f32 v[80:81], v[80:81], s[22:23] op_sel_hi:[1,0]
	v_pk_fma_f32 v[94:95], v[162:163], v[94:95], v[78:79] op_sel_hi:[0,1,1]
	v_pk_fma_f32 v[78:79], v[162:163], v[92:93], v[80:81] op_sel_hi:[0,1,1]
	v_pk_fma_f32 v[80:81], v[112:113], v[132:133], v[94:95] op_sel_hi:[0,1,1]
	v_mov_b32_e32 v92, v2
	v_mov_b32_e32 v93, v6
	v_mov_b32_e32 v94, v3
	v_mov_b32_e32 v95, v7
	v_pk_add_f32 v[92:93], v[92:93], v[94:95]
	v_mov_b32_e32 v94, v0
	v_mov_b32_e32 v95, v4
	v_mov_b32_e32 v102, v1
	v_mov_b32_e32 v103, v5
	v_pk_add_f32 v[94:95], v[94:95], v[102:103]
	v_mov_b32_e32 v102, v90
	v_pk_add_f32 v[92:93], v[92:93], v[94:95]
	v_pk_mov_b32 v[94:95], v[90:91], v[88:89] op_sel:[1,0]
	v_mov_b32_e32 v103, v89
	v_pk_add_f32 v[94:95], v[94:95], v[102:103]
	v_add_f32_e32 v92, 0, v92
	v_pk_add_f32 v[94:95], v[94:95], v[94:95] op_sel:[0,1] op_sel_hi:[1,0]
	v_add_f32_e32 v92, v92, v93
	v_add_f32_e32 v102, v100, v101
	v_add_f32_e32 v108, v96, v97
	v_mov_b32_e32 v93, v106
	v_mov_b32_e32 v95, v107
	v_mov_b32_e32 v103, v86
	v_mov_b32_e32 v109, v87
	v_pk_fma_f32 v[84:85], v[112:113], v[150:151], v[84:85] op_sel_hi:[0,1,1]
	v_pk_fma_f32 v[104:105], v[112:113], v[146:147], v[104:105] op_sel_hi:[0,1,1]
	v_pk_add_f32 v[92:93], v[92:93], v[94:95]
	v_pk_add_f32 v[94:95], v[102:103], v[108:109]
	v_mov_b32_e32 v102, v104
	v_pk_add_f32 v[92:93], v[92:93], v[94:95]
	v_pk_mov_b32 v[94:95], v[104:105], v[84:85] op_sel:[1,0]
	v_mov_b32_e32 v103, v85
	v_pk_add_f32 v[94:95], v[94:95], v[102:103]
	v_pk_fma_f32 v[82:83], v[112:113], v[144:145], v[82:83] op_sel_hi:[0,1,1]
	v_pk_fma_f32 v[98:99], v[112:113], v[140:141], v[98:99] op_sel_hi:[0,1,1]
	v_pk_fma_f32 v[78:79], v[112:113], v[136:137], v[78:79] op_sel_hi:[0,1,1]
	v_pk_add_f32 v[92:93], v[92:93], v[92:93] op_sel:[0,1] op_sel_hi:[1,0]
	v_pk_add_f32 v[94:95], v[94:95], v[94:95] op_sel:[0,1] op_sel_hi:[1,0]
	v_add_f32_e32 v102, v98, v99
	v_add_f32_e32 v108, v82, v83
	v_mov_b32_e32 v93, v80
	v_mov_b32_e32 v95, v81
	v_mov_b32_e32 v103, v78
	v_mov_b32_e32 v109, v79
	v_pk_add_f32 v[92:93], v[92:93], v[94:95]
	v_pk_add_f32 v[94:95], v[102:103], v[108:109]
	s_nop 0
	v_pk_add_f32 v[92:93], v[92:93], v[94:95]
	v_xor_b32_e32 v94, 1, v164
	v_add_f32_e32 v92, v92, v93
	v_and_b32_e32 v93, 64, v164
	v_add_u32_e32 v93, 64, v93
	v_cmp_lt_i32_e32 vcc, v94, v93
	s_nop 1
	v_cndmask_b32_e32 v94, v164, v94, vcc
	v_lshlrev_b32_e32 v143, 2, v94
	s_nop 1
	v_mov_b32_dpp v94, v92 quad_perm:[1,0,3,2] row_mask:0xf bank_mask:0xf
	s_waitcnt lgkmcnt(0)
	v_add_f32_e32 v92, v92, v94
	v_xor_b32_e32 v94, 2, v164
	v_cmp_lt_i32_e32 vcc, v94, v93
	s_nop 1
	v_cndmask_b32_e32 v94, v164, v94, vcc
	v_lshlrev_b32_e32 v145, 2, v94
	s_nop 1
	v_mov_b32_dpp v94, v92 quad_perm:[2,3,0,1] row_mask:0xf bank_mask:0xf
	s_waitcnt lgkmcnt(0)
	v_add_f32_e32 v92, v92, v94
	v_xor_b32_e32 v94, 4, v164
	v_cmp_lt_i32_e32 vcc, v94, v93
	s_nop 1
	v_cndmask_b32_e32 v94, v164, v94, vcc
	v_lshlrev_b32_e32 v146, 2, v94
	s_nop 1
	v_mov_b32_dpp v94, v92 row_half_mirror row_mask:0xf bank_mask:0xf
	s_waitcnt lgkmcnt(0)
	v_add_f32_e32 v92, v92, v94
	v_xor_b32_e32 v94, 8, v164
	v_cmp_lt_i32_e32 vcc, v94, v93
	s_nop 1
	v_cndmask_b32_e32 v94, v164, v94, vcc
	v_lshlrev_b32_e32 v147, 2, v94
	s_nop 1
	v_mov_b32_dpp v94, v92 row_mirror row_mask:0xf bank_mask:0xf
	s_waitcnt lgkmcnt(0)
	v_add_f32_e32 v92, v92, v94
	v_xor_b32_e32 v94, 16, v164
	v_cmp_lt_i32_e32 vcc, v94, v93
	s_nop 1
	v_cndmask_b32_e32 v94, v164, v94, vcc
	v_lshlrev_b32_e32 v148, 2, v94
	v_mov_b32_e32 v94, v92
	s_nop 1
	v_permlane16_swap_b32_e32 v92, v94
	s_waitcnt lgkmcnt(0)
	v_add_f32_e32 v92, v92, v94
	v_xor_b32_e32 v94, 32, v164
	v_cmp_lt_i32_e32 vcc, v94, v93
	s_nop 1
	v_cndmask_b32_e32 v93, v164, v94, vcc
	v_lshlrev_b32_e32 v149, 2, v93
	v_mov_b32_e32 v93, v92
	s_nop 1
	v_permlane32_swap_b32_e32 v92, v93
	s_andn2_b64 vcc, exec, s[16:17]
	s_waitcnt lgkmcnt(0)
; __device__ __forceinline__ void ln_norm2(f32x4 (&v)[8], const float* g, const float* b, int lane, float& mean_o, float& rstd_o) {
;     float s = 0.f;
; #pragma unroll
;     for (int j = 0; j < 8; ++j) s += (v[j][0] + v[j][1]) + (v[j][2] + v[j][3]);
;     const float mean = wave_sum(s) * (1.f / DM); float s2 = 0.f;
; #pragma unroll
;     for (int j = 0; j < 8; ++j) { v[j] = v[j] - mean; s2 += (v[j][0] * v[j][0] + v[j][1] * v[j][1]) + (v[j][2] * v[j][2] + v[j][3] * v[j][3]); }
;     const float rstd = 1.f / sqrtf(wave_sum(s2) * (1.f / DM) + LN_EPS);
; #pragma unroll
;     for (int j = 0; j < 8; ++j) { const f32x4 gv = *((const f32x4*)g + lane + 64 * j), bv = *((const f32x4*)b + lane + 64 * j); v[j] = v[j] * rstd * gv + bv; }
;     mean_o = mean; rstd_o = rstd;
; }
; __device__ __forceinline__ void ln_norm(f32x4 (&v)[8], const float* g, const float* b, int lane) { float m_, r_; ln_norm2(v, g, b, lane, m_, r_); }
;     if (hf) { f32x4* o = (f32x4*)(hf + m * DM) + lane;
; #pragma unroll
;         for (int j = 0; j < 8; ++j) __builtin_nontemporal_store(v[j], o + 64 * j); }
	v_add_f32_e32 v92, v92, v93
	v_fmamk_f32 v1, v92, 0xba000000, v1
	v_fmamk_f32 v3, v92, 0xba000000, v3
	v_fmac_f32_e32 v0, 0xba000000, v92
	v_fmac_f32_e32 v2, 0xba000000, v92
	v_mul_f32_e32 v93, v3, v3
	v_mul_f32_e32 v94, v1, v1
	v_fmac_f32_e32 v93, v2, v2
	v_fmac_f32_e32 v94, v0, v0
	v_fmamk_f32 v5, v92, 0xba000000, v5
	v_fmamk_f32 v7, v92, 0xba000000, v7
	v_add_f32_e32 v93, v93, v94
	v_fmac_f32_e32 v4, 0xba000000, v92
	v_fmac_f32_e32 v6, 0xba000000, v92
	v_mul_f32_e32 v94, v7, v7
	v_mul_f32_e32 v95, v5, v5
	v_fmac_f32_e32 v94, v6, v6
	v_fmac_f32_e32 v95, v4, v4
	v_add_f32_e32 v94, v94, v95
	v_fmamk_f32 v89, v92, 0xba000000, v89
	v_fmamk_f32 v91, v92, 0xba000000, v91
	v_add_f32_e32 v93, v93, v94
	v_fmac_f32_e32 v88, 0xba000000, v92
	v_fmac_f32_e32 v90, 0xba000000, v92
	v_mul_f32_e32 v94, v91, v91
	v_mul_f32_e32 v95, v89, v89
	v_fmac_f32_e32 v94, v90, v90
	v_fmac_f32_e32 v95, v88, v88
	v_add_f32_e32 v94, v94, v95
	v_fmamk_f32 v97, v92, 0xba000000, v97
	v_fmamk_f32 v101, v92, 0xba000000, v101
	v_add_f32_e32 v93, v94, v93
	v_fmac_f32_e32 v96, 0xba000000, v92
	v_fmac_f32_e32 v100, 0xba000000, v92
	v_mul_f32_e32 v94, v101, v101
	v_mul_f32_e32 v95, v97, v97
	v_fmac_f32_e32 v94, v100, v100
	v_fmac_f32_e32 v95, v96, v96
	v_add_f32_e32 v94, v94, v95
	v_fmamk_f32 v87, v92, 0xba000000, v87
	v_fmamk_f32 v107, v92, 0xba000000, v107
	v_add_f32_e32 v93, v94, v93
	v_fmac_f32_e32 v86, 0xba000000, v92
	v_fmac_f32_e32 v106, 0xba000000, v92
	v_mul_f32_e32 v94, v107, v107
	v_mul_f32_e32 v95, v87, v87
	v_fmac_f32_e32 v94, v106, v106
	v_fmac_f32_e32 v95, v86, v86
	v_add_f32_e32 v94, v94, v95
	v_fmamk_f32 v85, v92, 0xba000000, v85
	v_fmamk_f32 v105, v92, 0xba000000, v105
	v_add_f32_e32 v93, v94, v93
	v_fmac_f32_e32 v84, 0xba000000, v92
	v_fmac_f32_e32 v104, 0xba000000, v92
	v_mul_f32_e32 v94, v105, v105
	v_mul_f32_e32 v95, v85, v85
	v_fmac_f32_e32 v94, v104, v104
	v_fmac_f32_e32 v95, v84, v84
	v_add_f32_e32 v94, v94, v95
	v_fmamk_f32 v83, v92, 0xba000000, v83
	v_fmamk_f32 v99, v92, 0xba000000, v99
	v_add_f32_e32 v93, v94, v93
	v_fmac_f32_e32 v82, 0xba000000, v92
	v_fmac_f32_e32 v98, 0xba000000, v92
	v_mul_f32_e32 v94, v99, v99
	v_mul_f32_e32 v95, v83, v83
	v_fmac_f32_e32 v94, v98, v98
	v_fmac_f32_e32 v95, v82, v82
	v_add_f32_e32 v94, v94, v95
	v_fmamk_f32 v79, v92, 0xba000000, v79
	v_fmamk_f32 v81, v92, 0xba000000, v81
	v_add_f32_e32 v93, v94, v93
	v_fmac_f32_e32 v78, 0xba000000, v92
	v_fmac_f32_e32 v80, 0xba000000, v92
	v_mul_f32_e32 v92, v81, v81
	v_mul_f32_e32 v94, v79, v79
	v_fmac_f32_e32 v92, v80, v80
	v_fmac_f32_e32 v94, v78, v78
	v_add_f32_e32 v92, v92, v94
	v_add_f32_e32 v92, v92, v93
	s_nop 1
	v_mov_b32_dpp v93, v92 quad_perm:[1,0,3,2] row_mask:0xf bank_mask:0xf
	s_waitcnt lgkmcnt(0)
	v_add_f32_e32 v92, v92, v93
	s_nop 1
	v_mov_b32_dpp v93, v92 quad_perm:[2,3,0,1] row_mask:0xf bank_mask:0xf
	s_waitcnt lgkmcnt(0)
	v_add_f32_e32 v92, v92, v93
	s_nop 1
	v_mov_b32_dpp v93, v92 row_half_mirror row_mask:0xf bank_mask:0xf
	s_waitcnt lgkmcnt(0)
	v_add_f32_e32 v92, v92, v93
	s_nop 1
	v_mov_b32_dpp v93, v92 row_mirror row_mask:0xf bank_mask:0xf
	s_waitcnt lgkmcnt(0)
	v_add_f32_e32 v92, v92, v93
	v_mov_b32_e32 v93, v92
	s_nop 1
	v_permlane16_swap_b32_e32 v92, v93
	s_waitcnt lgkmcnt(0)
	v_add_f32_e32 v92, v92, v93
	ds_bpermute_b32 v93, v149, v92
	s_cbranch_vccnz .LBB0_4902
	global_load_dwordx4 v[108:111], v[34:35], off
	global_load_dwordx4 v[112:115], v[38:39], off
	global_load_dwordx4 v[116:119], v[40:41], off
	global_load_dwordx4 v[120:123], v[42:43], off
	global_load_dwordx4 v[124:127], v[44:45], off
	global_load_dwordx4 v[128:131], v[46:47], off
	global_load_dwordx4 v[132:135], v[48:49], off
	global_load_dwordx4 v[136:139], v[50:51], off
	global_load_dwordx4 v[150:153], v[36:37], off offset:3072
	global_load_dwordx4 v[154:157], v[32:33], off offset:3072
	global_load_dwordx4 v[158:161], v[32:33], off offset:2048
	global_load_dwordx4 v[184:187], v[36:37], off offset:2048
	global_load_dwordx4 v[188:191], v[36:37], off offset:1024
	global_load_dwordx4 v[192:195], v[32:33], off offset:1024
	global_load_dwordx4 v[196:199], v[32:33], off
	global_load_dwordx4 v[200:203], v[36:37], off
	s_waitcnt lgkmcnt(0)
	v_add_f32_e32 v92, v92, v93
	v_fmamk_f32 v92, v92, 0x3a000000, v165
	v_rsq_f32_e32 v251, v92
	s_nop 1
	s_nop 0
	s_nop 1
	v_lshlrev_b64 v[102:103], 13, v[8:9]
	v_lshl_add_u64 v[102:103], v[52:53], 0, v[102:103]
	s_nop 1
	v_mov_b32_e32 v92, v251
	v_pk_mul_f32 v[80:81], v[80:81], v[92:93] op_sel_hi:[1,0]
	v_pk_mul_f32 v[78:79], v[78:79], v[92:93] op_sel_hi:[1,0]
	v_pk_mul_f32 v[94:95], v[98:99], v[92:93] op_sel_hi:[1,0]
	v_pk_mul_f32 v[98:99], v[104:105], v[92:93] op_sel_hi:[1,0]
	v_pk_mul_f32 v[84:85], v[84:85], v[92:93] op_sel_hi:[1,0]
	v_pk_mul_f32 v[86:87], v[86:87], v[92:93] op_sel_hi:[1,0]
	v_pk_mul_f32 v[100:101], v[100:101], v[92:93] op_sel_hi:[1,0]
	v_pk_mul_f32 v[206:207], v[2:3], v[92:93] op_sel_hi:[1,0]
	v_pk_mul_f32 v[208:209], v[0:1], v[92:93] op_sel_hi:[1,0]
	v_pk_mul_f32 v[104:105], v[106:107], v[92:93] op_sel_hi:[1,0]
	v_pk_mul_f32 v[96:97], v[96:97], v[92:93] op_sel_hi:[1,0]
	v_pk_mul_f32 v[90:91], v[90:91], v[92:93] op_sel_hi:[1,0]
	v_pk_mul_f32 v[106:107], v[88:89], v[92:93] op_sel_hi:[1,0]
	v_pk_mul_f32 v[140:141], v[6:7], v[92:93] op_sel_hi:[1,0]
	v_pk_mul_f32 v[204:205], v[4:5], v[92:93] op_sel_hi:[1,0]
	v_pk_mul_f32 v[82:83], v[82:83], v[92:93] op_sel_hi:[1,0]
	s_waitcnt vmcnt(14)
	v_pk_fma_f32 v[2:3], v[78:79], v[114:115], v[110:111]
	v_pk_fma_f32 v[0:1], v[80:81], v[112:113], v[108:109]
	s_waitcnt vmcnt(12)
	v_pk_fma_f32 v[4:5], v[94:95], v[120:121], v[116:117]
	v_pk_fma_f32 v[6:7], v[82:83], v[122:123], v[118:119]
	s_waitcnt vmcnt(10)
	v_pk_fma_f32 v[80:81], v[84:85], v[130:131], v[126:127]
	v_pk_fma_f32 v[78:79], v[98:99], v[128:129], v[124:125]
	s_waitcnt vmcnt(8)
	v_pk_fma_f32 v[84:85], v[86:87], v[138:139], v[134:135]
	v_pk_fma_f32 v[82:83], v[104:105], v[136:137], v[132:133]
	s_waitcnt vmcnt(6)
	v_pk_fma_f32 v[86:87], v[100:101], v[150:151], v[154:155]
	v_pk_fma_f32 v[88:89], v[96:97], v[152:153], v[156:157]
	s_waitcnt vmcnt(4)
	v_pk_fma_f32 v[92:93], v[106:107], v[186:187], v[160:161]
	v_pk_fma_f32 v[90:91], v[90:91], v[184:185], v[158:159]
	s_waitcnt vmcnt(2)
	v_pk_fma_f32 v[96:97], v[204:205], v[190:191], v[194:195]
	v_pk_fma_f32 v[94:95], v[140:141], v[188:189], v[192:193]
	s_waitcnt vmcnt(0)
	v_pk_fma_f32 v[100:101], v[208:209], v[202:203], v[198:199]
	v_pk_fma_f32 v[98:99], v[206:207], v[200:201], v[196:197]
	global_store_dwordx4 v[102:103], v[98:101], off nt
	global_store_dwordx4 v[102:103], v[94:97], off offset:1024 nt
	global_store_dwordx4 v[102:103], v[90:93], off offset:2048 nt
	global_store_dwordx4 v[102:103], v[86:89], off offset:3072 nt
	s_nop 1
	v_add_co_u32_e32 v86, vcc, 0x1000, v102
	s_nop 1
	v_addc_co_u32_e32 v87, vcc, 0, v103, vcc
	global_store_dwordx4 v[86:87], v[82:85], off nt
	global_store_dwordx4 v[86:87], v[78:81], off offset:1024 nt
	global_store_dwordx4 v[86:87], v[4:7], off offset:2048 nt
	global_store_dwordx4 v[86:87], v[0:3], off offset:3072 nt

; __device__ __forceinline__ f32x4 f84(const unsigned w) { return (f32x4){(float)(w & 0xffu), (float)((w >> 8) & 0xffu), (float)((w >> 16) & 0xffu), (float)(w >> 24)}; }
; __device__ __forceinline__ void ln4_fin_y(f32x4 (&y)[8], const unsigned (&r)[8], const unsigned char* YP, int p, int main_rows, int sk, size_t pstride, int lane) {
; #pragma unroll
;     for (int j = 0; j < 8; ++j) y[j] = f84(r[j]) - 128.f;
;     if (p >= main_rows) for (int k = 1; k < sk; ++k) { const unsigned* s = (const unsigned*)(YP + (size_t)k * pstride + (size_t)(p - main_rows) * DM) + lane;
; #pragma unroll
;         for (int j = 0; j < 8; ++j) y[j] = y[j] + (f84(s[64 * j]) - 128.f); }
.LBB0_4908:
	global_load_dwordx4 v[0:3], v[14:15], off
	global_load_dwordx4 v[4:7], v[12:13], off
	global_load_dwordx4 v[150:153], v[12:13], off offset:1024
	global_load_dwordx4 v[154:157], v[14:15], off offset:1024
	global_load_dwordx4 v[158:161], v[14:15], off offset:2048
	global_load_dwordx4 v[168:171], v[12:13], off offset:2048
	global_load_dwordx4 v[172:175], v[12:13], off offset:3072
	global_load_dwordx4 v[176:179], v[14:15], off offset:3072
	global_load_dwordx4 v[180:183], v[16:17], off
	global_load_dwordx4 v[184:187], v[18:19], off
	global_load_dwordx4 v[188:191], v[20:21], off
	global_load_dwordx4 v[192:195], v[22:23], off
	global_load_dwordx4 v[196:199], v[24:25], off
	global_load_dwordx4 v[200:203], v[26:27], off
	global_load_dwordx4 v[204:207], v[28:29], off
	global_load_dwordx4 v[208:211], v[30:31], off
	v_lshlrev_b32_e32 v9, 16, v74
	v_and_b32_e32 v74, 0xffff0000, v74
	v_mul_f32_e32 v144, 0x3b23d70a, v76
	v_mul_f32_e32 v142, 0x3b23d70a, v77
	v_lshlrev_b32_e32 v76, 16, v75
	v_and_b32_e32 v75, 0xffff0000, v75
	v_lshlrev_b32_e32 v77, 16, v72
	v_and_b32_e32 v72, 0xffff0000, v72
	v_lshlrev_b32_e32 v212, 16, v70
	v_and_b32_e32 v213, 0xffff0000, v70
	v_lshlrev_b32_e32 v214, 16, v71
	v_and_b32_e32 v215, 0xffff0000, v71
	v_lshlrev_b32_e32 v216, 16, v68
	v_and_b32_e32 v217, 0xffff0000, v68
	v_lshlrev_b32_e32 v218, 16, v69
	v_and_b32_e32 v219, 0xffff0000, v69
	v_sub_f32_e32 v69, v74, v58
	v_sub_f32_e32 v68, v9, v58
	v_lshlrev_b32_e32 v162, 16, v73
	v_and_b32_e32 v167, 0xffff0000, v73
	v_sub_f32_e32 v71, v75, v58
	v_sub_f32_e32 v70, v76, v58
	v_sub_f32_e32 v73, v72, v58
	v_sub_f32_e32 v72, v77, v58
	v_sub_f32_e32 v77, v213, v58
	v_sub_f32_e32 v76, v212, v58
	v_sub_f32_e32 v213, v215, v58
	v_sub_f32_e32 v212, v214, v58
	v_sub_f32_e32 v215, v217, v58
	v_sub_f32_e32 v214, v216, v58
	v_pk_mul_f32 v[68:69], v[58:59], v[68:69] op_sel:[1,0]
	v_sub_f32_e32 v75, v167, v58
	v_sub_f32_e32 v74, v162, v58
	v_sub_f32_e32 v217, v219, v58
	v_sub_f32_e32 v216, v218, v58
	v_pk_mul_f32 v[70:71], v[58:59], v[70:71] op_sel:[1,0]
	v_pk_mul_f32 v[72:73], v[58:59], v[72:73] op_sel:[1,0]
	v_pk_mul_f32 v[214:215], v[58:59], v[214:215] op_sel:[1,0]
	v_pk_mul_f32 v[74:75], v[58:59], v[74:75] op_sel:[1,0]
	v_pk_mul_f32 v[76:77], v[58:59], v[76:77] op_sel:[1,0]
	v_pk_mul_f32 v[216:217], v[58:59], v[216:217] op_sel:[1,0]
	v_lshlrev_b32_e32 v9, 16, v66
	v_and_b32_e32 v66, 0xffff0000, v66
	v_pk_mul_f32 v[212:213], v[58:59], v[212:213] op_sel:[1,0]
	s_nor_b64 s[0:1], s[0:1], s[14:15]
	s_waitcnt vmcnt(14)
	v_pk_fma_f32 v[0:1], v[68:69], v[4:5], v[0:1]
	v_pk_fma_f32 v[2:3], v[70:71], v[6:7], v[2:3]
	s_waitcnt vmcnt(12)
	v_pk_fma_f32 v[4:5], v[72:73], v[150:151], v[154:155]
	v_pk_mul_f32 v[0:1], v[0:1], s[22:23] op_sel_hi:[1,0]
	v_pk_fma_f32 v[6:7], v[74:75], v[152:153], v[156:157]
	s_waitcnt vmcnt(10)
	v_pk_fma_f32 v[68:69], v[76:77], v[168:169], v[158:159]
	s_waitcnt vmcnt(8)
	v_pk_fma_f32 v[72:73], v[214:215], v[172:173], v[176:177]
	v_pk_fma_f32 v[74:75], v[216:217], v[174:175], v[178:179]
	v_pk_mul_f32 v[2:3], v[2:3], s[22:23] op_sel_hi:[1,0]
	v_pk_fma_f32 v[76:77], v[144:145], v[78:79], v[0:1] op_sel_hi:[0,1,1]
	v_pk_mul_f32 v[72:73], v[72:73], s[22:23] op_sel_hi:[1,0]
	v_pk_fma_f32 v[0:1], v[144:145], v[84:85], v[2:3] op_sel_hi:[0,1,1]
	v_pk_fma_f32 v[2:3], v[142:143], v[110:111], v[76:77] op_sel_hi:[0,1,1]
	v_pk_mul_f32 v[74:75], v[74:75], s[22:23] op_sel_hi:[1,0]
	v_pk_fma_f32 v[76:77], v[144:145], v[106:107], v[72:73] op_sel_hi:[0,1,1]
	v_pk_fma_f32 v[72:73], v[144:145], v[108:109], v[74:75] op_sel_hi:[0,1,1]
	v_pk_fma_f32 v[74:75], v[142:143], v[138:139], v[76:77] op_sel_hi:[0,1,1]
	v_lshlrev_b32_e32 v76, 16, v67
	v_and_b32_e32 v77, 0xffff0000, v67
	v_sub_f32_e32 v67, v66, v58
	v_sub_f32_e32 v66, v9, v58
	v_sub_f32_e32 v77, v77, v58
	v_sub_f32_e32 v76, v76, v58
	v_pk_mul_f32 v[66:67], v[58:59], v[66:67] op_sel:[1,0]
	v_pk_mul_f32 v[4:5], v[4:5], s[22:23] op_sel_hi:[1,0]
	v_pk_mul_f32 v[76:77], v[58:59], v[76:77] op_sel:[1,0]
	s_waitcnt vmcnt(6)
	v_pk_fma_f32 v[66:67], v[66:67], v[180:181], v[184:185]
	v_pk_mul_f32 v[6:7], v[6:7], s[22:23] op_sel_hi:[1,0]
	v_pk_fma_f32 v[78:79], v[144:145], v[88:89], v[4:5] op_sel_hi:[0,1,1]
	v_pk_fma_f32 v[76:77], v[76:77], v[182:183], v[186:187]
	v_pk_mul_f32 v[66:67], v[66:67], s[22:23] op_sel_hi:[1,0]
	v_pk_fma_f32 v[4:5], v[144:145], v[92:93], v[6:7] op_sel_hi:[0,1,1]
	v_pk_fma_f32 v[6:7], v[142:143], v[118:119], v[78:79] op_sel_hi:[0,1,1]
	v_pk_mul_f32 v[76:77], v[76:77], s[22:23] op_sel_hi:[1,0]
	v_pk_fma_f32 v[78:79], v[144:145], v[98:99], v[66:67] op_sel_hi:[0,1,1]
	v_lshlrev_b32_e32 v9, 16, v64
	v_and_b32_e32 v64, 0xffff0000, v64
	v_pk_fma_f32 v[66:67], v[144:145], v[100:101], v[76:77] op_sel_hi:[0,1,1]
	v_pk_fma_f32 v[76:77], v[142:143], v[132:133], v[78:79] op_sel_hi:[0,1,1]
	v_lshlrev_b32_e32 v78, 16, v65
	v_and_b32_e32 v79, 0xffff0000, v65
	v_sub_f32_e32 v65, v64, v58
	v_sub_f32_e32 v64, v9, v58
	v_sub_f32_e32 v79, v79, v58
	v_sub_f32_e32 v78, v78, v58
	v_pk_mul_f32 v[64:65], v[58:59], v[64:65] op_sel:[1,0]
	v_pk_fma_f32 v[70:71], v[212:213], v[170:171], v[160:161]
	v_pk_mul_f32 v[68:69], v[68:69], s[22:23] op_sel_hi:[1,0]
	v_pk_mul_f32 v[78:79], v[58:59], v[78:79] op_sel:[1,0]
	s_waitcnt vmcnt(4)
; __device__ __forceinline__ void ln_norm2(f32x4 (&v)[8], const float* g, const float* b, int lane, float& mean_o, float& rstd_o) {
;     float s = 0.f;
; #pragma unroll
;     for (int j = 0; j < 8; ++j) s += (v[j][0] + v[j][1]) + (v[j][2] + v[j][3]);
;     const float mean = wave_sum(s) * (1.f / DM); float s2 = 0.f;
	v_pk_fma_f32 v[64:65], v[64:65], v[188:189], v[192:193]
	v_pk_mul_f32 v[70:71], v[70:71], s[22:23] op_sel_hi:[1,0]
	v_pk_fma_f32 v[84:85], v[144:145], v[102:103], v[68:69] op_sel_hi:[0,1,1]
	v_pk_fma_f32 v[78:79], v[78:79], v[190:191], v[194:195]
	v_pk_mul_f32 v[64:65], v[64:65], s[22:23] op_sel_hi:[1,0]
	v_pk_fma_f32 v[68:69], v[144:145], v[104:105], v[70:71] op_sel_hi:[0,1,1]
	v_pk_fma_f32 v[70:71], v[142:143], v[128:129], v[84:85] op_sel_hi:[0,1,1]
	v_pk_mul_f32 v[78:79], v[78:79], s[22:23] op_sel_hi:[1,0]
	v_pk_fma_f32 v[84:85], v[144:145], v[94:95], v[64:65] op_sel_hi:[0,1,1]
	v_lshlrev_b32_e32 v9, 16, v62
	v_and_b32_e32 v62, 0xffff0000, v62
	v_pk_fma_f32 v[64:65], v[144:145], v[96:97], v[78:79] op_sel_hi:[0,1,1]
	v_pk_fma_f32 v[78:79], v[142:143], v[126:127], v[84:85] op_sel_hi:[0,1,1]
	v_lshlrev_b32_e32 v84, 16, v63
	v_and_b32_e32 v85, 0xffff0000, v63
	v_sub_f32_e32 v63, v62, v58
	v_sub_f32_e32 v62, v9, v58
	v_sub_f32_e32 v85, v85, v58
	v_sub_f32_e32 v84, v84, v58
	v_pk_mul_f32 v[62:63], v[58:59], v[62:63] op_sel:[1,0]
	v_pk_mul_f32 v[84:85], v[58:59], v[84:85] op_sel:[1,0]
	s_waitcnt vmcnt(2)
	v_pk_fma_f32 v[62:63], v[62:63], v[196:197], v[200:201]
	v_pk_fma_f32 v[84:85], v[84:85], v[198:199], v[202:203]
	v_pk_mul_f32 v[62:63], v[62:63], s[22:23] op_sel_hi:[1,0]
	v_pk_mul_f32 v[84:85], v[84:85], s[22:23] op_sel_hi:[1,0]
	v_pk_fma_f32 v[86:87], v[144:145], v[86:87], v[62:63] op_sel_hi:[0,1,1]
	v_pk_fma_f32 v[62:63], v[144:145], v[90:91], v[84:85] op_sel_hi:[0,1,1]
	v_pk_fma_f32 v[84:85], v[142:143], v[120:121], v[86:87] op_sel_hi:[0,1,1]
	v_lshlrev_b32_e32 v9, 16, v60
	v_and_b32_e32 v60, 0xffff0000, v60
	v_lshlrev_b32_e32 v86, 16, v61
	v_and_b32_e32 v87, 0xffff0000, v61
	v_sub_f32_e32 v61, v60, v58
	v_sub_f32_e32 v60, v9, v58
	v_sub_f32_e32 v87, v87, v58
	v_sub_f32_e32 v86, v86, v58
	v_pk_mul_f32 v[86:87], v[58:59], v[86:87] op_sel:[1,0]
	v_pk_mul_f32 v[58:59], v[58:59], v[60:61] op_sel:[1,0]
	s_waitcnt vmcnt(0)
	v_pk_fma_f32 v[60:61], v[86:87], v[206:207], v[210:211]
	v_pk_fma_f32 v[58:59], v[58:59], v[204:205], v[208:209]
	v_pk_mul_f32 v[60:61], v[60:61], s[22:23] op_sel_hi:[1,0]
	v_pk_mul_f32 v[58:59], v[58:59], s[22:23] op_sel_hi:[1,0]
	v_pk_fma_f32 v[0:1], v[142:143], v[114:115], v[0:1] op_sel_hi:[0,1,1]
	v_pk_fma_f32 v[82:83], v[144:145], v[82:83], v[58:59] op_sel_hi:[0,1,1]
	v_pk_fma_f32 v[4:5], v[142:143], v[122:123], v[4:5] op_sel_hi:[0,1,1]
	v_pk_fma_f32 v[58:59], v[144:145], v[80:81], v[60:61] op_sel_hi:[0,1,1]
	v_pk_fma_f32 v[60:61], v[142:143], v[112:113], v[82:83] op_sel_hi:[0,1,1]
	v_mov_b32_e32 v80, v2
	v_mov_b32_e32 v81, v6
	v_mov_b32_e32 v82, v3
	v_mov_b32_e32 v83, v7
	v_pk_add_f32 v[80:81], v[80:81], v[82:83]
	v_mov_b32_e32 v82, v0
	v_mov_b32_e32 v83, v4
	v_mov_b32_e32 v86, v1
	v_mov_b32_e32 v87, v5
	v_pk_fma_f32 v[68:69], v[142:143], v[134:135], v[68:69] op_sel_hi:[0,1,1]
	v_pk_add_f32 v[82:83], v[82:83], v[86:87]
	v_mov_b32_e32 v86, v70
	v_pk_add_f32 v[80:81], v[80:81], v[82:83]
	v_pk_mov_b32 v[82:83], v[70:71], v[68:69] op_sel:[1,0]
	v_mov_b32_e32 v87, v69
	v_pk_add_f32 v[82:83], v[82:83], v[86:87]
	v_pk_fma_f32 v[72:73], v[142:143], v[140:141], v[72:73] op_sel_hi:[0,1,1]
	v_pk_fma_f32 v[66:67], v[142:143], v[136:137], v[66:67] op_sel_hi:[0,1,1]
	v_add_f32_e32 v9, 0, v80
	v_pk_add_f32 v[82:83], v[82:83], v[82:83] op_sel:[0,1] op_sel_hi:[1,0]
	v_add_f32_e32 v80, v9, v81
	v_add_f32_e32 v86, v74, v75
	v_add_f32_e32 v88, v72, v73
	v_mov_b32_e32 v81, v76
	v_mov_b32_e32 v83, v77
	v_mov_b32_e32 v87, v66
	v_mov_b32_e32 v89, v67
	v_pk_fma_f32 v[64:65], v[142:143], v[130:131], v[64:65] op_sel_hi:[0,1,1]
	v_pk_add_f32 v[80:81], v[80:81], v[82:83]
	v_pk_add_f32 v[82:83], v[86:87], v[88:89]
	v_mov_b32_e32 v86, v78
	v_pk_add_f32 v[80:81], v[80:81], v[82:83]
	v_pk_mov_b32 v[82:83], v[78:79], v[64:65] op_sel:[1,0]
	v_mov_b32_e32 v87, v65
	v_pk_add_f32 v[82:83], v[82:83], v[86:87]
	v_pk_fma_f32 v[62:63], v[142:143], v[124:125], v[62:63] op_sel_hi:[0,1,1]
	v_pk_fma_f32 v[58:59], v[142:143], v[116:117], v[58:59] op_sel_hi:[0,1,1]
	v_pk_add_f32 v[80:81], v[80:81], v[80:81] op_sel:[0,1] op_sel_hi:[1,0]
	v_pk_add_f32 v[82:83], v[82:83], v[82:83] op_sel:[0,1] op_sel_hi:[1,0]
	v_add_f32_e32 v86, v84, v85
	v_add_f32_e32 v88, v62, v63
	v_mov_b32_e32 v81, v60
	v_mov_b32_e32 v83, v61
	v_mov_b32_e32 v87, v58
	v_mov_b32_e32 v89, v59
	v_pk_add_f32 v[80:81], v[80:81], v[82:83]
	v_pk_add_f32 v[82:83], v[86:87], v[88:89]
	s_nop 0
	v_pk_add_f32 v[80:81], v[80:81], v[82:83]
	s_nop 0
	v_add_f32_e32 v9, v80, v81
	s_nop 1
	v_mov_b32_dpp v80, v9 quad_perm:[1,0,3,2] row_mask:0xf bank_mask:0xf
	s_waitcnt lgkmcnt(0)
	v_add_f32_e32 v9, v9, v80
	s_nop 1
	v_mov_b32_dpp v80, v9 quad_perm:[2,3,0,1] row_mask:0xf bank_mask:0xf
	s_waitcnt lgkmcnt(0)
	v_add_f32_e32 v9, v9, v80
	s_nop 1
	v_mov_b32_dpp v80, v9 row_half_mirror row_mask:0xf bank_mask:0xf
	s_waitcnt lgkmcnt(0)
	v_add_f32_e32 v9, v9, v80
	s_nop 1
	v_mov_b32_dpp v80, v9 row_mirror row_mask:0xf bank_mask:0xf
	s_waitcnt lgkmcnt(0)
	v_add_f32_e32 v9, v9, v80
	v_mov_b32_e32 v80, v9
	s_nop 1
	v_permlane16_swap_b32_e32 v9, v80
	s_waitcnt lgkmcnt(0)
	v_add_f32_e32 v9, v9, v80
	v_mov_b32_e32 v80, v9
	s_nop 1
	v_permlane32_swap_b32_e32 v9, v80
	s_waitcnt lgkmcnt(0)
; __device__ __forceinline__ void ln_norm2(f32x4 (&v)[8], const float* g, const float* b, int lane, float& mean_o, float& rstd_o) {
;     float s = 0.f;
; #pragma unroll
;     for (int j = 0; j < 8; ++j) s += (v[j][0] + v[j][1]) + (v[j][2] + v[j][3]);
;     const float mean = wave_sum(s) * (1.f / DM); float s2 = 0.f;
; #pragma unroll
;     for (int j = 0; j < 8; ++j) { v[j] = v[j] - mean; s2 += (v[j][0] * v[j][0] + v[j][1] * v[j][1]) + (v[j][2] * v[j][2] + v[j][3] * v[j][3]); }
;     const float rstd = 1.f / sqrtf(wave_sum(s2) * (1.f / DM) + LN_EPS);
; #pragma unroll
;     for (int j = 0; j < 8; ++j) { const f32x4 gv = *((const f32x4*)g + lane + 64 * j), bv = *((const f32x4*)b + lane + 64 * j); v[j] = v[j] * rstd * gv + bv; }
;     mean_o = mean; rstd_o = rstd;
; }
; __device__ __forceinline__ void ln_norm(f32x4 (&v)[8], const float* g, const float* b, int lane) { float m_, r_; ln_norm2(v, g, b, lane, m_, r_); }
;     if (hf) { f32x4* o = (f32x4*)(hf + m * DM) + lane;
; #pragma unroll
;         for (int j = 0; j < 8; ++j) __builtin_nontemporal_store(v[j], o + 64 * j); }
	v_add_f32_e32 v9, v9, v80
	v_fmamk_f32 v1, v9, 0xba000000, v1
	v_fmamk_f32 v3, v9, 0xba000000, v3
	v_fmac_f32_e32 v0, 0xba000000, v9
	v_fmac_f32_e32 v2, 0xba000000, v9
	v_mul_f32_e32 v80, v3, v3
	v_mul_f32_e32 v81, v1, v1
	v_fmac_f32_e32 v80, v2, v2
	v_fmac_f32_e32 v81, v0, v0
	v_fmamk_f32 v5, v9, 0xba000000, v5
	v_fmamk_f32 v7, v9, 0xba000000, v7
	v_add_f32_e32 v80, v80, v81
	v_fmac_f32_e32 v4, 0xba000000, v9
	v_fmac_f32_e32 v6, 0xba000000, v9
	v_mul_f32_e32 v81, v7, v7
	v_mul_f32_e32 v82, v5, v5
	v_fmac_f32_e32 v81, v6, v6
	v_fmac_f32_e32 v82, v4, v4
	v_add_f32_e32 v81, v81, v82
	v_fmamk_f32 v69, v9, 0xba000000, v69
	v_fmamk_f32 v71, v9, 0xba000000, v71
	v_add_f32_e32 v80, v80, v81
	v_fmac_f32_e32 v68, 0xba000000, v9
	v_fmac_f32_e32 v70, 0xba000000, v9
	v_mul_f32_e32 v81, v71, v71
	v_mul_f32_e32 v82, v69, v69
	v_fmac_f32_e32 v81, v70, v70
	v_fmac_f32_e32 v82, v68, v68
	v_add_f32_e32 v81, v81, v82
	v_fmamk_f32 v73, v9, 0xba000000, v73
	v_fmamk_f32 v75, v9, 0xba000000, v75
	v_add_f32_e32 v80, v81, v80
	v_fmac_f32_e32 v72, 0xba000000, v9
	v_fmac_f32_e32 v74, 0xba000000, v9
	v_mul_f32_e32 v81, v75, v75
	v_mul_f32_e32 v82, v73, v73
	v_fmac_f32_e32 v81, v74, v74
	v_fmac_f32_e32 v82, v72, v72
	v_add_f32_e32 v81, v81, v82
	v_fmamk_f32 v67, v9, 0xba000000, v67
	v_fmamk_f32 v77, v9, 0xba000000, v77
	v_add_f32_e32 v80, v81, v80
	v_fmac_f32_e32 v66, 0xba000000, v9
	v_fmac_f32_e32 v76, 0xba000000, v9
	v_mul_f32_e32 v81, v77, v77
	v_mul_f32_e32 v82, v67, v67
	v_fmac_f32_e32 v81, v76, v76
	v_fmac_f32_e32 v82, v66, v66
	v_add_f32_e32 v81, v81, v82
	v_fmamk_f32 v65, v9, 0xba000000, v65
	v_fmamk_f32 v79, v9, 0xba000000, v79
	v_add_f32_e32 v80, v81, v80
	v_fmac_f32_e32 v64, 0xba000000, v9
	v_fmac_f32_e32 v78, 0xba000000, v9
	v_mul_f32_e32 v81, v79, v79
	v_mul_f32_e32 v82, v65, v65
	v_fmac_f32_e32 v81, v78, v78
	v_fmac_f32_e32 v82, v64, v64
	v_add_f32_e32 v81, v81, v82
	v_fmamk_f32 v63, v9, 0xba000000, v63
	v_fmamk_f32 v85, v9, 0xba000000, v85
	v_add_f32_e32 v80, v81, v80
	v_fmac_f32_e32 v62, 0xba000000, v9
	v_fmac_f32_e32 v84, 0xba000000, v9
	v_mul_f32_e32 v81, v85, v85
	v_mul_f32_e32 v82, v63, v63
	v_fmac_f32_e32 v81, v84, v84
	v_fmac_f32_e32 v82, v62, v62
	v_add_f32_e32 v81, v81, v82
	v_fmamk_f32 v59, v9, 0xba000000, v59
	v_fmamk_f32 v61, v9, 0xba000000, v61
	v_add_f32_e32 v80, v81, v80
	v_fmac_f32_e32 v58, 0xba000000, v9
	v_fmac_f32_e32 v60, 0xba000000, v9
	v_mul_f32_e32 v9, v61, v61
	v_mul_f32_e32 v81, v59, v59
	v_fmac_f32_e32 v9, v60, v60
	v_fmac_f32_e32 v81, v58, v58
	v_add_f32_e32 v9, v9, v81
	v_add_f32_e32 v9, v9, v80
	s_nop 1
	v_mov_b32_dpp v80, v9 quad_perm:[1,0,3,2] row_mask:0xf bank_mask:0xf
	s_waitcnt lgkmcnt(0)
	v_add_f32_e32 v9, v9, v80
	s_nop 1
	v_mov_b32_dpp v80, v9 quad_perm:[2,3,0,1] row_mask:0xf bank_mask:0xf
	s_waitcnt lgkmcnt(0)
	v_add_f32_e32 v9, v9, v80
	s_nop 1
	v_mov_b32_dpp v80, v9 row_half_mirror row_mask:0xf bank_mask:0xf
	s_waitcnt lgkmcnt(0)
	v_add_f32_e32 v9, v9, v80
	s_nop 1
	v_mov_b32_dpp v80, v9 row_mirror row_mask:0xf bank_mask:0xf
	s_waitcnt lgkmcnt(0)
	v_add_f32_e32 v9, v9, v80
	v_mov_b32_e32 v80, v9
	s_nop 1
	v_permlane16_swap_b32_e32 v9, v80
	s_waitcnt lgkmcnt(0)
	v_add_f32_e32 v9, v9, v80
	v_mov_b32_e32 v80, v9
	s_nop 1
	v_permlane32_swap_b32_e32 v9, v80
	s_and_saveexec_b64 s[2:3], s[0:1]
	s_cbranch_execz .LBB0_4893
	global_load_dwordx4 v[86:89], v[34:35], off
	global_load_dwordx4 v[90:93], v[38:39], off
	global_load_dwordx4 v[94:97], v[40:41], off
	global_load_dwordx4 v[98:101], v[42:43], off
	global_load_dwordx4 v[102:105], v[44:45], off
	global_load_dwordx4 v[106:109], v[46:47], off
	global_load_dwordx4 v[110:113], v[48:49], off
	global_load_dwordx4 v[114:117], v[50:51], off
	global_load_dwordx4 v[118:121], v[36:37], off offset:3072
	global_load_dwordx4 v[122:125], v[32:33], off offset:3072
	global_load_dwordx4 v[126:129], v[32:33], off offset:2048
	global_load_dwordx4 v[130:133], v[36:37], off offset:2048
	global_load_dwordx4 v[134:137], v[36:37], off offset:1024
	global_load_dwordx4 v[138:141], v[32:33], off offset:1024
	global_load_dwordx4 v[142:145], v[32:33], off
	global_load_dwordx4 v[146:149], v[36:37], off
	s_waitcnt lgkmcnt(0)
	v_add_f32_e32 v9, v9, v80
	v_fmamk_f32 v9, v9, 0x3a000000, v165
	v_rsq_f32_e32 v252, v9
	s_nop 1
	s_nop 0
	s_nop 1
	s_nop 1
	s_nop 1
	v_lshlrev_b64 v[80:81], 13, v[56:57]
	v_mov_b32_e32 v56, v252
	v_pk_mul_f32 v[60:61], v[60:61], v[56:57] op_sel_hi:[1,0]
	v_pk_mul_f32 v[58:59], v[58:59], v[56:57] op_sel_hi:[1,0]
	v_pk_mul_f32 v[78:79], v[78:79], v[56:57] op_sel_hi:[1,0]
	v_pk_mul_f32 v[64:65], v[64:65], v[56:57] op_sel_hi:[1,0]
	v_pk_mul_f32 v[76:77], v[76:77], v[56:57] op_sel_hi:[1,0]
	v_pk_mul_f32 v[74:75], v[74:75], v[56:57] op_sel_hi:[1,0]
	v_pk_mul_f32 v[154:155], v[2:3], v[56:57] op_sel_hi:[1,0]
	v_pk_mul_f32 v[156:157], v[0:1], v[56:57] op_sel_hi:[1,0]
	v_pk_mul_f32 v[82:83], v[84:85], v[56:57] op_sel_hi:[1,0]
	v_pk_mul_f32 v[62:63], v[62:63], v[56:57] op_sel_hi:[1,0]
	v_pk_mul_f32 v[66:67], v[66:67], v[56:57] op_sel_hi:[1,0]
	v_pk_mul_f32 v[72:73], v[72:73], v[56:57] op_sel_hi:[1,0]
	v_pk_mul_f32 v[84:85], v[70:71], v[56:57] op_sel_hi:[1,0]
	v_pk_mul_f32 v[68:69], v[68:69], v[56:57] op_sel_hi:[1,0]
	v_pk_mul_f32 v[150:151], v[6:7], v[56:57] op_sel_hi:[1,0]
	v_pk_mul_f32 v[152:153], v[4:5], v[56:57] op_sel_hi:[1,0]
	v_lshl_add_u64 v[80:81], v[52:53], 0, v[80:81]
	s_waitcnt vmcnt(14)
	v_pk_fma_f32 v[2:3], v[92:93], v[58:59], v[88:89]
	v_pk_fma_f32 v[0:1], v[90:91], v[60:61], v[86:87]
	s_waitcnt vmcnt(12)
	v_pk_fma_f32 v[6:7], v[100:101], v[62:63], v[96:97]
	v_pk_fma_f32 v[4:5], v[98:99], v[82:83], v[94:95]
	s_waitcnt vmcnt(10)
	v_pk_fma_f32 v[58:59], v[108:109], v[64:65], v[104:105]
	v_pk_fma_f32 v[56:57], v[106:107], v[78:79], v[102:103]
	s_waitcnt vmcnt(8)
	v_pk_fma_f32 v[60:61], v[114:115], v[76:77], v[110:111]
	v_pk_fma_f32 v[62:63], v[116:117], v[66:67], v[112:113]
	s_waitcnt vmcnt(6)
	v_pk_fma_f32 v[64:65], v[118:119], v[74:75], v[122:123]
	v_pk_fma_f32 v[66:67], v[120:121], v[72:73], v[124:125]
	s_waitcnt vmcnt(4)
	v_pk_fma_f32 v[70:71], v[132:133], v[68:69], v[128:129]
	v_pk_fma_f32 v[68:69], v[130:131], v[84:85], v[126:127]
	s_waitcnt vmcnt(2)
	v_pk_fma_f32 v[74:75], v[136:137], v[152:153], v[140:141]
	v_pk_fma_f32 v[72:73], v[134:135], v[150:151], v[138:139]
	s_waitcnt vmcnt(0)
	v_pk_fma_f32 v[78:79], v[148:149], v[156:157], v[144:145]
	v_pk_fma_f32 v[76:77], v[146:147], v[154:155], v[142:143]
	global_store_dwordx4 v[80:81], v[76:79], off nt
	global_store_dwordx4 v[80:81], v[72:75], off offset:1024 nt
	global_store_dwordx4 v[80:81], v[68:71], off offset:2048 nt
	global_store_dwordx4 v[80:81], v[64:67], off offset:3072 nt
	s_nop 1
	v_add_co_u32_e32 v64, vcc, 0x1000, v80
	s_nop 1
	v_addc_co_u32_e32 v65, vcc, 0, v81, vcc
	global_store_dwordx4 v[64:65], v[60:63], off nt
	global_store_dwordx4 v[64:65], v[56:59], off offset:1024 nt
	global_store_dwordx4 v[64:65], v[4:7], off offset:2048 nt
	global_store_dwordx4 v[64:65], v[0:3], off offset:3072 nt
	s_branch .LBB0_4893
